# v43 plus removal of the mid-segment s_setprio 0/1 flip between the two MFMA halves of every K-loop segment
# speedup vs baseline: 1.0041x; 1.0041x over previous
; template <class Epi, class Sched, bool ALIGN_EPI = false, bool SP2 = false, bool A_TILED = false>
; __device__ __forceinline__ void gemm_phase(PG8_LAS unsigned char* lds, const Gemm g, const Sched& S, const Epi& E, const int wave_s) {
;     ...
;         constexpr bool PEEL = SP2 && !Epi::AFTER_DRAIN;
;         if constexpr (PEEL) {
;             const char* a1 = cA + kstepA; const char* a2 = cA + 2 * kstepA; const char* b2 = cB + 2 * kstep; const char* a3 = a2 + kstepA; const char* b3 = b2 + kstep;
;             PG8_ITER(PG8_MMAZ)
.Lpw_1:
	s_setprio 1
	s_barrier
	v_mfma_f32_16x16x32_bf16 v[88:91], v[0:3], v[56:59], 0
	v_mfma_f32_16x16x32_bf16 v[64:67], v[0:3], v[32:35], 0
	v_mfma_f32_16x16x32_bf16 v[68:71], v[8:11], v[32:35], 0
	v_mfma_f32_16x16x32_bf16 v[72:75], v[0:3], v[40:43], 0
	v_mfma_f32_16x16x32_bf16 v[76:79], v[8:11], v[40:43], 0
	v_mfma_f32_16x16x32_bf16 v[80:83], v[0:3], v[48:51], 0
	v_mfma_f32_16x16x32_bf16 v[84:87], v[8:11], v[48:51], 0
	v_mfma_f32_16x16x32_bf16 v[92:95], v[4:7], v[60:63], v[88:91]
	v_mfma_f32_16x16x32_bf16 v[88:91], v[8:11], v[56:59], 0
	v_mfma_f32_16x16x32_bf16 v[64:67], v[4:7], v[36:39], v[64:67]
	v_mfma_f32_16x16x32_bf16 v[68:71], v[12:15], v[36:39], v[68:71]
	v_mfma_f32_16x16x32_bf16 v[72:75], v[4:7], v[44:47], v[72:75]
	v_mfma_f32_16x16x32_bf16 v[76:79], v[12:15], v[44:47], v[76:79]
	v_mfma_f32_16x16x32_bf16 v[80:83], v[4:7], v[52:55], v[80:83]
	v_mfma_f32_16x16x32_bf16 v[84:87], v[12:15], v[52:55], v[84:87]
	v_mfma_f32_16x16x32_bf16 v[100:103], v[12:15], v[60:63], v[88:91]
	v_mfma_f32_16x16x32_bf16 v[88:91], v[16:19], v[32:35], 0
	v_mfma_f32_16x16x32_bf16 v[32:35], v[24:27], v[32:35], 0
	v_mfma_f32_16x16x32_bf16 v[108:111], v[20:23], v[36:39], v[88:91]
	v_mfma_f32_16x16x32_bf16 v[32:35], v[28:31], v[36:39], v[32:35]
	v_mfma_f32_16x16x32_bf16 v[36:39], v[16:19], v[40:43], 0
	v_mfma_f32_16x16x32_bf16 v[40:43], v[24:27], v[40:43], 0
	v_mfma_f32_16x16x32_bf16 v[36:39], v[20:23], v[44:47], v[36:39]
	v_mfma_f32_16x16x32_bf16 v[40:43], v[28:31], v[44:47], v[40:43]
	v_mfma_f32_16x16x32_bf16 v[44:47], v[16:19], v[48:51], 0
	v_mfma_f32_16x16x32_bf16 v[48:51], v[24:27], v[48:51], 0
	v_mfma_f32_16x16x32_bf16 v[44:47], v[20:23], v[52:55], v[44:47]
	v_mfma_f32_16x16x32_bf16 v[52:55], v[28:31], v[52:55], v[48:51]
	v_mfma_f32_16x16x32_bf16 v[48:51], v[16:19], v[56:59], 0
	v_mfma_f32_16x16x32_bf16 v[152:155], v[20:23], v[60:63], v[48:51]
	v_mfma_f32_16x16x32_bf16 v[48:51], v[24:27], v[56:59], 0
	v_mfma_f32_16x16x32_bf16 v[156:159], v[28:31], v[60:63], v[48:51]
	s_barrier
	s_setprio 0
	s_add_i32 s55, s45, s15
	v_lshl_add_u64 v[146:147], s[80:81], 0, v[128:129]
	s_add_i32 s56, s55, 0x2000
	v_lshl_add_u64 v[120:121], v[146:147], 0, s[68:69]
	s_mov_b32 m0, s55
	v_lshl_add_u64 v[252:253], s[80:81], 0, v[130:131]
	s_add_u32 s58, s80, 0x80100
	ds_read_b128 v[48:51], v151 offset:16384
	ds_read_b128 v[56:59], v151 offset:17408
	ds_read_b128 v[60:63], v151 offset:18432
	ds_read_b128 v[88:91], v151 offset:19456
	ds_read_b128 v[96:99], v151 offset:20480
	ds_read_b128 v[104:107], v151 offset:21504
	ds_read_b128 v[112:115], v151 offset:22528
	ds_read_b128 v[116:119], v151 offset:23552
	global_load_lds_dwordx4 v[120:121], off
	v_lshl_add_u64 v[120:121], v[252:253], 0, s[68:69]
	s_mov_b32 m0, s56
	s_addc_u32 s59, s81, 0
	s_add_i32 s57, s46, s15
	global_load_lds_dwordx4 v[120:121], off
	v_lshl_add_u64 v[120:121], s[58:59], 0, v[128:129]
	s_mov_b32 m0, s57
	v_lshl_add_u64 v[140:141], s[82:83], 0, v[134:135]
	global_load_lds_dwordx4 v128, s[58:59]
	v_lshl_add_u64 v[120:121], s[58:59], 0, v[130:131]
	s_add_i32 s58, s57, 0x2000
	s_mov_b32 m0, s58
	v_lshl_add_u64 v[142:143], s[82:83], 0, v[132:133]
	global_load_lds_dwordx4 v[120:121], off
	v_lshl_add_u64 v[120:121], v[140:141], 0, s[68:69]
	s_mov_b32 m0, s23
	s_nop 0
	global_load_lds_dwordx4 v[120:121], off
	v_lshl_add_u64 v[120:121], v[142:143], 0, s[68:69]
	s_mov_b32 m0, s36
	s_nop 0
	global_load_lds_dwordx4 v[120:121], off
	s_waitcnt vmcnt(24) lgkmcnt(0)
	s_cmp_lg_u32 s98, 0
	s_cbranch_scc1 .Lpw_2
	s_waitcnt vmcnt(8)
.Lpw_2:
	s_setprio 1
	s_barrier
	v_mfma_f32_16x16x32_bf16 v[120:123], v[0:3], v[48:51], 0
	v_mfma_f32_16x16x32_bf16 v[160:163], v[4:7], v[56:59], v[120:123]
	v_mfma_f32_16x16x32_bf16 v[120:123], v[8:11], v[48:51], 0
	v_mfma_f32_16x16x32_bf16 v[164:167], v[12:15], v[56:59], v[120:123]
	v_mfma_f32_16x16x32_bf16 v[120:123], v[0:3], v[60:63], 0
	v_mfma_f32_16x16x32_bf16 v[168:171], v[4:7], v[88:91], v[120:123]
	v_mfma_f32_16x16x32_bf16 v[120:123], v[8:11], v[60:63], 0
	v_mfma_f32_16x16x32_bf16 v[172:175], v[12:15], v[88:91], v[120:123]
	v_mfma_f32_16x16x32_bf16 v[120:123], v[0:3], v[96:99], 0
	v_mfma_f32_16x16x32_bf16 v[0:3], v[0:3], v[112:115], 0
	v_mfma_f32_16x16x32_bf16 v[176:179], v[4:7], v[104:107], v[120:123]
	v_mfma_f32_16x16x32_bf16 v[0:3], v[4:7], v[116:119], v[0:3]
	v_mfma_f32_16x16x32_bf16 v[4:7], v[8:11], v[112:115], 0
	v_mfma_f32_16x16x32_bf16 v[120:123], v[8:11], v[96:99], 0
	v_mfma_f32_16x16x32_bf16 v[4:7], v[12:15], v[116:119], v[4:7]
	v_mfma_f32_16x16x32_bf16 v[180:183], v[12:15], v[104:107], v[120:123]
	v_mfma_f32_16x16x32_bf16 v[8:11], v[16:19], v[48:51], 0
	v_mfma_f32_16x16x32_bf16 v[12:15], v[20:23], v[56:59], v[8:11]
	v_mfma_f32_16x16x32_bf16 v[8:11], v[24:27], v[48:51], 0
	v_mfma_f32_16x16x32_bf16 v[184:187], v[28:31], v[56:59], v[8:11]
	v_mfma_f32_16x16x32_bf16 v[8:11], v[16:19], v[60:63], 0
	v_mfma_f32_16x16x32_bf16 v[188:191], v[20:23], v[88:91], v[8:11]
	v_mfma_f32_16x16x32_bf16 v[8:11], v[24:27], v[60:63], 0
	v_mfma_f32_16x16x32_bf16 v[192:195], v[28:31], v[88:91], v[8:11]
	v_mfma_f32_16x16x32_bf16 v[8:11], v[16:19], v[96:99], 0
	v_mfma_f32_16x16x32_bf16 v[196:199], v[20:23], v[104:107], v[8:11]
	v_mfma_f32_16x16x32_bf16 v[8:11], v[24:27], v[96:99], 0
	v_mfma_f32_16x16x32_bf16 v[200:203], v[28:31], v[104:107], v[8:11]
	v_mfma_f32_16x16x32_bf16 v[8:11], v[16:19], v[112:115], 0
	v_mfma_f32_16x16x32_bf16 v[204:207], v[20:23], v[116:119], v[8:11]
	v_mfma_f32_16x16x32_bf16 v[8:11], v[24:27], v[112:115], 0
	v_mfma_f32_16x16x32_bf16 v[208:211], v[28:31], v[116:119], v[8:11]
	s_barrier
; template <class Epi, class Sched, bool ALIGN_EPI = false, bool SP2 = false, bool A_TILED = false>
; __device__ __forceinline__ void gemm_phase(PG8_LAS unsigned char* lds, const Gemm g, const Sched& S, const Epi& E, const int wave_s) {
;     ...
;         for (int t = PEEL ? 2 : 0; t < nt; t += 2) {
;             const bool last = (t == nt - 2);
;             const char* a1 = cA + (size_t)(t + 1) * kstepA;
;             const char* a2 = last ? nA : cA + (size_t)(t + 2) * kstepA; const char* b2 = last ? nB : cB + (size_t)(t + 2) * kstep;
;             const char* a3 = a2 + kstepA; const char* b3 = b2 + kstep;
	s_setprio 0
	s_add_i32 s59, 0, 0x18000
	s_add_i32 s73, 0, 0x1c000
	v_add_u32_e32 v144, s59, v148
	v_add_u32_e32 v145, s73, v148
	s_nop 0
	ds_read_b128 v[8:11], v144
	ds_read_b128 v[20:23], v144 offset:1024
	ds_read_b128 v[28:31], v144 offset:2048
	ds_read_b128 v[212:215], v144 offset:3072
	ds_read_b128 v[216:219], v145
	ds_read_b128 v[220:223], v145 offset:1024
	ds_read_b128 v[224:227], v145 offset:2048
	ds_read_b128 v[228:231], v145 offset:3072
	s_add_u32 s84, s82, 0x80100
	s_addc_u32 s85, s83, 0
	s_mov_b32 m0, s37
	v_lshl_add_u64 v[48:49], s[84:85], 0, v[134:135]
	ds_read_b128 v[16:19], v151 offset:32768
	ds_read_b128 v[24:27], v151 offset:33792
	ds_read_b128 v[60:63], v151 offset:34816
	ds_read_b128 v[232:235], v151 offset:35840
	ds_read_b128 v[236:239], v151 offset:36864
	ds_read_b128 v[240:243], v151 offset:37888
	ds_read_b128 v[244:247], v151 offset:38912
	ds_read_b128 v[248:251], v151 offset:39936
	global_load_lds_dwordx4 v134, s[84:85]
	v_lshl_add_u64 v[48:49], s[84:85], 0, v[132:133]
	s_mov_b32 m0, s38
	s_nop 0
	global_load_lds_dwordx4 v132, s[84:85]
	s_waitcnt vmcnt(8) lgkmcnt(0)
	s_setprio 1
	s_barrier
	v_mfma_f32_16x16x32_bf16 v[48:51], v[8:11], v[16:19], v[64:67]
	v_mfma_f32_16x16x32_bf16 v[120:123], v[20:23], v[24:27], v[48:51]
	v_mfma_f32_16x16x32_bf16 v[48:51], v[28:31], v[16:19], v[68:71]
	v_mfma_f32_16x16x32_bf16 v[112:115], v[212:215], v[24:27], v[48:51]
	v_mfma_f32_16x16x32_bf16 v[48:51], v[8:11], v[60:63], v[72:75]
	v_mfma_f32_16x16x32_bf16 v[104:107], v[20:23], v[232:235], v[48:51]
	v_mfma_f32_16x16x32_bf16 v[48:51], v[28:31], v[60:63], v[76:79]
	v_mfma_f32_16x16x32_bf16 v[96:99], v[212:215], v[232:235], v[48:51]
	v_mfma_f32_16x16x32_bf16 v[48:51], v[8:11], v[236:239], v[80:83]
	v_mfma_f32_16x16x32_bf16 v[88:91], v[20:23], v[240:243], v[48:51]
	v_mfma_f32_16x16x32_bf16 v[48:51], v[28:31], v[236:239], v[84:87]
	v_mfma_f32_16x16x32_bf16 v[80:83], v[212:215], v[240:243], v[48:51]
	v_mfma_f32_16x16x32_bf16 v[48:51], v[8:11], v[244:247], v[92:95]
	v_mfma_f32_16x16x32_bf16 v[56:59], v[20:23], v[248:251], v[48:51]
	v_mfma_f32_16x16x32_bf16 v[48:51], v[28:31], v[244:247], v[100:103]
	v_mfma_f32_16x16x32_bf16 v[48:51], v[212:215], v[248:251], v[48:51]
	v_mfma_f32_16x16x32_bf16 v[64:67], v[216:219], v[16:19], v[108:111]
	v_mfma_f32_16x16x32_bf16 v[16:19], v[224:227], v[16:19], v[32:35]
	v_mfma_f32_16x16x32_bf16 v[116:119], v[228:231], v[24:27], v[16:19]
	v_mfma_f32_16x16x32_bf16 v[16:19], v[216:219], v[60:63], v[36:39]
	v_mfma_f32_16x16x32_bf16 v[108:111], v[220:223], v[232:235], v[16:19]
	v_mfma_f32_16x16x32_bf16 v[16:19], v[224:227], v[60:63], v[40:43]
	v_mfma_f32_16x16x32_bf16 v[100:103], v[228:231], v[232:235], v[16:19]
	v_mfma_f32_16x16x32_bf16 v[16:19], v[216:219], v[236:239], v[44:47]
	v_mfma_f32_16x16x32_bf16 v[92:95], v[220:223], v[240:243], v[16:19]
	v_mfma_f32_16x16x32_bf16 v[16:19], v[224:227], v[236:239], v[52:55]
	v_mfma_f32_16x16x32_bf16 v[84:87], v[228:231], v[240:243], v[16:19]
	v_mfma_f32_16x16x32_bf16 v[16:19], v[216:219], v[244:247], v[152:155]
	v_mfma_f32_16x16x32_bf16 v[60:63], v[220:223], v[248:251], v[16:19]
	v_mfma_f32_16x16x32_bf16 v[16:19], v[224:227], v[244:247], v[156:159]
	v_mfma_f32_16x16x32_bf16 v[124:127], v[220:223], v[24:27], v[64:67]
	v_mfma_f32_16x16x32_bf16 v[52:55], v[228:231], v[248:251], v[16:19]
	s_barrier
	s_setprio 0
	s_add_i32 s59, s59, s15
	s_add_i32 s71, s59, 0x2000
	s_nop 1
	v_lshl_add_u64 v[16:17], v[146:147], 0, s[66:67]
	s_mov_b32 m0, s59
	s_add_u32 s84, s80, 0x80180
	ds_read_b128 v[36:39], v151 offset:49152
	ds_read_b128 v[44:47], v151 offset:50176
	ds_read_b128 v[152:155], v151 offset:51200
	ds_read_b128 v[156:159], v151 offset:52224
	ds_read_b128 v[232:235], v151 offset:53248
	ds_read_b128 v[236:239], v151 offset:54272
	ds_read_b128 v[240:243], v151 offset:55296
	ds_read_b128 v[244:247], v151 offset:56320
	global_load_lds_dwordx4 v[16:17], off
	v_lshl_add_u64 v[16:17], v[252:253], 0, s[66:67]
	s_mov_b32 m0, s71
	s_addc_u32 s85, s81, 0
	s_add_i32 s73, s73, s15
	global_load_lds_dwordx4 v[16:17], off
	v_lshl_add_u64 v[16:17], s[84:85], 0, v[128:129]
	s_mov_b32 m0, s73
	s_add_i32 s79, s73, 0x2000
	global_load_lds_dwordx4 v128, s[84:85]
	v_lshl_add_u64 v[16:17], s[84:85], 0, v[130:131]
	s_mov_b32 m0, s79
	s_nop 0
	global_load_lds_dwordx4 v130, s[84:85]
	v_lshl_add_u64 v[16:17], v[140:141], 0, s[66:67]
	s_mov_b32 m0, s43
	s_nop 0
	global_load_lds_dwordx4 v[16:17], off
	v_lshl_add_u64 v[16:17], v[142:143], 0, s[66:67]
	s_mov_b32 m0, s44
	s_nop 0
	global_load_lds_dwordx4 v[16:17], off
	s_waitcnt vmcnt(8) lgkmcnt(0)
	s_setprio 1
	s_barrier
	v_mfma_f32_16x16x32_bf16 v[16:19], v[8:11], v[36:39], v[160:163]
	v_mfma_f32_16x16x32_bf16 v[72:75], v[20:23], v[44:47], v[16:19]
	v_mfma_f32_16x16x32_bf16 v[16:19], v[28:31], v[36:39], v[164:167]
	v_mfma_f32_16x16x32_bf16 v[64:67], v[212:215], v[44:47], v[16:19]
	v_mfma_f32_16x16x32_bf16 v[16:19], v[8:11], v[152:155], v[168:171]
	v_mfma_f32_16x16x32_bf16 v[40:43], v[20:23], v[156:159], v[16:19]
	v_mfma_f32_16x16x32_bf16 v[16:19], v[28:31], v[152:155], v[172:175]
	v_mfma_f32_16x16x32_bf16 v[32:35], v[212:215], v[156:159], v[16:19]
	v_mfma_f32_16x16x32_bf16 v[16:19], v[8:11], v[232:235], v[176:179]
	v_mfma_f32_16x16x32_bf16 v[0:3], v[8:11], v[240:243], v[0:3]
	v_mfma_f32_16x16x32_bf16 v[24:27], v[20:23], v[236:239], v[16:19]
	v_mfma_f32_16x16x32_bf16 v[16:19], v[28:31], v[232:235], v[180:183]
	v_mfma_f32_16x16x32_bf16 v[8:11], v[20:23], v[244:247], v[0:3]
	v_mfma_f32_16x16x32_bf16 v[0:3], v[28:31], v[240:243], v[4:7]
	v_mfma_f32_16x16x32_bf16 v[16:19], v[212:215], v[236:239], v[16:19]
	v_mfma_f32_16x16x32_bf16 v[0:3], v[212:215], v[244:247], v[0:3]
	v_mfma_f32_16x16x32_bf16 v[4:7], v[216:219], v[36:39], v[12:15]
	v_mfma_f32_16x16x32_bf16 v[76:79], v[220:223], v[44:47], v[4:7]
	v_mfma_f32_16x16x32_bf16 v[4:7], v[224:227], v[36:39], v[184:187]
	v_mfma_f32_16x16x32_bf16 v[68:71], v[228:231], v[44:47], v[4:7]
	v_mfma_f32_16x16x32_bf16 v[4:7], v[216:219], v[152:155], v[188:191]
	v_mfma_f32_16x16x32_bf16 v[44:47], v[220:223], v[156:159], v[4:7]
	v_mfma_f32_16x16x32_bf16 v[4:7], v[224:227], v[152:155], v[192:195]
	v_mfma_f32_16x16x32_bf16 v[36:39], v[228:231], v[156:159], v[4:7]
	v_mfma_f32_16x16x32_bf16 v[4:7], v[216:219], v[232:235], v[196:199]
	v_mfma_f32_16x16x32_bf16 v[28:31], v[220:223], v[236:239], v[4:7]
	v_mfma_f32_16x16x32_bf16 v[4:7], v[224:227], v[232:235], v[200:203]
	v_mfma_f32_16x16x32_bf16 v[20:23], v[228:231], v[236:239], v[4:7]
	v_mfma_f32_16x16x32_bf16 v[4:7], v[216:219], v[240:243], v[204:207]
	v_mfma_f32_16x16x32_bf16 v[12:15], v[220:223], v[244:247], v[4:7]
	v_mfma_f32_16x16x32_bf16 v[4:7], v[224:227], v[240:243], v[208:211]
	v_mfma_f32_16x16x32_bf16 v[4:7], v[228:231], v[244:247], v[4:7]
	s_barrier
	s_setprio 0
	s_add_u32 s88, s80, 0x200
	s_addc_u32 s89, s81, 0
	s_add_u32 s80, s82, 0x80180
	s_addc_u32 s81, s83, 0
	s_mov_b32 s90, 0
; #define PG8_MMA(ai, bj, At, Bt) do { __builtin_amdgcn_s_setprio(1); _Pragma("unroll") for (int m = 0; m < 4; ++m) _Pragma("unroll") for (int n = 0; n < 2; ++n) _Pragma("unroll") for (int k = 0; k < 2; ++k) \
;         acc[ai][bj][m][n] = __builtin_amdgcn_mfma_f32_16x16x32_bf16(Bt[n][k], At[m][k], acc[ai][bj][m][n], 0, 0, 0); __builtin_amdgcn_s_setprio(0); } while (0)
; template <class Epi, class Sched, bool ALIGN_EPI = false, bool SP2 = false, bool A_TILED = false>
; __device__ __forceinline__ void gemm_phase(PG8_LAS unsigned char* lds, const Gemm g, const Sched& S, const Epi& E, const int wave_s) {
;     ...
;         for (int t = PEEL ? 2 : 0; t < nt; t += 2) {
;             const bool last = (t == nt - 2);
;             const char* a1 = cA + (size_t)(t + 1) * kstepA;
;             const char* a2 = last ? nA : cA + (size_t)(t + 2) * kstepA; const char* b2 = last ? nB : cB + (size_t)(t + 2) * kstep;
;             const char* a3 = a2 + kstepA; const char* b3 = b2 + kstep;
;             if (last && has_next) S.a_ready(nxt);
;             if constexpr (SP2) {
;             PG8_ITER(PG8_MMA)
.LBB0_777:
	ds_read_b128 v[152:155], v149
	ds_read_b128 v[156:159], v149 offset:1024
	ds_read_b128 v[160:163], v149 offset:2048
	ds_read_b128 v[164:167], v149 offset:3072
	ds_read_b128 v[168:171], v150
	ds_read_b128 v[172:175], v150 offset:1024
	ds_read_b128 v[176:179], v150 offset:2048
	ds_read_b128 v[180:183], v150 offset:3072
	s_add_u32 s82, s80, 0xfff80080
	s_addc_u32 s83, s81, -1
	s_cmp_eq_u32 s90, 28
	s_cselect_b32 s85, s51, s83
	s_cselect_b32 s84, s52, s82
	s_cselect_b32 s83, s53, s89
	s_cselect_b32 s82, s54, s88
	s_mov_b32 m0, s48
	v_lshl_add_u64 v[140:141], s[80:81], 0, v[138:139]
	ds_read_b128 v[184:187], v151
	ds_read_b128 v[188:191], v151 offset:1024
	ds_read_b128 v[192:195], v151 offset:2048
	ds_read_b128 v[196:199], v151 offset:3072
	ds_read_b128 v[200:203], v151 offset:4096
	ds_read_b128 v[204:207], v151 offset:5120
	ds_read_b128 v[208:211], v151 offset:6144
	ds_read_b128 v[212:215], v151 offset:7168
	global_load_lds_dwordx4 v138, s[80:81]
	v_lshl_add_u64 v[140:141], s[80:81], 0, v[136:137]
	s_mov_b32 m0, s49
	s_nop 0
	global_load_lds_dwordx4 v136, s[80:81]
	s_waitcnt vmcnt(8) lgkmcnt(0)
	s_setprio 1
	s_barrier
	v_mfma_f32_16x16x32_bf16 v[120:123], v[152:155], v[184:187], v[120:123]
	v_mfma_f32_16x16x32_bf16 v[112:115], v[160:163], v[184:187], v[112:115]
	v_mfma_f32_16x16x32_bf16 v[104:107], v[152:155], v[192:195], v[104:107]
	v_mfma_f32_16x16x32_bf16 v[96:99], v[160:163], v[192:195], v[96:99]
	v_mfma_f32_16x16x32_bf16 v[88:91], v[152:155], v[200:203], v[88:91]
	v_mfma_f32_16x16x32_bf16 v[80:83], v[160:163], v[200:203], v[80:83]
	v_mfma_f32_16x16x32_bf16 v[56:59], v[152:155], v[208:211], v[56:59]
	v_mfma_f32_16x16x32_bf16 v[48:51], v[160:163], v[208:211], v[48:51]
	v_mfma_f32_16x16x32_bf16 v[120:123], v[156:159], v[188:191], v[120:123]
	v_mfma_f32_16x16x32_bf16 v[112:115], v[164:167], v[188:191], v[112:115]
	v_mfma_f32_16x16x32_bf16 v[104:107], v[156:159], v[196:199], v[104:107]
	v_mfma_f32_16x16x32_bf16 v[96:99], v[164:167], v[196:199], v[96:99]
	v_mfma_f32_16x16x32_bf16 v[88:91], v[156:159], v[204:207], v[88:91]
	v_mfma_f32_16x16x32_bf16 v[80:83], v[164:167], v[204:207], v[80:83]
	v_mfma_f32_16x16x32_bf16 v[56:59], v[156:159], v[212:215], v[56:59]
	v_mfma_f32_16x16x32_bf16 v[48:51], v[164:167], v[212:215], v[48:51]
	v_mfma_f32_16x16x32_bf16 v[124:127], v[168:171], v[184:187], v[124:127]
	v_mfma_f32_16x16x32_bf16 v[116:119], v[176:179], v[184:187], v[116:119]
	v_mfma_f32_16x16x32_bf16 v[108:111], v[168:171], v[192:195], v[108:111]
	v_mfma_f32_16x16x32_bf16 v[100:103], v[176:179], v[192:195], v[100:103]
	v_mfma_f32_16x16x32_bf16 v[92:95], v[168:171], v[200:203], v[92:95]
	v_mfma_f32_16x16x32_bf16 v[84:87], v[176:179], v[200:203], v[84:87]
	v_mfma_f32_16x16x32_bf16 v[60:63], v[168:171], v[208:211], v[60:63]
	v_mfma_f32_16x16x32_bf16 v[52:55], v[176:179], v[208:211], v[52:55]
	v_mfma_f32_16x16x32_bf16 v[124:127], v[172:175], v[188:191], v[124:127]
	v_mfma_f32_16x16x32_bf16 v[116:119], v[180:183], v[188:191], v[116:119]
	v_mfma_f32_16x16x32_bf16 v[108:111], v[172:175], v[196:199], v[108:111]
	v_mfma_f32_16x16x32_bf16 v[100:103], v[180:183], v[196:199], v[100:103]
	v_mfma_f32_16x16x32_bf16 v[92:95], v[172:175], v[204:207], v[92:95]
	v_mfma_f32_16x16x32_bf16 v[84:87], v[180:183], v[204:207], v[84:87]
	v_mfma_f32_16x16x32_bf16 v[60:63], v[172:175], v[212:215], v[60:63]
	v_mfma_f32_16x16x32_bf16 v[52:55], v[180:183], v[212:215], v[52:55]
	s_barrier
	s_setprio 0
	s_mov_b32 m0, s55
	v_lshl_add_u64 v[140:141], s[82:83], 0, v[128:129]
	s_add_u32 s94, s82, 0x80000
	ds_read_b128 v[184:187], v151 offset:16384
	ds_read_b128 v[188:191], v151 offset:17408
	ds_read_b128 v[192:195], v151 offset:18432
	ds_read_b128 v[196:199], v151 offset:19456
	ds_read_b128 v[200:203], v151 offset:20480
	ds_read_b128 v[204:207], v151 offset:21504
	ds_read_b128 v[208:211], v151 offset:22528
	ds_read_b128 v[212:215], v151 offset:23552
	global_load_lds_dwordx4 v128, s[82:83]
	v_lshl_add_u64 v[142:143], s[82:83], 0, v[130:131]
	s_mov_b32 m0, s56
	s_addc_u32 s95, s83, 0
	global_load_lds_dwordx4 v130, s[82:83]
	v_lshl_add_u64 v[146:147], s[94:95], 0, v[128:129]
	s_mov_b32 m0, s57
	v_lshl_add_u64 v[216:217], s[84:85], 0, v[132:133]
	global_load_lds_dwordx4 v128, s[94:95]
	v_lshl_add_u64 v[146:147], s[94:95], 0, v[130:131]
	s_mov_b32 m0, s58
	s_nop 0
	global_load_lds_dwordx4 v130, s[94:95]
	v_lshl_add_u64 v[146:147], s[84:85], 0, v[134:135]
	s_mov_b32 m0, s23
	s_nop 0
	global_load_lds_dwordx4 v134, s[84:85]
	s_mov_b32 m0, s36
	s_nop 0
	global_load_lds_dwordx4 v132, s[84:85]
	s_waitcnt vmcnt(8) lgkmcnt(0)
	s_setprio 1
	s_barrier
	v_mfma_f32_16x16x32_bf16 v[72:75], v[152:155], v[184:187], v[72:75]
	v_mfma_f32_16x16x32_bf16 v[64:67], v[160:163], v[184:187], v[64:67]
	v_mfma_f32_16x16x32_bf16 v[40:43], v[152:155], v[192:195], v[40:43]
	v_mfma_f32_16x16x32_bf16 v[32:35], v[160:163], v[192:195], v[32:35]
	v_mfma_f32_16x16x32_bf16 v[24:27], v[152:155], v[200:203], v[24:27]
	v_mfma_f32_16x16x32_bf16 v[16:19], v[160:163], v[200:203], v[16:19]
	v_mfma_f32_16x16x32_bf16 v[8:11], v[152:155], v[208:211], v[8:11]
	v_mfma_f32_16x16x32_bf16 v[0:3], v[160:163], v[208:211], v[0:3]
	v_mfma_f32_16x16x32_bf16 v[72:75], v[156:159], v[188:191], v[72:75]
	v_mfma_f32_16x16x32_bf16 v[64:67], v[164:167], v[188:191], v[64:67]
	v_mfma_f32_16x16x32_bf16 v[40:43], v[156:159], v[196:199], v[40:43]
	v_mfma_f32_16x16x32_bf16 v[32:35], v[164:167], v[196:199], v[32:35]
	v_mfma_f32_16x16x32_bf16 v[24:27], v[156:159], v[204:207], v[24:27]
	v_mfma_f32_16x16x32_bf16 v[16:19], v[164:167], v[204:207], v[16:19]
	v_mfma_f32_16x16x32_bf16 v[8:11], v[156:159], v[212:215], v[8:11]
	v_mfma_f32_16x16x32_bf16 v[0:3], v[164:167], v[212:215], v[0:3]
	v_mfma_f32_16x16x32_bf16 v[76:79], v[168:171], v[184:187], v[76:79]
	v_mfma_f32_16x16x32_bf16 v[68:71], v[176:179], v[184:187], v[68:71]
	v_mfma_f32_16x16x32_bf16 v[44:47], v[168:171], v[192:195], v[44:47]
	v_mfma_f32_16x16x32_bf16 v[36:39], v[176:179], v[192:195], v[36:39]
	v_mfma_f32_16x16x32_bf16 v[28:31], v[168:171], v[200:203], v[28:31]
	v_mfma_f32_16x16x32_bf16 v[20:23], v[176:179], v[200:203], v[20:23]
	v_mfma_f32_16x16x32_bf16 v[12:15], v[168:171], v[208:211], v[12:15]
	v_mfma_f32_16x16x32_bf16 v[4:7], v[176:179], v[208:211], v[4:7]
	v_mfma_f32_16x16x32_bf16 v[76:79], v[172:175], v[188:191], v[76:79]
	v_mfma_f32_16x16x32_bf16 v[68:71], v[180:183], v[188:191], v[68:71]
	v_mfma_f32_16x16x32_bf16 v[44:47], v[172:175], v[196:199], v[44:47]
	v_mfma_f32_16x16x32_bf16 v[36:39], v[180:183], v[196:199], v[36:39]
	v_mfma_f32_16x16x32_bf16 v[28:31], v[172:175], v[204:207], v[28:31]
	v_mfma_f32_16x16x32_bf16 v[20:23], v[180:183], v[204:207], v[20:23]
	v_mfma_f32_16x16x32_bf16 v[12:15], v[172:175], v[212:215], v[12:15]
	v_mfma_f32_16x16x32_bf16 v[4:7], v[180:183], v[212:215], v[4:7]
	s_barrier
	s_setprio 0
	ds_read_b128 v[152:155], v144
	ds_read_b128 v[156:159], v144 offset:1024
	ds_read_b128 v[160:163], v144 offset:2048
	ds_read_b128 v[164:167], v144 offset:3072
	ds_read_b128 v[168:171], v145
	ds_read_b128 v[172:175], v145 offset:1024
	ds_read_b128 v[176:179], v145 offset:2048
	ds_read_b128 v[180:183], v145 offset:3072
	s_add_u32 s84, s84, 0x80000
	s_addc_u32 s85, s85, 0
	s_mov_b32 m0, s37
	v_lshl_add_u64 v[218:219], s[84:85], 0, v[134:135]
	ds_read_b128 v[184:187], v151 offset:32768
	ds_read_b128 v[188:191], v151 offset:33792
	ds_read_b128 v[192:195], v151 offset:34816
	ds_read_b128 v[196:199], v151 offset:35840
	ds_read_b128 v[200:203], v151 offset:36864
	ds_read_b128 v[204:207], v151 offset:37888
	ds_read_b128 v[208:211], v151 offset:38912
	ds_read_b128 v[212:215], v151 offset:39936
	global_load_lds_dwordx4 v134, s[84:85]
	v_lshl_add_u64 v[218:219], s[84:85], 0, v[132:133]
	s_mov_b32 m0, s38
	s_nop 0
	global_load_lds_dwordx4 v132, s[84:85]
	s_waitcnt vmcnt(8) lgkmcnt(0)
	s_setprio 1
	s_barrier
	v_mfma_f32_16x16x32_bf16 v[120:123], v[152:155], v[184:187], v[120:123]
	v_mfma_f32_16x16x32_bf16 v[112:115], v[160:163], v[184:187], v[112:115]
	v_mfma_f32_16x16x32_bf16 v[104:107], v[152:155], v[192:195], v[104:107]
	v_mfma_f32_16x16x32_bf16 v[96:99], v[160:163], v[192:195], v[96:99]
	v_mfma_f32_16x16x32_bf16 v[88:91], v[152:155], v[200:203], v[88:91]
	v_mfma_f32_16x16x32_bf16 v[80:83], v[160:163], v[200:203], v[80:83]
	v_mfma_f32_16x16x32_bf16 v[56:59], v[152:155], v[208:211], v[56:59]
	v_mfma_f32_16x16x32_bf16 v[48:51], v[160:163], v[208:211], v[48:51]
	v_mfma_f32_16x16x32_bf16 v[120:123], v[156:159], v[188:191], v[120:123]
	v_mfma_f32_16x16x32_bf16 v[112:115], v[164:167], v[188:191], v[112:115]
	v_mfma_f32_16x16x32_bf16 v[104:107], v[156:159], v[196:199], v[104:107]
	v_mfma_f32_16x16x32_bf16 v[96:99], v[164:167], v[196:199], v[96:99]
	v_mfma_f32_16x16x32_bf16 v[88:91], v[156:159], v[204:207], v[88:91]
	v_mfma_f32_16x16x32_bf16 v[80:83], v[164:167], v[204:207], v[80:83]
	v_mfma_f32_16x16x32_bf16 v[56:59], v[156:159], v[212:215], v[56:59]
	v_mfma_f32_16x16x32_bf16 v[48:51], v[164:167], v[212:215], v[48:51]
	v_mfma_f32_16x16x32_bf16 v[124:127], v[168:171], v[184:187], v[124:127]
	v_mfma_f32_16x16x32_bf16 v[116:119], v[176:179], v[184:187], v[116:119]
	v_mfma_f32_16x16x32_bf16 v[108:111], v[168:171], v[192:195], v[108:111]
	v_mfma_f32_16x16x32_bf16 v[100:103], v[176:179], v[192:195], v[100:103]
	v_mfma_f32_16x16x32_bf16 v[92:95], v[168:171], v[200:203], v[92:95]
	v_mfma_f32_16x16x32_bf16 v[84:87], v[176:179], v[200:203], v[84:87]
	v_mfma_f32_16x16x32_bf16 v[60:63], v[168:171], v[208:211], v[60:63]
	v_mfma_f32_16x16x32_bf16 v[52:55], v[176:179], v[208:211], v[52:55]
	v_mfma_f32_16x16x32_bf16 v[124:127], v[172:175], v[188:191], v[124:127]
	v_mfma_f32_16x16x32_bf16 v[116:119], v[180:183], v[188:191], v[116:119]
	v_mfma_f32_16x16x32_bf16 v[108:111], v[172:175], v[196:199], v[108:111]
	v_mfma_f32_16x16x32_bf16 v[100:103], v[180:183], v[196:199], v[100:103]
	v_mfma_f32_16x16x32_bf16 v[92:95], v[172:175], v[204:207], v[92:95]
	v_mfma_f32_16x16x32_bf16 v[84:87], v[180:183], v[204:207], v[84:87]
	v_mfma_f32_16x16x32_bf16 v[60:63], v[172:175], v[212:215], v[60:63]
	v_mfma_f32_16x16x32_bf16 v[52:55], v[180:183], v[212:215], v[52:55]
	s_barrier
; __device__ __forceinline__ int tid_now(int wave_s) { unsigned z = 0u; asm volatile("" : "+v"(z)); return (wave_s << 6) | (int)__builtin_amdgcn_mbcnt_hi(~0u, __builtin_amdgcn_mbcnt_lo(~0u, z)); }
; #define PG8_BAR __builtin_amdgcn_s_barrier()
; template <class Epi, class Sched, bool ALIGN_EPI = false, bool SP2 = false, bool A_TILED = false>
; __device__ __forceinline__ void gemm_phase(PG8_LAS unsigned char* lds, const Gemm g, const Sched& S, const Epi& E, const int wave_s) {
;     ...
;         if constexpr (ALIGN_EPI) { if (wr == 0) PG8_BAR; }
;         if constexpr (!Epi::AFTER_DRAIN) { int te = tid_now(wave_s); asm volatile("" : "+v"(te));
;             E(acc, cur, wr, wc, te & 15, (te & 63) >> 4); S.done(cur); }
;         if (!has_next) break;
;         cur = nxt; cA = nA; cB = nB; ++ui;
;         if constexpr (ALIGN_EPI) { if (wr == 1) PG8_BAR; }
	s_setprio 0
	s_mov_b32 m0, s59
	v_lshl_add_u64 v[140:141], v[140:141], 0, s[62:63]
	s_add_u32 s82, s82, 0x80080
	ds_read_b128 v[184:187], v151 offset:49152
	ds_read_b128 v[188:191], v151 offset:50176
	ds_read_b128 v[192:195], v151 offset:51200
	ds_read_b128 v[196:199], v151 offset:52224
	ds_read_b128 v[200:203], v151 offset:53248
	ds_read_b128 v[204:207], v151 offset:54272
	ds_read_b128 v[208:211], v151 offset:55296
	ds_read_b128 v[212:215], v151 offset:56320
	global_load_lds_dwordx4 v[140:141], off
	v_lshl_add_u64 v[140:141], v[142:143], 0, s[62:63]
	s_mov_b32 m0, s71
	s_addc_u32 s83, s83, 0
	global_load_lds_dwordx4 v[140:141], off
	v_lshl_add_u64 v[140:141], s[82:83], 0, v[128:129]
	s_mov_b32 m0, s73
	s_nop 0
	global_load_lds_dwordx4 v128, s[82:83]
	v_lshl_add_u64 v[140:141], s[82:83], 0, v[130:131]
	s_mov_b32 m0, s79
	s_nop 0
	global_load_lds_dwordx4 v130, s[82:83]
	v_lshl_add_u64 v[140:141], v[146:147], 0, s[62:63]
	s_mov_b32 m0, s43
	s_nop 0
	global_load_lds_dwordx4 v[140:141], off
	v_lshl_add_u64 v[140:141], v[216:217], 0, s[62:63]
	s_mov_b32 m0, s44
	s_nop 0
	global_load_lds_dwordx4 v[140:141], off
	s_waitcnt vmcnt(8) lgkmcnt(0)
	s_setprio 1
	s_barrier
	v_mfma_f32_16x16x32_bf16 v[72:75], v[152:155], v[184:187], v[72:75]
	v_mfma_f32_16x16x32_bf16 v[64:67], v[160:163], v[184:187], v[64:67]
	v_mfma_f32_16x16x32_bf16 v[40:43], v[152:155], v[192:195], v[40:43]
	v_mfma_f32_16x16x32_bf16 v[32:35], v[160:163], v[192:195], v[32:35]
	v_mfma_f32_16x16x32_bf16 v[24:27], v[152:155], v[200:203], v[24:27]
	v_mfma_f32_16x16x32_bf16 v[16:19], v[160:163], v[200:203], v[16:19]
	v_mfma_f32_16x16x32_bf16 v[8:11], v[152:155], v[208:211], v[8:11]
	v_mfma_f32_16x16x32_bf16 v[0:3], v[160:163], v[208:211], v[0:3]
	v_mfma_f32_16x16x32_bf16 v[72:75], v[156:159], v[188:191], v[72:75]
	v_mfma_f32_16x16x32_bf16 v[64:67], v[164:167], v[188:191], v[64:67]
	v_mfma_f32_16x16x32_bf16 v[40:43], v[156:159], v[196:199], v[40:43]
	v_mfma_f32_16x16x32_bf16 v[32:35], v[164:167], v[196:199], v[32:35]
	v_mfma_f32_16x16x32_bf16 v[24:27], v[156:159], v[204:207], v[24:27]
	v_mfma_f32_16x16x32_bf16 v[16:19], v[164:167], v[204:207], v[16:19]
	v_mfma_f32_16x16x32_bf16 v[8:11], v[156:159], v[212:215], v[8:11]
	v_mfma_f32_16x16x32_bf16 v[0:3], v[164:167], v[212:215], v[0:3]
	v_mfma_f32_16x16x32_bf16 v[76:79], v[168:171], v[184:187], v[76:79]
	v_mfma_f32_16x16x32_bf16 v[68:71], v[176:179], v[184:187], v[68:71]
	v_mfma_f32_16x16x32_bf16 v[44:47], v[168:171], v[192:195], v[44:47]
	v_mfma_f32_16x16x32_bf16 v[36:39], v[176:179], v[192:195], v[36:39]
	v_mfma_f32_16x16x32_bf16 v[28:31], v[168:171], v[200:203], v[28:31]
	v_mfma_f32_16x16x32_bf16 v[20:23], v[176:179], v[200:203], v[20:23]
	v_mfma_f32_16x16x32_bf16 v[12:15], v[168:171], v[208:211], v[12:15]
	v_mfma_f32_16x16x32_bf16 v[4:7], v[176:179], v[208:211], v[4:7]
	v_mfma_f32_16x16x32_bf16 v[76:79], v[172:175], v[188:191], v[76:79]
	v_mfma_f32_16x16x32_bf16 v[68:71], v[180:183], v[188:191], v[68:71]
	v_mfma_f32_16x16x32_bf16 v[44:47], v[172:175], v[196:199], v[44:47]
	v_mfma_f32_16x16x32_bf16 v[36:39], v[180:183], v[196:199], v[36:39]
	v_mfma_f32_16x16x32_bf16 v[28:31], v[172:175], v[204:207], v[28:31]
	v_mfma_f32_16x16x32_bf16 v[20:23], v[180:183], v[204:207], v[20:23]
	v_mfma_f32_16x16x32_bf16 v[12:15], v[172:175], v[212:215], v[12:15]
	v_mfma_f32_16x16x32_bf16 v[4:7], v[180:183], v[212:215], v[4:7]
	s_barrier
	s_setprio 0
	s_add_i32 s90, s90, 2
	s_add_u32 s88, s88, 0x100
	s_addc_u32 s89, s89, 0
	s_add_u32 s80, s80, 0x100
	s_addc_u32 s81, s81, 0
	s_cmp_gt_u32 s90, 29
	s_cbranch_scc0 .LBB0_777
	s_and_b64 vcc, exec, s[64:65]
	s_cbranch_vccz .LBB0_780
	s_barrier

; #define PG8_MMA(ai, bj, At, Bt) do { __builtin_amdgcn_s_setprio(1); _Pragma("unroll") for (int m = 0; m < 4; ++m) _Pragma("unroll") for (int n = 0; n < 2; ++n) _Pragma("unroll") for (int k = 0; k < 2; ++k) \
;         acc[ai][bj][m][n] = __builtin_amdgcn_mfma_f32_16x16x32_bf16(Bt[n][k], At[m][k], acc[ai][bj][m][n], 0, 0, 0); __builtin_amdgcn_s_setprio(0); } while (0)
; template <class Epi, class Sched, bool ALIGN_EPI = false, bool SP2 = false, bool A_TILED = false>
; __device__ __forceinline__ void gemm_phase(PG8_LAS unsigned char* lds, const Gemm g, const Sched& S, const Epi& E, const int wave_s) {
;     ...
;         for (int t = PEEL ? 2 : 0; t < nt; t += 2) {
;             const bool last = (t == nt - 2);
;             const char* a1 = cA + (size_t)(t + 1) * kstepA;
;             const char* a2 = last ? nA : cA + (size_t)(t + 2) * kstepA; const char* b2 = last ? nB : cB + (size_t)(t + 2) * kstep;
;             const char* a3 = a2 + kstepA; const char* b3 = b2 + kstep;
;             if (last && has_next) S.a_ready(nxt);
;             if constexpr (SP2) {
;             PG8_ITER(PG8_MMA)
.LBB0_1043:
	ds_read_b128 v[146:149], v140
	ds_read_b128 v[150:153], v140 offset:1024
	ds_read_b128 v[154:157], v140 offset:2048
	ds_read_b128 v[158:161], v140 offset:3072
	ds_read_b128 v[162:165], v141
	ds_read_b128 v[166:169], v141 offset:1024
	ds_read_b128 v[170:173], v141 offset:2048
	ds_read_b128 v[174:177], v141 offset:3072
	s_add_u32 s52, s62, s39
	s_addc_u32 s53, s63, s40
	s_add_u32 s54, s62, s37
	s_addc_u32 s55, s63, s38
	s_cmp_eq_u32 s41, 28
	s_cselect_b32 s73, s5, s53
	s_cselect_b32 s72, s4, s52
	s_cselect_b32 s71, s1, s55
	s_cselect_b32 s70, s0, s54
	s_mov_b32 m0, s42
	v_lshl_add_u64 v[210:211], s[62:63], 0, v[138:139]
	ds_read_b128 v[178:181], v142
	ds_read_b128 v[182:185], v142 offset:1024
	ds_read_b128 v[186:189], v142 offset:2048
	ds_read_b128 v[190:193], v142 offset:3072
	ds_read_b128 v[194:197], v142 offset:4096
	ds_read_b128 v[198:201], v142 offset:5120
	ds_read_b128 v[202:205], v142 offset:6144
	ds_read_b128 v[206:209], v142 offset:7168
	global_load_lds_dwordx4 v[210:211], off
	v_lshl_add_u64 v[210:211], s[62:63], 0, v[136:137]
	s_mov_b32 m0, s43
	s_nop 0
	global_load_lds_dwordx4 v[210:211], off
	s_waitcnt vmcnt(8) lgkmcnt(0)
	s_setprio 1
	s_barrier
	v_mfma_f32_16x16x32_bf16 v[8:11], v[146:149], v[178:181], v[8:11]
	v_mfma_f32_16x16x32_bf16 v[12:15], v[154:157], v[178:181], v[12:15]
	v_mfma_f32_16x16x32_bf16 v[36:39], v[146:149], v[186:189], v[36:39]
	v_mfma_f32_16x16x32_bf16 v[32:35], v[154:157], v[186:189], v[32:35]
	v_mfma_f32_16x16x32_bf16 v[60:63], v[146:149], v[194:197], v[60:63]
	v_mfma_f32_16x16x32_bf16 v[56:59], v[154:157], v[194:197], v[56:59]
	v_mfma_f32_16x16x32_bf16 v[80:83], v[146:149], v[202:205], v[80:83]
	v_mfma_f32_16x16x32_bf16 v[72:75], v[154:157], v[202:205], v[72:75]
	v_mfma_f32_16x16x32_bf16 v[8:11], v[150:153], v[182:185], v[8:11]
	v_mfma_f32_16x16x32_bf16 v[12:15], v[158:161], v[182:185], v[12:15]
	v_mfma_f32_16x16x32_bf16 v[36:39], v[150:153], v[190:193], v[36:39]
	v_mfma_f32_16x16x32_bf16 v[32:35], v[158:161], v[190:193], v[32:35]
	v_mfma_f32_16x16x32_bf16 v[60:63], v[150:153], v[198:201], v[60:63]
	v_mfma_f32_16x16x32_bf16 v[56:59], v[158:161], v[198:201], v[56:59]
	v_mfma_f32_16x16x32_bf16 v[80:83], v[150:153], v[206:209], v[80:83]
	v_mfma_f32_16x16x32_bf16 v[72:75], v[158:161], v[206:209], v[72:75]
	v_mfma_f32_16x16x32_bf16 v[44:47], v[162:165], v[178:181], v[44:47]
	v_mfma_f32_16x16x32_bf16 v[40:43], v[170:173], v[178:181], v[40:43]
	v_mfma_f32_16x16x32_bf16 v[52:55], v[162:165], v[186:189], v[52:55]
	v_mfma_f32_16x16x32_bf16 v[48:51], v[170:173], v[186:189], v[48:51]
	v_mfma_f32_16x16x32_bf16 v[68:71], v[162:165], v[194:197], v[68:71]
	v_mfma_f32_16x16x32_bf16 v[64:67], v[170:173], v[194:197], v[64:67]
	v_mfma_f32_16x16x32_bf16 v[100:103], v[162:165], v[202:205], v[100:103]
	v_mfma_f32_16x16x32_bf16 v[96:99], v[170:173], v[202:205], v[96:99]
	v_mfma_f32_16x16x32_bf16 v[44:47], v[166:169], v[182:185], v[44:47]
	v_mfma_f32_16x16x32_bf16 v[40:43], v[174:177], v[182:185], v[40:43]
	v_mfma_f32_16x16x32_bf16 v[52:55], v[166:169], v[190:193], v[52:55]
	v_mfma_f32_16x16x32_bf16 v[48:51], v[174:177], v[190:193], v[48:51]
	v_mfma_f32_16x16x32_bf16 v[68:71], v[166:169], v[198:201], v[68:71]
	v_mfma_f32_16x16x32_bf16 v[64:67], v[174:177], v[198:201], v[64:67]
	v_mfma_f32_16x16x32_bf16 v[100:103], v[166:169], v[206:209], v[100:103]
	v_mfma_f32_16x16x32_bf16 v[96:99], v[174:177], v[206:209], v[96:99]
	s_barrier
	s_setprio 0
	s_mov_b32 m0, s44
	v_lshl_add_u64 v[210:211], s[70:71], 0, v[130:131]
	s_add_u32 s52, s70, 0x80000
	ds_read_b128 v[178:181], v142 offset:16384
	ds_read_b128 v[182:185], v142 offset:17408
	ds_read_b128 v[186:189], v142 offset:18432
	ds_read_b128 v[190:193], v142 offset:19456
	ds_read_b128 v[194:197], v142 offset:20480
	ds_read_b128 v[198:201], v142 offset:21504
	ds_read_b128 v[202:205], v142 offset:22528
	ds_read_b128 v[206:209], v142 offset:23552
	global_load_lds_dwordx4 v130, s[70:71]
	v_lshl_add_u64 v[212:213], s[70:71], 0, v[134:135]
	s_mov_b32 m0, s45
	s_addc_u32 s53, s71, 0
	global_load_lds_dwordx4 v134, s[70:71]
	v_lshl_add_u64 v[214:215], s[52:53], 0, v[130:131]
	s_mov_b32 m0, s46
	v_lshl_add_u64 v[216:217], s[72:73], 0, v[132:133]
	global_load_lds_dwordx4 v130, s[52:53]
	v_lshl_add_u64 v[214:215], s[52:53], 0, v[134:135]
	s_mov_b32 m0, s47
	s_nop 0
	global_load_lds_dwordx4 v134, s[52:53]
	v_lshl_add_u64 v[214:215], s[72:73], 0, v[128:129]
	s_mov_b32 m0, s14
	s_nop 0
	global_load_lds_dwordx4 v128, s[72:73]
	s_mov_b32 m0, s15
	s_nop 0
	global_load_lds_dwordx4 v132, s[72:73]
	s_waitcnt vmcnt(8) lgkmcnt(0)
	s_setprio 1
	s_barrier
	v_mfma_f32_16x16x32_bf16 v[108:111], v[146:149], v[178:181], v[108:111]
	v_mfma_f32_16x16x32_bf16 v[104:107], v[154:157], v[178:181], v[104:107]
	v_mfma_f32_16x16x32_bf16 v[124:127], v[146:149], v[186:189], v[124:127]
	v_mfma_f32_16x16x32_bf16 v[120:123], v[154:157], v[186:189], v[120:123]
	v_mfma_f32_16x16x32_bf16 v[84:87], v[146:149], v[194:197], v[84:87]
	v_mfma_f32_16x16x32_bf16 v[76:79], v[154:157], v[194:197], v[76:79]
	v_mfma_f32_16x16x32_bf16 v[20:23], v[146:149], v[202:205], v[20:23]
	v_mfma_f32_16x16x32_bf16 v[16:19], v[154:157], v[202:205], v[16:19]
	v_mfma_f32_16x16x32_bf16 v[108:111], v[150:153], v[182:185], v[108:111]
	v_mfma_f32_16x16x32_bf16 v[104:107], v[158:161], v[182:185], v[104:107]
	v_mfma_f32_16x16x32_bf16 v[124:127], v[150:153], v[190:193], v[124:127]
	v_mfma_f32_16x16x32_bf16 v[120:123], v[158:161], v[190:193], v[120:123]
	v_mfma_f32_16x16x32_bf16 v[84:87], v[150:153], v[198:201], v[84:87]
	v_mfma_f32_16x16x32_bf16 v[76:79], v[158:161], v[198:201], v[76:79]
	v_mfma_f32_16x16x32_bf16 v[20:23], v[150:153], v[206:209], v[20:23]
	v_mfma_f32_16x16x32_bf16 v[16:19], v[158:161], v[206:209], v[16:19]
	v_mfma_f32_16x16x32_bf16 v[116:119], v[162:165], v[178:181], v[116:119]
	v_mfma_f32_16x16x32_bf16 v[112:115], v[170:173], v[178:181], v[112:115]
	v_mfma_f32_16x16x32_bf16 v[92:95], v[162:165], v[186:189], v[92:95]
	v_mfma_f32_16x16x32_bf16 v[88:91], v[170:173], v[186:189], v[88:91]
	v_mfma_f32_16x16x32_bf16 v[28:31], v[162:165], v[194:197], v[28:31]
	v_mfma_f32_16x16x32_bf16 v[24:27], v[170:173], v[194:197], v[24:27]
	v_mfma_f32_16x16x32_bf16 v[4:7], v[162:165], v[202:205], v[4:7]
	v_mfma_f32_16x16x32_bf16 v[0:3], v[170:173], v[202:205], v[0:3]
	v_mfma_f32_16x16x32_bf16 v[116:119], v[166:169], v[182:185], v[116:119]
	v_mfma_f32_16x16x32_bf16 v[112:115], v[174:177], v[182:185], v[112:115]
	v_mfma_f32_16x16x32_bf16 v[92:95], v[166:169], v[190:193], v[92:95]
	v_mfma_f32_16x16x32_bf16 v[88:91], v[174:177], v[190:193], v[88:91]
	v_mfma_f32_16x16x32_bf16 v[28:31], v[166:169], v[198:201], v[28:31]
	v_mfma_f32_16x16x32_bf16 v[24:27], v[174:177], v[198:201], v[24:27]
	v_mfma_f32_16x16x32_bf16 v[4:7], v[166:169], v[206:209], v[4:7]
	v_mfma_f32_16x16x32_bf16 v[0:3], v[174:177], v[206:209], v[0:3]
	s_barrier
	s_setprio 0
	ds_read_b128 v[146:149], v143
	ds_read_b128 v[150:153], v143 offset:1024
	ds_read_b128 v[154:157], v143 offset:2048
	ds_read_b128 v[158:161], v143 offset:3072
	ds_read_b128 v[162:165], v144
	ds_read_b128 v[166:169], v144 offset:1024
	ds_read_b128 v[170:173], v144 offset:2048
	ds_read_b128 v[174:177], v144 offset:3072
	s_add_u32 s52, s72, 0x80000
	s_addc_u32 s53, s73, 0
	s_mov_b32 m0, s21
	v_lshl_add_u64 v[218:219], s[52:53], 0, v[128:129]
	ds_read_b128 v[178:181], v142 offset:32768
	ds_read_b128 v[182:185], v142 offset:33792
	ds_read_b128 v[186:189], v142 offset:34816
	ds_read_b128 v[190:193], v142 offset:35840
	ds_read_b128 v[194:197], v142 offset:36864
	ds_read_b128 v[198:201], v142 offset:37888
	ds_read_b128 v[202:205], v142 offset:38912
	ds_read_b128 v[206:209], v142 offset:39936
	global_load_lds_dwordx4 v128, s[52:53]
	v_lshl_add_u64 v[218:219], s[52:53], 0, v[132:133]
	s_mov_b32 m0, s22
	s_nop 0
	global_load_lds_dwordx4 v132, s[52:53]
	s_waitcnt vmcnt(8) lgkmcnt(0)
	s_setprio 1
	s_barrier
	v_mfma_f32_16x16x32_bf16 v[8:11], v[146:149], v[178:181], v[8:11]
	v_mfma_f32_16x16x32_bf16 v[12:15], v[154:157], v[178:181], v[12:15]
	v_mfma_f32_16x16x32_bf16 v[36:39], v[146:149], v[186:189], v[36:39]
	v_mfma_f32_16x16x32_bf16 v[32:35], v[154:157], v[186:189], v[32:35]
	v_mfma_f32_16x16x32_bf16 v[60:63], v[146:149], v[194:197], v[60:63]
	v_mfma_f32_16x16x32_bf16 v[56:59], v[154:157], v[194:197], v[56:59]
	v_mfma_f32_16x16x32_bf16 v[80:83], v[146:149], v[202:205], v[80:83]
	v_mfma_f32_16x16x32_bf16 v[72:75], v[154:157], v[202:205], v[72:75]
	v_mfma_f32_16x16x32_bf16 v[8:11], v[150:153], v[182:185], v[8:11]
	v_mfma_f32_16x16x32_bf16 v[12:15], v[158:161], v[182:185], v[12:15]
	v_mfma_f32_16x16x32_bf16 v[36:39], v[150:153], v[190:193], v[36:39]
	v_mfma_f32_16x16x32_bf16 v[32:35], v[158:161], v[190:193], v[32:35]
	v_mfma_f32_16x16x32_bf16 v[60:63], v[150:153], v[198:201], v[60:63]
	v_mfma_f32_16x16x32_bf16 v[56:59], v[158:161], v[198:201], v[56:59]
	v_mfma_f32_16x16x32_bf16 v[80:83], v[150:153], v[206:209], v[80:83]
	v_mfma_f32_16x16x32_bf16 v[72:75], v[158:161], v[206:209], v[72:75]
	v_mfma_f32_16x16x32_bf16 v[44:47], v[162:165], v[178:181], v[44:47]
	v_mfma_f32_16x16x32_bf16 v[40:43], v[170:173], v[178:181], v[40:43]
	v_mfma_f32_16x16x32_bf16 v[52:55], v[162:165], v[186:189], v[52:55]
	v_mfma_f32_16x16x32_bf16 v[48:51], v[170:173], v[186:189], v[48:51]
	v_mfma_f32_16x16x32_bf16 v[68:71], v[162:165], v[194:197], v[68:71]
	v_mfma_f32_16x16x32_bf16 v[64:67], v[170:173], v[194:197], v[64:67]
	v_mfma_f32_16x16x32_bf16 v[100:103], v[162:165], v[202:205], v[100:103]
	v_mfma_f32_16x16x32_bf16 v[96:99], v[170:173], v[202:205], v[96:99]
	v_mfma_f32_16x16x32_bf16 v[44:47], v[166:169], v[182:185], v[44:47]
	v_mfma_f32_16x16x32_bf16 v[40:43], v[174:177], v[182:185], v[40:43]
	v_mfma_f32_16x16x32_bf16 v[52:55], v[166:169], v[190:193], v[52:55]
	v_mfma_f32_16x16x32_bf16 v[48:51], v[174:177], v[190:193], v[48:51]
	v_mfma_f32_16x16x32_bf16 v[68:71], v[166:169], v[198:201], v[68:71]
	v_mfma_f32_16x16x32_bf16 v[64:67], v[174:177], v[198:201], v[64:67]
	v_mfma_f32_16x16x32_bf16 v[100:103], v[166:169], v[206:209], v[100:103]
	v_mfma_f32_16x16x32_bf16 v[96:99], v[174:177], v[206:209], v[96:99]
	s_barrier
; #define PG8_WAIT_V(n) asm volatile("s_waitcnt vmcnt(" #n ")" ::: "memory")
; #define PG8_BAR __builtin_amdgcn_s_barrier()
; template <class Epi, class Sched, bool ALIGN_EPI = false, bool SP2 = false, bool A_TILED = false>
; __device__ __forceinline__ void gemm_phase(PG8_LAS unsigned char* lds, const Gemm g, const Sched& S, const Epi& E, const int wave_s) {
;     ...
;     PG8_WAIT_V(0);
;     if constexpr (!ALIGN_EPI) { if (wr == 0) PG8_BAR; }
;     PG8_BAR;
	s_setprio 0
	s_mov_b32 m0, s48
	v_lshl_add_u64 v[210:211], v[210:211], 0, s[66:67]
	s_add_u32 s52, s70, 0x80080
	ds_read_b128 v[178:181], v142 offset:49152
	ds_read_b128 v[182:185], v142 offset:50176
	ds_read_b128 v[186:189], v142 offset:51200
	ds_read_b128 v[190:193], v142 offset:52224
	ds_read_b128 v[194:197], v142 offset:53248
	ds_read_b128 v[198:201], v142 offset:54272
	ds_read_b128 v[202:205], v142 offset:55296
	ds_read_b128 v[206:209], v142 offset:56320
	global_load_lds_dwordx4 v[210:211], off
	v_lshl_add_u64 v[210:211], v[212:213], 0, s[66:67]
	s_mov_b32 m0, s49
	s_addc_u32 s53, s71, 0
	global_load_lds_dwordx4 v[210:211], off
	v_lshl_add_u64 v[210:211], s[52:53], 0, v[130:131]
	s_mov_b32 m0, s50
	s_nop 0
	global_load_lds_dwordx4 v130, s[52:53]
	v_lshl_add_u64 v[210:211], s[52:53], 0, v[134:135]
	s_mov_b32 m0, s51
	s_nop 0
	global_load_lds_dwordx4 v134, s[52:53]
	v_lshl_add_u64 v[210:211], v[214:215], 0, s[66:67]
	s_mov_b32 m0, s23
	s_nop 0
	global_load_lds_dwordx4 v[210:211], off
	v_lshl_add_u64 v[210:211], v[216:217], 0, s[66:67]
	s_mov_b32 m0, s36
	s_nop 0
	global_load_lds_dwordx4 v[210:211], off
	s_waitcnt vmcnt(8) lgkmcnt(0)
	s_setprio 1
	s_barrier
	v_mfma_f32_16x16x32_bf16 v[108:111], v[146:149], v[178:181], v[108:111]
	v_mfma_f32_16x16x32_bf16 v[104:107], v[154:157], v[178:181], v[104:107]
	v_mfma_f32_16x16x32_bf16 v[124:127], v[146:149], v[186:189], v[124:127]
	v_mfma_f32_16x16x32_bf16 v[120:123], v[154:157], v[186:189], v[120:123]
	v_mfma_f32_16x16x32_bf16 v[84:87], v[146:149], v[194:197], v[84:87]
	v_mfma_f32_16x16x32_bf16 v[76:79], v[154:157], v[194:197], v[76:79]
	v_mfma_f32_16x16x32_bf16 v[20:23], v[146:149], v[202:205], v[20:23]
	v_mfma_f32_16x16x32_bf16 v[16:19], v[154:157], v[202:205], v[16:19]
	v_mfma_f32_16x16x32_bf16 v[108:111], v[150:153], v[182:185], v[108:111]
	v_mfma_f32_16x16x32_bf16 v[104:107], v[158:161], v[182:185], v[104:107]
	v_mfma_f32_16x16x32_bf16 v[124:127], v[150:153], v[190:193], v[124:127]
	v_mfma_f32_16x16x32_bf16 v[120:123], v[158:161], v[190:193], v[120:123]
	v_mfma_f32_16x16x32_bf16 v[84:87], v[150:153], v[198:201], v[84:87]
	v_mfma_f32_16x16x32_bf16 v[76:79], v[158:161], v[198:201], v[76:79]
	v_mfma_f32_16x16x32_bf16 v[20:23], v[150:153], v[206:209], v[20:23]
	v_mfma_f32_16x16x32_bf16 v[16:19], v[158:161], v[206:209], v[16:19]
	v_mfma_f32_16x16x32_bf16 v[116:119], v[162:165], v[178:181], v[116:119]
	v_mfma_f32_16x16x32_bf16 v[112:115], v[170:173], v[178:181], v[112:115]
	v_mfma_f32_16x16x32_bf16 v[92:95], v[162:165], v[186:189], v[92:95]
	v_mfma_f32_16x16x32_bf16 v[88:91], v[170:173], v[186:189], v[88:91]
	v_mfma_f32_16x16x32_bf16 v[28:31], v[162:165], v[194:197], v[28:31]
	v_mfma_f32_16x16x32_bf16 v[24:27], v[170:173], v[194:197], v[24:27]
	v_mfma_f32_16x16x32_bf16 v[4:7], v[162:165], v[202:205], v[4:7]
	v_mfma_f32_16x16x32_bf16 v[0:3], v[170:173], v[202:205], v[0:3]
	v_mfma_f32_16x16x32_bf16 v[116:119], v[166:169], v[182:185], v[116:119]
	v_mfma_f32_16x16x32_bf16 v[112:115], v[174:177], v[182:185], v[112:115]
	v_mfma_f32_16x16x32_bf16 v[92:95], v[166:169], v[190:193], v[92:95]
	v_mfma_f32_16x16x32_bf16 v[88:91], v[174:177], v[190:193], v[88:91]
	v_mfma_f32_16x16x32_bf16 v[28:31], v[166:169], v[198:201], v[28:31]
	v_mfma_f32_16x16x32_bf16 v[24:27], v[174:177], v[198:201], v[24:27]
	v_mfma_f32_16x16x32_bf16 v[4:7], v[166:169], v[206:209], v[4:7]
	v_mfma_f32_16x16x32_bf16 v[0:3], v[174:177], v[206:209], v[0:3]
	s_barrier
	s_setprio 0
	s_add_i32 s41, s41, 2
	s_add_u32 s37, s37, 0x100
	s_addc_u32 s38, s38, 0
	s_add_u32 s39, s39, 0x100
	s_addc_u32 s40, s40, 0
	v_lshl_add_u64 v[136:137], v[136:137], 0, s[68:69]
	s_cmp_gt_u32 s41, 29
	v_lshl_add_u64 v[138:139], v[138:139], 0, s[68:69]
	s_cbranch_scc0 .LBB0_1043
	s_waitcnt vmcnt(0)
	s_cmpk_lt_u32 s6, 0x100
	s_cbranch_scc0 .LBB0_1046
	s_barrier

; template <class Epi, class Sched, bool ALIGN_EPI = false, bool SP2 = false, bool A_TILED = false>
; __device__ __forceinline__ void gemm_phase(PG8_LAS unsigned char* lds, const Gemm g, const Sched& S, const Epi& E, const int wave_s) {
;     ...
;         constexpr bool PEEL = SP2 && !Epi::AFTER_DRAIN;
;         if constexpr (PEEL) {
;             const char* a1 = cA + kstepA; const char* a2 = cA + 2 * kstepA; const char* b2 = cB + 2 * kstep; const char* a3 = a2 + kstepA; const char* b3 = b2 + kstep;
;             PG8_ITER(PG8_MMAZ)
.Lpw_3:
	s_setprio 1
	s_barrier
	v_mfma_f32_16x16x32_bf16 v[88:91], v[0:3], v[56:59], 0
	v_mfma_f32_16x16x32_bf16 v[64:67], v[0:3], v[32:35], 0
	v_mfma_f32_16x16x32_bf16 v[68:71], v[8:11], v[32:35], 0
	v_mfma_f32_16x16x32_bf16 v[72:75], v[0:3], v[40:43], 0
	v_mfma_f32_16x16x32_bf16 v[76:79], v[8:11], v[40:43], 0
	v_mfma_f32_16x16x32_bf16 v[80:83], v[0:3], v[48:51], 0
	v_mfma_f32_16x16x32_bf16 v[84:87], v[8:11], v[48:51], 0
	v_mfma_f32_16x16x32_bf16 v[96:99], v[4:7], v[60:63], v[88:91]
	v_mfma_f32_16x16x32_bf16 v[88:91], v[8:11], v[56:59], 0
	v_mfma_f32_16x16x32_bf16 v[64:67], v[4:7], v[36:39], v[64:67]
	v_mfma_f32_16x16x32_bf16 v[68:71], v[12:15], v[36:39], v[68:71]
	v_mfma_f32_16x16x32_bf16 v[72:75], v[4:7], v[44:47], v[72:75]
	v_mfma_f32_16x16x32_bf16 v[76:79], v[12:15], v[44:47], v[76:79]
	v_mfma_f32_16x16x32_bf16 v[80:83], v[4:7], v[52:55], v[80:83]
	v_mfma_f32_16x16x32_bf16 v[84:87], v[12:15], v[52:55], v[84:87]
	v_mfma_f32_16x16x32_bf16 v[100:103], v[12:15], v[60:63], v[88:91]
	v_mfma_f32_16x16x32_bf16 v[88:91], v[16:19], v[32:35], 0
	v_mfma_f32_16x16x32_bf16 v[32:35], v[24:27], v[32:35], 0
	v_mfma_f32_16x16x32_bf16 v[112:115], v[20:23], v[36:39], v[88:91]
	v_mfma_f32_16x16x32_bf16 v[32:35], v[28:31], v[36:39], v[32:35]
	v_mfma_f32_16x16x32_bf16 v[36:39], v[16:19], v[40:43], 0
	v_mfma_f32_16x16x32_bf16 v[40:43], v[24:27], v[40:43], 0
	v_mfma_f32_16x16x32_bf16 v[36:39], v[20:23], v[44:47], v[36:39]
	v_mfma_f32_16x16x32_bf16 v[40:43], v[28:31], v[44:47], v[40:43]
	v_mfma_f32_16x16x32_bf16 v[44:47], v[16:19], v[48:51], 0
	v_mfma_f32_16x16x32_bf16 v[48:51], v[24:27], v[48:51], 0
	v_mfma_f32_16x16x32_bf16 v[44:47], v[20:23], v[52:55], v[44:47]
	v_mfma_f32_16x16x32_bf16 v[48:51], v[28:31], v[52:55], v[48:51]
	v_mfma_f32_16x16x32_bf16 v[52:55], v[16:19], v[56:59], 0
	v_mfma_f32_16x16x32_bf16 v[56:59], v[24:27], v[56:59], 0
	v_mfma_f32_16x16x32_bf16 v[52:55], v[20:23], v[60:63], v[52:55]
	v_mfma_f32_16x16x32_bf16 v[56:59], v[28:31], v[60:63], v[56:59]
	s_barrier
	s_setprio 0
	s_add_i32 s56, s47, s15
	v_lshl_add_u64 v[242:243], s[76:77], 0, v[128:129]
	s_add_i32 s57, s56, 0x2000
	v_lshl_add_u64 v[148:149], v[242:243], 0, s[62:63]
	s_mov_b32 m0, s56
	v_lshl_add_u64 v[244:245], s[76:77], 0, v[130:131]
	s_add_u32 s80, s76, 0x80100
	ds_read_b128 v[60:63], v147 offset:16384
	ds_read_b128 v[88:91], v147 offset:17408
	ds_read_b128 v[92:95], v147 offset:18432
	ds_read_b128 v[104:107], v147 offset:19456
	ds_read_b128 v[108:111], v147 offset:20480
	ds_read_b128 v[116:119], v147 offset:21504
	ds_read_b128 v[120:123], v147 offset:22528
	ds_read_b128 v[124:127], v147 offset:23552
	global_load_lds_dwordx4 v[148:149], off
	v_lshl_add_u64 v[148:149], v[244:245], 0, s[62:63]
	s_mov_b32 m0, s57
	s_addc_u32 s81, s77, 0
	s_add_i32 s58, s48, s15
	global_load_lds_dwordx4 v[148:149], off
	v_lshl_add_u64 v[148:149], s[80:81], 0, v[128:129]
	s_mov_b32 m0, s58
	s_add_i32 s59, s58, 0x2000
	global_load_lds_dwordx4 v128, s[80:81]
	v_lshl_add_u64 v[148:149], s[80:81], 0, v[130:131]
	s_mov_b32 m0, s59
	v_lshl_add_u64 v[246:247], s[78:79], 0, v[134:135]
	global_load_lds_dwordx4 v130, s[80:81]
	v_lshl_add_u64 v[148:149], v[246:247], 0, s[62:63]
	s_mov_b32 m0, s22
	v_lshl_add_u64 v[248:249], s[78:79], 0, v[132:133]
	global_load_lds_dwordx4 v[148:149], off
	v_lshl_add_u64 v[148:149], v[248:249], 0, s[62:63]
	s_mov_b32 m0, s23
	s_nop 0
	global_load_lds_dwordx4 v[148:149], off
	s_waitcnt vmcnt(24) lgkmcnt(0)
	s_cmp_lg_u32 s98, 0
	s_cbranch_scc1 .Lpw_4
	s_waitcnt vmcnt(8)
.Lpw_4:
	s_setprio 1
	s_barrier
	v_mfma_f32_16x16x32_bf16 v[148:151], v[0:3], v[60:63], 0
	v_mfma_f32_16x16x32_bf16 v[158:161], v[0:3], v[92:95], 0
	v_mfma_f32_16x16x32_bf16 v[166:169], v[0:3], v[108:111], 0
	v_mfma_f32_16x16x32_bf16 v[0:3], v[0:3], v[120:123], 0
	v_mfma_f32_16x16x32_bf16 v[150:153], v[4:7], v[88:91], v[148:151]
	v_mfma_f32_16x16x32_bf16 v[158:161], v[4:7], v[104:107], v[158:161]
	v_mfma_f32_16x16x32_bf16 v[166:169], v[4:7], v[116:119], v[166:169]
	v_mfma_f32_16x16x32_bf16 v[0:3], v[4:7], v[124:127], v[0:3]
	v_mfma_f32_16x16x32_bf16 v[4:7], v[8:11], v[120:123], 0
	v_mfma_f32_16x16x32_bf16 v[154:157], v[8:11], v[60:63], 0
	v_mfma_f32_16x16x32_bf16 v[162:165], v[8:11], v[92:95], 0
	v_mfma_f32_16x16x32_bf16 v[170:173], v[8:11], v[108:111], 0
	v_mfma_f32_16x16x32_bf16 v[4:7], v[12:15], v[124:127], v[4:7]
	v_mfma_f32_16x16x32_bf16 v[154:157], v[12:15], v[88:91], v[154:157]
	v_mfma_f32_16x16x32_bf16 v[162:165], v[12:15], v[104:107], v[162:165]
	v_mfma_f32_16x16x32_bf16 v[170:173], v[12:15], v[116:119], v[170:173]
	v_mfma_f32_16x16x32_bf16 v[8:11], v[16:19], v[60:63], 0
	v_mfma_f32_16x16x32_bf16 v[174:177], v[20:23], v[88:91], v[8:11]
	v_mfma_f32_16x16x32_bf16 v[8:11], v[24:27], v[60:63], 0
	v_mfma_f32_16x16x32_bf16 v[60:63], v[28:31], v[88:91], v[8:11]
	v_mfma_f32_16x16x32_bf16 v[8:11], v[16:19], v[92:95], 0
	v_mfma_f32_16x16x32_bf16 v[178:181], v[20:23], v[104:107], v[8:11]
	v_mfma_f32_16x16x32_bf16 v[8:11], v[24:27], v[92:95], 0
	v_mfma_f32_16x16x32_bf16 v[182:185], v[28:31], v[104:107], v[8:11]
	v_mfma_f32_16x16x32_bf16 v[8:11], v[16:19], v[108:111], 0
	v_mfma_f32_16x16x32_bf16 v[186:189], v[20:23], v[116:119], v[8:11]
	v_mfma_f32_16x16x32_bf16 v[8:11], v[24:27], v[108:111], 0
	v_mfma_f32_16x16x32_bf16 v[190:193], v[28:31], v[116:119], v[8:11]
	v_mfma_f32_16x16x32_bf16 v[8:11], v[16:19], v[120:123], 0
	v_mfma_f32_16x16x32_bf16 v[194:197], v[20:23], v[124:127], v[8:11]
	v_mfma_f32_16x16x32_bf16 v[8:11], v[24:27], v[120:123], 0
	v_mfma_f32_16x16x32_bf16 v[198:201], v[28:31], v[124:127], v[8:11]
	s_barrier
; template <class Epi, class Sched, bool ALIGN_EPI = false, bool SP2 = false, bool A_TILED = false>
; __device__ __forceinline__ void gemm_phase(PG8_LAS unsigned char* lds, const Gemm g, const Sched& S, const Epi& E, const int wave_s) {
;     ...
;         for (int t = PEEL ? 2 : 0; t < nt; t += 2) {
;             const bool last = (t == nt - 2);
;             const char* a1 = cA + (size_t)(t + 1) * kstepA;
;             const char* a2 = last ? nA : cA + (size_t)(t + 2) * kstepA; const char* b2 = last ? nB : cB + (size_t)(t + 2) * kstep;
;             const char* a3 = a2 + kstepA; const char* b3 = b2 + kstep;
	s_setprio 0
	s_add_i32 s67, 0, 0x18000
	s_add_i32 s75, 0, 0x1c000
	v_add_u32_e32 v148, s67, v144
	v_add_u32_e32 v149, s75, v144
	s_nop 0
	ds_read_b128 v[8:11], v148
	ds_read_b128 v[12:15], v148 offset:1024
	ds_read_b128 v[16:19], v148 offset:2048
	ds_read_b128 v[20:23], v148 offset:3072
	ds_read_b128 v[202:205], v149
	ds_read_b128 v[206:209], v149 offset:1024
	ds_read_b128 v[210:213], v149 offset:2048
	ds_read_b128 v[214:217], v149 offset:3072
	s_add_u32 s80, s78, 0x80100
	s_addc_u32 s81, s79, 0
	s_mov_b32 m0, s36
	v_lshl_add_u64 v[88:89], s[80:81], 0, v[134:135]
	ds_read_b128 v[24:27], v147 offset:32768
	ds_read_b128 v[28:31], v147 offset:33792
	ds_read_b128 v[218:221], v147 offset:34816
	ds_read_b128 v[222:225], v147 offset:35840
	ds_read_b128 v[226:229], v147 offset:36864
	ds_read_b128 v[230:233], v147 offset:37888
	ds_read_b128 v[234:237], v147 offset:38912
	ds_read_b128 v[238:241], v147 offset:39936
	global_load_lds_dwordx4 v134, s[80:81]
	v_lshl_add_u64 v[88:89], s[80:81], 0, v[132:133]
	s_mov_b32 m0, s37
	s_nop 0
	global_load_lds_dwordx4 v132, s[80:81]
	s_waitcnt vmcnt(8) lgkmcnt(0)
	s_setprio 1
	s_barrier
	v_mfma_f32_16x16x32_bf16 v[64:67], v[8:11], v[24:27], v[64:67]
	v_mfma_f32_16x16x32_bf16 v[120:123], v[12:15], v[28:31], v[64:67]
	v_mfma_f32_16x16x32_bf16 v[64:67], v[16:19], v[24:27], v[68:71]
	v_mfma_f32_16x16x32_bf16 v[124:127], v[20:23], v[28:31], v[64:67]
	v_mfma_f32_16x16x32_bf16 v[64:67], v[8:11], v[218:221], v[72:75]
	v_mfma_f32_16x16x32_bf16 v[104:107], v[12:15], v[222:225], v[64:67]
	v_mfma_f32_16x16x32_bf16 v[64:67], v[16:19], v[218:221], v[76:79]
	v_mfma_f32_16x16x32_bf16 v[108:111], v[20:23], v[222:225], v[64:67]
	v_mfma_f32_16x16x32_bf16 v[64:67], v[8:11], v[226:229], v[80:83]
	v_mfma_f32_16x16x32_bf16 v[88:91], v[12:15], v[230:233], v[64:67]
	v_mfma_f32_16x16x32_bf16 v[64:67], v[16:19], v[226:229], v[84:87]
	v_mfma_f32_16x16x32_bf16 v[92:95], v[20:23], v[230:233], v[64:67]
	v_mfma_f32_16x16x32_bf16 v[64:67], v[8:11], v[234:237], v[96:99]
	v_mfma_f32_16x16x32_bf16 v[68:71], v[16:19], v[234:237], v[100:103]
	v_mfma_f32_16x16x32_bf16 v[64:67], v[12:15], v[238:241], v[64:67]
	v_mfma_f32_16x16x32_bf16 v[68:71], v[20:23], v[238:241], v[68:71]
	v_mfma_f32_16x16x32_bf16 v[72:75], v[202:205], v[24:27], v[112:115]
	v_mfma_f32_16x16x32_bf16 v[24:27], v[210:213], v[24:27], v[32:35]
	v_mfma_f32_16x16x32_bf16 v[116:119], v[214:217], v[28:31], v[24:27]
	v_mfma_f32_16x16x32_bf16 v[24:27], v[202:205], v[218:221], v[36:39]
	v_mfma_f32_16x16x32_bf16 v[96:99], v[206:209], v[222:225], v[24:27]
	v_mfma_f32_16x16x32_bf16 v[24:27], v[210:213], v[218:221], v[40:43]
	v_mfma_f32_16x16x32_bf16 v[100:103], v[214:217], v[222:225], v[24:27]
	v_mfma_f32_16x16x32_bf16 v[24:27], v[202:205], v[226:229], v[44:47]
	v_mfma_f32_16x16x32_bf16 v[80:83], v[206:209], v[230:233], v[24:27]
	v_mfma_f32_16x16x32_bf16 v[24:27], v[210:213], v[226:229], v[48:51]
	v_mfma_f32_16x16x32_bf16 v[84:87], v[214:217], v[230:233], v[24:27]
	v_mfma_f32_16x16x32_bf16 v[24:27], v[202:205], v[234:237], v[52:55]
	v_mfma_f32_16x16x32_bf16 v[48:51], v[206:209], v[238:241], v[24:27]
	v_mfma_f32_16x16x32_bf16 v[24:27], v[210:213], v[234:237], v[56:59]
	v_mfma_f32_16x16x32_bf16 v[112:115], v[206:209], v[28:31], v[72:75]
	v_mfma_f32_16x16x32_bf16 v[52:55], v[214:217], v[238:241], v[24:27]
	s_barrier
	s_setprio 0
	s_add_i32 s67, s67, s15
	s_add_i32 s69, s67, 0x2000
	s_nop 1
	v_lshl_add_u64 v[24:25], v[242:243], 0, s[64:65]
	s_mov_b32 m0, s67
	s_add_u32 s80, s76, 0x80180
	ds_read_b128 v[32:35], v147 offset:49152
	ds_read_b128 v[36:39], v147 offset:50176
	ds_read_b128 v[218:221], v147 offset:51200
	ds_read_b128 v[222:225], v147 offset:52224
	ds_read_b128 v[226:229], v147 offset:53248
	ds_read_b128 v[230:233], v147 offset:54272
	ds_read_b128 v[234:237], v147 offset:55296
	ds_read_b128 v[238:241], v147 offset:56320
	global_load_lds_dwordx4 v[24:25], off
	v_lshl_add_u64 v[24:25], v[244:245], 0, s[64:65]
	s_mov_b32 m0, s69
	s_addc_u32 s81, s77, 0
	s_add_i32 s75, s75, s15
	global_load_lds_dwordx4 v[24:25], off
	v_lshl_add_u64 v[24:25], s[80:81], 0, v[128:129]
	s_mov_b32 m0, s75
	s_add_i32 s82, s75, 0x2000
	global_load_lds_dwordx4 v128, s[80:81]
	v_lshl_add_u64 v[24:25], s[80:81], 0, v[130:131]
	s_mov_b32 m0, s82
	s_nop 0
	global_load_lds_dwordx4 v130, s[80:81]
	v_lshl_add_u64 v[24:25], v[246:247], 0, s[64:65]
	s_mov_b32 m0, s43
	s_nop 0
	global_load_lds_dwordx4 v[24:25], off
	v_lshl_add_u64 v[24:25], v[248:249], 0, s[64:65]
	s_mov_b32 m0, s44
	s_nop 0
	global_load_lds_dwordx4 v[24:25], off
	s_waitcnt vmcnt(8) lgkmcnt(0)
	s_setprio 1
	s_barrier
	v_mfma_f32_16x16x32_bf16 v[24:27], v[8:11], v[32:35], v[150:153]
	v_mfma_f32_16x16x32_bf16 v[72:75], v[12:15], v[36:39], v[24:27]
	v_mfma_f32_16x16x32_bf16 v[24:27], v[16:19], v[32:35], v[154:157]
	v_mfma_f32_16x16x32_bf16 v[76:79], v[20:23], v[36:39], v[24:27]
	v_mfma_f32_16x16x32_bf16 v[24:27], v[8:11], v[218:221], v[158:161]
	v_mfma_f32_16x16x32_bf16 v[40:43], v[12:15], v[222:225], v[24:27]
	v_mfma_f32_16x16x32_bf16 v[24:27], v[16:19], v[218:221], v[162:165]
	v_mfma_f32_16x16x32_bf16 v[0:3], v[8:11], v[234:237], v[0:3]
	v_mfma_f32_16x16x32_bf16 v[44:47], v[20:23], v[222:225], v[24:27]
	v_mfma_f32_16x16x32_bf16 v[24:27], v[8:11], v[226:229], v[166:169]
	v_mfma_f32_16x16x32_bf16 v[28:31], v[16:19], v[226:229], v[170:173]
	v_mfma_f32_16x16x32_bf16 v[8:11], v[12:15], v[238:241], v[0:3]
	v_mfma_f32_16x16x32_bf16 v[0:3], v[16:19], v[234:237], v[4:7]
	v_mfma_f32_16x16x32_bf16 v[24:27], v[12:15], v[230:233], v[24:27]
	v_mfma_f32_16x16x32_bf16 v[28:31], v[20:23], v[230:233], v[28:31]
	v_mfma_f32_16x16x32_bf16 v[12:15], v[20:23], v[238:241], v[0:3]
	v_mfma_f32_16x16x32_bf16 v[0:3], v[202:205], v[32:35], v[174:177]
	v_mfma_f32_16x16x32_bf16 v[56:59], v[206:209], v[36:39], v[0:3]
	v_mfma_f32_16x16x32_bf16 v[0:3], v[210:213], v[32:35], v[60:63]
	v_mfma_f32_16x16x32_bf16 v[60:63], v[214:217], v[36:39], v[0:3]
	v_mfma_f32_16x16x32_bf16 v[0:3], v[202:205], v[218:221], v[178:181]
	v_mfma_f32_16x16x32_bf16 v[32:35], v[206:209], v[222:225], v[0:3]
	v_mfma_f32_16x16x32_bf16 v[0:3], v[210:213], v[218:221], v[182:185]
	v_mfma_f32_16x16x32_bf16 v[36:39], v[214:217], v[222:225], v[0:3]
	v_mfma_f32_16x16x32_bf16 v[0:3], v[202:205], v[226:229], v[186:189]
	v_mfma_f32_16x16x32_bf16 v[16:19], v[206:209], v[230:233], v[0:3]
	v_mfma_f32_16x16x32_bf16 v[0:3], v[210:213], v[226:229], v[190:193]
	v_mfma_f32_16x16x32_bf16 v[20:23], v[214:217], v[230:233], v[0:3]
	v_mfma_f32_16x16x32_bf16 v[0:3], v[202:205], v[234:237], v[194:197]
	v_mfma_f32_16x16x32_bf16 v[4:7], v[210:213], v[234:237], v[198:201]
	v_mfma_f32_16x16x32_bf16 v[0:3], v[206:209], v[238:241], v[0:3]
	v_mfma_f32_16x16x32_bf16 v[4:7], v[214:217], v[238:241], v[4:7]
	s_barrier
	s_setprio 0
	s_add_u32 s83, s76, 0x200
	s_addc_u32 s84, s77, 0
	s_add_u32 s76, s78, 0x80180
	s_addc_u32 s77, s79, 0
	s_mov_b32 s85, 0
; #define PG8_MMA(ai, bj, At, Bt) do { __builtin_amdgcn_s_setprio(1); _Pragma("unroll") for (int m = 0; m < 4; ++m) _Pragma("unroll") for (int n = 0; n < 2; ++n) _Pragma("unroll") for (int k = 0; k < 2; ++k) \
;         acc[ai][bj][m][n] = __builtin_amdgcn_mfma_f32_16x16x32_bf16(Bt[n][k], At[m][k], acc[ai][bj][m][n], 0, 0, 0); __builtin_amdgcn_s_setprio(0); } while (0)
; template <class Epi, class Sched, bool ALIGN_EPI = false, bool SP2 = false, bool A_TILED = false>
; __device__ __forceinline__ void gemm_phase(PG8_LAS unsigned char* lds, const Gemm g, const Sched& S, const Epi& E, const int wave_s) {
;     ...
;         for (int t = PEEL ? 2 : 0; t < nt; t += 2) {
;             const bool last = (t == nt - 2);
;             const char* a1 = cA + (size_t)(t + 1) * kstepA;
;             const char* a2 = last ? nA : cA + (size_t)(t + 2) * kstepA; const char* b2 = last ? nB : cB + (size_t)(t + 2) * kstep;
;             const char* a3 = a2 + kstepA; const char* b3 = b2 + kstep;
;             if (last && has_next) S.a_ready(nxt);
;             if constexpr (SP2) {
;             PG8_ITER(PG8_MMA)
.LBB0_1155:
	ds_read_b128 v[150:153], v145
	ds_read_b128 v[154:157], v145 offset:1024
	ds_read_b128 v[158:161], v145 offset:2048
	ds_read_b128 v[162:165], v145 offset:3072
	ds_read_b128 v[166:169], v146
	ds_read_b128 v[170:173], v146 offset:1024
	ds_read_b128 v[174:177], v146 offset:2048
	ds_read_b128 v[178:181], v146 offset:3072
	s_add_u32 s78, s76, 0xfff80080
	s_addc_u32 s79, s77, -1
	s_cmp_eq_u32 s85, 28
	s_cselect_b32 s81, s50, s79
	s_cselect_b32 s80, s51, s78
	s_cselect_b32 s79, s52, s84
	s_cselect_b32 s78, s53, s83
	s_mov_b32 m0, s54
	v_lshl_add_u64 v[214:215], s[76:77], 0, v[138:139]
	ds_read_b128 v[182:185], v147
	ds_read_b128 v[186:189], v147 offset:1024
	ds_read_b128 v[190:193], v147 offset:2048
	ds_read_b128 v[194:197], v147 offset:3072
	ds_read_b128 v[198:201], v147 offset:4096
	ds_read_b128 v[202:205], v147 offset:5120
	ds_read_b128 v[206:209], v147 offset:6144
	ds_read_b128 v[210:213], v147 offset:7168
	global_load_lds_dwordx4 v138, s[76:77]
	v_lshl_add_u64 v[214:215], s[76:77], 0, v[136:137]
	s_mov_b32 m0, s55
	s_nop 0
	global_load_lds_dwordx4 v136, s[76:77]
	s_waitcnt vmcnt(8) lgkmcnt(0)
	s_setprio 1
	s_barrier
	v_mfma_f32_16x16x32_bf16 v[120:123], v[150:153], v[182:185], v[120:123]
	v_mfma_f32_16x16x32_bf16 v[124:127], v[158:161], v[182:185], v[124:127]
	v_mfma_f32_16x16x32_bf16 v[104:107], v[150:153], v[190:193], v[104:107]
	v_mfma_f32_16x16x32_bf16 v[108:111], v[158:161], v[190:193], v[108:111]
	v_mfma_f32_16x16x32_bf16 v[88:91], v[150:153], v[198:201], v[88:91]
	v_mfma_f32_16x16x32_bf16 v[92:95], v[158:161], v[198:201], v[92:95]
	v_mfma_f32_16x16x32_bf16 v[64:67], v[150:153], v[206:209], v[64:67]
	v_mfma_f32_16x16x32_bf16 v[68:71], v[158:161], v[206:209], v[68:71]
	v_mfma_f32_16x16x32_bf16 v[120:123], v[154:157], v[186:189], v[120:123]
	v_mfma_f32_16x16x32_bf16 v[124:127], v[162:165], v[186:189], v[124:127]
	v_mfma_f32_16x16x32_bf16 v[104:107], v[154:157], v[194:197], v[104:107]
	v_mfma_f32_16x16x32_bf16 v[108:111], v[162:165], v[194:197], v[108:111]
	v_mfma_f32_16x16x32_bf16 v[88:91], v[154:157], v[202:205], v[88:91]
	v_mfma_f32_16x16x32_bf16 v[92:95], v[162:165], v[202:205], v[92:95]
	v_mfma_f32_16x16x32_bf16 v[64:67], v[154:157], v[210:213], v[64:67]
	v_mfma_f32_16x16x32_bf16 v[68:71], v[162:165], v[210:213], v[68:71]
	v_mfma_f32_16x16x32_bf16 v[112:115], v[166:169], v[182:185], v[112:115]
	v_mfma_f32_16x16x32_bf16 v[116:119], v[174:177], v[182:185], v[116:119]
	v_mfma_f32_16x16x32_bf16 v[96:99], v[166:169], v[190:193], v[96:99]
	v_mfma_f32_16x16x32_bf16 v[100:103], v[174:177], v[190:193], v[100:103]
	v_mfma_f32_16x16x32_bf16 v[80:83], v[166:169], v[198:201], v[80:83]
	v_mfma_f32_16x16x32_bf16 v[84:87], v[174:177], v[198:201], v[84:87]
	v_mfma_f32_16x16x32_bf16 v[48:51], v[166:169], v[206:209], v[48:51]
	v_mfma_f32_16x16x32_bf16 v[52:55], v[174:177], v[206:209], v[52:55]
	v_mfma_f32_16x16x32_bf16 v[112:115], v[170:173], v[186:189], v[112:115]
	v_mfma_f32_16x16x32_bf16 v[116:119], v[178:181], v[186:189], v[116:119]
	v_mfma_f32_16x16x32_bf16 v[96:99], v[170:173], v[194:197], v[96:99]
	v_mfma_f32_16x16x32_bf16 v[100:103], v[178:181], v[194:197], v[100:103]
	v_mfma_f32_16x16x32_bf16 v[80:83], v[170:173], v[202:205], v[80:83]
	v_mfma_f32_16x16x32_bf16 v[84:87], v[178:181], v[202:205], v[84:87]
	v_mfma_f32_16x16x32_bf16 v[48:51], v[170:173], v[210:213], v[48:51]
	v_mfma_f32_16x16x32_bf16 v[52:55], v[178:181], v[210:213], v[52:55]
	s_barrier
	s_setprio 0
	s_mov_b32 m0, s56
	v_lshl_add_u64 v[214:215], s[78:79], 0, v[128:129]
	s_add_u32 s88, s78, 0x80000
	ds_read_b128 v[182:185], v147 offset:16384
	ds_read_b128 v[186:189], v147 offset:17408
	ds_read_b128 v[190:193], v147 offset:18432
	ds_read_b128 v[194:197], v147 offset:19456
	ds_read_b128 v[198:201], v147 offset:20480
	ds_read_b128 v[202:205], v147 offset:21504
	ds_read_b128 v[206:209], v147 offset:22528
	ds_read_b128 v[210:213], v147 offset:23552
	global_load_lds_dwordx4 v128, s[78:79]
	v_lshl_add_u64 v[216:217], s[78:79], 0, v[130:131]
	s_mov_b32 m0, s57
	s_addc_u32 s89, s79, 0
	global_load_lds_dwordx4 v130, s[78:79]
	v_lshl_add_u64 v[218:219], s[88:89], 0, v[128:129]
	s_mov_b32 m0, s58
	v_lshl_add_u64 v[220:221], s[80:81], 0, v[132:133]
	global_load_lds_dwordx4 v128, s[88:89]
	v_lshl_add_u64 v[218:219], s[88:89], 0, v[130:131]
	s_mov_b32 m0, s59
	s_nop 0
	global_load_lds_dwordx4 v130, s[88:89]
	v_lshl_add_u64 v[218:219], s[80:81], 0, v[134:135]
	s_mov_b32 m0, s22
	s_nop 0
	global_load_lds_dwordx4 v134, s[80:81]
	s_mov_b32 m0, s23
	s_nop 0
	global_load_lds_dwordx4 v132, s[80:81]
	s_waitcnt vmcnt(8) lgkmcnt(0)
	s_setprio 1
	s_barrier
	v_mfma_f32_16x16x32_bf16 v[72:75], v[150:153], v[182:185], v[72:75]
	v_mfma_f32_16x16x32_bf16 v[76:79], v[158:161], v[182:185], v[76:79]
	v_mfma_f32_16x16x32_bf16 v[40:43], v[150:153], v[190:193], v[40:43]
	v_mfma_f32_16x16x32_bf16 v[44:47], v[158:161], v[190:193], v[44:47]
	v_mfma_f32_16x16x32_bf16 v[24:27], v[150:153], v[198:201], v[24:27]
	v_mfma_f32_16x16x32_bf16 v[28:31], v[158:161], v[198:201], v[28:31]
	v_mfma_f32_16x16x32_bf16 v[8:11], v[150:153], v[206:209], v[8:11]
	v_mfma_f32_16x16x32_bf16 v[12:15], v[158:161], v[206:209], v[12:15]
	v_mfma_f32_16x16x32_bf16 v[72:75], v[154:157], v[186:189], v[72:75]
	v_mfma_f32_16x16x32_bf16 v[76:79], v[162:165], v[186:189], v[76:79]
	v_mfma_f32_16x16x32_bf16 v[40:43], v[154:157], v[194:197], v[40:43]
	v_mfma_f32_16x16x32_bf16 v[44:47], v[162:165], v[194:197], v[44:47]
	v_mfma_f32_16x16x32_bf16 v[24:27], v[154:157], v[202:205], v[24:27]
	v_mfma_f32_16x16x32_bf16 v[28:31], v[162:165], v[202:205], v[28:31]
	v_mfma_f32_16x16x32_bf16 v[8:11], v[154:157], v[210:213], v[8:11]
	v_mfma_f32_16x16x32_bf16 v[12:15], v[162:165], v[210:213], v[12:15]
	v_mfma_f32_16x16x32_bf16 v[56:59], v[166:169], v[182:185], v[56:59]
	v_mfma_f32_16x16x32_bf16 v[60:63], v[174:177], v[182:185], v[60:63]
	v_mfma_f32_16x16x32_bf16 v[32:35], v[166:169], v[190:193], v[32:35]
	v_mfma_f32_16x16x32_bf16 v[36:39], v[174:177], v[190:193], v[36:39]
	v_mfma_f32_16x16x32_bf16 v[16:19], v[166:169], v[198:201], v[16:19]
	v_mfma_f32_16x16x32_bf16 v[20:23], v[174:177], v[198:201], v[20:23]
	v_mfma_f32_16x16x32_bf16 v[0:3], v[166:169], v[206:209], v[0:3]
	v_mfma_f32_16x16x32_bf16 v[4:7], v[174:177], v[206:209], v[4:7]
	v_mfma_f32_16x16x32_bf16 v[56:59], v[170:173], v[186:189], v[56:59]
	v_mfma_f32_16x16x32_bf16 v[60:63], v[178:181], v[186:189], v[60:63]
	v_mfma_f32_16x16x32_bf16 v[32:35], v[170:173], v[194:197], v[32:35]
	v_mfma_f32_16x16x32_bf16 v[36:39], v[178:181], v[194:197], v[36:39]
	v_mfma_f32_16x16x32_bf16 v[16:19], v[170:173], v[202:205], v[16:19]
	v_mfma_f32_16x16x32_bf16 v[20:23], v[178:181], v[202:205], v[20:23]
	v_mfma_f32_16x16x32_bf16 v[0:3], v[170:173], v[210:213], v[0:3]
	v_mfma_f32_16x16x32_bf16 v[4:7], v[178:181], v[210:213], v[4:7]
	s_barrier
	s_setprio 0
	ds_read_b128 v[150:153], v148
	ds_read_b128 v[154:157], v148 offset:1024
	ds_read_b128 v[158:161], v148 offset:2048
	ds_read_b128 v[162:165], v148 offset:3072
	ds_read_b128 v[166:169], v149
	ds_read_b128 v[170:173], v149 offset:1024
	ds_read_b128 v[174:177], v149 offset:2048
	ds_read_b128 v[178:181], v149 offset:3072
	s_add_u32 s80, s80, 0x80000
	s_addc_u32 s81, s81, 0
	s_mov_b32 m0, s36
	v_lshl_add_u64 v[222:223], s[80:81], 0, v[134:135]
	ds_read_b128 v[182:185], v147 offset:32768
	ds_read_b128 v[186:189], v147 offset:33792
	ds_read_b128 v[190:193], v147 offset:34816
	ds_read_b128 v[194:197], v147 offset:35840
	ds_read_b128 v[198:201], v147 offset:36864
	ds_read_b128 v[202:205], v147 offset:37888
	ds_read_b128 v[206:209], v147 offset:38912
	ds_read_b128 v[210:213], v147 offset:39936
	global_load_lds_dwordx4 v134, s[80:81]
	v_lshl_add_u64 v[222:223], s[80:81], 0, v[132:133]
	s_mov_b32 m0, s37
	s_nop 0
	global_load_lds_dwordx4 v132, s[80:81]
	s_waitcnt vmcnt(8) lgkmcnt(0)
	s_setprio 1
	s_barrier
	v_mfma_f32_16x16x32_bf16 v[120:123], v[150:153], v[182:185], v[120:123]
	v_mfma_f32_16x16x32_bf16 v[124:127], v[158:161], v[182:185], v[124:127]
	v_mfma_f32_16x16x32_bf16 v[104:107], v[150:153], v[190:193], v[104:107]
	v_mfma_f32_16x16x32_bf16 v[108:111], v[158:161], v[190:193], v[108:111]
	v_mfma_f32_16x16x32_bf16 v[88:91], v[150:153], v[198:201], v[88:91]
	v_mfma_f32_16x16x32_bf16 v[92:95], v[158:161], v[198:201], v[92:95]
	v_mfma_f32_16x16x32_bf16 v[64:67], v[150:153], v[206:209], v[64:67]
	v_mfma_f32_16x16x32_bf16 v[68:71], v[158:161], v[206:209], v[68:71]
	v_mfma_f32_16x16x32_bf16 v[120:123], v[154:157], v[186:189], v[120:123]
	v_mfma_f32_16x16x32_bf16 v[124:127], v[162:165], v[186:189], v[124:127]
	v_mfma_f32_16x16x32_bf16 v[104:107], v[154:157], v[194:197], v[104:107]
	v_mfma_f32_16x16x32_bf16 v[108:111], v[162:165], v[194:197], v[108:111]
	v_mfma_f32_16x16x32_bf16 v[88:91], v[154:157], v[202:205], v[88:91]
	v_mfma_f32_16x16x32_bf16 v[92:95], v[162:165], v[202:205], v[92:95]
	v_mfma_f32_16x16x32_bf16 v[64:67], v[154:157], v[210:213], v[64:67]
	v_mfma_f32_16x16x32_bf16 v[68:71], v[162:165], v[210:213], v[68:71]
	v_mfma_f32_16x16x32_bf16 v[112:115], v[166:169], v[182:185], v[112:115]
	v_mfma_f32_16x16x32_bf16 v[116:119], v[174:177], v[182:185], v[116:119]
	v_mfma_f32_16x16x32_bf16 v[96:99], v[166:169], v[190:193], v[96:99]
	v_mfma_f32_16x16x32_bf16 v[100:103], v[174:177], v[190:193], v[100:103]
	v_mfma_f32_16x16x32_bf16 v[80:83], v[166:169], v[198:201], v[80:83]
	v_mfma_f32_16x16x32_bf16 v[84:87], v[174:177], v[198:201], v[84:87]
	v_mfma_f32_16x16x32_bf16 v[48:51], v[166:169], v[206:209], v[48:51]
	v_mfma_f32_16x16x32_bf16 v[52:55], v[174:177], v[206:209], v[52:55]
	v_mfma_f32_16x16x32_bf16 v[112:115], v[170:173], v[186:189], v[112:115]
	v_mfma_f32_16x16x32_bf16 v[116:119], v[178:181], v[186:189], v[116:119]
	v_mfma_f32_16x16x32_bf16 v[96:99], v[170:173], v[194:197], v[96:99]
	v_mfma_f32_16x16x32_bf16 v[100:103], v[178:181], v[194:197], v[100:103]
	v_mfma_f32_16x16x32_bf16 v[80:83], v[170:173], v[202:205], v[80:83]
	v_mfma_f32_16x16x32_bf16 v[84:87], v[178:181], v[202:205], v[84:87]
	v_mfma_f32_16x16x32_bf16 v[48:51], v[170:173], v[210:213], v[48:51]
	v_mfma_f32_16x16x32_bf16 v[52:55], v[178:181], v[210:213], v[52:55]
	s_barrier
; __device__ __forceinline__ int tid_now(int wave_s) { unsigned z = 0u; asm volatile("" : "+v"(z)); return (wave_s << 6) | (int)__builtin_amdgcn_mbcnt_hi(~0u, __builtin_amdgcn_mbcnt_lo(~0u, z)); }
; #define PG8_BAR __builtin_amdgcn_s_barrier()
; template <class Epi, class Sched, bool ALIGN_EPI = false, bool SP2 = false, bool A_TILED = false>
; __device__ __forceinline__ void gemm_phase(PG8_LAS unsigned char* lds, const Gemm g, const Sched& S, const Epi& E, const int wave_s) {
;     ...
;         if constexpr (ALIGN_EPI) { if (wr == 0) PG8_BAR; }
;         if constexpr (!Epi::AFTER_DRAIN) { int te = tid_now(wave_s); asm volatile("" : "+v"(te));
;             E(acc, cur, wr, wc, te & 15, (te & 63) >> 4); S.done(cur); }
;         if (!has_next) break;
;         cur = nxt; cA = nA; cB = nB; ++ui;
;         if constexpr (ALIGN_EPI) { if (wr == 1) PG8_BAR; }
	s_setprio 0
	s_mov_b32 m0, s67
	v_lshl_add_u64 v[214:215], v[214:215], 0, s[12:13]
	s_add_u32 s78, s78, 0x80080
	ds_read_b128 v[182:185], v147 offset:49152
	ds_read_b128 v[186:189], v147 offset:50176
	ds_read_b128 v[190:193], v147 offset:51200
	ds_read_b128 v[194:197], v147 offset:52224
	ds_read_b128 v[198:201], v147 offset:53248
	ds_read_b128 v[202:205], v147 offset:54272
	ds_read_b128 v[206:209], v147 offset:55296
	ds_read_b128 v[210:213], v147 offset:56320
	global_load_lds_dwordx4 v[214:215], off
	v_lshl_add_u64 v[214:215], v[216:217], 0, s[12:13]
	s_mov_b32 m0, s69
	s_addc_u32 s79, s79, 0
	global_load_lds_dwordx4 v[214:215], off
	v_lshl_add_u64 v[214:215], s[78:79], 0, v[128:129]
	s_mov_b32 m0, s75
	s_nop 0
	global_load_lds_dwordx4 v128, s[78:79]
	v_lshl_add_u64 v[214:215], s[78:79], 0, v[130:131]
	s_mov_b32 m0, s82
	s_nop 0
	global_load_lds_dwordx4 v130, s[78:79]
	v_lshl_add_u64 v[214:215], v[218:219], 0, s[12:13]
	s_mov_b32 m0, s43
	s_nop 0
	global_load_lds_dwordx4 v[214:215], off
	v_lshl_add_u64 v[214:215], v[220:221], 0, s[12:13]
	s_mov_b32 m0, s44
	s_nop 0
	global_load_lds_dwordx4 v[214:215], off
	s_waitcnt vmcnt(8) lgkmcnt(0)
	s_setprio 1
	s_barrier
	v_mfma_f32_16x16x32_bf16 v[72:75], v[150:153], v[182:185], v[72:75]
	v_mfma_f32_16x16x32_bf16 v[76:79], v[158:161], v[182:185], v[76:79]
	v_mfma_f32_16x16x32_bf16 v[40:43], v[150:153], v[190:193], v[40:43]
	v_mfma_f32_16x16x32_bf16 v[44:47], v[158:161], v[190:193], v[44:47]
	v_mfma_f32_16x16x32_bf16 v[24:27], v[150:153], v[198:201], v[24:27]
	v_mfma_f32_16x16x32_bf16 v[28:31], v[158:161], v[198:201], v[28:31]
	v_mfma_f32_16x16x32_bf16 v[8:11], v[150:153], v[206:209], v[8:11]
	v_mfma_f32_16x16x32_bf16 v[12:15], v[158:161], v[206:209], v[12:15]
	v_mfma_f32_16x16x32_bf16 v[72:75], v[154:157], v[186:189], v[72:75]
	v_mfma_f32_16x16x32_bf16 v[76:79], v[162:165], v[186:189], v[76:79]
	v_mfma_f32_16x16x32_bf16 v[40:43], v[154:157], v[194:197], v[40:43]
	v_mfma_f32_16x16x32_bf16 v[44:47], v[162:165], v[194:197], v[44:47]
	v_mfma_f32_16x16x32_bf16 v[24:27], v[154:157], v[202:205], v[24:27]
	v_mfma_f32_16x16x32_bf16 v[28:31], v[162:165], v[202:205], v[28:31]
	v_mfma_f32_16x16x32_bf16 v[8:11], v[154:157], v[210:213], v[8:11]
	v_mfma_f32_16x16x32_bf16 v[12:15], v[162:165], v[210:213], v[12:15]
	v_mfma_f32_16x16x32_bf16 v[56:59], v[166:169], v[182:185], v[56:59]
	v_mfma_f32_16x16x32_bf16 v[60:63], v[174:177], v[182:185], v[60:63]
	v_mfma_f32_16x16x32_bf16 v[32:35], v[166:169], v[190:193], v[32:35]
	v_mfma_f32_16x16x32_bf16 v[36:39], v[174:177], v[190:193], v[36:39]
	v_mfma_f32_16x16x32_bf16 v[16:19], v[166:169], v[198:201], v[16:19]
	v_mfma_f32_16x16x32_bf16 v[20:23], v[174:177], v[198:201], v[20:23]
	v_mfma_f32_16x16x32_bf16 v[0:3], v[166:169], v[206:209], v[0:3]
	v_mfma_f32_16x16x32_bf16 v[4:7], v[174:177], v[206:209], v[4:7]
	v_mfma_f32_16x16x32_bf16 v[56:59], v[170:173], v[186:189], v[56:59]
	v_mfma_f32_16x16x32_bf16 v[60:63], v[178:181], v[186:189], v[60:63]
	v_mfma_f32_16x16x32_bf16 v[32:35], v[170:173], v[194:197], v[32:35]
	v_mfma_f32_16x16x32_bf16 v[36:39], v[178:181], v[194:197], v[36:39]
	v_mfma_f32_16x16x32_bf16 v[16:19], v[170:173], v[202:205], v[16:19]
	v_mfma_f32_16x16x32_bf16 v[20:23], v[178:181], v[202:205], v[20:23]
	v_mfma_f32_16x16x32_bf16 v[0:3], v[170:173], v[210:213], v[0:3]
	v_mfma_f32_16x16x32_bf16 v[4:7], v[178:181], v[210:213], v[4:7]
	s_barrier
	s_setprio 0
	s_add_i32 s85, s85, 2
	s_add_u32 s83, s83, 0x100
	s_addc_u32 s84, s84, 0
	s_add_u32 s76, s76, 0x100
	s_addc_u32 s77, s77, 0
	s_cmp_gt_u32 s85, 29
	s_cbranch_scc0 .LBB0_1155
	s_and_b64 vcc, exec, s[60:61]
	s_cbranch_vccz .LBB0_1158
	s_barrier

; #define PG8_MMA(ai, bj, At, Bt) do { __builtin_amdgcn_s_setprio(1); _Pragma("unroll") for (int m = 0; m < 4; ++m) _Pragma("unroll") for (int n = 0; n < 2; ++n) _Pragma("unroll") for (int k = 0; k < 2; ++k) \
;         acc[ai][bj][m][n] = __builtin_amdgcn_mfma_f32_16x16x32_bf16(Bt[n][k], At[m][k], acc[ai][bj][m][n], 0, 0, 0); __builtin_amdgcn_s_setprio(0); } while (0)
; template <class Epi, class Sched, bool ALIGN_EPI = false, bool SP2 = false, bool A_TILED = false>
; __device__ __forceinline__ void gemm_phase(PG8_LAS unsigned char* lds, const Gemm g, const Sched& S, const Epi& E, const int wave_s) {
;     ...
;         for (int t = PEEL ? 2 : 0; t < nt; t += 2) {
;             const bool last = (t == nt - 2);
;             const char* a1 = cA + (size_t)(t + 1) * kstepA;
;             const char* a2 = last ? nA : cA + (size_t)(t + 2) * kstepA; const char* b2 = last ? nB : cB + (size_t)(t + 2) * kstep;
;             const char* a3 = a2 + kstepA; const char* b3 = b2 + kstep;
;             if (last && has_next) S.a_ready(nxt);
;             if constexpr (SP2) {
;             PG8_ITER(PG8_MMA)
.LBB0_1228:
	ds_read_b128 v[146:149], v140
	ds_read_b128 v[150:153], v140 offset:1024
	ds_read_b128 v[154:157], v140 offset:2048
	ds_read_b128 v[158:161], v140 offset:3072
	ds_read_b128 v[162:165], v141
	ds_read_b128 v[166:169], v141 offset:1024
	ds_read_b128 v[170:173], v141 offset:2048
	ds_read_b128 v[174:177], v141 offset:3072
	s_add_u32 s52, s12, s39
	s_addc_u32 s53, s13, s40
	s_add_u32 s54, s12, s37
	s_addc_u32 s55, s13, s38
	s_cmpk_eq_i32 s41, 0x7c
	s_cselect_b32 s72, s4, s52
	s_cselect_b32 s73, s5, s53
	s_cselect_b32 s70, s0, s54
	s_cselect_b32 s71, s1, s55
	s_add_u32 s68, s72, 0x8000
	s_addc_u32 s69, s73, 0
	s_mov_b32 m0, s42
	v_lshl_add_u64 v[210:211], s[12:13], 0, v[138:139]
	ds_read_b128 v[178:181], v142
	ds_read_b128 v[182:185], v142 offset:1024
	ds_read_b128 v[186:189], v142 offset:2048
	ds_read_b128 v[190:193], v142 offset:3072
	ds_read_b128 v[194:197], v142 offset:4096
	ds_read_b128 v[198:201], v142 offset:5120
	ds_read_b128 v[202:205], v142 offset:6144
	ds_read_b128 v[206:209], v142 offset:7168
	global_load_lds_dwordx4 v[210:211], off
	v_lshl_add_u64 v[210:211], s[12:13], 0, v[136:137]
	s_mov_b32 m0, s43
	s_nop 0
	global_load_lds_dwordx4 v[210:211], off
	s_waitcnt vmcnt(8) lgkmcnt(0)
	s_setprio 1
	s_barrier
	v_mfma_f32_16x16x32_bf16 v[8:11], v[146:149], v[178:181], v[8:11]
	v_mfma_f32_16x16x32_bf16 v[12:15], v[154:157], v[178:181], v[12:15]
	v_mfma_f32_16x16x32_bf16 v[60:63], v[146:149], v[186:189], v[60:63]
	v_mfma_f32_16x16x32_bf16 v[20:23], v[154:157], v[186:189], v[20:23]
	v_mfma_f32_16x16x32_bf16 v[76:79], v[146:149], v[194:197], v[76:79]
	v_mfma_f32_16x16x32_bf16 v[52:55], v[154:157], v[194:197], v[52:55]
	v_mfma_f32_16x16x32_bf16 v[128:131], v[146:149], v[202:205], v[128:131]
	v_mfma_f32_16x16x32_bf16 v[68:71], v[154:157], v[202:205], v[68:71]
	v_mfma_f32_16x16x32_bf16 v[8:11], v[150:153], v[182:185], v[8:11]
	v_mfma_f32_16x16x32_bf16 v[12:15], v[158:161], v[182:185], v[12:15]
	v_mfma_f32_16x16x32_bf16 v[60:63], v[150:153], v[190:193], v[60:63]
	v_mfma_f32_16x16x32_bf16 v[20:23], v[158:161], v[190:193], v[20:23]
	v_mfma_f32_16x16x32_bf16 v[76:79], v[150:153], v[198:201], v[76:79]
	v_mfma_f32_16x16x32_bf16 v[52:55], v[158:161], v[198:201], v[52:55]
	v_mfma_f32_16x16x32_bf16 v[128:131], v[150:153], v[206:209], v[128:131]
	v_mfma_f32_16x16x32_bf16 v[68:71], v[158:161], v[206:209], v[68:71]
	v_mfma_f32_16x16x32_bf16 v[28:31], v[162:165], v[178:181], v[28:31]
	v_mfma_f32_16x16x32_bf16 v[16:19], v[170:173], v[178:181], v[16:19]
	v_mfma_f32_16x16x32_bf16 v[56:59], v[162:165], v[186:189], v[56:59]
	v_mfma_f32_16x16x32_bf16 v[48:51], v[170:173], v[186:189], v[48:51]
	v_mfma_f32_16x16x32_bf16 v[72:75], v[162:165], v[194:197], v[72:75]
	v_mfma_f32_16x16x32_bf16 v[64:67], v[170:173], v[194:197], v[64:67]
	v_mfma_f32_16x16x32_bf16 v[108:111], v[162:165], v[202:205], v[108:111]
	v_mfma_f32_16x16x32_bf16 v[96:99], v[170:173], v[202:205], v[96:99]
	v_mfma_f32_16x16x32_bf16 v[28:31], v[166:169], v[182:185], v[28:31]
	v_mfma_f32_16x16x32_bf16 v[16:19], v[174:177], v[182:185], v[16:19]
	v_mfma_f32_16x16x32_bf16 v[56:59], v[166:169], v[190:193], v[56:59]
	v_mfma_f32_16x16x32_bf16 v[48:51], v[174:177], v[190:193], v[48:51]
	v_mfma_f32_16x16x32_bf16 v[72:75], v[166:169], v[198:201], v[72:75]
	v_mfma_f32_16x16x32_bf16 v[64:67], v[174:177], v[198:201], v[64:67]
	v_mfma_f32_16x16x32_bf16 v[108:111], v[166:169], v[206:209], v[108:111]
	v_mfma_f32_16x16x32_bf16 v[96:99], v[174:177], v[206:209], v[96:99]
	s_barrier
	s_setprio 0
	s_mov_b32 m0, s44
	v_lshl_add_u64 v[210:211], s[70:71], 0, v[34:35]
	s_add_u32 s52, s70, 0x200000
	ds_read_b128 v[178:181], v142 offset:16384
	ds_read_b128 v[182:185], v142 offset:17408
	ds_read_b128 v[186:189], v142 offset:18432
	ds_read_b128 v[190:193], v142 offset:19456
	ds_read_b128 v[194:197], v142 offset:20480
	ds_read_b128 v[198:201], v142 offset:21504
	ds_read_b128 v[202:205], v142 offset:22528
	ds_read_b128 v[206:209], v142 offset:23552
	global_load_lds_dwordx4 v34, s[70:71]
	v_lshl_add_u64 v[212:213], s[70:71], 0, v[134:135]
	s_mov_b32 m0, s45
	s_addc_u32 s53, s71, 0
	global_load_lds_dwordx4 v134, s[70:71]
	v_lshl_add_u64 v[214:215], s[52:53], 0, v[34:35]
	s_mov_b32 m0, s46
	s_nop 0
	global_load_lds_dwordx4 v34, s[52:53]
	v_lshl_add_u64 v[214:215], s[52:53], 0, v[134:135]
	s_mov_b32 m0, s47
	s_nop 0
	global_load_lds_dwordx4 v134, s[52:53]
	v_lshl_add_u64 v[214:215], s[72:73], 0, v[32:33]
	s_mov_b32 m0, s14
	s_nop 0
	global_load_lds_dwordx4 v32, s[72:73]
	v_lshl_add_u64 v[214:215], s[72:73], 0, v[132:133]
	s_mov_b32 m0, s15
	s_nop 0
	global_load_lds_dwordx4 v132, s[72:73]
	s_waitcnt vmcnt(8) lgkmcnt(0)
	s_setprio 1
	s_barrier
	v_mfma_f32_16x16x32_bf16 v[100:103], v[146:149], v[178:181], v[100:103]
	v_mfma_f32_16x16x32_bf16 v[104:107], v[154:157], v[178:181], v[104:107]
	v_mfma_f32_16x16x32_bf16 v[116:119], v[146:149], v[186:189], v[116:119]
	v_mfma_f32_16x16x32_bf16 v[120:123], v[154:157], v[186:189], v[120:123]
	v_mfma_f32_16x16x32_bf16 v[84:87], v[146:149], v[194:197], v[84:87]
	v_mfma_f32_16x16x32_bf16 v[80:83], v[154:157], v[194:197], v[80:83]
	v_mfma_f32_16x16x32_bf16 v[36:39], v[146:149], v[202:205], v[36:39]
	v_mfma_f32_16x16x32_bf16 v[24:27], v[154:157], v[202:205], v[24:27]
	v_mfma_f32_16x16x32_bf16 v[100:103], v[150:153], v[182:185], v[100:103]
	v_mfma_f32_16x16x32_bf16 v[104:107], v[158:161], v[182:185], v[104:107]
	v_mfma_f32_16x16x32_bf16 v[116:119], v[150:153], v[190:193], v[116:119]
	v_mfma_f32_16x16x32_bf16 v[120:123], v[158:161], v[190:193], v[120:123]
	v_mfma_f32_16x16x32_bf16 v[84:87], v[150:153], v[198:201], v[84:87]
	v_mfma_f32_16x16x32_bf16 v[80:83], v[158:161], v[198:201], v[80:83]
	v_mfma_f32_16x16x32_bf16 v[36:39], v[150:153], v[206:209], v[36:39]
	v_mfma_f32_16x16x32_bf16 v[24:27], v[158:161], v[206:209], v[24:27]
	v_mfma_f32_16x16x32_bf16 v[124:127], v[162:165], v[178:181], v[124:127]
	v_mfma_f32_16x16x32_bf16 v[112:115], v[170:173], v[178:181], v[112:115]
	v_mfma_f32_16x16x32_bf16 v[92:95], v[162:165], v[186:189], v[92:95]
	v_mfma_f32_16x16x32_bf16 v[88:91], v[170:173], v[186:189], v[88:91]
	v_mfma_f32_16x16x32_bf16 v[44:47], v[162:165], v[194:197], v[44:47]
	v_mfma_f32_16x16x32_bf16 v[40:43], v[170:173], v[194:197], v[40:43]
	v_mfma_f32_16x16x32_bf16 v[4:7], v[162:165], v[202:205], v[4:7]
	v_mfma_f32_16x16x32_bf16 v[0:3], v[170:173], v[202:205], v[0:3]
	v_mfma_f32_16x16x32_bf16 v[124:127], v[166:169], v[182:185], v[124:127]
	v_mfma_f32_16x16x32_bf16 v[112:115], v[174:177], v[182:185], v[112:115]
	v_mfma_f32_16x16x32_bf16 v[92:95], v[166:169], v[190:193], v[92:95]
	v_mfma_f32_16x16x32_bf16 v[88:91], v[174:177], v[190:193], v[88:91]
	v_mfma_f32_16x16x32_bf16 v[44:47], v[166:169], v[198:201], v[44:47]
	v_mfma_f32_16x16x32_bf16 v[40:43], v[174:177], v[198:201], v[40:43]
	v_mfma_f32_16x16x32_bf16 v[4:7], v[166:169], v[206:209], v[4:7]
	v_mfma_f32_16x16x32_bf16 v[0:3], v[174:177], v[206:209], v[0:3]
	s_barrier
	s_setprio 0
	ds_read_b128 v[146:149], v143
	ds_read_b128 v[150:153], v143 offset:1024
	ds_read_b128 v[154:157], v143 offset:2048
	ds_read_b128 v[158:161], v143 offset:3072
	ds_read_b128 v[162:165], v144
	ds_read_b128 v[166:169], v144 offset:1024
	ds_read_b128 v[170:173], v144 offset:2048
	ds_read_b128 v[174:177], v144 offset:3072
	s_add_u32 s52, s72, 0x4000
	s_addc_u32 s53, s73, 0
	s_mov_b32 m0, s21
	v_lshl_add_u64 v[214:215], s[52:53], 0, v[32:33]
	ds_read_b128 v[178:181], v142 offset:32768
	ds_read_b128 v[182:185], v142 offset:33792
	ds_read_b128 v[186:189], v142 offset:34816
	ds_read_b128 v[190:193], v142 offset:35840
	ds_read_b128 v[194:197], v142 offset:36864
	ds_read_b128 v[198:201], v142 offset:37888
	ds_read_b128 v[202:205], v142 offset:38912
	ds_read_b128 v[206:209], v142 offset:39936
	global_load_lds_dwordx4 v32, s[52:53]
	v_lshl_add_u64 v[214:215], s[52:53], 0, v[132:133]
	s_mov_b32 m0, s22
	s_nop 0
	global_load_lds_dwordx4 v132, s[52:53]
	s_waitcnt vmcnt(8) lgkmcnt(0)
	s_setprio 1
	s_barrier
	v_mfma_f32_16x16x32_bf16 v[8:11], v[146:149], v[178:181], v[8:11]
	v_mfma_f32_16x16x32_bf16 v[12:15], v[154:157], v[178:181], v[12:15]
	v_mfma_f32_16x16x32_bf16 v[60:63], v[146:149], v[186:189], v[60:63]
	v_mfma_f32_16x16x32_bf16 v[20:23], v[154:157], v[186:189], v[20:23]
	v_mfma_f32_16x16x32_bf16 v[76:79], v[146:149], v[194:197], v[76:79]
	v_mfma_f32_16x16x32_bf16 v[52:55], v[154:157], v[194:197], v[52:55]
	v_mfma_f32_16x16x32_bf16 v[128:131], v[146:149], v[202:205], v[128:131]
	v_mfma_f32_16x16x32_bf16 v[68:71], v[154:157], v[202:205], v[68:71]
	v_mfma_f32_16x16x32_bf16 v[8:11], v[150:153], v[182:185], v[8:11]
	v_mfma_f32_16x16x32_bf16 v[12:15], v[158:161], v[182:185], v[12:15]
	v_mfma_f32_16x16x32_bf16 v[60:63], v[150:153], v[190:193], v[60:63]
	v_mfma_f32_16x16x32_bf16 v[20:23], v[158:161], v[190:193], v[20:23]
	v_mfma_f32_16x16x32_bf16 v[76:79], v[150:153], v[198:201], v[76:79]
	v_mfma_f32_16x16x32_bf16 v[52:55], v[158:161], v[198:201], v[52:55]
	v_mfma_f32_16x16x32_bf16 v[128:131], v[150:153], v[206:209], v[128:131]
	v_mfma_f32_16x16x32_bf16 v[68:71], v[158:161], v[206:209], v[68:71]
	v_mfma_f32_16x16x32_bf16 v[28:31], v[162:165], v[178:181], v[28:31]
	v_mfma_f32_16x16x32_bf16 v[16:19], v[170:173], v[178:181], v[16:19]
	v_mfma_f32_16x16x32_bf16 v[56:59], v[162:165], v[186:189], v[56:59]
	v_mfma_f32_16x16x32_bf16 v[48:51], v[170:173], v[186:189], v[48:51]
	v_mfma_f32_16x16x32_bf16 v[72:75], v[162:165], v[194:197], v[72:75]
	v_mfma_f32_16x16x32_bf16 v[64:67], v[170:173], v[194:197], v[64:67]
	v_mfma_f32_16x16x32_bf16 v[108:111], v[162:165], v[202:205], v[108:111]
	v_mfma_f32_16x16x32_bf16 v[96:99], v[170:173], v[202:205], v[96:99]
	v_mfma_f32_16x16x32_bf16 v[28:31], v[166:169], v[182:185], v[28:31]
	v_mfma_f32_16x16x32_bf16 v[16:19], v[174:177], v[182:185], v[16:19]
	v_mfma_f32_16x16x32_bf16 v[56:59], v[166:169], v[190:193], v[56:59]
	v_mfma_f32_16x16x32_bf16 v[48:51], v[174:177], v[190:193], v[48:51]
	v_mfma_f32_16x16x32_bf16 v[72:75], v[166:169], v[198:201], v[72:75]
	v_mfma_f32_16x16x32_bf16 v[64:67], v[174:177], v[198:201], v[64:67]
	v_mfma_f32_16x16x32_bf16 v[108:111], v[166:169], v[206:209], v[108:111]
	v_mfma_f32_16x16x32_bf16 v[96:99], v[174:177], v[206:209], v[96:99]
	s_barrier
; #define PG8_WAIT_V(n) asm volatile("s_waitcnt vmcnt(" #n ")" ::: "memory")
; #define PG8_BAR __builtin_amdgcn_s_barrier()
; template <class Epi, class Sched, bool ALIGN_EPI = false, bool SP2 = false, bool A_TILED = false>
; __device__ __forceinline__ void gemm_phase(PG8_LAS unsigned char* lds, const Gemm g, const Sched& S, const Epi& E, const int wave_s) {
;     ...
;     PG8_WAIT_V(0);
;     if constexpr (!ALIGN_EPI) { if (wr == 0) PG8_BAR; }
;     PG8_BAR;
	s_setprio 0
	s_mov_b32 m0, s48
	v_lshl_add_u64 v[210:211], v[210:211], 0, s[64:65]
	s_add_u32 s52, s70, 0x200080
	ds_read_b128 v[178:181], v142 offset:49152
	ds_read_b128 v[182:185], v142 offset:50176
	ds_read_b128 v[186:189], v142 offset:51200
	ds_read_b128 v[190:193], v142 offset:52224
	ds_read_b128 v[194:197], v142 offset:53248
	ds_read_b128 v[198:201], v142 offset:54272
	ds_read_b128 v[202:205], v142 offset:55296
	ds_read_b128 v[206:209], v142 offset:56320
	global_load_lds_dwordx4 v[210:211], off
	v_lshl_add_u64 v[210:211], v[212:213], 0, s[64:65]
	s_mov_b32 m0, s49
	s_addc_u32 s53, s71, 0
	global_load_lds_dwordx4 v[210:211], off
	v_lshl_add_u64 v[210:211], s[52:53], 0, v[34:35]
	s_mov_b32 m0, s50
	s_nop 0
	global_load_lds_dwordx4 v34, s[52:53]
	v_lshl_add_u64 v[210:211], s[52:53], 0, v[134:135]
	s_mov_b32 m0, s51
	s_nop 0
	global_load_lds_dwordx4 v134, s[52:53]
	v_lshl_add_u64 v[210:211], s[68:69], 0, v[32:33]
	s_mov_b32 m0, s23
	s_nop 0
	global_load_lds_dwordx4 v32, s[68:69]
	v_lshl_add_u64 v[210:211], s[68:69], 0, v[132:133]
	s_mov_b32 m0, s36
	s_nop 0
	global_load_lds_dwordx4 v132, s[68:69]
	s_waitcnt vmcnt(8) lgkmcnt(0)
	s_setprio 1
	s_barrier
	v_mfma_f32_16x16x32_bf16 v[100:103], v[146:149], v[178:181], v[100:103]
	v_mfma_f32_16x16x32_bf16 v[104:107], v[154:157], v[178:181], v[104:107]
	v_mfma_f32_16x16x32_bf16 v[116:119], v[146:149], v[186:189], v[116:119]
	v_mfma_f32_16x16x32_bf16 v[120:123], v[154:157], v[186:189], v[120:123]
	v_mfma_f32_16x16x32_bf16 v[84:87], v[146:149], v[194:197], v[84:87]
	v_mfma_f32_16x16x32_bf16 v[80:83], v[154:157], v[194:197], v[80:83]
	v_mfma_f32_16x16x32_bf16 v[36:39], v[146:149], v[202:205], v[36:39]
	v_mfma_f32_16x16x32_bf16 v[24:27], v[154:157], v[202:205], v[24:27]
	v_mfma_f32_16x16x32_bf16 v[100:103], v[150:153], v[182:185], v[100:103]
	v_mfma_f32_16x16x32_bf16 v[104:107], v[158:161], v[182:185], v[104:107]
	v_mfma_f32_16x16x32_bf16 v[116:119], v[150:153], v[190:193], v[116:119]
	v_mfma_f32_16x16x32_bf16 v[120:123], v[158:161], v[190:193], v[120:123]
	v_mfma_f32_16x16x32_bf16 v[84:87], v[150:153], v[198:201], v[84:87]
	v_mfma_f32_16x16x32_bf16 v[80:83], v[158:161], v[198:201], v[80:83]
	v_mfma_f32_16x16x32_bf16 v[36:39], v[150:153], v[206:209], v[36:39]
	v_mfma_f32_16x16x32_bf16 v[24:27], v[158:161], v[206:209], v[24:27]
	v_mfma_f32_16x16x32_bf16 v[124:127], v[162:165], v[178:181], v[124:127]
	v_mfma_f32_16x16x32_bf16 v[112:115], v[170:173], v[178:181], v[112:115]
	v_mfma_f32_16x16x32_bf16 v[92:95], v[162:165], v[186:189], v[92:95]
	v_mfma_f32_16x16x32_bf16 v[88:91], v[170:173], v[186:189], v[88:91]
	v_mfma_f32_16x16x32_bf16 v[44:47], v[162:165], v[194:197], v[44:47]
	v_mfma_f32_16x16x32_bf16 v[40:43], v[170:173], v[194:197], v[40:43]
	v_mfma_f32_16x16x32_bf16 v[4:7], v[162:165], v[202:205], v[4:7]
	v_mfma_f32_16x16x32_bf16 v[0:3], v[170:173], v[202:205], v[0:3]
	v_mfma_f32_16x16x32_bf16 v[124:127], v[166:169], v[182:185], v[124:127]
	v_mfma_f32_16x16x32_bf16 v[112:115], v[174:177], v[182:185], v[112:115]
	v_mfma_f32_16x16x32_bf16 v[92:95], v[166:169], v[190:193], v[92:95]
	v_mfma_f32_16x16x32_bf16 v[88:91], v[174:177], v[190:193], v[88:91]
	v_mfma_f32_16x16x32_bf16 v[44:47], v[166:169], v[198:201], v[44:47]
	v_mfma_f32_16x16x32_bf16 v[40:43], v[174:177], v[198:201], v[40:43]
	v_mfma_f32_16x16x32_bf16 v[4:7], v[166:169], v[206:209], v[4:7]
	v_mfma_f32_16x16x32_bf16 v[0:3], v[174:177], v[206:209], v[0:3]
	s_barrier
	s_setprio 0
	s_add_i32 s41, s41, 2
	s_add_u32 s37, s37, 0x100
	s_addc_u32 s38, s38, 0
	s_add_u32 s39, s39, 0x10000
	s_addc_u32 s40, s40, 0
	v_lshl_add_u64 v[136:137], v[136:137], 0, s[66:67]
	s_cmpk_gt_u32 s41, 0x7d
	v_lshl_add_u64 v[138:139], v[138:139], 0, s[66:67]
	s_cbranch_scc0 .LBB0_1228
	s_waitcnt vmcnt(0)
	s_cmpk_lt_u32 s8, 0x100
	s_cbranch_scc0 .LBB0_1231
	s_barrier

; template <class Epi, class Sched, bool ALIGN_EPI = false, bool SP2 = false, bool A_TILED = false>
; __device__ __forceinline__ void gemm_phase(PG8_LAS unsigned char* lds, const Gemm g, const Sched& S, const Epi& E, const int wave_s) {
;     ...
;         constexpr bool PEEL = SP2 && !Epi::AFTER_DRAIN;
;         if constexpr (PEEL) {
;             const char* a1 = cA + kstepA; const char* a2 = cA + 2 * kstepA; const char* b2 = cB + 2 * kstep; const char* a3 = a2 + kstepA; const char* b3 = b2 + kstep;
;             PG8_ITER(PG8_MMAZ)
.Lpw_5:
	s_setprio 1
	s_barrier
	v_mfma_f32_16x16x32_bf16 v[88:91], v[0:3], v[56:59], 0
	v_mfma_f32_16x16x32_bf16 v[64:67], v[0:3], v[32:35], 0
	v_mfma_f32_16x16x32_bf16 v[68:71], v[8:11], v[32:35], 0
	v_mfma_f32_16x16x32_bf16 v[72:75], v[0:3], v[40:43], 0
	v_mfma_f32_16x16x32_bf16 v[76:79], v[8:11], v[40:43], 0
	v_mfma_f32_16x16x32_bf16 v[80:83], v[0:3], v[48:51], 0
	v_mfma_f32_16x16x32_bf16 v[84:87], v[8:11], v[48:51], 0
	v_mfma_f32_16x16x32_bf16 v[96:99], v[4:7], v[60:63], v[88:91]
	v_mfma_f32_16x16x32_bf16 v[88:91], v[8:11], v[56:59], 0
	v_mfma_f32_16x16x32_bf16 v[64:67], v[4:7], v[36:39], v[64:67]
	v_mfma_f32_16x16x32_bf16 v[68:71], v[12:15], v[36:39], v[68:71]
	v_mfma_f32_16x16x32_bf16 v[72:75], v[4:7], v[44:47], v[72:75]
	v_mfma_f32_16x16x32_bf16 v[76:79], v[12:15], v[44:47], v[76:79]
	v_mfma_f32_16x16x32_bf16 v[80:83], v[4:7], v[52:55], v[80:83]
	v_mfma_f32_16x16x32_bf16 v[84:87], v[12:15], v[52:55], v[84:87]
	v_mfma_f32_16x16x32_bf16 v[100:103], v[12:15], v[60:63], v[88:91]
	v_mfma_f32_16x16x32_bf16 v[88:91], v[16:19], v[32:35], 0
	v_mfma_f32_16x16x32_bf16 v[32:35], v[24:27], v[32:35], 0
	v_mfma_f32_16x16x32_bf16 v[112:115], v[20:23], v[36:39], v[88:91]
	v_mfma_f32_16x16x32_bf16 v[32:35], v[28:31], v[36:39], v[32:35]
	v_mfma_f32_16x16x32_bf16 v[36:39], v[16:19], v[40:43], 0
	v_mfma_f32_16x16x32_bf16 v[40:43], v[24:27], v[40:43], 0
	v_mfma_f32_16x16x32_bf16 v[36:39], v[20:23], v[44:47], v[36:39]
	v_mfma_f32_16x16x32_bf16 v[40:43], v[28:31], v[44:47], v[40:43]
	v_mfma_f32_16x16x32_bf16 v[44:47], v[16:19], v[48:51], 0
	v_mfma_f32_16x16x32_bf16 v[48:51], v[24:27], v[48:51], 0
	v_mfma_f32_16x16x32_bf16 v[44:47], v[20:23], v[52:55], v[44:47]
	v_mfma_f32_16x16x32_bf16 v[48:51], v[28:31], v[52:55], v[48:51]
	v_mfma_f32_16x16x32_bf16 v[52:55], v[16:19], v[56:59], 0
	v_mfma_f32_16x16x32_bf16 v[56:59], v[24:27], v[56:59], 0
	v_mfma_f32_16x16x32_bf16 v[52:55], v[20:23], v[60:63], v[52:55]
	v_mfma_f32_16x16x32_bf16 v[56:59], v[28:31], v[60:63], v[56:59]
	s_barrier
	s_setprio 0
	s_add_i32 s57, s46, s15
	v_lshl_add_u64 v[250:251], s[78:79], 0, v[128:129]
	s_add_i32 s58, s57, 0x2000
	v_lshl_add_u64 v[144:145], v[250:251], 0, s[64:65]
	s_mov_b32 m0, s57
	v_lshl_add_u64 v[252:253], s[78:79], 0, v[130:131]
	s_add_u32 s82, s78, 0x80100
	ds_read_b128 v[60:63], v151 offset:16384
	ds_read_b128 v[88:91], v151 offset:17408
	ds_read_b128 v[92:95], v151 offset:18432
	ds_read_b128 v[104:107], v151 offset:19456
	ds_read_b128 v[108:111], v151 offset:20480
	ds_read_b128 v[116:119], v151 offset:21504
	ds_read_b128 v[120:123], v151 offset:22528
	ds_read_b128 v[124:127], v151 offset:23552
	global_load_lds_dwordx4 v[144:145], off
	v_lshl_add_u64 v[144:145], v[252:253], 0, s[64:65]
	s_mov_b32 m0, s58
	s_addc_u32 s83, s79, 0
	s_add_i32 s59, s47, s15
	global_load_lds_dwordx4 v[144:145], off
	v_lshl_add_u64 v[144:145], s[82:83], 0, v[128:129]
	s_mov_b32 m0, s59
	s_add_i32 s69, s59, 0x2000
	global_load_lds_dwordx4 v128, s[82:83]
	v_lshl_add_u64 v[144:145], s[82:83], 0, v[130:131]
	s_mov_b32 m0, s69
	v_lshl_add_u64 v[140:141], s[80:81], 0, v[134:135]
	global_load_lds_dwordx4 v130, s[82:83]
	v_lshl_add_u64 v[144:145], v[140:141], 0, s[64:65]
	s_mov_b32 m0, s23
	v_lshl_add_u64 v[142:143], s[80:81], 0, v[132:133]
	global_load_lds_dwordx4 v[144:145], off
	v_lshl_add_u64 v[144:145], v[142:143], 0, s[64:65]
	s_mov_b32 m0, s36
	s_nop 0
	global_load_lds_dwordx4 v[144:145], off
	s_waitcnt vmcnt(24) lgkmcnt(0)
	s_cmp_lg_u32 s98, 0
	s_cbranch_scc1 .Lpw_6
	s_waitcnt vmcnt(8)
.Lpw_6:
	s_setprio 1
	s_barrier
	v_mfma_f32_16x16x32_bf16 v[144:147], v[0:3], v[60:63], 0
	v_mfma_f32_16x16x32_bf16 v[154:157], v[4:7], v[88:91], v[144:147]
	v_mfma_f32_16x16x32_bf16 v[144:147], v[8:11], v[60:63], 0
	v_mfma_f32_16x16x32_bf16 v[158:161], v[12:15], v[88:91], v[144:147]
	v_mfma_f32_16x16x32_bf16 v[144:147], v[0:3], v[92:95], 0
	v_mfma_f32_16x16x32_bf16 v[162:165], v[4:7], v[104:107], v[144:147]
	v_mfma_f32_16x16x32_bf16 v[144:147], v[8:11], v[92:95], 0
	v_mfma_f32_16x16x32_bf16 v[166:169], v[12:15], v[104:107], v[144:147]
	v_mfma_f32_16x16x32_bf16 v[144:147], v[0:3], v[108:111], 0
	v_mfma_f32_16x16x32_bf16 v[0:3], v[0:3], v[120:123], 0
	v_mfma_f32_16x16x32_bf16 v[170:173], v[4:7], v[116:119], v[144:147]
	v_mfma_f32_16x16x32_bf16 v[0:3], v[4:7], v[124:127], v[0:3]
	v_mfma_f32_16x16x32_bf16 v[4:7], v[8:11], v[120:123], 0
	v_mfma_f32_16x16x32_bf16 v[144:147], v[8:11], v[108:111], 0
	v_mfma_f32_16x16x32_bf16 v[4:7], v[12:15], v[124:127], v[4:7]
	v_mfma_f32_16x16x32_bf16 v[174:177], v[12:15], v[116:119], v[144:147]
	v_mfma_f32_16x16x32_bf16 v[8:11], v[16:19], v[60:63], 0
	v_mfma_f32_16x16x32_bf16 v[178:181], v[20:23], v[88:91], v[8:11]
	v_mfma_f32_16x16x32_bf16 v[8:11], v[24:27], v[60:63], 0
	v_mfma_f32_16x16x32_bf16 v[182:185], v[28:31], v[88:91], v[8:11]
	v_mfma_f32_16x16x32_bf16 v[8:11], v[16:19], v[92:95], 0
	v_mfma_f32_16x16x32_bf16 v[186:189], v[20:23], v[104:107], v[8:11]
	v_mfma_f32_16x16x32_bf16 v[8:11], v[24:27], v[92:95], 0
	v_mfma_f32_16x16x32_bf16 v[190:193], v[28:31], v[104:107], v[8:11]
	v_mfma_f32_16x16x32_bf16 v[8:11], v[16:19], v[108:111], 0
	v_mfma_f32_16x16x32_bf16 v[194:197], v[20:23], v[116:119], v[8:11]
	v_mfma_f32_16x16x32_bf16 v[8:11], v[24:27], v[108:111], 0
	v_mfma_f32_16x16x32_bf16 v[198:201], v[28:31], v[116:119], v[8:11]
	v_mfma_f32_16x16x32_bf16 v[8:11], v[16:19], v[120:123], 0
	v_mfma_f32_16x16x32_bf16 v[202:205], v[20:23], v[124:127], v[8:11]
	v_mfma_f32_16x16x32_bf16 v[8:11], v[24:27], v[120:123], 0
	v_mfma_f32_16x16x32_bf16 v[206:209], v[28:31], v[124:127], v[8:11]
	s_barrier
; template <class Epi, class Sched, bool ALIGN_EPI = false, bool SP2 = false, bool A_TILED = false>
; __device__ __forceinline__ void gemm_phase(PG8_LAS unsigned char* lds, const Gemm g, const Sched& S, const Epi& E, const int wave_s) {
;     ...
;         for (int t = PEEL ? 2 : 0; t < nt; t += 2) {
;             const bool last = (t == nt - 2);
;             const char* a1 = cA + (size_t)(t + 1) * kstepA;
;             const char* a2 = last ? nA : cA + (size_t)(t + 2) * kstepA; const char* b2 = last ? nB : cB + (size_t)(t + 2) * kstep;
;             const char* a3 = a2 + kstepA; const char* b3 = b2 + kstep;
	s_setprio 0
	s_add_i32 s71, 0, 0x18000
	s_add_i32 s88, 0, 0x1c000
	v_add_u32_e32 v144, s71, v148
	v_add_u32_e32 v145, s88, v148
	s_nop 0
	ds_read_b128 v[8:11], v144
	ds_read_b128 v[12:15], v144 offset:1024
	ds_read_b128 v[16:19], v144 offset:2048
	ds_read_b128 v[20:23], v144 offset:3072
	ds_read_b128 v[210:213], v145
	ds_read_b128 v[214:217], v145 offset:1024
	ds_read_b128 v[218:221], v145 offset:2048
	ds_read_b128 v[222:225], v145 offset:3072
	s_add_u32 s82, s80, 0x80100
	s_addc_u32 s83, s81, 0
	s_mov_b32 m0, s37
	v_lshl_add_u64 v[88:89], s[82:83], 0, v[134:135]
	ds_read_b128 v[24:27], v151 offset:32768
	ds_read_b128 v[28:31], v151 offset:33792
	ds_read_b128 v[60:63], v151 offset:34816
	ds_read_b128 v[226:229], v151 offset:35840
	ds_read_b128 v[230:233], v151 offset:36864
	ds_read_b128 v[234:237], v151 offset:37888
	ds_read_b128 v[238:241], v151 offset:38912
	ds_read_b128 v[242:245], v151 offset:39936
	global_load_lds_dwordx4 v134, s[82:83]
	v_lshl_add_u64 v[88:89], s[82:83], 0, v[132:133]
	s_mov_b32 m0, s38
	s_nop 0
	global_load_lds_dwordx4 v132, s[82:83]
	s_waitcnt vmcnt(8) lgkmcnt(0)
	s_setprio 1
	s_barrier
	v_mfma_f32_16x16x32_bf16 v[64:67], v[8:11], v[24:27], v[64:67]
	v_mfma_f32_16x16x32_bf16 v[124:127], v[12:15], v[28:31], v[64:67]
	v_mfma_f32_16x16x32_bf16 v[64:67], v[16:19], v[24:27], v[68:71]
	v_mfma_f32_16x16x32_bf16 v[120:123], v[20:23], v[28:31], v[64:67]
	v_mfma_f32_16x16x32_bf16 v[64:67], v[8:11], v[60:63], v[72:75]
	v_mfma_f32_16x16x32_bf16 v[108:111], v[12:15], v[226:229], v[64:67]
	v_mfma_f32_16x16x32_bf16 v[64:67], v[16:19], v[60:63], v[76:79]
	v_mfma_f32_16x16x32_bf16 v[104:107], v[20:23], v[226:229], v[64:67]
	v_mfma_f32_16x16x32_bf16 v[64:67], v[8:11], v[230:233], v[80:83]
	v_mfma_f32_16x16x32_bf16 v[92:95], v[12:15], v[234:237], v[64:67]
	v_mfma_f32_16x16x32_bf16 v[64:67], v[16:19], v[230:233], v[84:87]
	v_mfma_f32_16x16x32_bf16 v[88:91], v[20:23], v[234:237], v[64:67]
	v_mfma_f32_16x16x32_bf16 v[64:67], v[8:11], v[238:241], v[96:99]
	v_mfma_f32_16x16x32_bf16 v[76:79], v[12:15], v[242:245], v[64:67]
	v_mfma_f32_16x16x32_bf16 v[64:67], v[16:19], v[238:241], v[100:103]
	v_mfma_f32_16x16x32_bf16 v[72:75], v[20:23], v[242:245], v[64:67]
	v_mfma_f32_16x16x32_bf16 v[64:67], v[210:213], v[24:27], v[112:115]
	v_mfma_f32_16x16x32_bf16 v[24:27], v[218:221], v[24:27], v[32:35]
	v_mfma_f32_16x16x32_bf16 v[112:115], v[222:225], v[28:31], v[24:27]
	v_mfma_f32_16x16x32_bf16 v[24:27], v[210:213], v[60:63], v[36:39]
	v_mfma_f32_16x16x32_bf16 v[100:103], v[214:217], v[226:229], v[24:27]
	v_mfma_f32_16x16x32_bf16 v[24:27], v[218:221], v[60:63], v[40:43]
	v_mfma_f32_16x16x32_bf16 v[96:99], v[222:225], v[226:229], v[24:27]
	v_mfma_f32_16x16x32_bf16 v[24:27], v[210:213], v[230:233], v[44:47]
	v_mfma_f32_16x16x32_bf16 v[84:87], v[214:217], v[234:237], v[24:27]
	v_mfma_f32_16x16x32_bf16 v[24:27], v[218:221], v[230:233], v[48:51]
	v_mfma_f32_16x16x32_bf16 v[80:83], v[222:225], v[234:237], v[24:27]
	v_mfma_f32_16x16x32_bf16 v[24:27], v[210:213], v[238:241], v[52:55]
	v_mfma_f32_16x16x32_bf16 v[68:71], v[214:217], v[242:245], v[24:27]
	v_mfma_f32_16x16x32_bf16 v[24:27], v[218:221], v[238:241], v[56:59]
	v_mfma_f32_16x16x32_bf16 v[116:119], v[214:217], v[28:31], v[64:67]
	v_mfma_f32_16x16x32_bf16 v[64:67], v[222:225], v[242:245], v[24:27]
	s_barrier
	s_setprio 0
	s_add_i32 s71, s71, s15
	s_add_i32 s77, s71, 0x2000
	s_nop 1
	v_lshl_add_u64 v[24:25], v[250:251], 0, s[66:67]
	s_mov_b32 m0, s71
	s_add_u32 s82, s78, 0x80180
	ds_read_b128 v[32:35], v151 offset:49152
	ds_read_b128 v[36:39], v151 offset:50176
	ds_read_b128 v[226:229], v151 offset:51200
	ds_read_b128 v[230:233], v151 offset:52224
	ds_read_b128 v[234:237], v151 offset:53248
	ds_read_b128 v[238:241], v151 offset:54272
	ds_read_b128 v[242:245], v151 offset:55296
	ds_read_b128 v[246:249], v151 offset:56320
	global_load_lds_dwordx4 v[24:25], off
	v_lshl_add_u64 v[24:25], v[252:253], 0, s[66:67]
	s_mov_b32 m0, s77
	s_addc_u32 s83, s79, 0
	s_add_i32 s88, s88, s15
	global_load_lds_dwordx4 v[24:25], off
	v_lshl_add_u64 v[24:25], s[82:83], 0, v[128:129]
	s_mov_b32 m0, s88
	s_add_i32 s89, s88, 0x2000
	global_load_lds_dwordx4 v128, s[82:83]
	v_lshl_add_u64 v[24:25], s[82:83], 0, v[130:131]
	s_mov_b32 m0, s89
	s_nop 0
	global_load_lds_dwordx4 v130, s[82:83]
	v_lshl_add_u64 v[24:25], v[140:141], 0, s[66:67]
	s_mov_b32 m0, s43
	s_nop 0
	global_load_lds_dwordx4 v[24:25], off
	v_lshl_add_u64 v[24:25], v[142:143], 0, s[66:67]
	s_mov_b32 m0, s44
	s_nop 0
	global_load_lds_dwordx4 v[24:25], off
	s_waitcnt vmcnt(8) lgkmcnt(0)
	s_setprio 1
	s_barrier
	v_mfma_f32_16x16x32_bf16 v[24:27], v[8:11], v[32:35], v[154:157]
	v_mfma_f32_16x16x32_bf16 v[60:63], v[12:15], v[36:39], v[24:27]
	v_mfma_f32_16x16x32_bf16 v[24:27], v[16:19], v[32:35], v[158:161]
	v_mfma_f32_16x16x32_bf16 v[56:59], v[20:23], v[36:39], v[24:27]
	v_mfma_f32_16x16x32_bf16 v[24:27], v[8:11], v[226:229], v[162:165]
	v_mfma_f32_16x16x32_bf16 v[44:47], v[12:15], v[230:233], v[24:27]
	v_mfma_f32_16x16x32_bf16 v[24:27], v[16:19], v[226:229], v[166:169]
	v_mfma_f32_16x16x32_bf16 v[40:43], v[20:23], v[230:233], v[24:27]
	v_mfma_f32_16x16x32_bf16 v[24:27], v[8:11], v[234:237], v[170:173]
	v_mfma_f32_16x16x32_bf16 v[0:3], v[8:11], v[242:245], v[0:3]
	v_mfma_f32_16x16x32_bf16 v[28:31], v[12:15], v[238:241], v[24:27]
	v_mfma_f32_16x16x32_bf16 v[24:27], v[16:19], v[234:237], v[174:177]
	v_mfma_f32_16x16x32_bf16 v[12:15], v[12:15], v[246:249], v[0:3]
	v_mfma_f32_16x16x32_bf16 v[0:3], v[16:19], v[242:245], v[4:7]
	v_mfma_f32_16x16x32_bf16 v[24:27], v[20:23], v[238:241], v[24:27]
	v_mfma_f32_16x16x32_bf16 v[8:11], v[20:23], v[246:249], v[0:3]
	v_mfma_f32_16x16x32_bf16 v[0:3], v[210:213], v[32:35], v[178:181]
	v_mfma_f32_16x16x32_bf16 v[52:55], v[214:217], v[36:39], v[0:3]
	v_mfma_f32_16x16x32_bf16 v[0:3], v[218:221], v[32:35], v[182:185]
	v_mfma_f32_16x16x32_bf16 v[48:51], v[222:225], v[36:39], v[0:3]
	v_mfma_f32_16x16x32_bf16 v[0:3], v[210:213], v[226:229], v[186:189]
	v_mfma_f32_16x16x32_bf16 v[36:39], v[214:217], v[230:233], v[0:3]
	v_mfma_f32_16x16x32_bf16 v[0:3], v[218:221], v[226:229], v[190:193]
	v_mfma_f32_16x16x32_bf16 v[32:35], v[222:225], v[230:233], v[0:3]
	v_mfma_f32_16x16x32_bf16 v[0:3], v[210:213], v[234:237], v[194:197]
	v_mfma_f32_16x16x32_bf16 v[20:23], v[214:217], v[238:241], v[0:3]
	v_mfma_f32_16x16x32_bf16 v[0:3], v[218:221], v[234:237], v[198:201]
	v_mfma_f32_16x16x32_bf16 v[16:19], v[222:225], v[238:241], v[0:3]
	v_mfma_f32_16x16x32_bf16 v[0:3], v[210:213], v[242:245], v[202:205]
	v_mfma_f32_16x16x32_bf16 v[4:7], v[214:217], v[246:249], v[0:3]
	v_mfma_f32_16x16x32_bf16 v[0:3], v[218:221], v[242:245], v[206:209]
	v_mfma_f32_16x16x32_bf16 v[0:3], v[222:225], v[246:249], v[0:3]
	s_barrier
	s_setprio 0
	s_add_u32 s90, s78, 0x200
	s_addc_u32 s85, s79, 0
	s_add_u32 s78, s80, 0x80180
	s_addc_u32 s79, s81, 0
	s_mov_b32 s91, 0
; #define PG8_MMA(ai, bj, At, Bt) do { __builtin_amdgcn_s_setprio(1); _Pragma("unroll") for (int m = 0; m < 4; ++m) _Pragma("unroll") for (int n = 0; n < 2; ++n) _Pragma("unroll") for (int k = 0; k < 2; ++k) \
;         acc[ai][bj][m][n] = __builtin_amdgcn_mfma_f32_16x16x32_bf16(Bt[n][k], At[m][k], acc[ai][bj][m][n], 0, 0, 0); __builtin_amdgcn_s_setprio(0); } while (0)
; template <class Epi, class Sched, bool ALIGN_EPI = false, bool SP2 = false, bool A_TILED = false>
; __device__ __forceinline__ void gemm_phase(PG8_LAS unsigned char* lds, const Gemm g, const Sched& S, const Epi& E, const int wave_s) {
;     ...
;         for (int t = PEEL ? 2 : 0; t < nt; t += 2) {
;             const bool last = (t == nt - 2);
;             const char* a1 = cA + (size_t)(t + 1) * kstepA;
;             const char* a2 = last ? nA : cA + (size_t)(t + 2) * kstepA; const char* b2 = last ? nB : cB + (size_t)(t + 2) * kstep;
;             const char* a3 = a2 + kstepA; const char* b3 = b2 + kstep;
;             if (last && has_next) S.a_ready(nxt);
;             if constexpr (SP2) {
;             PG8_ITER(PG8_MMA)
.LBB0_1619:
	ds_read_b128 v[154:157], v149
	ds_read_b128 v[158:161], v149 offset:1024
	ds_read_b128 v[162:165], v149 offset:2048
	ds_read_b128 v[166:169], v149 offset:3072
	ds_read_b128 v[170:173], v150
	ds_read_b128 v[174:177], v150 offset:1024
	ds_read_b128 v[178:181], v150 offset:2048
	ds_read_b128 v[182:185], v150 offset:3072
	s_add_u32 s80, s78, 0xfff80080
	s_addc_u32 s81, s79, -1
	s_cmp_eq_u32 s91, 28
	s_cselect_b32 s83, s51, s81
	s_cselect_b32 s82, s52, s80
	s_cselect_b32 s81, s53, s85
	s_cselect_b32 s80, s54, s90
	s_mov_b32 m0, s55
	v_lshl_add_u64 v[140:141], s[78:79], 0, v[138:139]
	ds_read_b128 v[186:189], v151
	ds_read_b128 v[190:193], v151 offset:1024
	ds_read_b128 v[194:197], v151 offset:2048
	ds_read_b128 v[198:201], v151 offset:3072
	ds_read_b128 v[202:205], v151 offset:4096
	ds_read_b128 v[206:209], v151 offset:5120
	ds_read_b128 v[210:213], v151 offset:6144
	ds_read_b128 v[214:217], v151 offset:7168
	global_load_lds_dwordx4 v138, s[78:79]
	v_lshl_add_u64 v[140:141], s[78:79], 0, v[136:137]
	s_mov_b32 m0, s56
	s_nop 0
	global_load_lds_dwordx4 v136, s[78:79]
	s_waitcnt vmcnt(8) lgkmcnt(0)
	s_setprio 1
	s_barrier
	v_mfma_f32_16x16x32_bf16 v[124:127], v[154:157], v[186:189], v[124:127]
	v_mfma_f32_16x16x32_bf16 v[120:123], v[162:165], v[186:189], v[120:123]
	v_mfma_f32_16x16x32_bf16 v[108:111], v[154:157], v[194:197], v[108:111]
	v_mfma_f32_16x16x32_bf16 v[104:107], v[162:165], v[194:197], v[104:107]
	v_mfma_f32_16x16x32_bf16 v[92:95], v[154:157], v[202:205], v[92:95]
	v_mfma_f32_16x16x32_bf16 v[88:91], v[162:165], v[202:205], v[88:91]
	v_mfma_f32_16x16x32_bf16 v[76:79], v[154:157], v[210:213], v[76:79]
	v_mfma_f32_16x16x32_bf16 v[72:75], v[162:165], v[210:213], v[72:75]
	v_mfma_f32_16x16x32_bf16 v[124:127], v[158:161], v[190:193], v[124:127]
	v_mfma_f32_16x16x32_bf16 v[120:123], v[166:169], v[190:193], v[120:123]
	v_mfma_f32_16x16x32_bf16 v[108:111], v[158:161], v[198:201], v[108:111]
	v_mfma_f32_16x16x32_bf16 v[104:107], v[166:169], v[198:201], v[104:107]
	v_mfma_f32_16x16x32_bf16 v[92:95], v[158:161], v[206:209], v[92:95]
	v_mfma_f32_16x16x32_bf16 v[88:91], v[166:169], v[206:209], v[88:91]
	v_mfma_f32_16x16x32_bf16 v[76:79], v[158:161], v[214:217], v[76:79]
	v_mfma_f32_16x16x32_bf16 v[72:75], v[166:169], v[214:217], v[72:75]
	v_mfma_f32_16x16x32_bf16 v[116:119], v[170:173], v[186:189], v[116:119]
	v_mfma_f32_16x16x32_bf16 v[112:115], v[178:181], v[186:189], v[112:115]
	v_mfma_f32_16x16x32_bf16 v[100:103], v[170:173], v[194:197], v[100:103]
	v_mfma_f32_16x16x32_bf16 v[96:99], v[178:181], v[194:197], v[96:99]
	v_mfma_f32_16x16x32_bf16 v[84:87], v[170:173], v[202:205], v[84:87]
	v_mfma_f32_16x16x32_bf16 v[80:83], v[178:181], v[202:205], v[80:83]
	v_mfma_f32_16x16x32_bf16 v[68:71], v[170:173], v[210:213], v[68:71]
	v_mfma_f32_16x16x32_bf16 v[64:67], v[178:181], v[210:213], v[64:67]
	v_mfma_f32_16x16x32_bf16 v[116:119], v[174:177], v[190:193], v[116:119]
	v_mfma_f32_16x16x32_bf16 v[112:115], v[182:185], v[190:193], v[112:115]
	v_mfma_f32_16x16x32_bf16 v[100:103], v[174:177], v[198:201], v[100:103]
	v_mfma_f32_16x16x32_bf16 v[96:99], v[182:185], v[198:201], v[96:99]
	v_mfma_f32_16x16x32_bf16 v[84:87], v[174:177], v[206:209], v[84:87]
	v_mfma_f32_16x16x32_bf16 v[80:83], v[182:185], v[206:209], v[80:83]
	v_mfma_f32_16x16x32_bf16 v[68:71], v[174:177], v[214:217], v[68:71]
	v_mfma_f32_16x16x32_bf16 v[64:67], v[182:185], v[214:217], v[64:67]
	s_barrier
	s_setprio 0
	s_mov_b32 m0, s57
	v_lshl_add_u64 v[140:141], s[80:81], 0, v[128:129]
	s_add_u32 s94, s80, 0x80000
	ds_read_b128 v[186:189], v151 offset:16384
	ds_read_b128 v[190:193], v151 offset:17408
	ds_read_b128 v[194:197], v151 offset:18432
	ds_read_b128 v[198:201], v151 offset:19456
	ds_read_b128 v[202:205], v151 offset:20480
	ds_read_b128 v[206:209], v151 offset:21504
	ds_read_b128 v[210:213], v151 offset:22528
	ds_read_b128 v[214:217], v151 offset:23552
	global_load_lds_dwordx4 v128, s[80:81]
	v_lshl_add_u64 v[142:143], s[80:81], 0, v[130:131]
	s_mov_b32 m0, s58
	s_addc_u32 s95, s81, 0
	global_load_lds_dwordx4 v130, s[80:81]
	v_lshl_add_u64 v[146:147], s[94:95], 0, v[128:129]
	s_mov_b32 m0, s59
	v_lshl_add_u64 v[218:219], s[82:83], 0, v[132:133]
	global_load_lds_dwordx4 v128, s[94:95]
	v_lshl_add_u64 v[146:147], s[94:95], 0, v[130:131]
	s_mov_b32 m0, s69
	s_nop 0
	global_load_lds_dwordx4 v130, s[94:95]
	v_lshl_add_u64 v[146:147], s[82:83], 0, v[134:135]
	s_mov_b32 m0, s23
	s_nop 0
	global_load_lds_dwordx4 v134, s[82:83]
	s_mov_b32 m0, s36
	s_nop 0
	global_load_lds_dwordx4 v132, s[82:83]
	s_waitcnt vmcnt(8) lgkmcnt(0)
	s_setprio 1
	s_barrier
	v_mfma_f32_16x16x32_bf16 v[60:63], v[154:157], v[186:189], v[60:63]
	v_mfma_f32_16x16x32_bf16 v[56:59], v[162:165], v[186:189], v[56:59]
	v_mfma_f32_16x16x32_bf16 v[44:47], v[154:157], v[194:197], v[44:47]
	v_mfma_f32_16x16x32_bf16 v[40:43], v[162:165], v[194:197], v[40:43]
	v_mfma_f32_16x16x32_bf16 v[28:31], v[154:157], v[202:205], v[28:31]
	v_mfma_f32_16x16x32_bf16 v[24:27], v[162:165], v[202:205], v[24:27]
	v_mfma_f32_16x16x32_bf16 v[12:15], v[154:157], v[210:213], v[12:15]
	v_mfma_f32_16x16x32_bf16 v[8:11], v[162:165], v[210:213], v[8:11]
	v_mfma_f32_16x16x32_bf16 v[60:63], v[158:161], v[190:193], v[60:63]
	v_mfma_f32_16x16x32_bf16 v[56:59], v[166:169], v[190:193], v[56:59]
	v_mfma_f32_16x16x32_bf16 v[44:47], v[158:161], v[198:201], v[44:47]
	v_mfma_f32_16x16x32_bf16 v[40:43], v[166:169], v[198:201], v[40:43]
	v_mfma_f32_16x16x32_bf16 v[28:31], v[158:161], v[206:209], v[28:31]
	v_mfma_f32_16x16x32_bf16 v[24:27], v[166:169], v[206:209], v[24:27]
	v_mfma_f32_16x16x32_bf16 v[12:15], v[158:161], v[214:217], v[12:15]
	v_mfma_f32_16x16x32_bf16 v[8:11], v[166:169], v[214:217], v[8:11]
	v_mfma_f32_16x16x32_bf16 v[52:55], v[170:173], v[186:189], v[52:55]
	v_mfma_f32_16x16x32_bf16 v[48:51], v[178:181], v[186:189], v[48:51]
	v_mfma_f32_16x16x32_bf16 v[36:39], v[170:173], v[194:197], v[36:39]
	v_mfma_f32_16x16x32_bf16 v[32:35], v[178:181], v[194:197], v[32:35]
	v_mfma_f32_16x16x32_bf16 v[20:23], v[170:173], v[202:205], v[20:23]
	v_mfma_f32_16x16x32_bf16 v[16:19], v[178:181], v[202:205], v[16:19]
	v_mfma_f32_16x16x32_bf16 v[4:7], v[170:173], v[210:213], v[4:7]
	v_mfma_f32_16x16x32_bf16 v[0:3], v[178:181], v[210:213], v[0:3]
	v_mfma_f32_16x16x32_bf16 v[52:55], v[174:177], v[190:193], v[52:55]
	v_mfma_f32_16x16x32_bf16 v[48:51], v[182:185], v[190:193], v[48:51]
	v_mfma_f32_16x16x32_bf16 v[36:39], v[174:177], v[198:201], v[36:39]
	v_mfma_f32_16x16x32_bf16 v[32:35], v[182:185], v[198:201], v[32:35]
	v_mfma_f32_16x16x32_bf16 v[20:23], v[174:177], v[206:209], v[20:23]
	v_mfma_f32_16x16x32_bf16 v[16:19], v[182:185], v[206:209], v[16:19]
	v_mfma_f32_16x16x32_bf16 v[4:7], v[174:177], v[214:217], v[4:7]
	v_mfma_f32_16x16x32_bf16 v[0:3], v[182:185], v[214:217], v[0:3]
	s_barrier
	s_setprio 0
	ds_read_b128 v[154:157], v144
	ds_read_b128 v[158:161], v144 offset:1024
	ds_read_b128 v[162:165], v144 offset:2048
	ds_read_b128 v[166:169], v144 offset:3072
	ds_read_b128 v[170:173], v145
	ds_read_b128 v[174:177], v145 offset:1024
	ds_read_b128 v[178:181], v145 offset:2048
	ds_read_b128 v[182:185], v145 offset:3072
	s_add_u32 s82, s82, 0x80000
	s_addc_u32 s83, s83, 0
	s_mov_b32 m0, s37
	v_lshl_add_u64 v[220:221], s[82:83], 0, v[134:135]
	ds_read_b128 v[186:189], v151 offset:32768
	ds_read_b128 v[190:193], v151 offset:33792
	ds_read_b128 v[194:197], v151 offset:34816
	ds_read_b128 v[198:201], v151 offset:35840
	ds_read_b128 v[202:205], v151 offset:36864
	ds_read_b128 v[206:209], v151 offset:37888
	ds_read_b128 v[210:213], v151 offset:38912
	ds_read_b128 v[214:217], v151 offset:39936
	global_load_lds_dwordx4 v134, s[82:83]
	v_lshl_add_u64 v[220:221], s[82:83], 0, v[132:133]
	s_mov_b32 m0, s38
	s_nop 0
	global_load_lds_dwordx4 v132, s[82:83]
	s_waitcnt vmcnt(8) lgkmcnt(0)
	s_setprio 1
	s_barrier
	v_mfma_f32_16x16x32_bf16 v[124:127], v[154:157], v[186:189], v[124:127]
	v_mfma_f32_16x16x32_bf16 v[120:123], v[162:165], v[186:189], v[120:123]
	v_mfma_f32_16x16x32_bf16 v[108:111], v[154:157], v[194:197], v[108:111]
	v_mfma_f32_16x16x32_bf16 v[104:107], v[162:165], v[194:197], v[104:107]
	v_mfma_f32_16x16x32_bf16 v[92:95], v[154:157], v[202:205], v[92:95]
	v_mfma_f32_16x16x32_bf16 v[88:91], v[162:165], v[202:205], v[88:91]
	v_mfma_f32_16x16x32_bf16 v[76:79], v[154:157], v[210:213], v[76:79]
	v_mfma_f32_16x16x32_bf16 v[72:75], v[162:165], v[210:213], v[72:75]
	v_mfma_f32_16x16x32_bf16 v[124:127], v[158:161], v[190:193], v[124:127]
	v_mfma_f32_16x16x32_bf16 v[120:123], v[166:169], v[190:193], v[120:123]
	v_mfma_f32_16x16x32_bf16 v[108:111], v[158:161], v[198:201], v[108:111]
	v_mfma_f32_16x16x32_bf16 v[104:107], v[166:169], v[198:201], v[104:107]
	v_mfma_f32_16x16x32_bf16 v[92:95], v[158:161], v[206:209], v[92:95]
	v_mfma_f32_16x16x32_bf16 v[88:91], v[166:169], v[206:209], v[88:91]
	v_mfma_f32_16x16x32_bf16 v[76:79], v[158:161], v[214:217], v[76:79]
	v_mfma_f32_16x16x32_bf16 v[72:75], v[166:169], v[214:217], v[72:75]
	v_mfma_f32_16x16x32_bf16 v[116:119], v[170:173], v[186:189], v[116:119]
	v_mfma_f32_16x16x32_bf16 v[112:115], v[178:181], v[186:189], v[112:115]
	v_mfma_f32_16x16x32_bf16 v[100:103], v[170:173], v[194:197], v[100:103]
	v_mfma_f32_16x16x32_bf16 v[96:99], v[178:181], v[194:197], v[96:99]
	v_mfma_f32_16x16x32_bf16 v[84:87], v[170:173], v[202:205], v[84:87]
	v_mfma_f32_16x16x32_bf16 v[80:83], v[178:181], v[202:205], v[80:83]
	v_mfma_f32_16x16x32_bf16 v[68:71], v[170:173], v[210:213], v[68:71]
	v_mfma_f32_16x16x32_bf16 v[64:67], v[178:181], v[210:213], v[64:67]
	v_mfma_f32_16x16x32_bf16 v[116:119], v[174:177], v[190:193], v[116:119]
	v_mfma_f32_16x16x32_bf16 v[112:115], v[182:185], v[190:193], v[112:115]
	v_mfma_f32_16x16x32_bf16 v[100:103], v[174:177], v[198:201], v[100:103]
	v_mfma_f32_16x16x32_bf16 v[96:99], v[182:185], v[198:201], v[96:99]
	v_mfma_f32_16x16x32_bf16 v[84:87], v[174:177], v[206:209], v[84:87]
	v_mfma_f32_16x16x32_bf16 v[80:83], v[182:185], v[206:209], v[80:83]
	v_mfma_f32_16x16x32_bf16 v[68:71], v[174:177], v[214:217], v[68:71]
	v_mfma_f32_16x16x32_bf16 v[64:67], v[182:185], v[214:217], v[64:67]
	s_barrier
; __device__ __forceinline__ int tid_now(int wave_s) { unsigned z = 0u; asm volatile("" : "+v"(z)); return (wave_s << 6) | (int)__builtin_amdgcn_mbcnt_hi(~0u, __builtin_amdgcn_mbcnt_lo(~0u, z)); }
; #define PG8_BAR __builtin_amdgcn_s_barrier()
; template <class Epi, class Sched, bool ALIGN_EPI = false, bool SP2 = false, bool A_TILED = false>
; __device__ __forceinline__ void gemm_phase(PG8_LAS unsigned char* lds, const Gemm g, const Sched& S, const Epi& E, const int wave_s) {
;     ...
;         if constexpr (ALIGN_EPI) { if (wr == 0) PG8_BAR; }
;         if constexpr (!Epi::AFTER_DRAIN) { int te = tid_now(wave_s); asm volatile("" : "+v"(te));
;             E(acc, cur, wr, wc, te & 15, (te & 63) >> 4); S.done(cur); }
;         if (!has_next) break;
;         cur = nxt; cA = nA; cB = nB; ++ui;
;         if constexpr (ALIGN_EPI) { if (wr == 1) PG8_BAR; }
	s_setprio 0
	s_mov_b32 m0, s71
	v_lshl_add_u64 v[140:141], v[140:141], 0, s[60:61]
	s_add_u32 s80, s80, 0x80080
	ds_read_b128 v[186:189], v151 offset:49152
	ds_read_b128 v[190:193], v151 offset:50176
	ds_read_b128 v[194:197], v151 offset:51200
	ds_read_b128 v[198:201], v151 offset:52224
	ds_read_b128 v[202:205], v151 offset:53248
	ds_read_b128 v[206:209], v151 offset:54272
	ds_read_b128 v[210:213], v151 offset:55296
	ds_read_b128 v[214:217], v151 offset:56320
	global_load_lds_dwordx4 v[140:141], off
	v_lshl_add_u64 v[140:141], v[142:143], 0, s[60:61]
	s_mov_b32 m0, s77
	s_addc_u32 s81, s81, 0
	global_load_lds_dwordx4 v[140:141], off
	v_lshl_add_u64 v[140:141], s[80:81], 0, v[128:129]
	s_mov_b32 m0, s88
	s_nop 0
	global_load_lds_dwordx4 v128, s[80:81]
	v_lshl_add_u64 v[140:141], s[80:81], 0, v[130:131]
	s_mov_b32 m0, s89
	s_nop 0
	global_load_lds_dwordx4 v130, s[80:81]
	v_lshl_add_u64 v[140:141], v[146:147], 0, s[60:61]
	s_mov_b32 m0, s43
	s_nop 0
	global_load_lds_dwordx4 v[140:141], off
	v_lshl_add_u64 v[140:141], v[218:219], 0, s[60:61]
	s_mov_b32 m0, s44
	s_nop 0
	global_load_lds_dwordx4 v[140:141], off
	s_waitcnt vmcnt(8) lgkmcnt(0)
	s_setprio 1
	s_barrier
	v_mfma_f32_16x16x32_bf16 v[60:63], v[154:157], v[186:189], v[60:63]
	v_mfma_f32_16x16x32_bf16 v[56:59], v[162:165], v[186:189], v[56:59]
	v_mfma_f32_16x16x32_bf16 v[44:47], v[154:157], v[194:197], v[44:47]
	v_mfma_f32_16x16x32_bf16 v[40:43], v[162:165], v[194:197], v[40:43]
	v_mfma_f32_16x16x32_bf16 v[28:31], v[154:157], v[202:205], v[28:31]
	v_mfma_f32_16x16x32_bf16 v[24:27], v[162:165], v[202:205], v[24:27]
	v_mfma_f32_16x16x32_bf16 v[12:15], v[154:157], v[210:213], v[12:15]
	v_mfma_f32_16x16x32_bf16 v[8:11], v[162:165], v[210:213], v[8:11]
	v_mfma_f32_16x16x32_bf16 v[60:63], v[158:161], v[190:193], v[60:63]
	v_mfma_f32_16x16x32_bf16 v[56:59], v[166:169], v[190:193], v[56:59]
	v_mfma_f32_16x16x32_bf16 v[44:47], v[158:161], v[198:201], v[44:47]
	v_mfma_f32_16x16x32_bf16 v[40:43], v[166:169], v[198:201], v[40:43]
	v_mfma_f32_16x16x32_bf16 v[28:31], v[158:161], v[206:209], v[28:31]
	v_mfma_f32_16x16x32_bf16 v[24:27], v[166:169], v[206:209], v[24:27]
	v_mfma_f32_16x16x32_bf16 v[12:15], v[158:161], v[214:217], v[12:15]
	v_mfma_f32_16x16x32_bf16 v[8:11], v[166:169], v[214:217], v[8:11]
	v_mfma_f32_16x16x32_bf16 v[52:55], v[170:173], v[186:189], v[52:55]
	v_mfma_f32_16x16x32_bf16 v[48:51], v[178:181], v[186:189], v[48:51]
	v_mfma_f32_16x16x32_bf16 v[36:39], v[170:173], v[194:197], v[36:39]
	v_mfma_f32_16x16x32_bf16 v[32:35], v[178:181], v[194:197], v[32:35]
	v_mfma_f32_16x16x32_bf16 v[20:23], v[170:173], v[202:205], v[20:23]
	v_mfma_f32_16x16x32_bf16 v[16:19], v[178:181], v[202:205], v[16:19]
	v_mfma_f32_16x16x32_bf16 v[4:7], v[170:173], v[210:213], v[4:7]
	v_mfma_f32_16x16x32_bf16 v[0:3], v[178:181], v[210:213], v[0:3]
	v_mfma_f32_16x16x32_bf16 v[52:55], v[174:177], v[190:193], v[52:55]
	v_mfma_f32_16x16x32_bf16 v[48:51], v[182:185], v[190:193], v[48:51]
	v_mfma_f32_16x16x32_bf16 v[36:39], v[174:177], v[198:201], v[36:39]
	v_mfma_f32_16x16x32_bf16 v[32:35], v[182:185], v[198:201], v[32:35]
	v_mfma_f32_16x16x32_bf16 v[20:23], v[174:177], v[206:209], v[20:23]
	v_mfma_f32_16x16x32_bf16 v[16:19], v[182:185], v[206:209], v[16:19]
	v_mfma_f32_16x16x32_bf16 v[4:7], v[174:177], v[214:217], v[4:7]
	v_mfma_f32_16x16x32_bf16 v[0:3], v[182:185], v[214:217], v[0:3]
	s_barrier
	s_setprio 0
	s_add_i32 s91, s91, 2
	s_add_u32 s90, s90, 0x100
	s_addc_u32 s85, s85, 0
	s_add_u32 s78, s78, 0x100
	s_addc_u32 s79, s79, 0
	s_cmp_gt_u32 s91, 29
	s_cbranch_scc0 .LBB0_1619
	s_and_b64 vcc, exec, s[62:63]
	s_cbranch_vccz .LBB0_1622
	s_barrier

; #define PG8_MMA(ai, bj, At, Bt) do { __builtin_amdgcn_s_setprio(1); _Pragma("unroll") for (int m = 0; m < 4; ++m) _Pragma("unroll") for (int n = 0; n < 2; ++n) _Pragma("unroll") for (int k = 0; k < 2; ++k) \
;         acc[ai][bj][m][n] = __builtin_amdgcn_mfma_f32_16x16x32_bf16(Bt[n][k], At[m][k], acc[ai][bj][m][n], 0, 0, 0); __builtin_amdgcn_s_setprio(0); } while (0)
; template <class Epi, class Sched, bool ALIGN_EPI = false, bool SP2 = false, bool A_TILED = false>
; __device__ __forceinline__ void gemm_phase(PG8_LAS unsigned char* lds, const Gemm g, const Sched& S, const Epi& E, const int wave_s) {
;     ...
;         for (int t = PEEL ? 2 : 0; t < nt; t += 2) {
;             const bool last = (t == nt - 2);
;             const char* a1 = cA + (size_t)(t + 1) * kstepA;
;             const char* a2 = last ? nA : cA + (size_t)(t + 2) * kstepA; const char* b2 = last ? nB : cB + (size_t)(t + 2) * kstep;
;             const char* a3 = a2 + kstepA; const char* b3 = b2 + kstep;
;             if (last && has_next) S.a_ready(nxt);
;             if constexpr (SP2) {
;             PG8_ITER(PG8_MMA)
.LBB0_1841:
	ds_read_b128 v[146:149], v140
	ds_read_b128 v[150:153], v140 offset:1024
	ds_read_b128 v[154:157], v140 offset:2048
	ds_read_b128 v[158:161], v140 offset:3072
	ds_read_b128 v[162:165], v141
	ds_read_b128 v[166:169], v141 offset:1024
	ds_read_b128 v[170:173], v141 offset:2048
	ds_read_b128 v[174:177], v141 offset:3072
	s_add_u32 s52, s60, s39
	s_addc_u32 s53, s61, s40
	s_add_u32 s54, s60, s37
	s_addc_u32 s55, s61, s38
	s_cmp_eq_u32 s41, 28
	s_cselect_b32 s71, s7, s53
	s_cselect_b32 s70, s6, s52
	s_cselect_b32 s69, s3, s55
	s_cselect_b32 s68, s2, s54
	s_mov_b32 m0, s42
	v_lshl_add_u64 v[210:211], s[60:61], 0, v[138:139]
	ds_read_b128 v[178:181], v142
	ds_read_b128 v[182:185], v142 offset:1024
	ds_read_b128 v[186:189], v142 offset:2048
	ds_read_b128 v[190:193], v142 offset:3072
	ds_read_b128 v[194:197], v142 offset:4096
	ds_read_b128 v[198:201], v142 offset:5120
	ds_read_b128 v[202:205], v142 offset:6144
	ds_read_b128 v[206:209], v142 offset:7168
	global_load_lds_dwordx4 v[210:211], off
	v_lshl_add_u64 v[210:211], s[60:61], 0, v[136:137]
	s_mov_b32 m0, s43
	s_nop 0
	global_load_lds_dwordx4 v[210:211], off
	s_waitcnt vmcnt(8) lgkmcnt(0)
	s_setprio 1
	s_barrier
	v_mfma_f32_16x16x32_bf16 v[8:11], v[146:149], v[178:181], v[8:11]
	v_mfma_f32_16x16x32_bf16 v[12:15], v[154:157], v[178:181], v[12:15]
	v_mfma_f32_16x16x32_bf16 v[60:63], v[146:149], v[186:189], v[60:63]
	v_mfma_f32_16x16x32_bf16 v[20:23], v[154:157], v[186:189], v[20:23]
	v_mfma_f32_16x16x32_bf16 v[76:79], v[146:149], v[194:197], v[76:79]
	v_mfma_f32_16x16x32_bf16 v[52:55], v[154:157], v[194:197], v[52:55]
	v_mfma_f32_16x16x32_bf16 v[128:131], v[146:149], v[202:205], v[128:131]
	v_mfma_f32_16x16x32_bf16 v[68:71], v[154:157], v[202:205], v[68:71]
	v_mfma_f32_16x16x32_bf16 v[8:11], v[150:153], v[182:185], v[8:11]
	v_mfma_f32_16x16x32_bf16 v[12:15], v[158:161], v[182:185], v[12:15]
	v_mfma_f32_16x16x32_bf16 v[60:63], v[150:153], v[190:193], v[60:63]
	v_mfma_f32_16x16x32_bf16 v[20:23], v[158:161], v[190:193], v[20:23]
	v_mfma_f32_16x16x32_bf16 v[76:79], v[150:153], v[198:201], v[76:79]
	v_mfma_f32_16x16x32_bf16 v[52:55], v[158:161], v[198:201], v[52:55]
	v_mfma_f32_16x16x32_bf16 v[128:131], v[150:153], v[206:209], v[128:131]
	v_mfma_f32_16x16x32_bf16 v[68:71], v[158:161], v[206:209], v[68:71]
	v_mfma_f32_16x16x32_bf16 v[24:27], v[162:165], v[178:181], v[24:27]
	v_mfma_f32_16x16x32_bf16 v[16:19], v[170:173], v[178:181], v[16:19]
	v_mfma_f32_16x16x32_bf16 v[56:59], v[162:165], v[186:189], v[56:59]
	v_mfma_f32_16x16x32_bf16 v[48:51], v[170:173], v[186:189], v[48:51]
	v_mfma_f32_16x16x32_bf16 v[72:75], v[162:165], v[194:197], v[72:75]
	v_mfma_f32_16x16x32_bf16 v[64:67], v[170:173], v[194:197], v[64:67]
	v_mfma_f32_16x16x32_bf16 v[108:111], v[162:165], v[202:205], v[108:111]
	v_mfma_f32_16x16x32_bf16 v[96:99], v[170:173], v[202:205], v[96:99]
	v_mfma_f32_16x16x32_bf16 v[24:27], v[166:169], v[182:185], v[24:27]
	v_mfma_f32_16x16x32_bf16 v[16:19], v[174:177], v[182:185], v[16:19]
	v_mfma_f32_16x16x32_bf16 v[56:59], v[166:169], v[190:193], v[56:59]
	v_mfma_f32_16x16x32_bf16 v[48:51], v[174:177], v[190:193], v[48:51]
	v_mfma_f32_16x16x32_bf16 v[72:75], v[166:169], v[198:201], v[72:75]
	v_mfma_f32_16x16x32_bf16 v[64:67], v[174:177], v[198:201], v[64:67]
	v_mfma_f32_16x16x32_bf16 v[108:111], v[166:169], v[206:209], v[108:111]
	v_mfma_f32_16x16x32_bf16 v[96:99], v[174:177], v[206:209], v[96:99]
	s_barrier
	s_setprio 0
	s_mov_b32 m0, s44
	v_lshl_add_u64 v[210:211], s[68:69], 0, v[34:35]
	s_add_u32 s52, s68, 0x80000
	ds_read_b128 v[178:181], v142 offset:16384
	ds_read_b128 v[182:185], v142 offset:17408
	ds_read_b128 v[186:189], v142 offset:18432
	ds_read_b128 v[190:193], v142 offset:19456
	ds_read_b128 v[194:197], v142 offset:20480
	ds_read_b128 v[198:201], v142 offset:21504
	ds_read_b128 v[202:205], v142 offset:22528
	ds_read_b128 v[206:209], v142 offset:23552
	global_load_lds_dwordx4 v34, s[68:69]
	v_lshl_add_u64 v[212:213], s[68:69], 0, v[134:135]
	s_mov_b32 m0, s45
	s_addc_u32 s53, s69, 0
	global_load_lds_dwordx4 v134, s[68:69]
	v_lshl_add_u64 v[214:215], s[52:53], 0, v[34:35]
	s_mov_b32 m0, s46
	v_lshl_add_u64 v[216:217], s[70:71], 0, v[132:133]
	global_load_lds_dwordx4 v34, s[52:53]
	v_lshl_add_u64 v[214:215], s[52:53], 0, v[134:135]
	s_mov_b32 m0, s47
	s_nop 0
	global_load_lds_dwordx4 v134, s[52:53]
	v_lshl_add_u64 v[214:215], s[70:71], 0, v[32:33]
	s_mov_b32 m0, s14
	s_nop 0
	global_load_lds_dwordx4 v32, s[70:71]
	s_mov_b32 m0, s15
	s_nop 0
	global_load_lds_dwordx4 v132, s[70:71]
	s_waitcnt vmcnt(8) lgkmcnt(0)
	s_setprio 1
	s_barrier
	v_mfma_f32_16x16x32_bf16 v[100:103], v[146:149], v[178:181], v[100:103]
	v_mfma_f32_16x16x32_bf16 v[104:107], v[154:157], v[178:181], v[104:107]
	v_mfma_f32_16x16x32_bf16 v[116:119], v[146:149], v[186:189], v[116:119]
	v_mfma_f32_16x16x32_bf16 v[120:123], v[154:157], v[186:189], v[120:123]
	v_mfma_f32_16x16x32_bf16 v[84:87], v[146:149], v[194:197], v[84:87]
	v_mfma_f32_16x16x32_bf16 v[80:83], v[154:157], v[194:197], v[80:83]
	v_mfma_f32_16x16x32_bf16 v[36:39], v[146:149], v[202:205], v[36:39]
	v_mfma_f32_16x16x32_bf16 v[28:31], v[154:157], v[202:205], v[28:31]
	v_mfma_f32_16x16x32_bf16 v[100:103], v[150:153], v[182:185], v[100:103]
	v_mfma_f32_16x16x32_bf16 v[104:107], v[158:161], v[182:185], v[104:107]
	v_mfma_f32_16x16x32_bf16 v[116:119], v[150:153], v[190:193], v[116:119]
	v_mfma_f32_16x16x32_bf16 v[120:123], v[158:161], v[190:193], v[120:123]
	v_mfma_f32_16x16x32_bf16 v[84:87], v[150:153], v[198:201], v[84:87]
	v_mfma_f32_16x16x32_bf16 v[80:83], v[158:161], v[198:201], v[80:83]
	v_mfma_f32_16x16x32_bf16 v[36:39], v[150:153], v[206:209], v[36:39]
	v_mfma_f32_16x16x32_bf16 v[28:31], v[158:161], v[206:209], v[28:31]
	v_mfma_f32_16x16x32_bf16 v[124:127], v[162:165], v[178:181], v[124:127]
	v_mfma_f32_16x16x32_bf16 v[112:115], v[170:173], v[178:181], v[112:115]
	v_mfma_f32_16x16x32_bf16 v[92:95], v[162:165], v[186:189], v[92:95]
	v_mfma_f32_16x16x32_bf16 v[88:91], v[170:173], v[186:189], v[88:91]
	v_mfma_f32_16x16x32_bf16 v[44:47], v[162:165], v[194:197], v[44:47]
	v_mfma_f32_16x16x32_bf16 v[40:43], v[170:173], v[194:197], v[40:43]
	v_mfma_f32_16x16x32_bf16 v[4:7], v[162:165], v[202:205], v[4:7]
	v_mfma_f32_16x16x32_bf16 v[0:3], v[170:173], v[202:205], v[0:3]
	v_mfma_f32_16x16x32_bf16 v[124:127], v[166:169], v[182:185], v[124:127]
	v_mfma_f32_16x16x32_bf16 v[112:115], v[174:177], v[182:185], v[112:115]
	v_mfma_f32_16x16x32_bf16 v[92:95], v[166:169], v[190:193], v[92:95]
	v_mfma_f32_16x16x32_bf16 v[88:91], v[174:177], v[190:193], v[88:91]
	v_mfma_f32_16x16x32_bf16 v[44:47], v[166:169], v[198:201], v[44:47]
	v_mfma_f32_16x16x32_bf16 v[40:43], v[174:177], v[198:201], v[40:43]
	v_mfma_f32_16x16x32_bf16 v[4:7], v[166:169], v[206:209], v[4:7]
	v_mfma_f32_16x16x32_bf16 v[0:3], v[174:177], v[206:209], v[0:3]
	s_barrier
	s_setprio 0
	ds_read_b128 v[146:149], v143
	ds_read_b128 v[150:153], v143 offset:1024
	ds_read_b128 v[154:157], v143 offset:2048
	ds_read_b128 v[158:161], v143 offset:3072
	ds_read_b128 v[162:165], v144
	ds_read_b128 v[166:169], v144 offset:1024
	ds_read_b128 v[170:173], v144 offset:2048
	ds_read_b128 v[174:177], v144 offset:3072
	s_add_u32 s52, s70, 0x80000
	s_addc_u32 s53, s71, 0
	s_mov_b32 m0, s21
	v_lshl_add_u64 v[218:219], s[52:53], 0, v[32:33]
	ds_read_b128 v[178:181], v142 offset:32768
	ds_read_b128 v[182:185], v142 offset:33792
	ds_read_b128 v[186:189], v142 offset:34816
	ds_read_b128 v[190:193], v142 offset:35840
	ds_read_b128 v[194:197], v142 offset:36864
	ds_read_b128 v[198:201], v142 offset:37888
	ds_read_b128 v[202:205], v142 offset:38912
	ds_read_b128 v[206:209], v142 offset:39936
	global_load_lds_dwordx4 v32, s[52:53]
	v_lshl_add_u64 v[218:219], s[52:53], 0, v[132:133]
	s_mov_b32 m0, s22
	s_nop 0
	global_load_lds_dwordx4 v132, s[52:53]
	s_waitcnt vmcnt(8) lgkmcnt(0)
	s_setprio 1
	s_barrier
	v_mfma_f32_16x16x32_bf16 v[8:11], v[146:149], v[178:181], v[8:11]
	v_mfma_f32_16x16x32_bf16 v[12:15], v[154:157], v[178:181], v[12:15]
	v_mfma_f32_16x16x32_bf16 v[60:63], v[146:149], v[186:189], v[60:63]
	v_mfma_f32_16x16x32_bf16 v[20:23], v[154:157], v[186:189], v[20:23]
	v_mfma_f32_16x16x32_bf16 v[76:79], v[146:149], v[194:197], v[76:79]
	v_mfma_f32_16x16x32_bf16 v[52:55], v[154:157], v[194:197], v[52:55]
	v_mfma_f32_16x16x32_bf16 v[128:131], v[146:149], v[202:205], v[128:131]
	v_mfma_f32_16x16x32_bf16 v[68:71], v[154:157], v[202:205], v[68:71]
	v_mfma_f32_16x16x32_bf16 v[8:11], v[150:153], v[182:185], v[8:11]
	v_mfma_f32_16x16x32_bf16 v[12:15], v[158:161], v[182:185], v[12:15]
	v_mfma_f32_16x16x32_bf16 v[60:63], v[150:153], v[190:193], v[60:63]
	v_mfma_f32_16x16x32_bf16 v[20:23], v[158:161], v[190:193], v[20:23]
	v_mfma_f32_16x16x32_bf16 v[76:79], v[150:153], v[198:201], v[76:79]
	v_mfma_f32_16x16x32_bf16 v[52:55], v[158:161], v[198:201], v[52:55]
	v_mfma_f32_16x16x32_bf16 v[128:131], v[150:153], v[206:209], v[128:131]
	v_mfma_f32_16x16x32_bf16 v[68:71], v[158:161], v[206:209], v[68:71]
	v_mfma_f32_16x16x32_bf16 v[24:27], v[162:165], v[178:181], v[24:27]
	v_mfma_f32_16x16x32_bf16 v[16:19], v[170:173], v[178:181], v[16:19]
	v_mfma_f32_16x16x32_bf16 v[56:59], v[162:165], v[186:189], v[56:59]
	v_mfma_f32_16x16x32_bf16 v[48:51], v[170:173], v[186:189], v[48:51]
	v_mfma_f32_16x16x32_bf16 v[72:75], v[162:165], v[194:197], v[72:75]
	v_mfma_f32_16x16x32_bf16 v[64:67], v[170:173], v[194:197], v[64:67]
	v_mfma_f32_16x16x32_bf16 v[108:111], v[162:165], v[202:205], v[108:111]
	v_mfma_f32_16x16x32_bf16 v[96:99], v[170:173], v[202:205], v[96:99]
	v_mfma_f32_16x16x32_bf16 v[24:27], v[166:169], v[182:185], v[24:27]
	v_mfma_f32_16x16x32_bf16 v[16:19], v[174:177], v[182:185], v[16:19]
	v_mfma_f32_16x16x32_bf16 v[56:59], v[166:169], v[190:193], v[56:59]
	v_mfma_f32_16x16x32_bf16 v[48:51], v[174:177], v[190:193], v[48:51]
	v_mfma_f32_16x16x32_bf16 v[72:75], v[166:169], v[198:201], v[72:75]
	v_mfma_f32_16x16x32_bf16 v[64:67], v[174:177], v[198:201], v[64:67]
	v_mfma_f32_16x16x32_bf16 v[108:111], v[166:169], v[206:209], v[108:111]
	v_mfma_f32_16x16x32_bf16 v[96:99], v[174:177], v[206:209], v[96:99]
	s_barrier
; #define PG8_WAIT_V(n) asm volatile("s_waitcnt vmcnt(" #n ")" ::: "memory")
; #define PG8_BAR __builtin_amdgcn_s_barrier()
; template <class Epi, class Sched, bool ALIGN_EPI = false, bool SP2 = false, bool A_TILED = false>
; __device__ __forceinline__ void gemm_phase(PG8_LAS unsigned char* lds, const Gemm g, const Sched& S, const Epi& E, const int wave_s) {
;     ...
;     PG8_WAIT_V(0);
;     if constexpr (!ALIGN_EPI) { if (wr == 0) PG8_BAR; }
;     PG8_BAR;
	s_setprio 0
	s_mov_b32 m0, s48
	v_lshl_add_u64 v[210:211], v[210:211], 0, s[64:65]
	s_add_u32 s52, s68, 0x80080
	ds_read_b128 v[178:181], v142 offset:49152
	ds_read_b128 v[182:185], v142 offset:50176
	ds_read_b128 v[186:189], v142 offset:51200
	ds_read_b128 v[190:193], v142 offset:52224
	ds_read_b128 v[194:197], v142 offset:53248
	ds_read_b128 v[198:201], v142 offset:54272
	ds_read_b128 v[202:205], v142 offset:55296
	ds_read_b128 v[206:209], v142 offset:56320
	global_load_lds_dwordx4 v[210:211], off
	v_lshl_add_u64 v[210:211], v[212:213], 0, s[64:65]
	s_mov_b32 m0, s49
	s_addc_u32 s53, s69, 0
	global_load_lds_dwordx4 v[210:211], off
	v_lshl_add_u64 v[210:211], s[52:53], 0, v[34:35]
	s_mov_b32 m0, s50
	s_nop 0
	global_load_lds_dwordx4 v34, s[52:53]
	v_lshl_add_u64 v[210:211], s[52:53], 0, v[134:135]
	s_mov_b32 m0, s51
	s_nop 0
	global_load_lds_dwordx4 v134, s[52:53]
	v_lshl_add_u64 v[210:211], v[214:215], 0, s[64:65]
	s_mov_b32 m0, s23
	s_nop 0
	global_load_lds_dwordx4 v[210:211], off
	v_lshl_add_u64 v[210:211], v[216:217], 0, s[64:65]
	s_mov_b32 m0, s36
	s_nop 0
	global_load_lds_dwordx4 v[210:211], off
	s_waitcnt vmcnt(8) lgkmcnt(0)
	s_setprio 1
	s_barrier
	v_mfma_f32_16x16x32_bf16 v[100:103], v[146:149], v[178:181], v[100:103]
	v_mfma_f32_16x16x32_bf16 v[104:107], v[154:157], v[178:181], v[104:107]
	v_mfma_f32_16x16x32_bf16 v[116:119], v[146:149], v[186:189], v[116:119]
	v_mfma_f32_16x16x32_bf16 v[120:123], v[154:157], v[186:189], v[120:123]
	v_mfma_f32_16x16x32_bf16 v[84:87], v[146:149], v[194:197], v[84:87]
	v_mfma_f32_16x16x32_bf16 v[80:83], v[154:157], v[194:197], v[80:83]
	v_mfma_f32_16x16x32_bf16 v[36:39], v[146:149], v[202:205], v[36:39]
	v_mfma_f32_16x16x32_bf16 v[28:31], v[154:157], v[202:205], v[28:31]
	v_mfma_f32_16x16x32_bf16 v[100:103], v[150:153], v[182:185], v[100:103]
	v_mfma_f32_16x16x32_bf16 v[104:107], v[158:161], v[182:185], v[104:107]
	v_mfma_f32_16x16x32_bf16 v[116:119], v[150:153], v[190:193], v[116:119]
	v_mfma_f32_16x16x32_bf16 v[120:123], v[158:161], v[190:193], v[120:123]
	v_mfma_f32_16x16x32_bf16 v[84:87], v[150:153], v[198:201], v[84:87]
	v_mfma_f32_16x16x32_bf16 v[80:83], v[158:161], v[198:201], v[80:83]
	v_mfma_f32_16x16x32_bf16 v[36:39], v[150:153], v[206:209], v[36:39]
	v_mfma_f32_16x16x32_bf16 v[28:31], v[158:161], v[206:209], v[28:31]
	v_mfma_f32_16x16x32_bf16 v[124:127], v[162:165], v[178:181], v[124:127]
	v_mfma_f32_16x16x32_bf16 v[112:115], v[170:173], v[178:181], v[112:115]
	v_mfma_f32_16x16x32_bf16 v[92:95], v[162:165], v[186:189], v[92:95]
	v_mfma_f32_16x16x32_bf16 v[88:91], v[170:173], v[186:189], v[88:91]
	v_mfma_f32_16x16x32_bf16 v[44:47], v[162:165], v[194:197], v[44:47]
	v_mfma_f32_16x16x32_bf16 v[40:43], v[170:173], v[194:197], v[40:43]
	v_mfma_f32_16x16x32_bf16 v[4:7], v[162:165], v[202:205], v[4:7]
	v_mfma_f32_16x16x32_bf16 v[0:3], v[170:173], v[202:205], v[0:3]
	v_mfma_f32_16x16x32_bf16 v[124:127], v[166:169], v[182:185], v[124:127]
	v_mfma_f32_16x16x32_bf16 v[112:115], v[174:177], v[182:185], v[112:115]
	v_mfma_f32_16x16x32_bf16 v[92:95], v[166:169], v[190:193], v[92:95]
	v_mfma_f32_16x16x32_bf16 v[88:91], v[174:177], v[190:193], v[88:91]
	v_mfma_f32_16x16x32_bf16 v[44:47], v[166:169], v[198:201], v[44:47]
	v_mfma_f32_16x16x32_bf16 v[40:43], v[174:177], v[198:201], v[40:43]
	v_mfma_f32_16x16x32_bf16 v[4:7], v[166:169], v[206:209], v[4:7]
	v_mfma_f32_16x16x32_bf16 v[0:3], v[174:177], v[206:209], v[0:3]
	s_barrier
	s_setprio 0
	s_add_i32 s41, s41, 2
	s_add_u32 s37, s37, 0x100
	s_addc_u32 s38, s38, 0
	s_add_u32 s39, s39, 0x100
	s_addc_u32 s40, s40, 0
	v_lshl_add_u64 v[136:137], v[136:137], 0, s[66:67]
	s_cmp_gt_u32 s41, 29
	v_lshl_add_u64 v[138:139], v[138:139], 0, s[66:67]
	s_cbranch_scc0 .LBB0_1841
	s_waitcnt vmcnt(0)
	s_cmpk_lt_u32 s0, 0x100
	s_cbranch_scc0 .LBB0_1844
	s_barrier

; template <class Epi, class Sched, bool ALIGN_EPI = false, bool SP2 = false, bool A_TILED = false>
; __device__ __forceinline__ void gemm_phase(PG8_LAS unsigned char* lds, const Gemm g, const Sched& S, const Epi& E, const int wave_s) {
;     ...
;         if constexpr (PEEL) {
;             const char* a1 = cA + kstepA; const char* a2 = cA + 2 * kstepA; const char* b2 = cB + 2 * kstep; const char* a3 = a2 + kstepA; const char* b3 = b2 + kstep;
;             PG8_ITER(PG8_MMAZ)
.Lpw_8:
	s_setprio 1
	s_barrier
	v_mfma_f32_16x16x32_bf16 v[148:151], v[0:3], v[60:63], 0
	v_mfma_f32_16x16x32_bf16 v[158:161], v[0:3], v[92:95], 0
	v_mfma_f32_16x16x32_bf16 v[166:169], v[0:3], v[108:111], 0
	v_mfma_f32_16x16x32_bf16 v[0:3], v[0:3], v[120:123], 0
	v_mfma_f32_16x16x32_bf16 v[150:153], v[4:7], v[88:91], v[148:151]
	v_mfma_f32_16x16x32_bf16 v[158:161], v[4:7], v[104:107], v[158:161]
	v_mfma_f32_16x16x32_bf16 v[166:169], v[4:7], v[116:119], v[166:169]
	v_mfma_f32_16x16x32_bf16 v[0:3], v[4:7], v[124:127], v[0:3]
	v_mfma_f32_16x16x32_bf16 v[4:7], v[8:11], v[120:123], 0
	v_mfma_f32_16x16x32_bf16 v[154:157], v[8:11], v[60:63], 0
	v_mfma_f32_16x16x32_bf16 v[162:165], v[8:11], v[92:95], 0
	v_mfma_f32_16x16x32_bf16 v[170:173], v[8:11], v[108:111], 0
	v_mfma_f32_16x16x32_bf16 v[4:7], v[12:15], v[124:127], v[4:7]
	v_mfma_f32_16x16x32_bf16 v[154:157], v[12:15], v[88:91], v[154:157]
	v_mfma_f32_16x16x32_bf16 v[162:165], v[12:15], v[104:107], v[162:165]
	v_mfma_f32_16x16x32_bf16 v[170:173], v[12:15], v[116:119], v[170:173]
	v_mfma_f32_16x16x32_bf16 v[8:11], v[16:19], v[60:63], 0
	v_mfma_f32_16x16x32_bf16 v[174:177], v[20:23], v[88:91], v[8:11]
	v_mfma_f32_16x16x32_bf16 v[8:11], v[24:27], v[60:63], 0
	v_mfma_f32_16x16x32_bf16 v[60:63], v[28:31], v[88:91], v[8:11]
	v_mfma_f32_16x16x32_bf16 v[8:11], v[16:19], v[92:95], 0
	v_mfma_f32_16x16x32_bf16 v[178:181], v[20:23], v[104:107], v[8:11]
	v_mfma_f32_16x16x32_bf16 v[8:11], v[24:27], v[92:95], 0
	v_mfma_f32_16x16x32_bf16 v[182:185], v[28:31], v[104:107], v[8:11]
	v_mfma_f32_16x16x32_bf16 v[8:11], v[16:19], v[108:111], 0
	v_mfma_f32_16x16x32_bf16 v[186:189], v[20:23], v[116:119], v[8:11]
	v_mfma_f32_16x16x32_bf16 v[8:11], v[24:27], v[108:111], 0
	v_mfma_f32_16x16x32_bf16 v[190:193], v[28:31], v[116:119], v[8:11]
	v_mfma_f32_16x16x32_bf16 v[8:11], v[16:19], v[120:123], 0
	v_mfma_f32_16x16x32_bf16 v[194:197], v[20:23], v[124:127], v[8:11]
	v_mfma_f32_16x16x32_bf16 v[8:11], v[24:27], v[120:123], 0
	v_mfma_f32_16x16x32_bf16 v[198:201], v[28:31], v[124:127], v[8:11]
	s_barrier
	s_setprio 0
	s_add_i32 s67, 0, 0x18000
	s_add_i32 s75, 0, 0x1c000
	v_add_u32_e32 v148, s67, v144
	v_add_u32_e32 v149, s75, v144
	s_nop 0
	ds_read_b128 v[8:11], v148
	ds_read_b128 v[12:15], v148 offset:1024
	ds_read_b128 v[16:19], v148 offset:2048
	ds_read_b128 v[20:23], v148 offset:3072
	ds_read_b128 v[202:205], v149
	ds_read_b128 v[206:209], v149 offset:1024
	ds_read_b128 v[210:213], v149 offset:2048
	ds_read_b128 v[214:217], v149 offset:3072
	s_add_u32 s80, s78, 0x80100
	s_addc_u32 s81, s79, 0
	s_mov_b32 m0, s36
	v_lshl_add_u64 v[88:89], s[80:81], 0, v[134:135]
	ds_read_b128 v[24:27], v147 offset:32768
	ds_read_b128 v[28:31], v147 offset:33792
	ds_read_b128 v[218:221], v147 offset:34816
	ds_read_b128 v[222:225], v147 offset:35840
	ds_read_b128 v[226:229], v147 offset:36864
	ds_read_b128 v[230:233], v147 offset:37888
	ds_read_b128 v[234:237], v147 offset:38912
	ds_read_b128 v[238:241], v147 offset:39936
	global_load_lds_dwordx4 v134, s[80:81]
	v_lshl_add_u64 v[88:89], s[80:81], 0, v[132:133]
	s_mov_b32 m0, s37
	s_nop 0
	global_load_lds_dwordx4 v132, s[80:81]
	s_waitcnt vmcnt(8) lgkmcnt(0)
	s_setprio 1
	s_barrier
	v_mfma_f32_16x16x32_bf16 v[64:67], v[8:11], v[24:27], v[64:67]
	v_mfma_f32_16x16x32_bf16 v[120:123], v[12:15], v[28:31], v[64:67]
	v_mfma_f32_16x16x32_bf16 v[64:67], v[16:19], v[24:27], v[68:71]
	v_mfma_f32_16x16x32_bf16 v[124:127], v[20:23], v[28:31], v[64:67]
	v_mfma_f32_16x16x32_bf16 v[64:67], v[8:11], v[218:221], v[72:75]
	v_mfma_f32_16x16x32_bf16 v[104:107], v[12:15], v[222:225], v[64:67]
	v_mfma_f32_16x16x32_bf16 v[64:67], v[16:19], v[218:221], v[76:79]
	v_mfma_f32_16x16x32_bf16 v[108:111], v[20:23], v[222:225], v[64:67]
	v_mfma_f32_16x16x32_bf16 v[64:67], v[8:11], v[226:229], v[80:83]
	v_mfma_f32_16x16x32_bf16 v[88:91], v[12:15], v[230:233], v[64:67]
	v_mfma_f32_16x16x32_bf16 v[64:67], v[16:19], v[226:229], v[84:87]
	v_mfma_f32_16x16x32_bf16 v[92:95], v[20:23], v[230:233], v[64:67]
	v_mfma_f32_16x16x32_bf16 v[64:67], v[8:11], v[234:237], v[96:99]
	v_mfma_f32_16x16x32_bf16 v[68:71], v[16:19], v[234:237], v[100:103]
	v_mfma_f32_16x16x32_bf16 v[64:67], v[12:15], v[238:241], v[64:67]
	v_mfma_f32_16x16x32_bf16 v[68:71], v[20:23], v[238:241], v[68:71]
	v_mfma_f32_16x16x32_bf16 v[72:75], v[202:205], v[24:27], v[112:115]
	v_mfma_f32_16x16x32_bf16 v[24:27], v[210:213], v[24:27], v[32:35]
	v_mfma_f32_16x16x32_bf16 v[116:119], v[214:217], v[28:31], v[24:27]
	v_mfma_f32_16x16x32_bf16 v[24:27], v[202:205], v[218:221], v[36:39]
	v_mfma_f32_16x16x32_bf16 v[96:99], v[206:209], v[222:225], v[24:27]
	v_mfma_f32_16x16x32_bf16 v[24:27], v[210:213], v[218:221], v[40:43]
	v_mfma_f32_16x16x32_bf16 v[100:103], v[214:217], v[222:225], v[24:27]
	v_mfma_f32_16x16x32_bf16 v[24:27], v[202:205], v[226:229], v[44:47]
	v_mfma_f32_16x16x32_bf16 v[80:83], v[206:209], v[230:233], v[24:27]
	v_mfma_f32_16x16x32_bf16 v[24:27], v[210:213], v[226:229], v[48:51]
	v_mfma_f32_16x16x32_bf16 v[84:87], v[214:217], v[230:233], v[24:27]
	v_mfma_f32_16x16x32_bf16 v[24:27], v[202:205], v[234:237], v[52:55]
	v_mfma_f32_16x16x32_bf16 v[48:51], v[206:209], v[238:241], v[24:27]
	v_mfma_f32_16x16x32_bf16 v[24:27], v[210:213], v[234:237], v[56:59]
	v_mfma_f32_16x16x32_bf16 v[112:115], v[206:209], v[28:31], v[72:75]
	v_mfma_f32_16x16x32_bf16 v[52:55], v[214:217], v[238:241], v[24:27]
	s_barrier
; #define PG8_MMA(ai, bj, At, Bt) do { __builtin_amdgcn_s_setprio(1); _Pragma("unroll") for (int m = 0; m < 4; ++m) _Pragma("unroll") for (int n = 0; n < 2; ++n) _Pragma("unroll") for (int k = 0; k < 2; ++k) \
;         acc[ai][bj][m][n] = __builtin_amdgcn_mfma_f32_16x16x32_bf16(Bt[n][k], At[m][k], acc[ai][bj][m][n], 0, 0, 0); __builtin_amdgcn_s_setprio(0); } while (0)
; template <class Epi, class Sched, bool ALIGN_EPI = false, bool SP2 = false, bool A_TILED = false>
; __device__ __forceinline__ void gemm_phase(PG8_LAS unsigned char* lds, const Gemm g, const Sched& S, const Epi& E, const int wave_s) {
;     ...
;         for (int t = PEEL ? 2 : 0; t < nt; t += 2) {
;             const bool last = (t == nt - 2);
;             const char* a1 = cA + (size_t)(t + 1) * kstepA;
;             const char* a2 = last ? nA : cA + (size_t)(t + 2) * kstepA; const char* b2 = last ? nB : cB + (size_t)(t + 2) * kstep;
;             const char* a3 = a2 + kstepA; const char* b3 = b2 + kstep;
;             if (last && has_next) S.a_ready(nxt);
;             if constexpr (SP2) {
;             PG8_ITER(PG8_MMA)
	s_setprio 0
	s_add_i32 s67, s67, s15
	s_add_i32 s69, s67, 0x2000
	s_nop 1
	v_lshl_add_u64 v[24:25], v[242:243], 0, s[64:65]
	s_mov_b32 m0, s67
	s_add_u32 s80, s76, 0x80180
	ds_read_b128 v[32:35], v147 offset:49152
	ds_read_b128 v[36:39], v147 offset:50176
	ds_read_b128 v[218:221], v147 offset:51200
	ds_read_b128 v[222:225], v147 offset:52224
	ds_read_b128 v[226:229], v147 offset:53248
	ds_read_b128 v[230:233], v147 offset:54272
	ds_read_b128 v[234:237], v147 offset:55296
	ds_read_b128 v[238:241], v147 offset:56320
	global_load_lds_dwordx4 v[24:25], off
	v_lshl_add_u64 v[24:25], v[244:245], 0, s[64:65]
	s_mov_b32 m0, s69
	s_addc_u32 s81, s77, 0
	s_add_i32 s75, s75, s15
	global_load_lds_dwordx4 v[24:25], off
	v_lshl_add_u64 v[24:25], s[80:81], 0, v[128:129]
	s_mov_b32 m0, s75
	s_add_i32 s82, s75, 0x2000
	global_load_lds_dwordx4 v128, s[80:81]
	v_lshl_add_u64 v[24:25], s[80:81], 0, v[130:131]
	s_mov_b32 m0, s82
	s_nop 0
	global_load_lds_dwordx4 v130, s[80:81]
	v_lshl_add_u64 v[24:25], v[246:247], 0, s[64:65]
	s_mov_b32 m0, s43
	s_nop 0
	global_load_lds_dwordx4 v[24:25], off
	v_lshl_add_u64 v[24:25], v[248:249], 0, s[64:65]
	s_mov_b32 m0, s44
	s_nop 0
	global_load_lds_dwordx4 v[24:25], off
	s_waitcnt vmcnt(8) lgkmcnt(0)
	s_setprio 1
	s_barrier
	v_mfma_f32_16x16x32_bf16 v[24:27], v[8:11], v[32:35], v[150:153]
	v_mfma_f32_16x16x32_bf16 v[72:75], v[12:15], v[36:39], v[24:27]
	v_mfma_f32_16x16x32_bf16 v[24:27], v[16:19], v[32:35], v[154:157]
	v_mfma_f32_16x16x32_bf16 v[76:79], v[20:23], v[36:39], v[24:27]
	v_mfma_f32_16x16x32_bf16 v[24:27], v[8:11], v[218:221], v[158:161]
	v_mfma_f32_16x16x32_bf16 v[40:43], v[12:15], v[222:225], v[24:27]
	v_mfma_f32_16x16x32_bf16 v[24:27], v[16:19], v[218:221], v[162:165]
	v_mfma_f32_16x16x32_bf16 v[0:3], v[8:11], v[234:237], v[0:3]
	v_mfma_f32_16x16x32_bf16 v[44:47], v[20:23], v[222:225], v[24:27]
	v_mfma_f32_16x16x32_bf16 v[24:27], v[8:11], v[226:229], v[166:169]
	v_mfma_f32_16x16x32_bf16 v[28:31], v[16:19], v[226:229], v[170:173]
	v_mfma_f32_16x16x32_bf16 v[8:11], v[12:15], v[238:241], v[0:3]
	v_mfma_f32_16x16x32_bf16 v[0:3], v[16:19], v[234:237], v[4:7]
	v_mfma_f32_16x16x32_bf16 v[24:27], v[12:15], v[230:233], v[24:27]
	v_mfma_f32_16x16x32_bf16 v[28:31], v[20:23], v[230:233], v[28:31]
	v_mfma_f32_16x16x32_bf16 v[12:15], v[20:23], v[238:241], v[0:3]
	v_mfma_f32_16x16x32_bf16 v[0:3], v[202:205], v[32:35], v[174:177]
	v_mfma_f32_16x16x32_bf16 v[56:59], v[206:209], v[36:39], v[0:3]
	v_mfma_f32_16x16x32_bf16 v[0:3], v[210:213], v[32:35], v[60:63]
	v_mfma_f32_16x16x32_bf16 v[60:63], v[214:217], v[36:39], v[0:3]
	v_mfma_f32_16x16x32_bf16 v[0:3], v[202:205], v[218:221], v[178:181]
	v_mfma_f32_16x16x32_bf16 v[32:35], v[206:209], v[222:225], v[0:3]
	v_mfma_f32_16x16x32_bf16 v[0:3], v[210:213], v[218:221], v[182:185]
	v_mfma_f32_16x16x32_bf16 v[36:39], v[214:217], v[222:225], v[0:3]
	v_mfma_f32_16x16x32_bf16 v[0:3], v[202:205], v[226:229], v[186:189]
	v_mfma_f32_16x16x32_bf16 v[16:19], v[206:209], v[230:233], v[0:3]
	v_mfma_f32_16x16x32_bf16 v[0:3], v[210:213], v[226:229], v[190:193]
	v_mfma_f32_16x16x32_bf16 v[20:23], v[214:217], v[230:233], v[0:3]
	v_mfma_f32_16x16x32_bf16 v[0:3], v[202:205], v[234:237], v[194:197]
	v_mfma_f32_16x16x32_bf16 v[4:7], v[210:213], v[234:237], v[198:201]
	v_mfma_f32_16x16x32_bf16 v[0:3], v[206:209], v[238:241], v[0:3]
	v_mfma_f32_16x16x32_bf16 v[4:7], v[214:217], v[238:241], v[4:7]
	s_barrier
	s_setprio 0
	s_add_u32 s83, s76, 0x200
	s_addc_u32 s85, s77, 0
	s_add_u32 s76, s78, 0x80180
	s_addc_u32 s77, s79, 0
	s_mov_b32 s88, 0
.LBB0_1953:
	ds_read_b128 v[150:153], v145
	ds_read_b128 v[154:157], v145 offset:1024
	ds_read_b128 v[158:161], v145 offset:2048
	ds_read_b128 v[162:165], v145 offset:3072
	ds_read_b128 v[166:169], v146
	ds_read_b128 v[170:173], v146 offset:1024
	ds_read_b128 v[174:177], v146 offset:2048
	ds_read_b128 v[178:181], v146 offset:3072
	s_add_u32 s78, s76, 0xfff80080
	s_addc_u32 s79, s77, -1
	s_cmp_eq_u32 s88, 28
	s_cselect_b32 s81, s50, s79
	s_cselect_b32 s80, s51, s78
	s_cselect_b32 s79, s52, s85
	s_cselect_b32 s78, s53, s83
	s_mov_b32 m0, s54
	v_lshl_add_u64 v[214:215], s[76:77], 0, v[138:139]
	ds_read_b128 v[182:185], v147
	ds_read_b128 v[186:189], v147 offset:1024
	ds_read_b128 v[190:193], v147 offset:2048
	ds_read_b128 v[194:197], v147 offset:3072
	ds_read_b128 v[198:201], v147 offset:4096
	ds_read_b128 v[202:205], v147 offset:5120
	ds_read_b128 v[206:209], v147 offset:6144
	ds_read_b128 v[210:213], v147 offset:7168
	global_load_lds_dwordx4 v138, s[76:77]
	v_lshl_add_u64 v[214:215], s[76:77], 0, v[136:137]
	s_mov_b32 m0, s55
	s_nop 0
	global_load_lds_dwordx4 v136, s[76:77]
	s_waitcnt vmcnt(8) lgkmcnt(0)
	s_setprio 1
	s_barrier
; #define PG8_MMA(ai, bj, At, Bt) do { __builtin_amdgcn_s_setprio(1); _Pragma("unroll") for (int m = 0; m < 4; ++m) _Pragma("unroll") for (int n = 0; n < 2; ++n) _Pragma("unroll") for (int k = 0; k < 2; ++k) \
;         acc[ai][bj][m][n] = __builtin_amdgcn_mfma_f32_16x16x32_bf16(Bt[n][k], At[m][k], acc[ai][bj][m][n], 0, 0, 0); __builtin_amdgcn_s_setprio(0); } while (0)
; template <class Epi, class Sched, bool ALIGN_EPI = false, bool SP2 = false, bool A_TILED = false>
; __device__ __forceinline__ void gemm_phase(PG8_LAS unsigned char* lds, const Gemm g, const Sched& S, const Epi& E, const int wave_s) {
;     ...
;         for (int t = PEEL ? 2 : 0; t < nt; t += 2) {
;             const bool last = (t == nt - 2);
;             const char* a1 = cA + (size_t)(t + 1) * kstepA;
;             const char* a2 = last ? nA : cA + (size_t)(t + 2) * kstepA; const char* b2 = last ? nB : cB + (size_t)(t + 2) * kstep;
;             const char* a3 = a2 + kstepA; const char* b3 = b2 + kstep;
;             if (last && has_next) S.a_ready(nxt);
;             if constexpr (SP2) {
;             PG8_ITER(PG8_MMA)
	v_mfma_f32_16x16x32_bf16 v[120:123], v[150:153], v[182:185], v[120:123]
	v_mfma_f32_16x16x32_bf16 v[124:127], v[158:161], v[182:185], v[124:127]
	v_mfma_f32_16x16x32_bf16 v[104:107], v[150:153], v[190:193], v[104:107]
	v_mfma_f32_16x16x32_bf16 v[108:111], v[158:161], v[190:193], v[108:111]
	v_mfma_f32_16x16x32_bf16 v[88:91], v[150:153], v[198:201], v[88:91]
	v_mfma_f32_16x16x32_bf16 v[92:95], v[158:161], v[198:201], v[92:95]
	v_mfma_f32_16x16x32_bf16 v[64:67], v[150:153], v[206:209], v[64:67]
	v_mfma_f32_16x16x32_bf16 v[68:71], v[158:161], v[206:209], v[68:71]
	v_mfma_f32_16x16x32_bf16 v[120:123], v[154:157], v[186:189], v[120:123]
	v_mfma_f32_16x16x32_bf16 v[124:127], v[162:165], v[186:189], v[124:127]
	v_mfma_f32_16x16x32_bf16 v[104:107], v[154:157], v[194:197], v[104:107]
	v_mfma_f32_16x16x32_bf16 v[108:111], v[162:165], v[194:197], v[108:111]
	v_mfma_f32_16x16x32_bf16 v[88:91], v[154:157], v[202:205], v[88:91]
	v_mfma_f32_16x16x32_bf16 v[92:95], v[162:165], v[202:205], v[92:95]
	v_mfma_f32_16x16x32_bf16 v[64:67], v[154:157], v[210:213], v[64:67]
	v_mfma_f32_16x16x32_bf16 v[68:71], v[162:165], v[210:213], v[68:71]
	v_mfma_f32_16x16x32_bf16 v[112:115], v[166:169], v[182:185], v[112:115]
	v_mfma_f32_16x16x32_bf16 v[116:119], v[174:177], v[182:185], v[116:119]
	v_mfma_f32_16x16x32_bf16 v[96:99], v[166:169], v[190:193], v[96:99]
	v_mfma_f32_16x16x32_bf16 v[100:103], v[174:177], v[190:193], v[100:103]
	v_mfma_f32_16x16x32_bf16 v[80:83], v[166:169], v[198:201], v[80:83]
	v_mfma_f32_16x16x32_bf16 v[84:87], v[174:177], v[198:201], v[84:87]
	v_mfma_f32_16x16x32_bf16 v[48:51], v[166:169], v[206:209], v[48:51]
	v_mfma_f32_16x16x32_bf16 v[52:55], v[174:177], v[206:209], v[52:55]
	v_mfma_f32_16x16x32_bf16 v[112:115], v[170:173], v[186:189], v[112:115]
	v_mfma_f32_16x16x32_bf16 v[116:119], v[178:181], v[186:189], v[116:119]
	v_mfma_f32_16x16x32_bf16 v[96:99], v[170:173], v[194:197], v[96:99]
	v_mfma_f32_16x16x32_bf16 v[100:103], v[178:181], v[194:197], v[100:103]
	v_mfma_f32_16x16x32_bf16 v[80:83], v[170:173], v[202:205], v[80:83]
	v_mfma_f32_16x16x32_bf16 v[84:87], v[178:181], v[202:205], v[84:87]
	v_mfma_f32_16x16x32_bf16 v[48:51], v[170:173], v[210:213], v[48:51]
	v_mfma_f32_16x16x32_bf16 v[52:55], v[178:181], v[210:213], v[52:55]
	s_barrier
	s_setprio 0
	s_mov_b32 m0, s56
	v_lshl_add_u64 v[214:215], s[78:79], 0, v[128:129]
	s_add_u32 s90, s78, 0x80000
	ds_read_b128 v[182:185], v147 offset:16384
	ds_read_b128 v[186:189], v147 offset:17408
	ds_read_b128 v[190:193], v147 offset:18432
	ds_read_b128 v[194:197], v147 offset:19456
	ds_read_b128 v[198:201], v147 offset:20480
	ds_read_b128 v[202:205], v147 offset:21504
	ds_read_b128 v[206:209], v147 offset:22528
	ds_read_b128 v[210:213], v147 offset:23552
	global_load_lds_dwordx4 v128, s[78:79]
	v_lshl_add_u64 v[216:217], s[78:79], 0, v[130:131]
	s_mov_b32 m0, s57
	s_addc_u32 s91, s79, 0
	global_load_lds_dwordx4 v130, s[78:79]
	v_lshl_add_u64 v[218:219], s[90:91], 0, v[128:129]
	s_mov_b32 m0, s58
	v_lshl_add_u64 v[220:221], s[80:81], 0, v[132:133]
	global_load_lds_dwordx4 v128, s[90:91]
	v_lshl_add_u64 v[218:219], s[90:91], 0, v[130:131]
	s_mov_b32 m0, s59
	s_nop 0
	global_load_lds_dwordx4 v130, s[90:91]
	v_lshl_add_u64 v[218:219], s[80:81], 0, v[134:135]
	s_mov_b32 m0, s22
	s_nop 0
	global_load_lds_dwordx4 v134, s[80:81]
	s_mov_b32 m0, s23
	s_nop 0
	global_load_lds_dwordx4 v132, s[80:81]
	s_waitcnt vmcnt(8) lgkmcnt(0)
	s_setprio 1
	s_barrier
	v_mfma_f32_16x16x32_bf16 v[72:75], v[150:153], v[182:185], v[72:75]
	v_mfma_f32_16x16x32_bf16 v[76:79], v[158:161], v[182:185], v[76:79]
	v_mfma_f32_16x16x32_bf16 v[40:43], v[150:153], v[190:193], v[40:43]
	v_mfma_f32_16x16x32_bf16 v[44:47], v[158:161], v[190:193], v[44:47]
	v_mfma_f32_16x16x32_bf16 v[24:27], v[150:153], v[198:201], v[24:27]
	v_mfma_f32_16x16x32_bf16 v[28:31], v[158:161], v[198:201], v[28:31]
	v_mfma_f32_16x16x32_bf16 v[8:11], v[150:153], v[206:209], v[8:11]
	v_mfma_f32_16x16x32_bf16 v[12:15], v[158:161], v[206:209], v[12:15]
	v_mfma_f32_16x16x32_bf16 v[72:75], v[154:157], v[186:189], v[72:75]
	v_mfma_f32_16x16x32_bf16 v[76:79], v[162:165], v[186:189], v[76:79]
	v_mfma_f32_16x16x32_bf16 v[40:43], v[154:157], v[194:197], v[40:43]
	v_mfma_f32_16x16x32_bf16 v[44:47], v[162:165], v[194:197], v[44:47]
	v_mfma_f32_16x16x32_bf16 v[24:27], v[154:157], v[202:205], v[24:27]
	v_mfma_f32_16x16x32_bf16 v[28:31], v[162:165], v[202:205], v[28:31]
	v_mfma_f32_16x16x32_bf16 v[8:11], v[154:157], v[210:213], v[8:11]
	v_mfma_f32_16x16x32_bf16 v[12:15], v[162:165], v[210:213], v[12:15]
	v_mfma_f32_16x16x32_bf16 v[56:59], v[166:169], v[182:185], v[56:59]
	v_mfma_f32_16x16x32_bf16 v[60:63], v[174:177], v[182:185], v[60:63]
	v_mfma_f32_16x16x32_bf16 v[32:35], v[166:169], v[190:193], v[32:35]
	v_mfma_f32_16x16x32_bf16 v[36:39], v[174:177], v[190:193], v[36:39]
	v_mfma_f32_16x16x32_bf16 v[16:19], v[166:169], v[198:201], v[16:19]
	v_mfma_f32_16x16x32_bf16 v[20:23], v[174:177], v[198:201], v[20:23]
	v_mfma_f32_16x16x32_bf16 v[0:3], v[166:169], v[206:209], v[0:3]
	v_mfma_f32_16x16x32_bf16 v[4:7], v[174:177], v[206:209], v[4:7]
	v_mfma_f32_16x16x32_bf16 v[56:59], v[170:173], v[186:189], v[56:59]
	v_mfma_f32_16x16x32_bf16 v[60:63], v[178:181], v[186:189], v[60:63]
	v_mfma_f32_16x16x32_bf16 v[32:35], v[170:173], v[194:197], v[32:35]
	v_mfma_f32_16x16x32_bf16 v[36:39], v[178:181], v[194:197], v[36:39]
	v_mfma_f32_16x16x32_bf16 v[16:19], v[170:173], v[202:205], v[16:19]
	v_mfma_f32_16x16x32_bf16 v[20:23], v[178:181], v[202:205], v[20:23]
	v_mfma_f32_16x16x32_bf16 v[0:3], v[170:173], v[210:213], v[0:3]
	v_mfma_f32_16x16x32_bf16 v[4:7], v[178:181], v[210:213], v[4:7]
	s_barrier
; #define PG8_STAGE(bufoff, gbase, voff) do { _Pragma("unroll") for (int _i = 0; _i < 2; ++_i) \
;         __builtin_amdgcn_global_load_lds((const unsigned*)((const char*)(gbase) + (voff)[_i]), (PG8_LAS unsigned*)(lds + (bufoff) + ldsw + _i * 8192), 16, 0, 0); } while (0)
; #define PG8_BAR __builtin_amdgcn_s_barrier()
; template <class Epi, class Sched, bool ALIGN_EPI = false, bool SP2 = false, bool A_TILED = false>
; __device__ __forceinline__ void gemm_phase(PG8_LAS unsigned char* lds, const Gemm g, const Sched& S, const Epi& E, const int wave_s) {
;     ...
;         for (int t = PEEL ? 2 : 0; t < nt; t += 2) {
;             const bool last = (t == nt - 2);
;             const char* a1 = cA + (size_t)(t + 1) * kstepA;
;             const char* a2 = last ? nA : cA + (size_t)(t + 2) * kstepA; const char* b2 = last ? nB : cB + (size_t)(t + 2) * kstep;
;             const char* a3 = a2 + kstepA; const char* b3 = b2 + kstep;
;             if (last && has_next) S.a_ready(nxt);
;             if constexpr (SP2) {
;             PG8_ITER(PG8_MMA)
;             } else {
;             PG8_LDB(B0, 0, 0); PG8_SCHED; PG8_LDA(At, 0, 0); PG8_STAGE(PG8_SA(1, 1), a1 + hstepA, voffA);
;             PG8_WAIT_L(8); PG8_BAR; PG8_WAIT_L(0); PG8_MMA(0, 0, At, B0); PG8_BAR; PG8_SCHED;
;             PG8_LDB(B1, 0, 1); PG8_STAGE(PG8_SB(0, 0), b2, voffB);
;             PG8_BAR; PG8_WAIT_L(0); PG8_MMA(0, 1, At, B1); PG8_BAR;
;             PG8_LDA(At, 0, 1); PG8_STAGE(PG8_SA(0, 0), a2, voffA);
;             PG8_BAR; PG8_WAIT_L(0); PG8_MMA(1, 0, At, B0); PG8_BAR; PG8_SCHED;
;             PG8_STAGE(PG8_SB(0, 1), b2 + hstep, voffB);
;             PG8_WAIT_V(6); PG8_BAR; PG8_MMA(1, 1, At, B1); PG8_BAR;
;             PG8_LDB(B0, 1, 0); PG8_SCHED; PG8_LDA(At, 1, 0); PG8_STAGE(PG8_SA(0, 1), a2 + hstepA, voffA);
;             PG8_WAIT_L(8); PG8_BAR; PG8_WAIT_L(0); PG8_MMA(0, 0, At, B0); PG8_BAR; PG8_SCHED;
;             PG8_LDB(B1, 1, 1); PG8_STAGE(PG8_SB(1, 0), b3, voffB);
;             PG8_BAR; PG8_WAIT_L(0); PG8_MMA(0, 1, At, B1); PG8_BAR;
;             PG8_LDA(At, 1, 1); PG8_STAGE(PG8_SA(1, 0), a3, voffA);
;             PG8_BAR; PG8_WAIT_L(0); PG8_MMA(1, 0, At, B0); PG8_BAR; PG8_SCHED;
;             PG8_STAGE(PG8_SB(1, 1), b3 + hstep, voffB);
;             PG8_WAIT_V(6); PG8_BAR; PG8_MMA(1, 1, At, B1); PG8_BAR;
;             }
;         }
;         if constexpr (ALIGN_EPI) { if (wr == 0) PG8_BAR; }
	s_setprio 0
	ds_read_b128 v[150:153], v148
	ds_read_b128 v[154:157], v148 offset:1024
	ds_read_b128 v[158:161], v148 offset:2048
	ds_read_b128 v[162:165], v148 offset:3072
	ds_read_b128 v[166:169], v149
	ds_read_b128 v[170:173], v149 offset:1024
	ds_read_b128 v[174:177], v149 offset:2048
	ds_read_b128 v[178:181], v149 offset:3072
	s_add_u32 s80, s80, 0x80000
	s_addc_u32 s81, s81, 0
	s_mov_b32 m0, s36
	v_lshl_add_u64 v[222:223], s[80:81], 0, v[134:135]
	ds_read_b128 v[182:185], v147 offset:32768
	ds_read_b128 v[186:189], v147 offset:33792
	ds_read_b128 v[190:193], v147 offset:34816
	ds_read_b128 v[194:197], v147 offset:35840
	ds_read_b128 v[198:201], v147 offset:36864
	ds_read_b128 v[202:205], v147 offset:37888
	ds_read_b128 v[206:209], v147 offset:38912
	ds_read_b128 v[210:213], v147 offset:39936
	global_load_lds_dwordx4 v134, s[80:81]
	v_lshl_add_u64 v[222:223], s[80:81], 0, v[132:133]
	s_mov_b32 m0, s37
	s_nop 0
	global_load_lds_dwordx4 v132, s[80:81]
	s_waitcnt vmcnt(8) lgkmcnt(0)
	s_setprio 1
	s_barrier
	v_mfma_f32_16x16x32_bf16 v[120:123], v[150:153], v[182:185], v[120:123]
	v_mfma_f32_16x16x32_bf16 v[124:127], v[158:161], v[182:185], v[124:127]
	v_mfma_f32_16x16x32_bf16 v[104:107], v[150:153], v[190:193], v[104:107]
	v_mfma_f32_16x16x32_bf16 v[108:111], v[158:161], v[190:193], v[108:111]
	v_mfma_f32_16x16x32_bf16 v[88:91], v[150:153], v[198:201], v[88:91]
	v_mfma_f32_16x16x32_bf16 v[92:95], v[158:161], v[198:201], v[92:95]
	v_mfma_f32_16x16x32_bf16 v[64:67], v[150:153], v[206:209], v[64:67]
	v_mfma_f32_16x16x32_bf16 v[68:71], v[158:161], v[206:209], v[68:71]
	v_mfma_f32_16x16x32_bf16 v[120:123], v[154:157], v[186:189], v[120:123]
	v_mfma_f32_16x16x32_bf16 v[124:127], v[162:165], v[186:189], v[124:127]
	v_mfma_f32_16x16x32_bf16 v[104:107], v[154:157], v[194:197], v[104:107]
	v_mfma_f32_16x16x32_bf16 v[108:111], v[162:165], v[194:197], v[108:111]
	v_mfma_f32_16x16x32_bf16 v[88:91], v[154:157], v[202:205], v[88:91]
	v_mfma_f32_16x16x32_bf16 v[92:95], v[162:165], v[202:205], v[92:95]
	v_mfma_f32_16x16x32_bf16 v[64:67], v[154:157], v[210:213], v[64:67]
	v_mfma_f32_16x16x32_bf16 v[68:71], v[162:165], v[210:213], v[68:71]
	v_mfma_f32_16x16x32_bf16 v[112:115], v[166:169], v[182:185], v[112:115]
	v_mfma_f32_16x16x32_bf16 v[116:119], v[174:177], v[182:185], v[116:119]
	v_mfma_f32_16x16x32_bf16 v[96:99], v[166:169], v[190:193], v[96:99]
	v_mfma_f32_16x16x32_bf16 v[100:103], v[174:177], v[190:193], v[100:103]
	v_mfma_f32_16x16x32_bf16 v[80:83], v[166:169], v[198:201], v[80:83]
	v_mfma_f32_16x16x32_bf16 v[84:87], v[174:177], v[198:201], v[84:87]
	v_mfma_f32_16x16x32_bf16 v[48:51], v[166:169], v[206:209], v[48:51]
	v_mfma_f32_16x16x32_bf16 v[52:55], v[174:177], v[206:209], v[52:55]
	v_mfma_f32_16x16x32_bf16 v[112:115], v[170:173], v[186:189], v[112:115]
	v_mfma_f32_16x16x32_bf16 v[116:119], v[178:181], v[186:189], v[116:119]
	v_mfma_f32_16x16x32_bf16 v[96:99], v[170:173], v[194:197], v[96:99]
	v_mfma_f32_16x16x32_bf16 v[100:103], v[178:181], v[194:197], v[100:103]
	v_mfma_f32_16x16x32_bf16 v[80:83], v[170:173], v[202:205], v[80:83]
	v_mfma_f32_16x16x32_bf16 v[84:87], v[178:181], v[202:205], v[84:87]
	v_mfma_f32_16x16x32_bf16 v[48:51], v[170:173], v[210:213], v[48:51]
	v_mfma_f32_16x16x32_bf16 v[52:55], v[178:181], v[210:213], v[52:55]
	s_barrier
	s_setprio 0
	s_mov_b32 m0, s67
	v_lshl_add_u64 v[214:215], v[214:215], 0, s[12:13]
	s_add_u32 s78, s78, 0x80080
	ds_read_b128 v[182:185], v147 offset:49152
	ds_read_b128 v[186:189], v147 offset:50176
	ds_read_b128 v[190:193], v147 offset:51200
	ds_read_b128 v[194:197], v147 offset:52224
	ds_read_b128 v[198:201], v147 offset:53248
	ds_read_b128 v[202:205], v147 offset:54272
	ds_read_b128 v[206:209], v147 offset:55296
	ds_read_b128 v[210:213], v147 offset:56320
	global_load_lds_dwordx4 v[214:215], off
	v_lshl_add_u64 v[214:215], v[216:217], 0, s[12:13]
	s_mov_b32 m0, s69
	s_addc_u32 s79, s79, 0
	global_load_lds_dwordx4 v[214:215], off
	v_lshl_add_u64 v[214:215], s[78:79], 0, v[128:129]
	s_mov_b32 m0, s75
	s_nop 0
	global_load_lds_dwordx4 v128, s[78:79]
	v_lshl_add_u64 v[214:215], s[78:79], 0, v[130:131]
	s_mov_b32 m0, s82
	s_nop 0
	global_load_lds_dwordx4 v130, s[78:79]
	v_lshl_add_u64 v[214:215], v[218:219], 0, s[12:13]
	s_mov_b32 m0, s43
	s_nop 0
	global_load_lds_dwordx4 v[214:215], off
	v_lshl_add_u64 v[214:215], v[220:221], 0, s[12:13]
	s_mov_b32 m0, s44
	s_nop 0
	global_load_lds_dwordx4 v[214:215], off
	s_waitcnt vmcnt(8) lgkmcnt(0)
	s_setprio 1
	s_barrier
	v_mfma_f32_16x16x32_bf16 v[72:75], v[150:153], v[182:185], v[72:75]
	v_mfma_f32_16x16x32_bf16 v[76:79], v[158:161], v[182:185], v[76:79]
	v_mfma_f32_16x16x32_bf16 v[40:43], v[150:153], v[190:193], v[40:43]
	v_mfma_f32_16x16x32_bf16 v[44:47], v[158:161], v[190:193], v[44:47]
	v_mfma_f32_16x16x32_bf16 v[24:27], v[150:153], v[198:201], v[24:27]
	v_mfma_f32_16x16x32_bf16 v[28:31], v[158:161], v[198:201], v[28:31]
	v_mfma_f32_16x16x32_bf16 v[8:11], v[150:153], v[206:209], v[8:11]
	v_mfma_f32_16x16x32_bf16 v[12:15], v[158:161], v[206:209], v[12:15]
	v_mfma_f32_16x16x32_bf16 v[72:75], v[154:157], v[186:189], v[72:75]
	v_mfma_f32_16x16x32_bf16 v[76:79], v[162:165], v[186:189], v[76:79]
	v_mfma_f32_16x16x32_bf16 v[40:43], v[154:157], v[194:197], v[40:43]
	v_mfma_f32_16x16x32_bf16 v[44:47], v[162:165], v[194:197], v[44:47]
	v_mfma_f32_16x16x32_bf16 v[24:27], v[154:157], v[202:205], v[24:27]
	v_mfma_f32_16x16x32_bf16 v[28:31], v[162:165], v[202:205], v[28:31]
	v_mfma_f32_16x16x32_bf16 v[8:11], v[154:157], v[210:213], v[8:11]
	v_mfma_f32_16x16x32_bf16 v[12:15], v[162:165], v[210:213], v[12:15]
	v_mfma_f32_16x16x32_bf16 v[56:59], v[166:169], v[182:185], v[56:59]
	v_mfma_f32_16x16x32_bf16 v[60:63], v[174:177], v[182:185], v[60:63]
	v_mfma_f32_16x16x32_bf16 v[32:35], v[166:169], v[190:193], v[32:35]
	v_mfma_f32_16x16x32_bf16 v[36:39], v[174:177], v[190:193], v[36:39]
	v_mfma_f32_16x16x32_bf16 v[16:19], v[166:169], v[198:201], v[16:19]
	v_mfma_f32_16x16x32_bf16 v[20:23], v[174:177], v[198:201], v[20:23]
	v_mfma_f32_16x16x32_bf16 v[0:3], v[166:169], v[206:209], v[0:3]
	v_mfma_f32_16x16x32_bf16 v[4:7], v[174:177], v[206:209], v[4:7]
	v_mfma_f32_16x16x32_bf16 v[56:59], v[170:173], v[186:189], v[56:59]
	v_mfma_f32_16x16x32_bf16 v[60:63], v[178:181], v[186:189], v[60:63]
	v_mfma_f32_16x16x32_bf16 v[32:35], v[170:173], v[194:197], v[32:35]
	v_mfma_f32_16x16x32_bf16 v[36:39], v[178:181], v[194:197], v[36:39]
	v_mfma_f32_16x16x32_bf16 v[16:19], v[170:173], v[202:205], v[16:19]
	v_mfma_f32_16x16x32_bf16 v[20:23], v[178:181], v[202:205], v[20:23]
	v_mfma_f32_16x16x32_bf16 v[0:3], v[170:173], v[210:213], v[0:3]
	v_mfma_f32_16x16x32_bf16 v[4:7], v[178:181], v[210:213], v[4:7]
	s_barrier
	s_setprio 0
	s_add_i32 s88, s88, 2
	s_add_u32 s83, s83, 0x100
	s_addc_u32 s85, s85, 0
	s_add_u32 s76, s76, 0x100
	s_addc_u32 s77, s77, 0
	s_cmp_gt_u32 s88, 29
	s_cbranch_scc0 .LBB0_1953
	s_and_b64 vcc, exec, s[60:61]
	s_cbranch_vccz .LBB0_1956
	s_barrier

; #define PG8_MMA(ai, bj, At, Bt) do { __builtin_amdgcn_s_setprio(1); _Pragma("unroll") for (int m = 0; m < 4; ++m) _Pragma("unroll") for (int n = 0; n < 2; ++n) _Pragma("unroll") for (int k = 0; k < 2; ++k) \
;         acc[ai][bj][m][n] = __builtin_amdgcn_mfma_f32_16x16x32_bf16(Bt[n][k], At[m][k], acc[ai][bj][m][n], 0, 0, 0); __builtin_amdgcn_s_setprio(0); } while (0)
; template <class Epi, class Sched, bool ALIGN_EPI = false, bool SP2 = false, bool A_TILED = false>
; __device__ __forceinline__ void gemm_phase(PG8_LAS unsigned char* lds, const Gemm g, const Sched& S, const Epi& E, const int wave_s) {
;     ...
;         for (int t = PEEL ? 2 : 0; t < nt; t += 2) {
;             const bool last = (t == nt - 2);
;             const char* a1 = cA + (size_t)(t + 1) * kstepA;
;             const char* a2 = last ? nA : cA + (size_t)(t + 2) * kstepA; const char* b2 = last ? nB : cB + (size_t)(t + 2) * kstep;
;             const char* a3 = a2 + kstepA; const char* b3 = b2 + kstep;
;             if (last && has_next) S.a_ready(nxt);
;             if constexpr (SP2) {
;             PG8_ITER(PG8_MMA)
.LBB0_2026:
	ds_read_b128 v[146:149], v140
	ds_read_b128 v[150:153], v140 offset:1024
	ds_read_b128 v[154:157], v140 offset:2048
	ds_read_b128 v[158:161], v140 offset:3072
	ds_read_b128 v[162:165], v141
	ds_read_b128 v[166:169], v141 offset:1024
	ds_read_b128 v[170:173], v141 offset:2048
	ds_read_b128 v[174:177], v141 offset:3072
	s_add_u32 s52, s60, s39
	s_addc_u32 s53, s61, s40
	s_add_u32 s54, s60, s37
	s_addc_u32 s55, s61, s38
	s_cmpk_eq_i32 s41, 0x7c
	s_cselect_b32 s72, s6, s52
	s_cselect_b32 s73, s7, s53
	s_cselect_b32 s70, s2, s54
	s_cselect_b32 s71, s3, s55
	s_add_u32 s68, s72, 0x8000
	s_addc_u32 s69, s73, 0
	s_mov_b32 m0, s42
	v_lshl_add_u64 v[210:211], s[60:61], 0, v[138:139]
	ds_read_b128 v[178:181], v142
	ds_read_b128 v[182:185], v142 offset:1024
	ds_read_b128 v[186:189], v142 offset:2048
	ds_read_b128 v[190:193], v142 offset:3072
	ds_read_b128 v[194:197], v142 offset:4096
	ds_read_b128 v[198:201], v142 offset:5120
	ds_read_b128 v[202:205], v142 offset:6144
	ds_read_b128 v[206:209], v142 offset:7168
	global_load_lds_dwordx4 v[210:211], off
	v_lshl_add_u64 v[210:211], s[60:61], 0, v[136:137]
	s_mov_b32 m0, s43
	s_nop 0
	global_load_lds_dwordx4 v[210:211], off
	s_waitcnt vmcnt(8) lgkmcnt(0)
	s_setprio 1
	s_barrier
	v_mfma_f32_16x16x32_bf16 v[8:11], v[146:149], v[178:181], v[8:11]
	v_mfma_f32_16x16x32_bf16 v[12:15], v[154:157], v[178:181], v[12:15]
	v_mfma_f32_16x16x32_bf16 v[60:63], v[146:149], v[186:189], v[60:63]
	v_mfma_f32_16x16x32_bf16 v[20:23], v[154:157], v[186:189], v[20:23]
	v_mfma_f32_16x16x32_bf16 v[76:79], v[146:149], v[194:197], v[76:79]
	v_mfma_f32_16x16x32_bf16 v[52:55], v[154:157], v[194:197], v[52:55]
	v_mfma_f32_16x16x32_bf16 v[128:131], v[146:149], v[202:205], v[128:131]
	v_mfma_f32_16x16x32_bf16 v[68:71], v[154:157], v[202:205], v[68:71]
	v_mfma_f32_16x16x32_bf16 v[8:11], v[150:153], v[182:185], v[8:11]
	v_mfma_f32_16x16x32_bf16 v[12:15], v[158:161], v[182:185], v[12:15]
	v_mfma_f32_16x16x32_bf16 v[60:63], v[150:153], v[190:193], v[60:63]
	v_mfma_f32_16x16x32_bf16 v[20:23], v[158:161], v[190:193], v[20:23]
	v_mfma_f32_16x16x32_bf16 v[76:79], v[150:153], v[198:201], v[76:79]
	v_mfma_f32_16x16x32_bf16 v[52:55], v[158:161], v[198:201], v[52:55]
	v_mfma_f32_16x16x32_bf16 v[128:131], v[150:153], v[206:209], v[128:131]
	v_mfma_f32_16x16x32_bf16 v[68:71], v[158:161], v[206:209], v[68:71]
	v_mfma_f32_16x16x32_bf16 v[28:31], v[162:165], v[178:181], v[28:31]
	v_mfma_f32_16x16x32_bf16 v[16:19], v[170:173], v[178:181], v[16:19]
	v_mfma_f32_16x16x32_bf16 v[56:59], v[162:165], v[186:189], v[56:59]
	v_mfma_f32_16x16x32_bf16 v[48:51], v[170:173], v[186:189], v[48:51]
	v_mfma_f32_16x16x32_bf16 v[72:75], v[162:165], v[194:197], v[72:75]
	v_mfma_f32_16x16x32_bf16 v[64:67], v[170:173], v[194:197], v[64:67]
	v_mfma_f32_16x16x32_bf16 v[108:111], v[162:165], v[202:205], v[108:111]
	v_mfma_f32_16x16x32_bf16 v[96:99], v[170:173], v[202:205], v[96:99]
	v_mfma_f32_16x16x32_bf16 v[28:31], v[166:169], v[182:185], v[28:31]
	v_mfma_f32_16x16x32_bf16 v[16:19], v[174:177], v[182:185], v[16:19]
	v_mfma_f32_16x16x32_bf16 v[56:59], v[166:169], v[190:193], v[56:59]
	v_mfma_f32_16x16x32_bf16 v[48:51], v[174:177], v[190:193], v[48:51]
	v_mfma_f32_16x16x32_bf16 v[72:75], v[166:169], v[198:201], v[72:75]
	v_mfma_f32_16x16x32_bf16 v[64:67], v[174:177], v[198:201], v[64:67]
	v_mfma_f32_16x16x32_bf16 v[108:111], v[166:169], v[206:209], v[108:111]
	v_mfma_f32_16x16x32_bf16 v[96:99], v[174:177], v[206:209], v[96:99]
	s_barrier
	s_setprio 0
	s_mov_b32 m0, s44
	v_lshl_add_u64 v[210:211], s[70:71], 0, v[34:35]
	s_add_u32 s52, s70, 0x200000
	ds_read_b128 v[178:181], v142 offset:16384
	ds_read_b128 v[182:185], v142 offset:17408
	ds_read_b128 v[186:189], v142 offset:18432
	ds_read_b128 v[190:193], v142 offset:19456
	ds_read_b128 v[194:197], v142 offset:20480
	ds_read_b128 v[198:201], v142 offset:21504
	ds_read_b128 v[202:205], v142 offset:22528
	ds_read_b128 v[206:209], v142 offset:23552
	global_load_lds_dwordx4 v34, s[70:71]
	v_lshl_add_u64 v[212:213], s[70:71], 0, v[134:135]
	s_mov_b32 m0, s45
	s_addc_u32 s53, s71, 0
	global_load_lds_dwordx4 v134, s[70:71]
	v_lshl_add_u64 v[214:215], s[52:53], 0, v[34:35]
	s_mov_b32 m0, s46
	s_nop 0
	global_load_lds_dwordx4 v34, s[52:53]
	v_lshl_add_u64 v[214:215], s[52:53], 0, v[134:135]
	s_mov_b32 m0, s47
	s_nop 0
	global_load_lds_dwordx4 v134, s[52:53]
	v_lshl_add_u64 v[214:215], s[72:73], 0, v[32:33]
	s_mov_b32 m0, s14
	s_nop 0
	global_load_lds_dwordx4 v32, s[72:73]
	v_lshl_add_u64 v[214:215], s[72:73], 0, v[132:133]
	s_mov_b32 m0, s15
	s_nop 0
	global_load_lds_dwordx4 v132, s[72:73]
	s_waitcnt vmcnt(8) lgkmcnt(0)
	s_setprio 1
	s_barrier
	v_mfma_f32_16x16x32_bf16 v[100:103], v[146:149], v[178:181], v[100:103]
	v_mfma_f32_16x16x32_bf16 v[104:107], v[154:157], v[178:181], v[104:107]
	v_mfma_f32_16x16x32_bf16 v[116:119], v[146:149], v[186:189], v[116:119]
	v_mfma_f32_16x16x32_bf16 v[120:123], v[154:157], v[186:189], v[120:123]
	v_mfma_f32_16x16x32_bf16 v[84:87], v[146:149], v[194:197], v[84:87]
	v_mfma_f32_16x16x32_bf16 v[80:83], v[154:157], v[194:197], v[80:83]
	v_mfma_f32_16x16x32_bf16 v[36:39], v[146:149], v[202:205], v[36:39]
	v_mfma_f32_16x16x32_bf16 v[24:27], v[154:157], v[202:205], v[24:27]
	v_mfma_f32_16x16x32_bf16 v[100:103], v[150:153], v[182:185], v[100:103]
	v_mfma_f32_16x16x32_bf16 v[104:107], v[158:161], v[182:185], v[104:107]
	v_mfma_f32_16x16x32_bf16 v[116:119], v[150:153], v[190:193], v[116:119]
	v_mfma_f32_16x16x32_bf16 v[120:123], v[158:161], v[190:193], v[120:123]
	v_mfma_f32_16x16x32_bf16 v[84:87], v[150:153], v[198:201], v[84:87]
	v_mfma_f32_16x16x32_bf16 v[80:83], v[158:161], v[198:201], v[80:83]
	v_mfma_f32_16x16x32_bf16 v[36:39], v[150:153], v[206:209], v[36:39]
	v_mfma_f32_16x16x32_bf16 v[24:27], v[158:161], v[206:209], v[24:27]
	v_mfma_f32_16x16x32_bf16 v[124:127], v[162:165], v[178:181], v[124:127]
	v_mfma_f32_16x16x32_bf16 v[112:115], v[170:173], v[178:181], v[112:115]
	v_mfma_f32_16x16x32_bf16 v[92:95], v[162:165], v[186:189], v[92:95]
	v_mfma_f32_16x16x32_bf16 v[88:91], v[170:173], v[186:189], v[88:91]
	v_mfma_f32_16x16x32_bf16 v[44:47], v[162:165], v[194:197], v[44:47]
	v_mfma_f32_16x16x32_bf16 v[40:43], v[170:173], v[194:197], v[40:43]
	v_mfma_f32_16x16x32_bf16 v[4:7], v[162:165], v[202:205], v[4:7]
	v_mfma_f32_16x16x32_bf16 v[0:3], v[170:173], v[202:205], v[0:3]
	v_mfma_f32_16x16x32_bf16 v[124:127], v[166:169], v[182:185], v[124:127]
	v_mfma_f32_16x16x32_bf16 v[112:115], v[174:177], v[182:185], v[112:115]
	v_mfma_f32_16x16x32_bf16 v[92:95], v[166:169], v[190:193], v[92:95]
	v_mfma_f32_16x16x32_bf16 v[88:91], v[174:177], v[190:193], v[88:91]
	v_mfma_f32_16x16x32_bf16 v[44:47], v[166:169], v[198:201], v[44:47]
	v_mfma_f32_16x16x32_bf16 v[40:43], v[174:177], v[198:201], v[40:43]
	v_mfma_f32_16x16x32_bf16 v[4:7], v[166:169], v[206:209], v[4:7]
	v_mfma_f32_16x16x32_bf16 v[0:3], v[174:177], v[206:209], v[0:3]
	s_barrier
	s_setprio 0
	ds_read_b128 v[146:149], v143
	ds_read_b128 v[150:153], v143 offset:1024
	ds_read_b128 v[154:157], v143 offset:2048
	ds_read_b128 v[158:161], v143 offset:3072
	ds_read_b128 v[162:165], v144
	ds_read_b128 v[166:169], v144 offset:1024
	ds_read_b128 v[170:173], v144 offset:2048
	ds_read_b128 v[174:177], v144 offset:3072
	s_add_u32 s52, s72, 0x4000
	s_addc_u32 s53, s73, 0
	s_mov_b32 m0, s21
	v_lshl_add_u64 v[214:215], s[52:53], 0, v[32:33]
	ds_read_b128 v[178:181], v142 offset:32768
	ds_read_b128 v[182:185], v142 offset:33792
	ds_read_b128 v[186:189], v142 offset:34816
	ds_read_b128 v[190:193], v142 offset:35840
	ds_read_b128 v[194:197], v142 offset:36864
	ds_read_b128 v[198:201], v142 offset:37888
	ds_read_b128 v[202:205], v142 offset:38912
	ds_read_b128 v[206:209], v142 offset:39936
	global_load_lds_dwordx4 v32, s[52:53]
	v_lshl_add_u64 v[214:215], s[52:53], 0, v[132:133]
	s_mov_b32 m0, s22
	s_nop 0
	global_load_lds_dwordx4 v132, s[52:53]
	s_waitcnt vmcnt(8) lgkmcnt(0)
	s_setprio 1
	s_barrier
	v_mfma_f32_16x16x32_bf16 v[8:11], v[146:149], v[178:181], v[8:11]
	v_mfma_f32_16x16x32_bf16 v[12:15], v[154:157], v[178:181], v[12:15]
	v_mfma_f32_16x16x32_bf16 v[60:63], v[146:149], v[186:189], v[60:63]
	v_mfma_f32_16x16x32_bf16 v[20:23], v[154:157], v[186:189], v[20:23]
	v_mfma_f32_16x16x32_bf16 v[76:79], v[146:149], v[194:197], v[76:79]
	v_mfma_f32_16x16x32_bf16 v[52:55], v[154:157], v[194:197], v[52:55]
	v_mfma_f32_16x16x32_bf16 v[128:131], v[146:149], v[202:205], v[128:131]
	v_mfma_f32_16x16x32_bf16 v[68:71], v[154:157], v[202:205], v[68:71]
	v_mfma_f32_16x16x32_bf16 v[8:11], v[150:153], v[182:185], v[8:11]
	v_mfma_f32_16x16x32_bf16 v[12:15], v[158:161], v[182:185], v[12:15]
	v_mfma_f32_16x16x32_bf16 v[60:63], v[150:153], v[190:193], v[60:63]
	v_mfma_f32_16x16x32_bf16 v[20:23], v[158:161], v[190:193], v[20:23]
	v_mfma_f32_16x16x32_bf16 v[76:79], v[150:153], v[198:201], v[76:79]
	v_mfma_f32_16x16x32_bf16 v[52:55], v[158:161], v[198:201], v[52:55]
	v_mfma_f32_16x16x32_bf16 v[128:131], v[150:153], v[206:209], v[128:131]
	v_mfma_f32_16x16x32_bf16 v[68:71], v[158:161], v[206:209], v[68:71]
	v_mfma_f32_16x16x32_bf16 v[28:31], v[162:165], v[178:181], v[28:31]
	v_mfma_f32_16x16x32_bf16 v[16:19], v[170:173], v[178:181], v[16:19]
	v_mfma_f32_16x16x32_bf16 v[56:59], v[162:165], v[186:189], v[56:59]
	v_mfma_f32_16x16x32_bf16 v[48:51], v[170:173], v[186:189], v[48:51]
	v_mfma_f32_16x16x32_bf16 v[72:75], v[162:165], v[194:197], v[72:75]
	v_mfma_f32_16x16x32_bf16 v[64:67], v[170:173], v[194:197], v[64:67]
	v_mfma_f32_16x16x32_bf16 v[108:111], v[162:165], v[202:205], v[108:111]
	v_mfma_f32_16x16x32_bf16 v[96:99], v[170:173], v[202:205], v[96:99]
	v_mfma_f32_16x16x32_bf16 v[28:31], v[166:169], v[182:185], v[28:31]
	v_mfma_f32_16x16x32_bf16 v[16:19], v[174:177], v[182:185], v[16:19]
	v_mfma_f32_16x16x32_bf16 v[56:59], v[166:169], v[190:193], v[56:59]
	v_mfma_f32_16x16x32_bf16 v[48:51], v[174:177], v[190:193], v[48:51]
	v_mfma_f32_16x16x32_bf16 v[72:75], v[166:169], v[198:201], v[72:75]
	v_mfma_f32_16x16x32_bf16 v[64:67], v[174:177], v[198:201], v[64:67]
	v_mfma_f32_16x16x32_bf16 v[108:111], v[166:169], v[206:209], v[108:111]
	v_mfma_f32_16x16x32_bf16 v[96:99], v[174:177], v[206:209], v[96:99]
	s_barrier
; template <class Epi, class Sched, bool ALIGN_EPI = false, bool SP2 = false, bool A_TILED = false>
; __device__ __forceinline__ void gemm_phase(PG8_LAS unsigned char* lds, const Gemm g, const Sched& S, const Epi& E, const int wave_s) {
;     ...
;         for (int t = PEEL ? 2 : 0; t < nt; t += 2) {
;             const bool last = (t == nt - 2);
;             const char* a1 = cA + (size_t)(t + 1) * kstepA;
;             const char* a2 = last ? nA : cA + (size_t)(t + 2) * kstepA; const char* b2 = last ? nB : cB + (size_t)(t + 2) * kstep;
;             const char* a3 = a2 + kstepA; const char* b3 = b2 + kstep;
;             if (last && has_next) S.a_ready(nxt);
;             if constexpr (SP2) {
;             PG8_ITER(PG8_MMA)
;             } else {
;             PG8_LDB(B0, 0, 0); PG8_SCHED; PG8_LDA(At, 0, 0); PG8_STAGE(PG8_SA(1, 1), a1 + hstepA, voffA);
;             PG8_WAIT_L(8); PG8_BAR; PG8_WAIT_L(0); PG8_MMA(0, 0, At, B0); PG8_BAR; PG8_SCHED;
;             PG8_LDB(B1, 0, 1); PG8_STAGE(PG8_SB(0, 0), b2, voffB);
;             PG8_BAR; PG8_WAIT_L(0); PG8_MMA(0, 1, At, B1); PG8_BAR;
;             PG8_LDA(At, 0, 1); PG8_STAGE(PG8_SA(0, 0), a2, voffA);
;             PG8_BAR; PG8_WAIT_L(0); PG8_MMA(1, 0, At, B0); PG8_BAR; PG8_SCHED;
;             PG8_STAGE(PG8_SB(0, 1), b2 + hstep, voffB);
;             PG8_WAIT_V(6); PG8_BAR; PG8_MMA(1, 1, At, B1); PG8_BAR;
;             PG8_LDB(B0, 1, 0); PG8_SCHED; PG8_LDA(At, 1, 0); PG8_STAGE(PG8_SA(0, 1), a2 + hstepA, voffA);
;             PG8_WAIT_L(8); PG8_BAR; PG8_WAIT_L(0); PG8_MMA(0, 0, At, B0); PG8_BAR; PG8_SCHED;
;             PG8_LDB(B1, 1, 1); PG8_STAGE(PG8_SB(1, 0), b3, voffB);
;             PG8_BAR; PG8_WAIT_L(0); PG8_MMA(0, 1, At, B1); PG8_BAR;
;             PG8_LDA(At, 1, 1); PG8_STAGE(PG8_SA(1, 0), a3, voffA);
;             PG8_BAR; PG8_WAIT_L(0); PG8_MMA(1, 0, At, B0); PG8_BAR; PG8_SCHED;
;             PG8_STAGE(PG8_SB(1, 1), b3 + hstep, voffB);
;             PG8_WAIT_V(6); PG8_BAR; PG8_MMA(1, 1, At, B1); PG8_BAR;
;             }
;         }
;         if constexpr (ALIGN_EPI) { if (wr == 0) PG8_BAR; }
;         if constexpr (!Epi::AFTER_DRAIN) { int te = tid_now(wave_s); asm volatile("" : "+v"(te));
;             E(acc, cur, wr, wc, te & 15, (te & 63) >> 4); S.done(cur); }
;         if (!has_next) break;
;         cur = nxt; cA = nA; cB = nB; ++ui;
;         if constexpr (ALIGN_EPI) { if (wr == 1) PG8_BAR; }
	s_setprio 0
	s_mov_b32 m0, s48
	v_lshl_add_u64 v[210:211], v[210:211], 0, s[64:65]
	s_add_u32 s52, s70, 0x200080
	ds_read_b128 v[178:181], v142 offset:49152
	ds_read_b128 v[182:185], v142 offset:50176
	ds_read_b128 v[186:189], v142 offset:51200
	ds_read_b128 v[190:193], v142 offset:52224
	ds_read_b128 v[194:197], v142 offset:53248
	ds_read_b128 v[198:201], v142 offset:54272
	ds_read_b128 v[202:205], v142 offset:55296
	ds_read_b128 v[206:209], v142 offset:56320
	global_load_lds_dwordx4 v[210:211], off
	v_lshl_add_u64 v[210:211], v[212:213], 0, s[64:65]
	s_mov_b32 m0, s49
	s_addc_u32 s53, s71, 0
	global_load_lds_dwordx4 v[210:211], off
	v_lshl_add_u64 v[210:211], s[52:53], 0, v[34:35]
	s_mov_b32 m0, s50
	s_nop 0
	global_load_lds_dwordx4 v34, s[52:53]
	v_lshl_add_u64 v[210:211], s[52:53], 0, v[134:135]
	s_mov_b32 m0, s51
	s_nop 0
	global_load_lds_dwordx4 v134, s[52:53]
	v_lshl_add_u64 v[210:211], s[68:69], 0, v[32:33]
	s_mov_b32 m0, s23
	s_nop 0
	global_load_lds_dwordx4 v32, s[68:69]
	v_lshl_add_u64 v[210:211], s[68:69], 0, v[132:133]
	s_mov_b32 m0, s36
	s_nop 0
	global_load_lds_dwordx4 v132, s[68:69]
	s_waitcnt vmcnt(8) lgkmcnt(0)
	s_setprio 1
	s_barrier
	v_mfma_f32_16x16x32_bf16 v[100:103], v[146:149], v[178:181], v[100:103]
	v_mfma_f32_16x16x32_bf16 v[104:107], v[154:157], v[178:181], v[104:107]
	v_mfma_f32_16x16x32_bf16 v[116:119], v[146:149], v[186:189], v[116:119]
	v_mfma_f32_16x16x32_bf16 v[120:123], v[154:157], v[186:189], v[120:123]
	v_mfma_f32_16x16x32_bf16 v[84:87], v[146:149], v[194:197], v[84:87]
	v_mfma_f32_16x16x32_bf16 v[80:83], v[154:157], v[194:197], v[80:83]
	v_mfma_f32_16x16x32_bf16 v[36:39], v[146:149], v[202:205], v[36:39]
	v_mfma_f32_16x16x32_bf16 v[24:27], v[154:157], v[202:205], v[24:27]
	v_mfma_f32_16x16x32_bf16 v[100:103], v[150:153], v[182:185], v[100:103]
	v_mfma_f32_16x16x32_bf16 v[104:107], v[158:161], v[182:185], v[104:107]
	v_mfma_f32_16x16x32_bf16 v[116:119], v[150:153], v[190:193], v[116:119]
	v_mfma_f32_16x16x32_bf16 v[120:123], v[158:161], v[190:193], v[120:123]
	v_mfma_f32_16x16x32_bf16 v[84:87], v[150:153], v[198:201], v[84:87]
	v_mfma_f32_16x16x32_bf16 v[80:83], v[158:161], v[198:201], v[80:83]
	v_mfma_f32_16x16x32_bf16 v[36:39], v[150:153], v[206:209], v[36:39]
	v_mfma_f32_16x16x32_bf16 v[24:27], v[158:161], v[206:209], v[24:27]
	v_mfma_f32_16x16x32_bf16 v[124:127], v[162:165], v[178:181], v[124:127]
	v_mfma_f32_16x16x32_bf16 v[112:115], v[170:173], v[178:181], v[112:115]
	v_mfma_f32_16x16x32_bf16 v[92:95], v[162:165], v[186:189], v[92:95]
	v_mfma_f32_16x16x32_bf16 v[88:91], v[170:173], v[186:189], v[88:91]
	v_mfma_f32_16x16x32_bf16 v[44:47], v[162:165], v[194:197], v[44:47]
	v_mfma_f32_16x16x32_bf16 v[40:43], v[170:173], v[194:197], v[40:43]
	v_mfma_f32_16x16x32_bf16 v[4:7], v[162:165], v[202:205], v[4:7]
	v_mfma_f32_16x16x32_bf16 v[0:3], v[170:173], v[202:205], v[0:3]
	v_mfma_f32_16x16x32_bf16 v[124:127], v[166:169], v[182:185], v[124:127]
	v_mfma_f32_16x16x32_bf16 v[112:115], v[174:177], v[182:185], v[112:115]
	v_mfma_f32_16x16x32_bf16 v[92:95], v[166:169], v[190:193], v[92:95]
	v_mfma_f32_16x16x32_bf16 v[88:91], v[174:177], v[190:193], v[88:91]
	v_mfma_f32_16x16x32_bf16 v[44:47], v[166:169], v[198:201], v[44:47]
	v_mfma_f32_16x16x32_bf16 v[40:43], v[174:177], v[198:201], v[40:43]
	v_mfma_f32_16x16x32_bf16 v[4:7], v[166:169], v[206:209], v[4:7]
	v_mfma_f32_16x16x32_bf16 v[0:3], v[174:177], v[206:209], v[0:3]
	s_barrier
	s_setprio 0
	s_add_i32 s41, s41, 2
	s_add_u32 s37, s37, 0x100
	s_addc_u32 s38, s38, 0
	s_add_u32 s39, s39, 0x10000
	s_addc_u32 s40, s40, 0
	v_lshl_add_u64 v[136:137], v[136:137], 0, s[66:67]
	s_cmpk_gt_u32 s41, 0x7d
	v_lshl_add_u64 v[138:139], v[138:139], 0, s[66:67]
	s_cbranch_scc0 .LBB0_2026
	s_waitcnt vmcnt(0)
	s_cmpk_lt_u32 s0, 0x100
	s_cbranch_scc0 .LBB0_2029
	s_barrier

; template <class Epi, class Sched, bool ALIGN_EPI = false, bool SP2 = false, bool A_TILED = false>
; __device__ __forceinline__ void gemm_phase(PG8_LAS unsigned char* lds, const Gemm g, const Sched& S, const Epi& E, const int wave_s) {
;     ...
;         if constexpr (PEEL) {
;             const char* a1 = cA + kstepA; const char* a2 = cA + 2 * kstepA; const char* b2 = cB + 2 * kstep; const char* a3 = a2 + kstepA; const char* b3 = b2 + kstep;
;             PG8_ITER(PG8_MMAZ)
.Lpw_9:
	s_setprio 1
	s_barrier
	v_mfma_f32_16x16x32_bf16 v[64:67], v[0:3], v[32:35], 0
	v_mfma_f32_16x16x32_bf16 v[68:71], v[8:11], v[32:35], 0
	v_mfma_f32_16x16x32_bf16 v[72:75], v[0:3], v[40:43], 0
	v_mfma_f32_16x16x32_bf16 v[76:79], v[8:11], v[40:43], 0
	v_mfma_f32_16x16x32_bf16 v[80:83], v[0:3], v[48:51], 0
	v_mfma_f32_16x16x32_bf16 v[84:87], v[8:11], v[48:51], 0
	v_mfma_f32_16x16x32_bf16 v[88:91], v[0:3], v[56:59], 0
	v_mfma_f32_16x16x32_bf16 v[92:95], v[8:11], v[56:59], 0
	v_mfma_f32_16x16x32_bf16 v[64:67], v[4:7], v[36:39], v[64:67]
	v_mfma_f32_16x16x32_bf16 v[68:71], v[12:15], v[36:39], v[68:71]
	v_mfma_f32_16x16x32_bf16 v[72:75], v[4:7], v[44:47], v[72:75]
	v_mfma_f32_16x16x32_bf16 v[76:79], v[12:15], v[44:47], v[76:79]
	v_mfma_f32_16x16x32_bf16 v[80:83], v[4:7], v[52:55], v[80:83]
	v_mfma_f32_16x16x32_bf16 v[84:87], v[12:15], v[52:55], v[84:87]
	v_mfma_f32_16x16x32_bf16 v[88:91], v[4:7], v[60:63], v[88:91]
	v_mfma_f32_16x16x32_bf16 v[92:95], v[12:15], v[60:63], v[92:95]
	v_mfma_f32_16x16x32_bf16 v[96:99], v[16:19], v[32:35], 0
	v_mfma_f32_16x16x32_bf16 v[32:35], v[24:27], v[32:35], 0
	v_mfma_f32_16x16x32_bf16 v[96:99], v[20:23], v[36:39], v[96:99]
	v_mfma_f32_16x16x32_bf16 v[32:35], v[28:31], v[36:39], v[32:35]
	v_mfma_f32_16x16x32_bf16 v[36:39], v[16:19], v[40:43], 0
	v_mfma_f32_16x16x32_bf16 v[40:43], v[24:27], v[40:43], 0
	v_mfma_f32_16x16x32_bf16 v[36:39], v[20:23], v[44:47], v[36:39]
	v_mfma_f32_16x16x32_bf16 v[40:43], v[28:31], v[44:47], v[40:43]
	v_mfma_f32_16x16x32_bf16 v[44:47], v[16:19], v[48:51], 0
	v_mfma_f32_16x16x32_bf16 v[48:51], v[24:27], v[48:51], 0
	v_mfma_f32_16x16x32_bf16 v[100:103], v[28:31], v[52:55], v[48:51]
	v_mfma_f32_16x16x32_bf16 v[48:51], v[16:19], v[56:59], 0
	v_mfma_f32_16x16x32_bf16 v[104:107], v[20:23], v[60:63], v[48:51]
	v_mfma_f32_16x16x32_bf16 v[48:51], v[24:27], v[56:59], 0
	v_mfma_f32_16x16x32_bf16 v[44:47], v[20:23], v[52:55], v[44:47]
	v_mfma_f32_16x16x32_bf16 v[108:111], v[28:31], v[60:63], v[48:51]
	s_barrier
	s_setprio 0
	s_add_i32 s54, s45, s15
	v_lshl_add_u64 v[250:251], s[78:79], 0, v[128:129]
	s_add_i32 s55, s54, 0x2000
	v_lshl_add_u64 v[144:145], v[250:251], 0, s[66:67]
	s_mov_b32 m0, s54
	v_lshl_add_u64 v[252:253], s[78:79], 0, v[130:131]
	s_add_u32 s58, s78, 0x80100
	ds_read_b128 v[48:51], v143 offset:16384
	ds_read_b128 v[52:55], v143 offset:17408
	ds_read_b128 v[56:59], v143 offset:18432
	ds_read_b128 v[60:63], v143 offset:19456
	ds_read_b128 v[112:115], v143 offset:20480
	ds_read_b128 v[116:119], v143 offset:21504
	ds_read_b128 v[120:123], v143 offset:22528
	ds_read_b128 v[124:127], v143 offset:23552
	global_load_lds_dwordx4 v[144:145], off
	v_lshl_add_u64 v[144:145], v[252:253], 0, s[66:67]
	s_mov_b32 m0, s55
	s_addc_u32 s59, s79, 0
	s_add_i32 s56, s46, s15
	global_load_lds_dwordx4 v[144:145], off
	v_lshl_add_u64 v[144:145], s[58:59], 0, v[128:129]
	s_mov_b32 m0, s56
	s_add_i32 s57, s56, 0x2000
	global_load_lds_dwordx4 v128, s[58:59]
	v_lshl_add_u64 v[144:145], s[58:59], 0, v[130:131]
	s_mov_b32 m0, s57
	v_lshl_add_u64 v[136:137], s[80:81], 0, v[128:129]
	global_load_lds_dwordx4 v130, s[58:59]
	v_lshl_add_u64 v[144:145], v[136:137], 0, s[66:67]
	s_mov_b32 m0, s22
	v_lshl_add_u64 v[138:139], s[80:81], 0, v[130:131]
	global_load_lds_dwordx4 v[144:145], off
	v_lshl_add_u64 v[144:145], v[138:139], 0, s[66:67]
	s_mov_b32 m0, s23
	s_nop 0
	global_load_lds_dwordx4 v[144:145], off
	s_waitcnt vmcnt(40) lgkmcnt(0)
	s_cmp_lg_u32 s98, 0
	s_cbranch_scc1 .Lpw_10
	s_waitcnt vmcnt(8)
.Lpw_10:
	s_setprio 1
	s_barrier
	v_mfma_f32_16x16x32_bf16 v[144:147], v[0:3], v[48:51], 0
	v_mfma_f32_16x16x32_bf16 v[154:157], v[0:3], v[56:59], 0
	v_mfma_f32_16x16x32_bf16 v[162:165], v[0:3], v[112:115], 0
	v_mfma_f32_16x16x32_bf16 v[0:3], v[0:3], v[120:123], 0
	v_mfma_f32_16x16x32_bf16 v[150:153], v[8:11], v[48:51], 0
	v_mfma_f32_16x16x32_bf16 v[158:161], v[8:11], v[56:59], 0
	v_mfma_f32_16x16x32_bf16 v[166:169], v[8:11], v[112:115], 0
	v_mfma_f32_16x16x32_bf16 v[170:173], v[4:7], v[124:127], v[0:3]
	v_mfma_f32_16x16x32_bf16 v[0:3], v[8:11], v[120:123], 0
	v_mfma_f32_16x16x32_bf16 v[146:149], v[4:7], v[52:55], v[144:147]
	v_mfma_f32_16x16x32_bf16 v[150:153], v[12:15], v[52:55], v[150:153]
	v_mfma_f32_16x16x32_bf16 v[154:157], v[4:7], v[60:63], v[154:157]
	v_mfma_f32_16x16x32_bf16 v[158:161], v[12:15], v[60:63], v[158:161]
	v_mfma_f32_16x16x32_bf16 v[162:165], v[4:7], v[116:119], v[162:165]
	v_mfma_f32_16x16x32_bf16 v[166:169], v[12:15], v[116:119], v[166:169]
	v_mfma_f32_16x16x32_bf16 v[174:177], v[12:15], v[124:127], v[0:3]
	v_mfma_f32_16x16x32_bf16 v[0:3], v[16:19], v[48:51], 0
	v_mfma_f32_16x16x32_bf16 v[178:181], v[20:23], v[52:55], v[0:3]
	v_mfma_f32_16x16x32_bf16 v[0:3], v[24:27], v[48:51], 0
	v_mfma_f32_16x16x32_bf16 v[182:185], v[28:31], v[52:55], v[0:3]
	v_mfma_f32_16x16x32_bf16 v[0:3], v[16:19], v[56:59], 0
	v_mfma_f32_16x16x32_bf16 v[186:189], v[20:23], v[60:63], v[0:3]
	v_mfma_f32_16x16x32_bf16 v[0:3], v[24:27], v[56:59], 0
	v_mfma_f32_16x16x32_bf16 v[190:193], v[28:31], v[60:63], v[0:3]
	v_mfma_f32_16x16x32_bf16 v[0:3], v[16:19], v[112:115], 0
	v_mfma_f32_16x16x32_bf16 v[194:197], v[20:23], v[116:119], v[0:3]
	v_mfma_f32_16x16x32_bf16 v[0:3], v[24:27], v[112:115], 0
	v_mfma_f32_16x16x32_bf16 v[198:201], v[28:31], v[116:119], v[0:3]
	v_mfma_f32_16x16x32_bf16 v[0:3], v[16:19], v[120:123], 0
	v_mfma_f32_16x16x32_bf16 v[202:205], v[20:23], v[124:127], v[0:3]
	v_mfma_f32_16x16x32_bf16 v[0:3], v[24:27], v[120:123], 0
	v_mfma_f32_16x16x32_bf16 v[206:209], v[28:31], v[124:127], v[0:3]
	s_barrier
; template <class Epi, class Sched, bool ALIGN_EPI = false, bool SP2 = false, bool A_TILED = false>
; __device__ __forceinline__ void gemm_phase(PG8_LAS unsigned char* lds, const Gemm g, const Sched& S, const Epi& E, const int wave_s) {
;     ...
;     Unit cur, nxt; int ui = 0;
;     if (!S.next(0, cur)) return;
;     f32x4 acc[2][2][4][2];
;     bf16x8 At[4][2], B0[2][2], B1[2][2];
;     const char* cA = (const char*)g.A + (size_t)cur.pm * tstepA; const char* cB = (const char*)g.Bt + (size_t)cur.pn * tstep;
;     S.a_ready(cur);
;     if constexpr (SP2) {
;         PG8_STAGE(PG8_SB(0, 0), cB, voffB); PG8_STAGE(PG8_SB(0, 1), cB + hstep, voffB); PG8_STAGE(PG8_SA(0, 0), cA, voffA); PG8_STAGE(PG8_SA(0, 1), cA + hstepA, voffA);
;         if (wr == 1) PG8_BAR;
;         PG8_WAIT_V(2); PG8_BAR;
;         PG8_STAGE(PG8_SB(1, 0), cB + kstep, voffB); PG8_STAGE(PG8_SA(1, 0), cA + kstepA, voffA); PG8_STAGE(PG8_SB(1, 1), cB + hstep + kstep, voffB);
;         PG8_WAIT_V(6); PG8_BAR;
;     } else {
;         PG8_STAGE(PG8_SB(0, 0), cB, voffB); PG8_STAGE(PG8_SA(0, 0), cA, voffA); PG8_STAGE(PG8_SB(0, 1), cB + hstep, voffB); PG8_STAGE(PG8_SA(0, 1), cA + hstepA, voffA);
;         if (wr == 1) PG8_BAR;
;         PG8_WAIT_V(4); PG8_BAR;
;         PG8_STAGE(PG8_SB(1, 0), cB + kstep, voffB); PG8_STAGE(PG8_SA(1, 0), cA + kstepA, voffA); PG8_STAGE(PG8_SB(1, 1), cB + hstep + kstep, voffB);
;         PG8_WAIT_V(6); PG8_BAR;
;     }
;     for (;;) {
;         const bool has_next = Epi::AFTER_DRAIN ? false : S.next(ui + 1, nxt);
;         const char* nA = has_next ? (const char*)g.A + (size_t)nxt.pm * tstepA : cA; const char* nB = has_next ? (const char*)g.Bt + (size_t)nxt.pn * tstep : cB;
;         constexpr bool PEEL = SP2 && !Epi::AFTER_DRAIN;
;         if constexpr (PEEL) {
;             const char* a1 = cA + kstepA; const char* a2 = cA + 2 * kstepA; const char* b2 = cB + 2 * kstep; const char* a3 = a2 + kstepA; const char* b3 = b2 + kstep;
;             PG8_ITER(PG8_MMAZ)
;         } else {
; #pragma unroll
;             for (int a = 0; a < 2; ++a)
; #pragma unroll
;                 for (int b = 0; b < 2; ++b)
; #pragma unroll
;                     for (int m = 0; m < 4; ++m)
; #pragma unroll
;                         for (int n = 0; n < 2; ++n) acc[a][b][m][n] = (f32x4){0.f, 0.f, 0.f, 0.f};
;         }
; #pragma nounroll
;         for (int t = PEEL ? 2 : 0; t < nt; t += 2) {
	s_setprio 0
	s_add_i32 s61, 0, 0x18000
	s_add_i32 s71, 0, 0x1c000
	v_add_u32_e32 v144, s61, v140
	v_add_u32_e32 v145, s71, v140
	ds_read_b128 v[112:115], v144
	ds_read_b128 v[116:119], v144 offset:1024
	ds_read_b128 v[120:123], v144 offset:2048
	ds_read_b128 v[124:127], v144 offset:3072
	ds_read_b128 v[210:213], v145
	ds_read_b128 v[214:217], v145 offset:1024
	ds_read_b128 v[218:221], v145 offset:2048
	ds_read_b128 v[222:225], v145 offset:3072
	s_add_u32 s58, s80, 0x80100
	s_addc_u32 s59, s81, 0
	s_mov_b32 m0, s36
	v_lshl_add_u64 v[0:1], s[58:59], 0, v[128:129]
	ds_read_b128 v[48:51], v143 offset:32768
	ds_read_b128 v[52:55], v143 offset:33792
	ds_read_b128 v[226:229], v143 offset:34816
	ds_read_b128 v[230:233], v143 offset:35840
	ds_read_b128 v[234:237], v143 offset:36864
	ds_read_b128 v[238:241], v143 offset:37888
	ds_read_b128 v[242:245], v143 offset:38912
	ds_read_b128 v[246:249], v143 offset:39936
	global_load_lds_dwordx4 v128, s[58:59]
	v_lshl_add_u64 v[0:1], s[58:59], 0, v[130:131]
	s_mov_b32 m0, s37
	s_nop 0
	global_load_lds_dwordx4 v130, s[58:59]
	s_waitcnt vmcnt(8) lgkmcnt(0)
	s_setprio 1
	s_barrier
	v_mfma_f32_16x16x32_bf16 v[0:3], v[112:115], v[48:51], v[64:67]
	v_mfma_f32_16x16x32_bf16 v[24:27], v[116:119], v[52:55], v[0:3]
	v_mfma_f32_16x16x32_bf16 v[0:3], v[120:123], v[48:51], v[68:71]
	v_mfma_f32_16x16x32_bf16 v[28:31], v[124:127], v[52:55], v[0:3]
	v_mfma_f32_16x16x32_bf16 v[0:3], v[112:115], v[226:229], v[72:75]
	v_mfma_f32_16x16x32_bf16 v[16:19], v[116:119], v[230:233], v[0:3]
	v_mfma_f32_16x16x32_bf16 v[0:3], v[120:123], v[226:229], v[76:79]
	v_mfma_f32_16x16x32_bf16 v[20:23], v[124:127], v[230:233], v[0:3]
	v_mfma_f32_16x16x32_bf16 v[0:3], v[112:115], v[234:237], v[80:83]
	v_mfma_f32_16x16x32_bf16 v[8:11], v[116:119], v[238:241], v[0:3]
	v_mfma_f32_16x16x32_bf16 v[0:3], v[120:123], v[234:237], v[84:87]
	v_mfma_f32_16x16x32_bf16 v[12:15], v[124:127], v[238:241], v[0:3]
	v_mfma_f32_16x16x32_bf16 v[0:3], v[112:115], v[242:245], v[88:91]
	v_mfma_f32_16x16x32_bf16 v[4:7], v[120:123], v[242:245], v[92:95]
	v_mfma_f32_16x16x32_bf16 v[0:3], v[116:119], v[246:249], v[0:3]
	v_mfma_f32_16x16x32_bf16 v[4:7], v[124:127], v[246:249], v[4:7]
	v_mfma_f32_16x16x32_bf16 v[32:35], v[218:221], v[48:51], v[32:35]
	v_mfma_f32_16x16x32_bf16 v[60:63], v[222:225], v[52:55], v[32:35]
	v_mfma_f32_16x16x32_bf16 v[32:35], v[210:213], v[226:229], v[36:39]
	v_mfma_f32_16x16x32_bf16 v[56:59], v[210:213], v[48:51], v[96:99]
	v_mfma_f32_16x16x32_bf16 v[48:51], v[214:217], v[230:233], v[32:35]
	v_mfma_f32_16x16x32_bf16 v[32:35], v[218:221], v[226:229], v[40:43]
	v_mfma_f32_16x16x32_bf16 v[56:59], v[214:217], v[52:55], v[56:59]
	v_mfma_f32_16x16x32_bf16 v[52:55], v[222:225], v[230:233], v[32:35]
	v_mfma_f32_16x16x32_bf16 v[32:35], v[210:213], v[234:237], v[44:47]
	v_mfma_f32_16x16x32_bf16 v[40:43], v[214:217], v[238:241], v[32:35]
	v_mfma_f32_16x16x32_bf16 v[32:35], v[218:221], v[234:237], v[100:103]
	v_mfma_f32_16x16x32_bf16 v[44:47], v[222:225], v[238:241], v[32:35]
	v_mfma_f32_16x16x32_bf16 v[32:35], v[210:213], v[242:245], v[104:107]
	v_mfma_f32_16x16x32_bf16 v[36:39], v[218:221], v[242:245], v[108:111]
	v_mfma_f32_16x16x32_bf16 v[32:35], v[214:217], v[246:249], v[32:35]
	v_mfma_f32_16x16x32_bf16 v[36:39], v[222:225], v[246:249], v[36:39]
	s_barrier
	s_setprio 0
	s_add_i32 s58, s61, s15
	s_add_i32 s59, s58, 0x2000
	v_lshl_add_u64 v[64:65], v[250:251], 0, s[68:69]
	s_mov_b32 m0, s58
	s_add_u32 s82, s78, 0x80180
	ds_read_b128 v[96:99], v143 offset:49152
	ds_read_b128 v[100:103], v143 offset:50176
	ds_read_b128 v[104:107], v143 offset:51200
	ds_read_b128 v[108:111], v143 offset:52224
	ds_read_b128 v[226:229], v143 offset:53248
	ds_read_b128 v[230:233], v143 offset:54272
	ds_read_b128 v[234:237], v143 offset:55296
	ds_read_b128 v[238:241], v143 offset:56320
	global_load_lds_dwordx4 v[64:65], off
	v_lshl_add_u64 v[64:65], v[252:253], 0, s[68:69]
	s_mov_b32 m0, s59
	s_addc_u32 s83, s79, 0
	s_add_i32 s61, s71, s15
	global_load_lds_dwordx4 v[64:65], off
	v_lshl_add_u64 v[64:65], s[82:83], 0, v[128:129]
	s_mov_b32 m0, s61
	s_add_i32 s71, s61, 0x2000
	global_load_lds_dwordx4 v128, s[82:83]
	v_lshl_add_u64 v[64:65], s[82:83], 0, v[130:131]
	s_mov_b32 m0, s71
	s_nop 0
	global_load_lds_dwordx4 v130, s[82:83]
	v_lshl_add_u64 v[64:65], v[136:137], 0, s[68:69]
	s_mov_b32 m0, s42
	s_nop 0
	global_load_lds_dwordx4 v[64:65], off
	v_lshl_add_u64 v[64:65], v[138:139], 0, s[68:69]
	s_mov_b32 m0, s43
	s_nop 0
	global_load_lds_dwordx4 v[64:65], off
	s_waitcnt vmcnt(8) lgkmcnt(0)
	s_setprio 1
	s_barrier
	v_mfma_f32_16x16x32_bf16 v[64:67], v[112:115], v[96:99], v[146:149]
	v_mfma_f32_16x16x32_bf16 v[88:91], v[116:119], v[100:103], v[64:67]
	v_mfma_f32_16x16x32_bf16 v[64:67], v[120:123], v[96:99], v[150:153]
	v_mfma_f32_16x16x32_bf16 v[92:95], v[124:127], v[100:103], v[64:67]
	v_mfma_f32_16x16x32_bf16 v[64:67], v[112:115], v[104:107], v[154:157]
	v_mfma_f32_16x16x32_bf16 v[80:83], v[116:119], v[108:111], v[64:67]
	v_mfma_f32_16x16x32_bf16 v[64:67], v[120:123], v[104:107], v[158:161]
	v_mfma_f32_16x16x32_bf16 v[84:87], v[124:127], v[108:111], v[64:67]
	v_mfma_f32_16x16x32_bf16 v[64:67], v[112:115], v[226:229], v[162:165]
	v_mfma_f32_16x16x32_bf16 v[72:75], v[116:119], v[230:233], v[64:67]
	v_mfma_f32_16x16x32_bf16 v[64:67], v[120:123], v[226:229], v[166:169]
	v_mfma_f32_16x16x32_bf16 v[76:79], v[124:127], v[230:233], v[64:67]
	v_mfma_f32_16x16x32_bf16 v[64:67], v[112:115], v[234:237], v[170:173]
	v_mfma_f32_16x16x32_bf16 v[68:71], v[120:123], v[234:237], v[174:177]
	v_mfma_f32_16x16x32_bf16 v[64:67], v[116:119], v[238:241], v[64:67]
	v_mfma_f32_16x16x32_bf16 v[68:71], v[124:127], v[238:241], v[68:71]
	v_mfma_f32_16x16x32_bf16 v[112:115], v[210:213], v[96:99], v[178:181]
	v_mfma_f32_16x16x32_bf16 v[96:99], v[218:221], v[96:99], v[182:185]
	v_mfma_f32_16x16x32_bf16 v[124:127], v[222:225], v[100:103], v[96:99]
	v_mfma_f32_16x16x32_bf16 v[96:99], v[210:213], v[104:107], v[186:189]
	v_mfma_f32_16x16x32_bf16 v[120:123], v[214:217], v[100:103], v[112:115]
	v_mfma_f32_16x16x32_bf16 v[112:115], v[214:217], v[108:111], v[96:99]
	v_mfma_f32_16x16x32_bf16 v[96:99], v[218:221], v[104:107], v[190:193]
	v_mfma_f32_16x16x32_bf16 v[116:119], v[222:225], v[108:111], v[96:99]
	v_mfma_f32_16x16x32_bf16 v[96:99], v[210:213], v[226:229], v[194:197]
	v_mfma_f32_16x16x32_bf16 v[104:107], v[214:217], v[230:233], v[96:99]
	v_mfma_f32_16x16x32_bf16 v[96:99], v[218:221], v[226:229], v[198:201]
	v_mfma_f32_16x16x32_bf16 v[108:111], v[222:225], v[230:233], v[96:99]
	v_mfma_f32_16x16x32_bf16 v[96:99], v[210:213], v[234:237], v[202:205]
	v_mfma_f32_16x16x32_bf16 v[100:103], v[218:221], v[234:237], v[206:209]
	v_mfma_f32_16x16x32_bf16 v[96:99], v[214:217], v[238:241], v[96:99]
	v_mfma_f32_16x16x32_bf16 v[100:103], v[222:225], v[238:241], v[100:103]
	s_barrier
	s_setprio 0
	s_add_u32 s73, s78, 0x200
	s_addc_u32 s85, s79, 0
	s_add_u32 s78, s80, 0x80180
	s_addc_u32 s79, s81, 0
	s_mov_b32 s88, 0
; #define PG8_MMA(ai, bj, At, Bt) do { __builtin_amdgcn_s_setprio(1); _Pragma("unroll") for (int m = 0; m < 4; ++m) _Pragma("unroll") for (int n = 0; n < 2; ++n) _Pragma("unroll") for (int k = 0; k < 2; ++k) \
;         acc[ai][bj][m][n] = __builtin_amdgcn_mfma_f32_16x16x32_bf16(Bt[n][k], At[m][k], acc[ai][bj][m][n], 0, 0, 0); __builtin_amdgcn_s_setprio(0); } while (0)
; template <class Epi, class Sched, bool ALIGN_EPI = false, bool SP2 = false, bool A_TILED = false>
; __device__ __forceinline__ void gemm_phase(PG8_LAS unsigned char* lds, const Gemm g, const Sched& S, const Epi& E, const int wave_s) {
;     ...
;         for (int t = PEEL ? 2 : 0; t < nt; t += 2) {
;             const bool last = (t == nt - 2);
;             const char* a1 = cA + (size_t)(t + 1) * kstepA;
;             const char* a2 = last ? nA : cA + (size_t)(t + 2) * kstepA; const char* b2 = last ? nB : cB + (size_t)(t + 2) * kstep;
;             const char* a3 = a2 + kstepA; const char* b3 = b2 + kstep;
;             if (last && has_next) S.a_ready(nxt);
;             if constexpr (SP2) {
;             PG8_ITER(PG8_MMA)
.LBB0_2417:
	ds_read_b128 v[146:149], v141
	ds_read_b128 v[150:153], v141 offset:1024
	ds_read_b128 v[154:157], v141 offset:2048
	ds_read_b128 v[158:161], v141 offset:3072
	ds_read_b128 v[162:165], v142
	ds_read_b128 v[166:169], v142 offset:1024
	ds_read_b128 v[170:173], v142 offset:2048
	ds_read_b128 v[174:177], v142 offset:3072
	s_add_u32 s80, s78, 0xfff80080
	s_addc_u32 s81, s79, -1
	s_cmp_eq_u32 s88, 28
	s_cselect_b32 s83, s50, s81
	s_cselect_b32 s82, s51, s80
	s_cselect_b32 s81, s52, s85
	s_cselect_b32 s80, s53, s73
	s_mov_b32 m0, s48
	v_lshl_add_u64 v[136:137], s[78:79], 0, v[134:135]
	ds_read_b128 v[178:181], v143
	ds_read_b128 v[182:185], v143 offset:1024
	ds_read_b128 v[186:189], v143 offset:2048
	ds_read_b128 v[190:193], v143 offset:3072
	ds_read_b128 v[194:197], v143 offset:4096
	ds_read_b128 v[198:201], v143 offset:5120
	ds_read_b128 v[202:205], v143 offset:6144
	ds_read_b128 v[206:209], v143 offset:7168
	global_load_lds_dwordx4 v134, s[78:79]
	v_lshl_add_u64 v[136:137], s[78:79], 0, v[132:133]
	s_mov_b32 m0, s49
	s_nop 0
	global_load_lds_dwordx4 v132, s[78:79]
	s_waitcnt vmcnt(8) lgkmcnt(0)
	s_setprio 1
	s_barrier
	v_mfma_f32_16x16x32_bf16 v[24:27], v[146:149], v[178:181], v[24:27]
	v_mfma_f32_16x16x32_bf16 v[28:31], v[154:157], v[178:181], v[28:31]
	v_mfma_f32_16x16x32_bf16 v[16:19], v[146:149], v[186:189], v[16:19]
	v_mfma_f32_16x16x32_bf16 v[20:23], v[154:157], v[186:189], v[20:23]
	v_mfma_f32_16x16x32_bf16 v[8:11], v[146:149], v[194:197], v[8:11]
	v_mfma_f32_16x16x32_bf16 v[12:15], v[154:157], v[194:197], v[12:15]
	v_mfma_f32_16x16x32_bf16 v[0:3], v[146:149], v[202:205], v[0:3]
	v_mfma_f32_16x16x32_bf16 v[4:7], v[154:157], v[202:205], v[4:7]
	v_mfma_f32_16x16x32_bf16 v[24:27], v[150:153], v[182:185], v[24:27]
	v_mfma_f32_16x16x32_bf16 v[28:31], v[158:161], v[182:185], v[28:31]
	v_mfma_f32_16x16x32_bf16 v[16:19], v[150:153], v[190:193], v[16:19]
	v_mfma_f32_16x16x32_bf16 v[20:23], v[158:161], v[190:193], v[20:23]
	v_mfma_f32_16x16x32_bf16 v[8:11], v[150:153], v[198:201], v[8:11]
	v_mfma_f32_16x16x32_bf16 v[12:15], v[158:161], v[198:201], v[12:15]
	v_mfma_f32_16x16x32_bf16 v[0:3], v[150:153], v[206:209], v[0:3]
	v_mfma_f32_16x16x32_bf16 v[4:7], v[158:161], v[206:209], v[4:7]
	v_mfma_f32_16x16x32_bf16 v[56:59], v[162:165], v[178:181], v[56:59]
	v_mfma_f32_16x16x32_bf16 v[60:63], v[170:173], v[178:181], v[60:63]
	v_mfma_f32_16x16x32_bf16 v[48:51], v[162:165], v[186:189], v[48:51]
	v_mfma_f32_16x16x32_bf16 v[52:55], v[170:173], v[186:189], v[52:55]
	v_mfma_f32_16x16x32_bf16 v[40:43], v[162:165], v[194:197], v[40:43]
	v_mfma_f32_16x16x32_bf16 v[44:47], v[170:173], v[194:197], v[44:47]
	v_mfma_f32_16x16x32_bf16 v[32:35], v[162:165], v[202:205], v[32:35]
	v_mfma_f32_16x16x32_bf16 v[36:39], v[170:173], v[202:205], v[36:39]
	v_mfma_f32_16x16x32_bf16 v[56:59], v[166:169], v[182:185], v[56:59]
	v_mfma_f32_16x16x32_bf16 v[60:63], v[174:177], v[182:185], v[60:63]
	v_mfma_f32_16x16x32_bf16 v[48:51], v[166:169], v[190:193], v[48:51]
	v_mfma_f32_16x16x32_bf16 v[52:55], v[174:177], v[190:193], v[52:55]
	v_mfma_f32_16x16x32_bf16 v[40:43], v[166:169], v[198:201], v[40:43]
	v_mfma_f32_16x16x32_bf16 v[44:47], v[174:177], v[198:201], v[44:47]
	v_mfma_f32_16x16x32_bf16 v[32:35], v[166:169], v[206:209], v[32:35]
	v_mfma_f32_16x16x32_bf16 v[36:39], v[174:177], v[206:209], v[36:39]
	s_barrier
	s_setprio 0
	s_mov_b32 m0, s54
	v_lshl_add_u64 v[136:137], s[80:81], 0, v[128:129]
	s_add_u32 s90, s80, 0x80000
	ds_read_b128 v[178:181], v143 offset:16384
	ds_read_b128 v[182:185], v143 offset:17408
	ds_read_b128 v[186:189], v143 offset:18432
	ds_read_b128 v[190:193], v143 offset:19456
	ds_read_b128 v[194:197], v143 offset:20480
	ds_read_b128 v[198:201], v143 offset:21504
	ds_read_b128 v[202:205], v143 offset:22528
	ds_read_b128 v[206:209], v143 offset:23552
	global_load_lds_dwordx4 v128, s[80:81]
	v_lshl_add_u64 v[138:139], s[80:81], 0, v[130:131]
	s_mov_b32 m0, s55
	s_addc_u32 s91, s81, 0
	global_load_lds_dwordx4 v130, s[80:81]
	v_lshl_add_u64 v[210:211], s[90:91], 0, v[128:129]
	s_mov_b32 m0, s56
	v_lshl_add_u64 v[212:213], s[82:83], 0, v[130:131]
	global_load_lds_dwordx4 v128, s[90:91]
	v_lshl_add_u64 v[210:211], s[90:91], 0, v[130:131]
	s_mov_b32 m0, s57
	s_nop 0
	global_load_lds_dwordx4 v130, s[90:91]
	v_lshl_add_u64 v[210:211], s[82:83], 0, v[128:129]
	s_mov_b32 m0, s22
	s_nop 0
	global_load_lds_dwordx4 v128, s[82:83]
	s_mov_b32 m0, s23
	s_nop 0
	global_load_lds_dwordx4 v130, s[82:83]
	s_waitcnt vmcnt(8) lgkmcnt(0)
	s_setprio 1
	s_barrier
	v_mfma_f32_16x16x32_bf16 v[88:91], v[146:149], v[178:181], v[88:91]
	v_mfma_f32_16x16x32_bf16 v[92:95], v[154:157], v[178:181], v[92:95]
	v_mfma_f32_16x16x32_bf16 v[80:83], v[146:149], v[186:189], v[80:83]
	v_mfma_f32_16x16x32_bf16 v[84:87], v[154:157], v[186:189], v[84:87]
	v_mfma_f32_16x16x32_bf16 v[72:75], v[146:149], v[194:197], v[72:75]
	v_mfma_f32_16x16x32_bf16 v[76:79], v[154:157], v[194:197], v[76:79]
	v_mfma_f32_16x16x32_bf16 v[64:67], v[146:149], v[202:205], v[64:67]
	v_mfma_f32_16x16x32_bf16 v[68:71], v[154:157], v[202:205], v[68:71]
	v_mfma_f32_16x16x32_bf16 v[88:91], v[150:153], v[182:185], v[88:91]
	v_mfma_f32_16x16x32_bf16 v[92:95], v[158:161], v[182:185], v[92:95]
	v_mfma_f32_16x16x32_bf16 v[80:83], v[150:153], v[190:193], v[80:83]
	v_mfma_f32_16x16x32_bf16 v[84:87], v[158:161], v[190:193], v[84:87]
	v_mfma_f32_16x16x32_bf16 v[72:75], v[150:153], v[198:201], v[72:75]
	v_mfma_f32_16x16x32_bf16 v[76:79], v[158:161], v[198:201], v[76:79]
	v_mfma_f32_16x16x32_bf16 v[64:67], v[150:153], v[206:209], v[64:67]
	v_mfma_f32_16x16x32_bf16 v[68:71], v[158:161], v[206:209], v[68:71]
	v_mfma_f32_16x16x32_bf16 v[120:123], v[162:165], v[178:181], v[120:123]
	v_mfma_f32_16x16x32_bf16 v[124:127], v[170:173], v[178:181], v[124:127]
	v_mfma_f32_16x16x32_bf16 v[112:115], v[162:165], v[186:189], v[112:115]
	v_mfma_f32_16x16x32_bf16 v[116:119], v[170:173], v[186:189], v[116:119]
	v_mfma_f32_16x16x32_bf16 v[104:107], v[162:165], v[194:197], v[104:107]
	v_mfma_f32_16x16x32_bf16 v[108:111], v[170:173], v[194:197], v[108:111]
	v_mfma_f32_16x16x32_bf16 v[96:99], v[162:165], v[202:205], v[96:99]
	v_mfma_f32_16x16x32_bf16 v[100:103], v[170:173], v[202:205], v[100:103]
	v_mfma_f32_16x16x32_bf16 v[120:123], v[166:169], v[182:185], v[120:123]
	v_mfma_f32_16x16x32_bf16 v[124:127], v[174:177], v[182:185], v[124:127]
	v_mfma_f32_16x16x32_bf16 v[112:115], v[166:169], v[190:193], v[112:115]
	v_mfma_f32_16x16x32_bf16 v[116:119], v[174:177], v[190:193], v[116:119]
	v_mfma_f32_16x16x32_bf16 v[104:107], v[166:169], v[198:201], v[104:107]
	v_mfma_f32_16x16x32_bf16 v[108:111], v[174:177], v[198:201], v[108:111]
	v_mfma_f32_16x16x32_bf16 v[96:99], v[166:169], v[206:209], v[96:99]
	v_mfma_f32_16x16x32_bf16 v[100:103], v[174:177], v[206:209], v[100:103]
	s_barrier
	s_setprio 0
	ds_read_b128 v[146:149], v144
	ds_read_b128 v[150:153], v144 offset:1024
	ds_read_b128 v[154:157], v144 offset:2048
	ds_read_b128 v[158:161], v144 offset:3072
	ds_read_b128 v[162:165], v145
	ds_read_b128 v[166:169], v145 offset:1024
	ds_read_b128 v[170:173], v145 offset:2048
	ds_read_b128 v[174:177], v145 offset:3072
	s_add_u32 s82, s82, 0x80000
	s_addc_u32 s83, s83, 0
	s_mov_b32 m0, s36
	v_lshl_add_u64 v[214:215], s[82:83], 0, v[128:129]
	ds_read_b128 v[178:181], v143 offset:32768
	ds_read_b128 v[182:185], v143 offset:33792
	ds_read_b128 v[186:189], v143 offset:34816
	ds_read_b128 v[190:193], v143 offset:35840
	ds_read_b128 v[194:197], v143 offset:36864
	ds_read_b128 v[198:201], v143 offset:37888
	ds_read_b128 v[202:205], v143 offset:38912
	ds_read_b128 v[206:209], v143 offset:39936
	global_load_lds_dwordx4 v128, s[82:83]
	v_lshl_add_u64 v[214:215], s[82:83], 0, v[130:131]
	s_mov_b32 m0, s37
	s_nop 0
	global_load_lds_dwordx4 v130, s[82:83]
	s_waitcnt vmcnt(8) lgkmcnt(0)
	s_setprio 1
	s_barrier
	v_mfma_f32_16x16x32_bf16 v[24:27], v[146:149], v[178:181], v[24:27]
	v_mfma_f32_16x16x32_bf16 v[28:31], v[154:157], v[178:181], v[28:31]
	v_mfma_f32_16x16x32_bf16 v[16:19], v[146:149], v[186:189], v[16:19]
	v_mfma_f32_16x16x32_bf16 v[20:23], v[154:157], v[186:189], v[20:23]
	v_mfma_f32_16x16x32_bf16 v[8:11], v[146:149], v[194:197], v[8:11]
	v_mfma_f32_16x16x32_bf16 v[12:15], v[154:157], v[194:197], v[12:15]
	v_mfma_f32_16x16x32_bf16 v[0:3], v[146:149], v[202:205], v[0:3]
	v_mfma_f32_16x16x32_bf16 v[4:7], v[154:157], v[202:205], v[4:7]
	v_mfma_f32_16x16x32_bf16 v[24:27], v[150:153], v[182:185], v[24:27]
	v_mfma_f32_16x16x32_bf16 v[28:31], v[158:161], v[182:185], v[28:31]
	v_mfma_f32_16x16x32_bf16 v[16:19], v[150:153], v[190:193], v[16:19]
	v_mfma_f32_16x16x32_bf16 v[20:23], v[158:161], v[190:193], v[20:23]
	v_mfma_f32_16x16x32_bf16 v[8:11], v[150:153], v[198:201], v[8:11]
	v_mfma_f32_16x16x32_bf16 v[12:15], v[158:161], v[198:201], v[12:15]
	v_mfma_f32_16x16x32_bf16 v[0:3], v[150:153], v[206:209], v[0:3]
	v_mfma_f32_16x16x32_bf16 v[4:7], v[158:161], v[206:209], v[4:7]
	v_mfma_f32_16x16x32_bf16 v[56:59], v[162:165], v[178:181], v[56:59]
	v_mfma_f32_16x16x32_bf16 v[60:63], v[170:173], v[178:181], v[60:63]
	v_mfma_f32_16x16x32_bf16 v[48:51], v[162:165], v[186:189], v[48:51]
	v_mfma_f32_16x16x32_bf16 v[52:55], v[170:173], v[186:189], v[52:55]
	v_mfma_f32_16x16x32_bf16 v[40:43], v[162:165], v[194:197], v[40:43]
	v_mfma_f32_16x16x32_bf16 v[44:47], v[170:173], v[194:197], v[44:47]
	v_mfma_f32_16x16x32_bf16 v[32:35], v[162:165], v[202:205], v[32:35]
	v_mfma_f32_16x16x32_bf16 v[36:39], v[170:173], v[202:205], v[36:39]
	v_mfma_f32_16x16x32_bf16 v[56:59], v[166:169], v[182:185], v[56:59]
	v_mfma_f32_16x16x32_bf16 v[60:63], v[174:177], v[182:185], v[60:63]
	v_mfma_f32_16x16x32_bf16 v[48:51], v[166:169], v[190:193], v[48:51]
	v_mfma_f32_16x16x32_bf16 v[52:55], v[174:177], v[190:193], v[52:55]
	v_mfma_f32_16x16x32_bf16 v[40:43], v[166:169], v[198:201], v[40:43]
	v_mfma_f32_16x16x32_bf16 v[44:47], v[174:177], v[198:201], v[44:47]
	v_mfma_f32_16x16x32_bf16 v[32:35], v[166:169], v[206:209], v[32:35]
	v_mfma_f32_16x16x32_bf16 v[36:39], v[174:177], v[206:209], v[36:39]
	s_barrier
; #define PG8_STAGE(bufoff, gbase, voff) do { _Pragma("unroll") for (int _i = 0; _i < 2; ++_i) \
;         __builtin_amdgcn_global_load_lds((const unsigned*)((const char*)(gbase) + (voff)[_i]), (PG8_LAS unsigned*)(lds + (bufoff) + ldsw + _i * 8192), 16, 0, 0); } while (0)
; #define PG8_BAR __builtin_amdgcn_s_barrier()
; template <class Epi, class Sched, bool ALIGN_EPI = false, bool SP2 = false, bool A_TILED = false>
; __device__ __forceinline__ void gemm_phase(PG8_LAS unsigned char* lds, const Gemm g, const Sched& S, const Epi& E, const int wave_s) {
;     ...
;         for (int t = PEEL ? 2 : 0; t < nt; t += 2) {
;             const bool last = (t == nt - 2);
;             const char* a1 = cA + (size_t)(t + 1) * kstepA;
;             const char* a2 = last ? nA : cA + (size_t)(t + 2) * kstepA; const char* b2 = last ? nB : cB + (size_t)(t + 2) * kstep;
;             const char* a3 = a2 + kstepA; const char* b3 = b2 + kstep;
;             if (last && has_next) S.a_ready(nxt);
;             if constexpr (SP2) {
;             PG8_ITER(PG8_MMA)
;             } else {
;             PG8_LDB(B0, 0, 0); PG8_SCHED; PG8_LDA(At, 0, 0); PG8_STAGE(PG8_SA(1, 1), a1 + hstepA, voffA);
;             PG8_WAIT_L(8); PG8_BAR; PG8_WAIT_L(0); PG8_MMA(0, 0, At, B0); PG8_BAR; PG8_SCHED;
;             PG8_LDB(B1, 0, 1); PG8_STAGE(PG8_SB(0, 0), b2, voffB);
;             PG8_BAR; PG8_WAIT_L(0); PG8_MMA(0, 1, At, B1); PG8_BAR;
;             PG8_LDA(At, 0, 1); PG8_STAGE(PG8_SA(0, 0), a2, voffA);
;             PG8_BAR; PG8_WAIT_L(0); PG8_MMA(1, 0, At, B0); PG8_BAR; PG8_SCHED;
;             PG8_STAGE(PG8_SB(0, 1), b2 + hstep, voffB);
;             PG8_WAIT_V(6); PG8_BAR; PG8_MMA(1, 1, At, B1); PG8_BAR;
;             PG8_LDB(B0, 1, 0); PG8_SCHED; PG8_LDA(At, 1, 0); PG8_STAGE(PG8_SA(0, 1), a2 + hstepA, voffA);
;             PG8_WAIT_L(8); PG8_BAR; PG8_WAIT_L(0); PG8_MMA(0, 0, At, B0); PG8_BAR; PG8_SCHED;
;             PG8_LDB(B1, 1, 1); PG8_STAGE(PG8_SB(1, 0), b3, voffB);
;             PG8_BAR; PG8_WAIT_L(0); PG8_MMA(0, 1, At, B1); PG8_BAR;
;             PG8_LDA(At, 1, 1); PG8_STAGE(PG8_SA(1, 0), a3, voffA);
;             PG8_BAR; PG8_WAIT_L(0); PG8_MMA(1, 0, At, B0); PG8_BAR; PG8_SCHED;
;             PG8_STAGE(PG8_SB(1, 1), b3 + hstep, voffB);
;             PG8_WAIT_V(6); PG8_BAR; PG8_MMA(1, 1, At, B1); PG8_BAR;
;             }
;         }
;         if constexpr (ALIGN_EPI) { if (wr == 0) PG8_BAR; }
	s_setprio 0
	s_mov_b32 m0, s58
	v_lshl_add_u64 v[136:137], v[136:137], 0, s[62:63]
	s_add_u32 s80, s80, 0x80080
	ds_read_b128 v[178:181], v143 offset:49152
	ds_read_b128 v[182:185], v143 offset:50176
	ds_read_b128 v[186:189], v143 offset:51200
	ds_read_b128 v[190:193], v143 offset:52224
	ds_read_b128 v[194:197], v143 offset:53248
	ds_read_b128 v[198:201], v143 offset:54272
	ds_read_b128 v[202:205], v143 offset:55296
	ds_read_b128 v[206:209], v143 offset:56320
	global_load_lds_dwordx4 v[136:137], off
	v_lshl_add_u64 v[136:137], v[138:139], 0, s[62:63]
	s_mov_b32 m0, s59
	s_addc_u32 s81, s81, 0
	global_load_lds_dwordx4 v[136:137], off
	v_lshl_add_u64 v[136:137], s[80:81], 0, v[128:129]
	s_mov_b32 m0, s61
	s_nop 0
	global_load_lds_dwordx4 v128, s[80:81]
	v_lshl_add_u64 v[136:137], s[80:81], 0, v[130:131]
	s_mov_b32 m0, s71
	s_nop 0
	global_load_lds_dwordx4 v130, s[80:81]
	v_lshl_add_u64 v[136:137], v[210:211], 0, s[62:63]
	s_mov_b32 m0, s42
	s_nop 0
	global_load_lds_dwordx4 v[136:137], off
	v_lshl_add_u64 v[136:137], v[212:213], 0, s[62:63]
	s_mov_b32 m0, s43
	s_nop 0
	global_load_lds_dwordx4 v[136:137], off
	s_waitcnt vmcnt(8) lgkmcnt(0)
	s_setprio 1
	s_barrier
	v_mfma_f32_16x16x32_bf16 v[88:91], v[146:149], v[178:181], v[88:91]
	v_mfma_f32_16x16x32_bf16 v[92:95], v[154:157], v[178:181], v[92:95]
	v_mfma_f32_16x16x32_bf16 v[80:83], v[146:149], v[186:189], v[80:83]
	v_mfma_f32_16x16x32_bf16 v[84:87], v[154:157], v[186:189], v[84:87]
	v_mfma_f32_16x16x32_bf16 v[72:75], v[146:149], v[194:197], v[72:75]
	v_mfma_f32_16x16x32_bf16 v[76:79], v[154:157], v[194:197], v[76:79]
	v_mfma_f32_16x16x32_bf16 v[64:67], v[146:149], v[202:205], v[64:67]
	v_mfma_f32_16x16x32_bf16 v[68:71], v[154:157], v[202:205], v[68:71]
	v_mfma_f32_16x16x32_bf16 v[88:91], v[150:153], v[182:185], v[88:91]
	v_mfma_f32_16x16x32_bf16 v[92:95], v[158:161], v[182:185], v[92:95]
	v_mfma_f32_16x16x32_bf16 v[80:83], v[150:153], v[190:193], v[80:83]
	v_mfma_f32_16x16x32_bf16 v[84:87], v[158:161], v[190:193], v[84:87]
	v_mfma_f32_16x16x32_bf16 v[72:75], v[150:153], v[198:201], v[72:75]
	v_mfma_f32_16x16x32_bf16 v[76:79], v[158:161], v[198:201], v[76:79]
	v_mfma_f32_16x16x32_bf16 v[64:67], v[150:153], v[206:209], v[64:67]
	v_mfma_f32_16x16x32_bf16 v[68:71], v[158:161], v[206:209], v[68:71]
	v_mfma_f32_16x16x32_bf16 v[120:123], v[162:165], v[178:181], v[120:123]
	v_mfma_f32_16x16x32_bf16 v[124:127], v[170:173], v[178:181], v[124:127]
	v_mfma_f32_16x16x32_bf16 v[112:115], v[162:165], v[186:189], v[112:115]
	v_mfma_f32_16x16x32_bf16 v[116:119], v[170:173], v[186:189], v[116:119]
	v_mfma_f32_16x16x32_bf16 v[104:107], v[162:165], v[194:197], v[104:107]
	v_mfma_f32_16x16x32_bf16 v[108:111], v[170:173], v[194:197], v[108:111]
	v_mfma_f32_16x16x32_bf16 v[96:99], v[162:165], v[202:205], v[96:99]
	v_mfma_f32_16x16x32_bf16 v[100:103], v[170:173], v[202:205], v[100:103]
	v_mfma_f32_16x16x32_bf16 v[120:123], v[166:169], v[182:185], v[120:123]
	v_mfma_f32_16x16x32_bf16 v[124:127], v[174:177], v[182:185], v[124:127]
	v_mfma_f32_16x16x32_bf16 v[112:115], v[166:169], v[190:193], v[112:115]
	v_mfma_f32_16x16x32_bf16 v[116:119], v[174:177], v[190:193], v[116:119]
	v_mfma_f32_16x16x32_bf16 v[104:107], v[166:169], v[198:201], v[104:107]
	v_mfma_f32_16x16x32_bf16 v[108:111], v[174:177], v[198:201], v[108:111]
	v_mfma_f32_16x16x32_bf16 v[96:99], v[166:169], v[206:209], v[96:99]
	v_mfma_f32_16x16x32_bf16 v[100:103], v[174:177], v[206:209], v[100:103]
	s_barrier
	s_setprio 0
	s_add_i32 s88, s88, 2
	s_add_u32 s73, s73, 0x100
	s_addc_u32 s85, s85, 0
	s_add_u32 s78, s78, 0x100
	s_addc_u32 s79, s79, 0
	s_cmp_gt_u32 s88, 29
	s_cbranch_scc0 .LBB0_2417
	s_and_b64 vcc, exec, s[64:65]
	s_cbranch_vccz .LBB0_2420
	s_barrier

; template <class Epi, class Sched, bool ALIGN_EPI = false, bool SP2 = false, bool A_TILED = false>
; __device__ __forceinline__ void gemm_phase(PG8_LAS unsigned char* lds, const Gemm g, const Sched& S, const Epi& E, const int wave_s) {
;     ...
;         if constexpr (PEEL) {
;             const char* a1 = cA + kstepA; const char* a2 = cA + 2 * kstepA; const char* b2 = cB + 2 * kstep; const char* a3 = a2 + kstepA; const char* b3 = b2 + kstep;
;             PG8_ITER(PG8_MMAZ)
.Lpw_11:
	s_setprio 1
	s_barrier
	v_mfma_f32_16x16x32_bf16 v[88:91], v[0:3], v[56:59], 0
	v_mfma_f32_16x16x32_bf16 v[64:67], v[0:3], v[32:35], 0
	v_mfma_f32_16x16x32_bf16 v[68:71], v[8:11], v[32:35], 0
	v_mfma_f32_16x16x32_bf16 v[72:75], v[0:3], v[40:43], 0
	v_mfma_f32_16x16x32_bf16 v[76:79], v[8:11], v[40:43], 0
	v_mfma_f32_16x16x32_bf16 v[80:83], v[0:3], v[48:51], 0
	v_mfma_f32_16x16x32_bf16 v[84:87], v[8:11], v[48:51], 0
	v_mfma_f32_16x16x32_bf16 v[96:99], v[4:7], v[60:63], v[88:91]
	v_mfma_f32_16x16x32_bf16 v[88:91], v[8:11], v[56:59], 0
	v_mfma_f32_16x16x32_bf16 v[64:67], v[4:7], v[36:39], v[64:67]
	v_mfma_f32_16x16x32_bf16 v[68:71], v[12:15], v[36:39], v[68:71]
	v_mfma_f32_16x16x32_bf16 v[72:75], v[4:7], v[44:47], v[72:75]
	v_mfma_f32_16x16x32_bf16 v[76:79], v[12:15], v[44:47], v[76:79]
	v_mfma_f32_16x16x32_bf16 v[80:83], v[4:7], v[52:55], v[80:83]
	v_mfma_f32_16x16x32_bf16 v[84:87], v[12:15], v[52:55], v[84:87]
	v_mfma_f32_16x16x32_bf16 v[100:103], v[12:15], v[60:63], v[88:91]
	v_mfma_f32_16x16x32_bf16 v[88:91], v[16:19], v[32:35], 0
	v_mfma_f32_16x16x32_bf16 v[32:35], v[24:27], v[32:35], 0
	v_mfma_f32_16x16x32_bf16 v[112:115], v[20:23], v[36:39], v[88:91]
	v_mfma_f32_16x16x32_bf16 v[32:35], v[28:31], v[36:39], v[32:35]
	v_mfma_f32_16x16x32_bf16 v[36:39], v[16:19], v[40:43], 0
	v_mfma_f32_16x16x32_bf16 v[40:43], v[24:27], v[40:43], 0
	v_mfma_f32_16x16x32_bf16 v[36:39], v[20:23], v[44:47], v[36:39]
	v_mfma_f32_16x16x32_bf16 v[40:43], v[28:31], v[44:47], v[40:43]
	v_mfma_f32_16x16x32_bf16 v[44:47], v[16:19], v[48:51], 0
	v_mfma_f32_16x16x32_bf16 v[48:51], v[24:27], v[48:51], 0
	v_mfma_f32_16x16x32_bf16 v[44:47], v[20:23], v[52:55], v[44:47]
	v_mfma_f32_16x16x32_bf16 v[48:51], v[28:31], v[52:55], v[48:51]
	v_mfma_f32_16x16x32_bf16 v[52:55], v[16:19], v[56:59], 0
	v_mfma_f32_16x16x32_bf16 v[56:59], v[24:27], v[56:59], 0
	v_mfma_f32_16x16x32_bf16 v[52:55], v[20:23], v[60:63], v[52:55]
	v_mfma_f32_16x16x32_bf16 v[56:59], v[28:31], v[60:63], v[56:59]
	s_barrier
	s_setprio 0
	s_add_i32 s90, s53, s37
	v_lshl_add_u64 v[250:251], s[78:79], 0, v[128:129]
	s_add_i32 s91, s90, 0x2000
	v_lshl_add_u64 v[144:145], v[250:251], 0, s[66:67]
	s_mov_b32 m0, s90
	v_lshl_add_u64 v[252:253], s[78:79], 0, v[130:131]
	s_add_u32 s82, s78, 0x20100
	ds_read_b128 v[60:63], v151 offset:16384
	ds_read_b128 v[88:91], v151 offset:17408
	ds_read_b128 v[92:95], v151 offset:18432
	ds_read_b128 v[104:107], v151 offset:19456
	ds_read_b128 v[108:111], v151 offset:20480
	ds_read_b128 v[116:119], v151 offset:21504
	ds_read_b128 v[120:123], v151 offset:22528
	ds_read_b128 v[124:127], v151 offset:23552
	global_load_lds_dwordx4 v[144:145], off
	v_lshl_add_u64 v[144:145], v[252:253], 0, s[66:67]
	s_mov_b32 m0, s91
	s_addc_u32 s83, s79, 0
	s_add_i32 s93, s54, s37
	global_load_lds_dwordx4 v[144:145], off
	v_lshl_add_u64 v[144:145], s[82:83], 0, v[128:129]
	s_mov_b32 m0, s93
	s_add_i32 s95, s93, 0x2000
	global_load_lds_dwordx4 v128, s[82:83]
	v_lshl_add_u64 v[144:145], s[82:83], 0, v[130:131]
	s_mov_b32 m0, s95
	v_lshl_add_u64 v[140:141], s[80:81], 0, v[134:135]
	global_load_lds_dwordx4 v130, s[82:83]
	v_lshl_add_u64 v[144:145], v[140:141], 0, s[66:67]
	s_mov_b32 m0, s38
	v_lshl_add_u64 v[142:143], s[80:81], 0, v[132:133]
	global_load_lds_dwordx4 v[144:145], off
	v_lshl_add_u64 v[144:145], v[142:143], 0, s[66:67]
	s_mov_b32 m0, s39
	s_nop 0
	global_load_lds_dwordx4 v[144:145], off
	s_waitcnt vmcnt(24) lgkmcnt(0)
	s_cmp_lg_u32 s98, 0
	s_cbranch_scc1 .Lpw_12
	s_waitcnt vmcnt(8)
.Lpw_12:
	s_setprio 1
	s_barrier
	v_mfma_f32_16x16x32_bf16 v[144:147], v[0:3], v[60:63], 0
	v_mfma_f32_16x16x32_bf16 v[154:157], v[4:7], v[88:91], v[144:147]
	v_mfma_f32_16x16x32_bf16 v[144:147], v[8:11], v[60:63], 0
	v_mfma_f32_16x16x32_bf16 v[158:161], v[12:15], v[88:91], v[144:147]
	v_mfma_f32_16x16x32_bf16 v[144:147], v[0:3], v[92:95], 0
	v_mfma_f32_16x16x32_bf16 v[162:165], v[4:7], v[104:107], v[144:147]
	v_mfma_f32_16x16x32_bf16 v[144:147], v[8:11], v[92:95], 0
	v_mfma_f32_16x16x32_bf16 v[166:169], v[12:15], v[104:107], v[144:147]
	v_mfma_f32_16x16x32_bf16 v[144:147], v[0:3], v[108:111], 0
	v_mfma_f32_16x16x32_bf16 v[0:3], v[0:3], v[120:123], 0
	v_mfma_f32_16x16x32_bf16 v[170:173], v[4:7], v[116:119], v[144:147]
	v_mfma_f32_16x16x32_bf16 v[0:3], v[4:7], v[124:127], v[0:3]
	v_mfma_f32_16x16x32_bf16 v[4:7], v[8:11], v[120:123], 0
	v_mfma_f32_16x16x32_bf16 v[144:147], v[8:11], v[108:111], 0
	v_mfma_f32_16x16x32_bf16 v[4:7], v[12:15], v[124:127], v[4:7]
	v_mfma_f32_16x16x32_bf16 v[174:177], v[12:15], v[116:119], v[144:147]
	v_mfma_f32_16x16x32_bf16 v[8:11], v[16:19], v[60:63], 0
	v_mfma_f32_16x16x32_bf16 v[178:181], v[20:23], v[88:91], v[8:11]
	v_mfma_f32_16x16x32_bf16 v[8:11], v[24:27], v[60:63], 0
	v_mfma_f32_16x16x32_bf16 v[182:185], v[28:31], v[88:91], v[8:11]
	v_mfma_f32_16x16x32_bf16 v[8:11], v[16:19], v[92:95], 0
	v_mfma_f32_16x16x32_bf16 v[186:189], v[20:23], v[104:107], v[8:11]
	v_mfma_f32_16x16x32_bf16 v[8:11], v[24:27], v[92:95], 0
	v_mfma_f32_16x16x32_bf16 v[190:193], v[28:31], v[104:107], v[8:11]
	v_mfma_f32_16x16x32_bf16 v[8:11], v[16:19], v[108:111], 0
	v_mfma_f32_16x16x32_bf16 v[194:197], v[20:23], v[116:119], v[8:11]
	v_mfma_f32_16x16x32_bf16 v[8:11], v[24:27], v[108:111], 0
	v_mfma_f32_16x16x32_bf16 v[198:201], v[28:31], v[116:119], v[8:11]
	v_mfma_f32_16x16x32_bf16 v[8:11], v[16:19], v[120:123], 0
	v_mfma_f32_16x16x32_bf16 v[202:205], v[20:23], v[124:127], v[8:11]
	v_mfma_f32_16x16x32_bf16 v[8:11], v[24:27], v[120:123], 0
	v_mfma_f32_16x16x32_bf16 v[206:209], v[28:31], v[124:127], v[8:11]
	s_barrier
; template <class Epi, class Sched, bool ALIGN_EPI = false, bool SP2 = false, bool A_TILED = false>
; __device__ __forceinline__ void gemm_phase(PG8_LAS unsigned char* lds, const Gemm g, const Sched& S, const Epi& E, const int wave_s) {
;     ...
;     Unit cur, nxt; int ui = 0;
;     if (!S.next(0, cur)) return;
;     f32x4 acc[2][2][4][2];
;     bf16x8 At[4][2], B0[2][2], B1[2][2];
;     const char* cA = (const char*)g.A + (size_t)cur.pm * tstepA; const char* cB = (const char*)g.Bt + (size_t)cur.pn * tstep;
;     S.a_ready(cur);
;     if constexpr (SP2) {
;         PG8_STAGE(PG8_SB(0, 0), cB, voffB); PG8_STAGE(PG8_SB(0, 1), cB + hstep, voffB); PG8_STAGE(PG8_SA(0, 0), cA, voffA); PG8_STAGE(PG8_SA(0, 1), cA + hstepA, voffA);
;         if (wr == 1) PG8_BAR;
;         PG8_WAIT_V(2); PG8_BAR;
;         PG8_STAGE(PG8_SB(1, 0), cB + kstep, voffB); PG8_STAGE(PG8_SA(1, 0), cA + kstepA, voffA); PG8_STAGE(PG8_SB(1, 1), cB + hstep + kstep, voffB);
;         PG8_WAIT_V(6); PG8_BAR;
;     } else {
;         PG8_STAGE(PG8_SB(0, 0), cB, voffB); PG8_STAGE(PG8_SA(0, 0), cA, voffA); PG8_STAGE(PG8_SB(0, 1), cB + hstep, voffB); PG8_STAGE(PG8_SA(0, 1), cA + hstepA, voffA);
;         if (wr == 1) PG8_BAR;
;         PG8_WAIT_V(4); PG8_BAR;
;         PG8_STAGE(PG8_SB(1, 0), cB + kstep, voffB); PG8_STAGE(PG8_SA(1, 0), cA + kstepA, voffA); PG8_STAGE(PG8_SB(1, 1), cB + hstep + kstep, voffB);
;         PG8_WAIT_V(6); PG8_BAR;
;     }
;     for (;;) {
;         const bool has_next = Epi::AFTER_DRAIN ? false : S.next(ui + 1, nxt);
;         const char* nA = has_next ? (const char*)g.A + (size_t)nxt.pm * tstepA : cA; const char* nB = has_next ? (const char*)g.Bt + (size_t)nxt.pn * tstep : cB;
;         constexpr bool PEEL = SP2 && !Epi::AFTER_DRAIN;
;         if constexpr (PEEL) {
;             const char* a1 = cA + kstepA; const char* a2 = cA + 2 * kstepA; const char* b2 = cB + 2 * kstep; const char* a3 = a2 + kstepA; const char* b3 = b2 + kstep;
;             PG8_ITER(PG8_MMAZ)
;         } else {
; #pragma unroll
;             for (int a = 0; a < 2; ++a)
; #pragma unroll
;                 for (int b = 0; b < 2; ++b)
; #pragma unroll
;                     for (int m = 0; m < 4; ++m)
; #pragma unroll
;                         for (int n = 0; n < 2; ++n) acc[a][b][m][n] = (f32x4){0.f, 0.f, 0.f, 0.f};
;         }
; #pragma nounroll
;         for (int t = PEEL ? 2 : 0; t < nt; t += 2) {
	s_setprio 0
	s_add_i32 s96, 0, 0x18000
	s_add_i32 vcc_lo, 0, 0x1c000
	v_add_u32_e32 v144, s96, v148
	v_add_u32_e32 v145, vcc_lo, v148
	s_nop 0
	ds_read_b128 v[8:11], v144
	ds_read_b128 v[12:15], v144 offset:1024
	ds_read_b128 v[16:19], v144 offset:2048
	ds_read_b128 v[20:23], v144 offset:3072
	ds_read_b128 v[210:213], v145
	ds_read_b128 v[214:217], v145 offset:1024
	ds_read_b128 v[218:221], v145 offset:2048
	ds_read_b128 v[222:225], v145 offset:3072
	s_add_u32 s82, s80, 0x20100
	s_addc_u32 s83, s81, 0
	s_mov_b32 m0, s40
	v_lshl_add_u64 v[88:89], s[82:83], 0, v[134:135]
	ds_read_b128 v[24:27], v151 offset:32768
	ds_read_b128 v[28:31], v151 offset:33792
	ds_read_b128 v[60:63], v151 offset:34816
	ds_read_b128 v[226:229], v151 offset:35840
	ds_read_b128 v[230:233], v151 offset:36864
	ds_read_b128 v[234:237], v151 offset:37888
	ds_read_b128 v[238:241], v151 offset:38912
	ds_read_b128 v[242:245], v151 offset:39936
	global_load_lds_dwordx4 v134, s[82:83]
	v_lshl_add_u64 v[88:89], s[82:83], 0, v[132:133]
	s_mov_b32 m0, s41
	s_nop 0
	global_load_lds_dwordx4 v132, s[82:83]
	s_waitcnt vmcnt(8) lgkmcnt(0)
	s_setprio 1
	s_barrier
	v_mfma_f32_16x16x32_bf16 v[64:67], v[8:11], v[24:27], v[64:67]
	v_mfma_f32_16x16x32_bf16 v[124:127], v[12:15], v[28:31], v[64:67]
	v_mfma_f32_16x16x32_bf16 v[64:67], v[16:19], v[24:27], v[68:71]
	v_mfma_f32_16x16x32_bf16 v[120:123], v[20:23], v[28:31], v[64:67]
	v_mfma_f32_16x16x32_bf16 v[64:67], v[8:11], v[60:63], v[72:75]
	v_mfma_f32_16x16x32_bf16 v[108:111], v[12:15], v[226:229], v[64:67]
	v_mfma_f32_16x16x32_bf16 v[64:67], v[16:19], v[60:63], v[76:79]
	v_mfma_f32_16x16x32_bf16 v[104:107], v[20:23], v[226:229], v[64:67]
	v_mfma_f32_16x16x32_bf16 v[64:67], v[8:11], v[230:233], v[80:83]
	v_mfma_f32_16x16x32_bf16 v[92:95], v[12:15], v[234:237], v[64:67]
	v_mfma_f32_16x16x32_bf16 v[64:67], v[16:19], v[230:233], v[84:87]
	v_mfma_f32_16x16x32_bf16 v[88:91], v[20:23], v[234:237], v[64:67]
	v_mfma_f32_16x16x32_bf16 v[64:67], v[8:11], v[238:241], v[96:99]
	v_mfma_f32_16x16x32_bf16 v[76:79], v[12:15], v[242:245], v[64:67]
	v_mfma_f32_16x16x32_bf16 v[64:67], v[16:19], v[238:241], v[100:103]
	v_mfma_f32_16x16x32_bf16 v[72:75], v[20:23], v[242:245], v[64:67]
	v_mfma_f32_16x16x32_bf16 v[64:67], v[210:213], v[24:27], v[112:115]
	v_mfma_f32_16x16x32_bf16 v[24:27], v[218:221], v[24:27], v[32:35]
	v_mfma_f32_16x16x32_bf16 v[112:115], v[222:225], v[28:31], v[24:27]
	v_mfma_f32_16x16x32_bf16 v[24:27], v[210:213], v[60:63], v[36:39]
	v_mfma_f32_16x16x32_bf16 v[100:103], v[214:217], v[226:229], v[24:27]
	v_mfma_f32_16x16x32_bf16 v[24:27], v[218:221], v[60:63], v[40:43]
	v_mfma_f32_16x16x32_bf16 v[96:99], v[222:225], v[226:229], v[24:27]
	v_mfma_f32_16x16x32_bf16 v[24:27], v[210:213], v[230:233], v[44:47]
	v_mfma_f32_16x16x32_bf16 v[84:87], v[214:217], v[234:237], v[24:27]
	v_mfma_f32_16x16x32_bf16 v[24:27], v[218:221], v[230:233], v[48:51]
	v_mfma_f32_16x16x32_bf16 v[80:83], v[222:225], v[234:237], v[24:27]
	v_mfma_f32_16x16x32_bf16 v[24:27], v[210:213], v[238:241], v[52:55]
	v_mfma_f32_16x16x32_bf16 v[68:71], v[214:217], v[242:245], v[24:27]
	v_mfma_f32_16x16x32_bf16 v[24:27], v[218:221], v[238:241], v[56:59]
	v_mfma_f32_16x16x32_bf16 v[116:119], v[214:217], v[28:31], v[64:67]
	v_mfma_f32_16x16x32_bf16 v[64:67], v[222:225], v[242:245], v[24:27]
	s_barrier
	s_setprio 0
	s_add_i32 s96, s96, s37
	s_add_i32 s97, s96, 0x2000
	s_nop 1
	v_lshl_add_u64 v[24:25], v[250:251], 0, s[68:69]
	s_mov_b32 m0, s96
	s_add_u32 s82, s78, 0x20180
	ds_read_b128 v[32:35], v151 offset:49152
	ds_read_b128 v[36:39], v151 offset:50176
	ds_read_b128 v[226:229], v151 offset:51200
	ds_read_b128 v[230:233], v151 offset:52224
	ds_read_b128 v[234:237], v151 offset:53248
	ds_read_b128 v[238:241], v151 offset:54272
	ds_read_b128 v[242:245], v151 offset:55296
	ds_read_b128 v[246:249], v151 offset:56320
	global_load_lds_dwordx4 v[24:25], off
	v_lshl_add_u64 v[24:25], v[252:253], 0, s[68:69]
	s_mov_b32 m0, s97
	s_addc_u32 s83, s79, 0
	s_add_i32 vcc_lo, vcc_lo, s37
	global_load_lds_dwordx4 v[24:25], off
	v_lshl_add_u64 v[24:25], s[82:83], 0, v[128:129]
	s_mov_b32 m0, vcc_lo
	s_add_i32 vcc_hi, vcc_lo, 0x2000
	global_load_lds_dwordx4 v128, s[82:83]
	v_lshl_add_u64 v[24:25], s[82:83], 0, v[130:131]
	s_mov_b32 m0, vcc_hi
	s_nop 0
	global_load_lds_dwordx4 v130, s[82:83]
	v_lshl_add_u64 v[24:25], v[140:141], 0, s[68:69]
	s_mov_b32 m0, s51
	s_nop 0
	global_load_lds_dwordx4 v[24:25], off
	v_lshl_add_u64 v[24:25], v[142:143], 0, s[68:69]
	s_mov_b32 m0, s52
	s_nop 0
	global_load_lds_dwordx4 v[24:25], off
	s_waitcnt vmcnt(8) lgkmcnt(0)
	s_setprio 1
	s_barrier
	v_mfma_f32_16x16x32_bf16 v[24:27], v[8:11], v[32:35], v[154:157]
	v_mfma_f32_16x16x32_bf16 v[60:63], v[12:15], v[36:39], v[24:27]
	v_mfma_f32_16x16x32_bf16 v[24:27], v[16:19], v[32:35], v[158:161]
	v_mfma_f32_16x16x32_bf16 v[56:59], v[20:23], v[36:39], v[24:27]
	v_mfma_f32_16x16x32_bf16 v[24:27], v[8:11], v[226:229], v[162:165]
	v_mfma_f32_16x16x32_bf16 v[44:47], v[12:15], v[230:233], v[24:27]
	v_mfma_f32_16x16x32_bf16 v[24:27], v[16:19], v[226:229], v[166:169]
	v_mfma_f32_16x16x32_bf16 v[40:43], v[20:23], v[230:233], v[24:27]
	v_mfma_f32_16x16x32_bf16 v[24:27], v[8:11], v[234:237], v[170:173]
	v_mfma_f32_16x16x32_bf16 v[0:3], v[8:11], v[242:245], v[0:3]
	v_mfma_f32_16x16x32_bf16 v[28:31], v[12:15], v[238:241], v[24:27]
	v_mfma_f32_16x16x32_bf16 v[24:27], v[16:19], v[234:237], v[174:177]
	v_mfma_f32_16x16x32_bf16 v[12:15], v[12:15], v[246:249], v[0:3]
	v_mfma_f32_16x16x32_bf16 v[0:3], v[16:19], v[242:245], v[4:7]
	v_mfma_f32_16x16x32_bf16 v[24:27], v[20:23], v[238:241], v[24:27]
	v_mfma_f32_16x16x32_bf16 v[8:11], v[20:23], v[246:249], v[0:3]
	v_mfma_f32_16x16x32_bf16 v[0:3], v[210:213], v[32:35], v[178:181]
	v_mfma_f32_16x16x32_bf16 v[52:55], v[214:217], v[36:39], v[0:3]
	v_mfma_f32_16x16x32_bf16 v[0:3], v[218:221], v[32:35], v[182:185]
	v_mfma_f32_16x16x32_bf16 v[48:51], v[222:225], v[36:39], v[0:3]
	v_mfma_f32_16x16x32_bf16 v[0:3], v[210:213], v[226:229], v[186:189]
	v_mfma_f32_16x16x32_bf16 v[36:39], v[214:217], v[230:233], v[0:3]
	v_mfma_f32_16x16x32_bf16 v[0:3], v[218:221], v[226:229], v[190:193]
	v_mfma_f32_16x16x32_bf16 v[32:35], v[222:225], v[230:233], v[0:3]
	v_mfma_f32_16x16x32_bf16 v[0:3], v[210:213], v[234:237], v[194:197]
	v_mfma_f32_16x16x32_bf16 v[20:23], v[214:217], v[238:241], v[0:3]
	v_mfma_f32_16x16x32_bf16 v[0:3], v[218:221], v[234:237], v[198:201]
	v_mfma_f32_16x16x32_bf16 v[16:19], v[222:225], v[238:241], v[0:3]
	v_mfma_f32_16x16x32_bf16 v[0:3], v[210:213], v[242:245], v[202:205]
	v_mfma_f32_16x16x32_bf16 v[4:7], v[214:217], v[246:249], v[0:3]
	v_mfma_f32_16x16x32_bf16 v[0:3], v[218:221], v[242:245], v[206:209]
	v_mfma_f32_16x16x32_bf16 v[0:3], v[222:225], v[246:249], v[0:3]
	s_barrier
	s_setprio 0
	s_add_u32 s85, s78, 0x200
	s_addc_u32 s8, s79, 0
	s_add_u32 s78, s80, 0x20180
	s_addc_u32 s79, s81, 0
	s_mov_b32 s94, 0
; #define PG8_MMA(ai, bj, At, Bt) do { __builtin_amdgcn_s_setprio(1); _Pragma("unroll") for (int m = 0; m < 4; ++m) _Pragma("unroll") for (int n = 0; n < 2; ++n) _Pragma("unroll") for (int k = 0; k < 2; ++k) \
;         acc[ai][bj][m][n] = __builtin_amdgcn_mfma_f32_16x16x32_bf16(Bt[n][k], At[m][k], acc[ai][bj][m][n], 0, 0, 0); __builtin_amdgcn_s_setprio(0); } while (0)
; template <class Epi, class Sched, bool ALIGN_EPI = false, bool SP2 = false, bool A_TILED = false>
; __device__ __forceinline__ void gemm_phase(PG8_LAS unsigned char* lds, const Gemm g, const Sched& S, const Epi& E, const int wave_s) {
;     ...
;         for (int t = PEEL ? 2 : 0; t < nt; t += 2) {
;             const bool last = (t == nt - 2);
;             const char* a1 = cA + (size_t)(t + 1) * kstepA;
;             const char* a2 = last ? nA : cA + (size_t)(t + 2) * kstepA; const char* b2 = last ? nB : cB + (size_t)(t + 2) * kstep;
;             const char* a3 = a2 + kstepA; const char* b3 = b2 + kstep;
;             if (last && has_next) S.a_ready(nxt);
;             if constexpr (SP2) {
;             PG8_ITER(PG8_MMA)
.LBB0_2546:
	ds_read_b128 v[154:157], v149
	ds_read_b128 v[158:161], v149 offset:1024
	ds_read_b128 v[162:165], v149 offset:2048
	ds_read_b128 v[166:169], v149 offset:3072
	ds_read_b128 v[170:173], v150
	ds_read_b128 v[174:177], v150 offset:1024
	ds_read_b128 v[178:181], v150 offset:2048
	ds_read_b128 v[182:185], v150 offset:3072
	s_add_u32 s44, s78, 0xfffe0080
	s_addc_u32 s45, s79, -1
	s_cmp_eq_u32 s94, 4
	s_cselect_b32 s83, s58, s45
	s_cselect_b32 s82, s59, s44
	s_cselect_b32 s81, s71, s8
	s_cselect_b32 s80, s73, s85
	s_mov_b32 m0, s88
	v_lshl_add_u64 v[140:141], s[78:79], 0, v[138:139]
	ds_read_b128 v[186:189], v151
	ds_read_b128 v[190:193], v151 offset:1024
	ds_read_b128 v[194:197], v151 offset:2048
	ds_read_b128 v[198:201], v151 offset:3072
	ds_read_b128 v[202:205], v151 offset:4096
	ds_read_b128 v[206:209], v151 offset:5120
	ds_read_b128 v[210:213], v151 offset:6144
	ds_read_b128 v[214:217], v151 offset:7168
	global_load_lds_dwordx4 v138, s[78:79]
	v_lshl_add_u64 v[140:141], s[78:79], 0, v[136:137]
	s_mov_b32 m0, s89
	s_nop 0
	global_load_lds_dwordx4 v136, s[78:79]
	s_waitcnt vmcnt(8) lgkmcnt(0)
	s_setprio 1
	s_barrier
	v_mfma_f32_16x16x32_bf16 v[124:127], v[154:157], v[186:189], v[124:127]
	v_mfma_f32_16x16x32_bf16 v[120:123], v[162:165], v[186:189], v[120:123]
	v_mfma_f32_16x16x32_bf16 v[108:111], v[154:157], v[194:197], v[108:111]
	v_mfma_f32_16x16x32_bf16 v[104:107], v[162:165], v[194:197], v[104:107]
	v_mfma_f32_16x16x32_bf16 v[92:95], v[154:157], v[202:205], v[92:95]
	v_mfma_f32_16x16x32_bf16 v[88:91], v[162:165], v[202:205], v[88:91]
	v_mfma_f32_16x16x32_bf16 v[76:79], v[154:157], v[210:213], v[76:79]
	v_mfma_f32_16x16x32_bf16 v[72:75], v[162:165], v[210:213], v[72:75]
	v_mfma_f32_16x16x32_bf16 v[124:127], v[158:161], v[190:193], v[124:127]
	v_mfma_f32_16x16x32_bf16 v[120:123], v[166:169], v[190:193], v[120:123]
	v_mfma_f32_16x16x32_bf16 v[108:111], v[158:161], v[198:201], v[108:111]
	v_mfma_f32_16x16x32_bf16 v[104:107], v[166:169], v[198:201], v[104:107]
	v_mfma_f32_16x16x32_bf16 v[92:95], v[158:161], v[206:209], v[92:95]
	v_mfma_f32_16x16x32_bf16 v[88:91], v[166:169], v[206:209], v[88:91]
	v_mfma_f32_16x16x32_bf16 v[76:79], v[158:161], v[214:217], v[76:79]
	v_mfma_f32_16x16x32_bf16 v[72:75], v[166:169], v[214:217], v[72:75]
	v_mfma_f32_16x16x32_bf16 v[116:119], v[170:173], v[186:189], v[116:119]
	v_mfma_f32_16x16x32_bf16 v[112:115], v[178:181], v[186:189], v[112:115]
	v_mfma_f32_16x16x32_bf16 v[100:103], v[170:173], v[194:197], v[100:103]
	v_mfma_f32_16x16x32_bf16 v[96:99], v[178:181], v[194:197], v[96:99]
	v_mfma_f32_16x16x32_bf16 v[84:87], v[170:173], v[202:205], v[84:87]
	v_mfma_f32_16x16x32_bf16 v[80:83], v[178:181], v[202:205], v[80:83]
	v_mfma_f32_16x16x32_bf16 v[68:71], v[170:173], v[210:213], v[68:71]
	v_mfma_f32_16x16x32_bf16 v[64:67], v[178:181], v[210:213], v[64:67]
	v_mfma_f32_16x16x32_bf16 v[116:119], v[174:177], v[190:193], v[116:119]
	v_mfma_f32_16x16x32_bf16 v[112:115], v[182:185], v[190:193], v[112:115]
	v_mfma_f32_16x16x32_bf16 v[100:103], v[174:177], v[198:201], v[100:103]
	v_mfma_f32_16x16x32_bf16 v[96:99], v[182:185], v[198:201], v[96:99]
	v_mfma_f32_16x16x32_bf16 v[84:87], v[174:177], v[206:209], v[84:87]
	v_mfma_f32_16x16x32_bf16 v[80:83], v[182:185], v[206:209], v[80:83]
	v_mfma_f32_16x16x32_bf16 v[68:71], v[174:177], v[214:217], v[68:71]
	v_mfma_f32_16x16x32_bf16 v[64:67], v[182:185], v[214:217], v[64:67]
	s_barrier
	s_setprio 0
	s_mov_b32 m0, s90
	v_lshl_add_u64 v[140:141], s[80:81], 0, v[128:129]
	s_add_u32 s44, s80, 0x20000
	ds_read_b128 v[186:189], v151 offset:16384
	ds_read_b128 v[190:193], v151 offset:17408
	ds_read_b128 v[194:197], v151 offset:18432
	ds_read_b128 v[198:201], v151 offset:19456
	ds_read_b128 v[202:205], v151 offset:20480
	ds_read_b128 v[206:209], v151 offset:21504
	ds_read_b128 v[210:213], v151 offset:22528
	ds_read_b128 v[214:217], v151 offset:23552
	global_load_lds_dwordx4 v128, s[80:81]
	v_lshl_add_u64 v[142:143], s[80:81], 0, v[130:131]
	s_mov_b32 m0, s91
	s_addc_u32 s45, s81, 0
	global_load_lds_dwordx4 v130, s[80:81]
	v_lshl_add_u64 v[146:147], s[44:45], 0, v[128:129]
	s_mov_b32 m0, s93
	v_lshl_add_u64 v[218:219], s[82:83], 0, v[132:133]
	global_load_lds_dwordx4 v128, s[44:45]
	v_lshl_add_u64 v[146:147], s[44:45], 0, v[130:131]
	s_mov_b32 m0, s95
	s_nop 0
	global_load_lds_dwordx4 v130, s[44:45]
	v_lshl_add_u64 v[146:147], s[82:83], 0, v[134:135]
	s_mov_b32 m0, s38
	s_nop 0
	global_load_lds_dwordx4 v134, s[82:83]
	s_mov_b32 m0, s39
	s_nop 0
	global_load_lds_dwordx4 v132, s[82:83]
	s_waitcnt vmcnt(8) lgkmcnt(0)
	s_setprio 1
	s_barrier
	v_mfma_f32_16x16x32_bf16 v[60:63], v[154:157], v[186:189], v[60:63]
	v_mfma_f32_16x16x32_bf16 v[56:59], v[162:165], v[186:189], v[56:59]
	v_mfma_f32_16x16x32_bf16 v[44:47], v[154:157], v[194:197], v[44:47]
	v_mfma_f32_16x16x32_bf16 v[40:43], v[162:165], v[194:197], v[40:43]
	v_mfma_f32_16x16x32_bf16 v[28:31], v[154:157], v[202:205], v[28:31]
	v_mfma_f32_16x16x32_bf16 v[24:27], v[162:165], v[202:205], v[24:27]
	v_mfma_f32_16x16x32_bf16 v[12:15], v[154:157], v[210:213], v[12:15]
	v_mfma_f32_16x16x32_bf16 v[8:11], v[162:165], v[210:213], v[8:11]
	v_mfma_f32_16x16x32_bf16 v[60:63], v[158:161], v[190:193], v[60:63]
	v_mfma_f32_16x16x32_bf16 v[56:59], v[166:169], v[190:193], v[56:59]
	v_mfma_f32_16x16x32_bf16 v[44:47], v[158:161], v[198:201], v[44:47]
	v_mfma_f32_16x16x32_bf16 v[40:43], v[166:169], v[198:201], v[40:43]
	v_mfma_f32_16x16x32_bf16 v[28:31], v[158:161], v[206:209], v[28:31]
	v_mfma_f32_16x16x32_bf16 v[24:27], v[166:169], v[206:209], v[24:27]
	v_mfma_f32_16x16x32_bf16 v[12:15], v[158:161], v[214:217], v[12:15]
	v_mfma_f32_16x16x32_bf16 v[8:11], v[166:169], v[214:217], v[8:11]
	v_mfma_f32_16x16x32_bf16 v[52:55], v[170:173], v[186:189], v[52:55]
	v_mfma_f32_16x16x32_bf16 v[48:51], v[178:181], v[186:189], v[48:51]
	v_mfma_f32_16x16x32_bf16 v[36:39], v[170:173], v[194:197], v[36:39]
	v_mfma_f32_16x16x32_bf16 v[32:35], v[178:181], v[194:197], v[32:35]
	v_mfma_f32_16x16x32_bf16 v[20:23], v[170:173], v[202:205], v[20:23]
	v_mfma_f32_16x16x32_bf16 v[16:19], v[178:181], v[202:205], v[16:19]
	v_mfma_f32_16x16x32_bf16 v[4:7], v[170:173], v[210:213], v[4:7]
	v_mfma_f32_16x16x32_bf16 v[0:3], v[178:181], v[210:213], v[0:3]
	v_mfma_f32_16x16x32_bf16 v[52:55], v[174:177], v[190:193], v[52:55]
	v_mfma_f32_16x16x32_bf16 v[48:51], v[182:185], v[190:193], v[48:51]
	v_mfma_f32_16x16x32_bf16 v[36:39], v[174:177], v[198:201], v[36:39]
	v_mfma_f32_16x16x32_bf16 v[32:35], v[182:185], v[198:201], v[32:35]
	v_mfma_f32_16x16x32_bf16 v[20:23], v[174:177], v[206:209], v[20:23]
	v_mfma_f32_16x16x32_bf16 v[16:19], v[182:185], v[206:209], v[16:19]
	v_mfma_f32_16x16x32_bf16 v[4:7], v[174:177], v[214:217], v[4:7]
	v_mfma_f32_16x16x32_bf16 v[0:3], v[182:185], v[214:217], v[0:3]
	s_barrier
	s_setprio 0
	ds_read_b128 v[154:157], v144
	ds_read_b128 v[158:161], v144 offset:1024
	ds_read_b128 v[162:165], v144 offset:2048
	ds_read_b128 v[166:169], v144 offset:3072
	ds_read_b128 v[170:173], v145
	ds_read_b128 v[174:177], v145 offset:1024
	ds_read_b128 v[178:181], v145 offset:2048
	ds_read_b128 v[182:185], v145 offset:3072
	s_add_u32 s44, s82, 0x20000
	s_addc_u32 s45, s83, 0
	s_mov_b32 m0, s40
	v_lshl_add_u64 v[220:221], s[44:45], 0, v[134:135]
	ds_read_b128 v[186:189], v151 offset:32768
	ds_read_b128 v[190:193], v151 offset:33792
	ds_read_b128 v[194:197], v151 offset:34816
	ds_read_b128 v[198:201], v151 offset:35840
	ds_read_b128 v[202:205], v151 offset:36864
	ds_read_b128 v[206:209], v151 offset:37888
	ds_read_b128 v[210:213], v151 offset:38912
	ds_read_b128 v[214:217], v151 offset:39936
	global_load_lds_dwordx4 v134, s[44:45]
	v_lshl_add_u64 v[220:221], s[44:45], 0, v[132:133]
	s_mov_b32 m0, s41
	s_nop 0
	global_load_lds_dwordx4 v132, s[44:45]
	s_waitcnt vmcnt(8) lgkmcnt(0)
	s_setprio 1
	s_barrier
	v_mfma_f32_16x16x32_bf16 v[124:127], v[154:157], v[186:189], v[124:127]
	v_mfma_f32_16x16x32_bf16 v[120:123], v[162:165], v[186:189], v[120:123]
	v_mfma_f32_16x16x32_bf16 v[108:111], v[154:157], v[194:197], v[108:111]
	v_mfma_f32_16x16x32_bf16 v[104:107], v[162:165], v[194:197], v[104:107]
	v_mfma_f32_16x16x32_bf16 v[92:95], v[154:157], v[202:205], v[92:95]
	v_mfma_f32_16x16x32_bf16 v[88:91], v[162:165], v[202:205], v[88:91]
	v_mfma_f32_16x16x32_bf16 v[76:79], v[154:157], v[210:213], v[76:79]
	v_mfma_f32_16x16x32_bf16 v[72:75], v[162:165], v[210:213], v[72:75]
	v_mfma_f32_16x16x32_bf16 v[124:127], v[158:161], v[190:193], v[124:127]
	v_mfma_f32_16x16x32_bf16 v[120:123], v[166:169], v[190:193], v[120:123]
	v_mfma_f32_16x16x32_bf16 v[108:111], v[158:161], v[198:201], v[108:111]
	v_mfma_f32_16x16x32_bf16 v[104:107], v[166:169], v[198:201], v[104:107]
	v_mfma_f32_16x16x32_bf16 v[92:95], v[158:161], v[206:209], v[92:95]
	v_mfma_f32_16x16x32_bf16 v[88:91], v[166:169], v[206:209], v[88:91]
	v_mfma_f32_16x16x32_bf16 v[76:79], v[158:161], v[214:217], v[76:79]
	v_mfma_f32_16x16x32_bf16 v[72:75], v[166:169], v[214:217], v[72:75]
	v_mfma_f32_16x16x32_bf16 v[116:119], v[170:173], v[186:189], v[116:119]
	v_mfma_f32_16x16x32_bf16 v[112:115], v[178:181], v[186:189], v[112:115]
	v_mfma_f32_16x16x32_bf16 v[100:103], v[170:173], v[194:197], v[100:103]
	v_mfma_f32_16x16x32_bf16 v[96:99], v[178:181], v[194:197], v[96:99]
	v_mfma_f32_16x16x32_bf16 v[84:87], v[170:173], v[202:205], v[84:87]
	v_mfma_f32_16x16x32_bf16 v[80:83], v[178:181], v[202:205], v[80:83]
	v_mfma_f32_16x16x32_bf16 v[68:71], v[170:173], v[210:213], v[68:71]
	v_mfma_f32_16x16x32_bf16 v[64:67], v[178:181], v[210:213], v[64:67]
	v_mfma_f32_16x16x32_bf16 v[116:119], v[174:177], v[190:193], v[116:119]
	v_mfma_f32_16x16x32_bf16 v[112:115], v[182:185], v[190:193], v[112:115]
	v_mfma_f32_16x16x32_bf16 v[100:103], v[174:177], v[198:201], v[100:103]
	v_mfma_f32_16x16x32_bf16 v[96:99], v[182:185], v[198:201], v[96:99]
	v_mfma_f32_16x16x32_bf16 v[84:87], v[174:177], v[206:209], v[84:87]
	v_mfma_f32_16x16x32_bf16 v[80:83], v[182:185], v[206:209], v[80:83]
	v_mfma_f32_16x16x32_bf16 v[68:71], v[174:177], v[214:217], v[68:71]
	v_mfma_f32_16x16x32_bf16 v[64:67], v[182:185], v[214:217], v[64:67]
	s_barrier
; #define PG8_STAGE(bufoff, gbase, voff) do { _Pragma("unroll") for (int _i = 0; _i < 2; ++_i) \
;         __builtin_amdgcn_global_load_lds((const unsigned*)((const char*)(gbase) + (voff)[_i]), (PG8_LAS unsigned*)(lds + (bufoff) + ldsw + _i * 8192), 16, 0, 0); } while (0)
; #define PG8_BAR __builtin_amdgcn_s_barrier()
; template <class Epi, class Sched, bool ALIGN_EPI = false, bool SP2 = false, bool A_TILED = false>
; __device__ __forceinline__ void gemm_phase(PG8_LAS unsigned char* lds, const Gemm g, const Sched& S, const Epi& E, const int wave_s) {
;     ...
;         for (int t = PEEL ? 2 : 0; t < nt; t += 2) {
;             const bool last = (t == nt - 2);
;             const char* a1 = cA + (size_t)(t + 1) * kstepA;
;             const char* a2 = last ? nA : cA + (size_t)(t + 2) * kstepA; const char* b2 = last ? nB : cB + (size_t)(t + 2) * kstep;
;             const char* a3 = a2 + kstepA; const char* b3 = b2 + kstep;
;             if (last && has_next) S.a_ready(nxt);
;             if constexpr (SP2) {
;             PG8_ITER(PG8_MMA)
;             } else {
;             PG8_LDB(B0, 0, 0); PG8_SCHED; PG8_LDA(At, 0, 0); PG8_STAGE(PG8_SA(1, 1), a1 + hstepA, voffA);
;             PG8_WAIT_L(8); PG8_BAR; PG8_WAIT_L(0); PG8_MMA(0, 0, At, B0); PG8_BAR; PG8_SCHED;
;             PG8_LDB(B1, 0, 1); PG8_STAGE(PG8_SB(0, 0), b2, voffB);
;             PG8_BAR; PG8_WAIT_L(0); PG8_MMA(0, 1, At, B1); PG8_BAR;
;             PG8_LDA(At, 0, 1); PG8_STAGE(PG8_SA(0, 0), a2, voffA);
;             PG8_BAR; PG8_WAIT_L(0); PG8_MMA(1, 0, At, B0); PG8_BAR; PG8_SCHED;
;             PG8_STAGE(PG8_SB(0, 1), b2 + hstep, voffB);
;             PG8_WAIT_V(6); PG8_BAR; PG8_MMA(1, 1, At, B1); PG8_BAR;
;             PG8_LDB(B0, 1, 0); PG8_SCHED; PG8_LDA(At, 1, 0); PG8_STAGE(PG8_SA(0, 1), a2 + hstepA, voffA);
;             PG8_WAIT_L(8); PG8_BAR; PG8_WAIT_L(0); PG8_MMA(0, 0, At, B0); PG8_BAR; PG8_SCHED;
;             PG8_LDB(B1, 1, 1); PG8_STAGE(PG8_SB(1, 0), b3, voffB);
;             PG8_BAR; PG8_WAIT_L(0); PG8_MMA(0, 1, At, B1); PG8_BAR;
;             PG8_LDA(At, 1, 1); PG8_STAGE(PG8_SA(1, 0), a3, voffA);
;             PG8_BAR; PG8_WAIT_L(0); PG8_MMA(1, 0, At, B0); PG8_BAR; PG8_SCHED;
;             PG8_STAGE(PG8_SB(1, 1), b3 + hstep, voffB);
;             PG8_WAIT_V(6); PG8_BAR; PG8_MMA(1, 1, At, B1); PG8_BAR;
;             }
;         }
;         if constexpr (ALIGN_EPI) { if (wr == 0) PG8_BAR; }
	s_setprio 0
	s_mov_b32 m0, s96
	v_lshl_add_u64 v[140:141], v[140:141], 0, s[62:63]
	s_add_u32 s44, s80, 0x20080
	ds_read_b128 v[186:189], v151 offset:49152
	ds_read_b128 v[190:193], v151 offset:50176
	ds_read_b128 v[194:197], v151 offset:51200
	ds_read_b128 v[198:201], v151 offset:52224
	ds_read_b128 v[202:205], v151 offset:53248
	ds_read_b128 v[206:209], v151 offset:54272
	ds_read_b128 v[210:213], v151 offset:55296
	ds_read_b128 v[214:217], v151 offset:56320
	global_load_lds_dwordx4 v[140:141], off
	v_lshl_add_u64 v[140:141], v[142:143], 0, s[62:63]
	s_mov_b32 m0, s97
	s_addc_u32 s45, s81, 0
	global_load_lds_dwordx4 v[140:141], off
	v_lshl_add_u64 v[140:141], s[44:45], 0, v[128:129]
	s_mov_b32 m0, vcc_lo
	s_nop 0
	global_load_lds_dwordx4 v128, s[44:45]
	v_lshl_add_u64 v[140:141], s[44:45], 0, v[130:131]
	s_mov_b32 m0, vcc_hi
	s_nop 0
	global_load_lds_dwordx4 v130, s[44:45]
	v_lshl_add_u64 v[140:141], v[146:147], 0, s[62:63]
	s_mov_b32 m0, s51
	s_nop 0
	global_load_lds_dwordx4 v[140:141], off
	v_lshl_add_u64 v[140:141], v[218:219], 0, s[62:63]
	s_mov_b32 m0, s52
	s_nop 0
	global_load_lds_dwordx4 v[140:141], off
	s_waitcnt vmcnt(8) lgkmcnt(0)
	s_setprio 1
	s_barrier
	v_mfma_f32_16x16x32_bf16 v[60:63], v[154:157], v[186:189], v[60:63]
	v_mfma_f32_16x16x32_bf16 v[56:59], v[162:165], v[186:189], v[56:59]
	v_mfma_f32_16x16x32_bf16 v[44:47], v[154:157], v[194:197], v[44:47]
	v_mfma_f32_16x16x32_bf16 v[40:43], v[162:165], v[194:197], v[40:43]
	v_mfma_f32_16x16x32_bf16 v[28:31], v[154:157], v[202:205], v[28:31]
	v_mfma_f32_16x16x32_bf16 v[24:27], v[162:165], v[202:205], v[24:27]
	v_mfma_f32_16x16x32_bf16 v[12:15], v[154:157], v[210:213], v[12:15]
	v_mfma_f32_16x16x32_bf16 v[8:11], v[162:165], v[210:213], v[8:11]
	v_mfma_f32_16x16x32_bf16 v[60:63], v[158:161], v[190:193], v[60:63]
	v_mfma_f32_16x16x32_bf16 v[56:59], v[166:169], v[190:193], v[56:59]
	v_mfma_f32_16x16x32_bf16 v[44:47], v[158:161], v[198:201], v[44:47]
	v_mfma_f32_16x16x32_bf16 v[40:43], v[166:169], v[198:201], v[40:43]
	v_mfma_f32_16x16x32_bf16 v[28:31], v[158:161], v[206:209], v[28:31]
	v_mfma_f32_16x16x32_bf16 v[24:27], v[166:169], v[206:209], v[24:27]
	v_mfma_f32_16x16x32_bf16 v[12:15], v[158:161], v[214:217], v[12:15]
	v_mfma_f32_16x16x32_bf16 v[8:11], v[166:169], v[214:217], v[8:11]
	v_mfma_f32_16x16x32_bf16 v[52:55], v[170:173], v[186:189], v[52:55]
	v_mfma_f32_16x16x32_bf16 v[48:51], v[178:181], v[186:189], v[48:51]
	v_mfma_f32_16x16x32_bf16 v[36:39], v[170:173], v[194:197], v[36:39]
	v_mfma_f32_16x16x32_bf16 v[32:35], v[178:181], v[194:197], v[32:35]
	v_mfma_f32_16x16x32_bf16 v[20:23], v[170:173], v[202:205], v[20:23]
	v_mfma_f32_16x16x32_bf16 v[16:19], v[178:181], v[202:205], v[16:19]
	v_mfma_f32_16x16x32_bf16 v[4:7], v[170:173], v[210:213], v[4:7]
	v_mfma_f32_16x16x32_bf16 v[0:3], v[178:181], v[210:213], v[0:3]
	v_mfma_f32_16x16x32_bf16 v[52:55], v[174:177], v[190:193], v[52:55]
	v_mfma_f32_16x16x32_bf16 v[48:51], v[182:185], v[190:193], v[48:51]
	v_mfma_f32_16x16x32_bf16 v[36:39], v[174:177], v[198:201], v[36:39]
	v_mfma_f32_16x16x32_bf16 v[32:35], v[182:185], v[198:201], v[32:35]
	v_mfma_f32_16x16x32_bf16 v[20:23], v[174:177], v[206:209], v[20:23]
	v_mfma_f32_16x16x32_bf16 v[16:19], v[182:185], v[206:209], v[16:19]
	v_mfma_f32_16x16x32_bf16 v[4:7], v[174:177], v[214:217], v[4:7]
	v_mfma_f32_16x16x32_bf16 v[0:3], v[182:185], v[214:217], v[0:3]
	s_barrier
	s_setprio 0
	s_add_i32 s94, s94, 2
	s_add_u32 s85, s85, 0x100
	s_addc_u32 s8, s8, 0
	s_add_u32 s78, s78, 0x100
	s_addc_u32 s79, s79, 0
	s_cmp_gt_u32 s94, 5
	s_cbranch_scc0 .LBB0_2546
	s_and_b64 vcc, exec, s[64:65]
	s_cbranch_vccz .LBB0_2549
	s_barrier

; template <class Epi, class Sched, bool ALIGN_EPI = false, bool SP2 = false, bool A_TILED = false>
; __device__ __forceinline__ void gemm_phase(PG8_LAS unsigned char* lds, const Gemm g, const Sched& S, const Epi& E, const int wave_s) {
;     ...
;         if constexpr (PEEL) {
;             const char* a1 = cA + kstepA; const char* a2 = cA + 2 * kstepA; const char* b2 = cB + 2 * kstep; const char* a3 = a2 + kstepA; const char* b3 = b2 + kstep;
;             PG8_ITER(PG8_MMAZ)
.Lpw_13:
	s_setprio 1
	s_barrier
	v_mfma_f32_16x16x32_bf16 v[88:91], v[0:3], v[56:59], 0
	v_mfma_f32_16x16x32_bf16 v[64:67], v[0:3], v[32:35], 0
	v_mfma_f32_16x16x32_bf16 v[68:71], v[8:11], v[32:35], 0
	v_mfma_f32_16x16x32_bf16 v[72:75], v[0:3], v[40:43], 0
	v_mfma_f32_16x16x32_bf16 v[76:79], v[8:11], v[40:43], 0
	v_mfma_f32_16x16x32_bf16 v[80:83], v[0:3], v[48:51], 0
	v_mfma_f32_16x16x32_bf16 v[84:87], v[8:11], v[48:51], 0
	v_mfma_f32_16x16x32_bf16 v[92:95], v[4:7], v[60:63], v[88:91]
	v_mfma_f32_16x16x32_bf16 v[88:91], v[8:11], v[56:59], 0
	v_mfma_f32_16x16x32_bf16 v[64:67], v[4:7], v[36:39], v[64:67]
	v_mfma_f32_16x16x32_bf16 v[68:71], v[12:15], v[36:39], v[68:71]
	v_mfma_f32_16x16x32_bf16 v[72:75], v[4:7], v[44:47], v[72:75]
	v_mfma_f32_16x16x32_bf16 v[76:79], v[12:15], v[44:47], v[76:79]
	v_mfma_f32_16x16x32_bf16 v[80:83], v[4:7], v[52:55], v[80:83]
	v_mfma_f32_16x16x32_bf16 v[84:87], v[12:15], v[52:55], v[84:87]
	v_mfma_f32_16x16x32_bf16 v[100:103], v[12:15], v[60:63], v[88:91]
	v_mfma_f32_16x16x32_bf16 v[88:91], v[16:19], v[32:35], 0
	v_mfma_f32_16x16x32_bf16 v[32:35], v[24:27], v[32:35], 0
	v_mfma_f32_16x16x32_bf16 v[108:111], v[20:23], v[36:39], v[88:91]
	v_mfma_f32_16x16x32_bf16 v[32:35], v[28:31], v[36:39], v[32:35]
	v_mfma_f32_16x16x32_bf16 v[36:39], v[16:19], v[40:43], 0
	v_mfma_f32_16x16x32_bf16 v[40:43], v[24:27], v[40:43], 0
	v_mfma_f32_16x16x32_bf16 v[36:39], v[20:23], v[44:47], v[36:39]
	v_mfma_f32_16x16x32_bf16 v[40:43], v[28:31], v[44:47], v[40:43]
	v_mfma_f32_16x16x32_bf16 v[44:47], v[16:19], v[48:51], 0
	v_mfma_f32_16x16x32_bf16 v[48:51], v[24:27], v[48:51], 0
	v_mfma_f32_16x16x32_bf16 v[44:47], v[20:23], v[52:55], v[44:47]
	v_mfma_f32_16x16x32_bf16 v[52:55], v[28:31], v[52:55], v[48:51]
	v_mfma_f32_16x16x32_bf16 v[48:51], v[16:19], v[56:59], 0
	v_mfma_f32_16x16x32_bf16 v[150:153], v[20:23], v[60:63], v[48:51]
	v_mfma_f32_16x16x32_bf16 v[48:51], v[24:27], v[56:59], 0
	v_mfma_f32_16x16x32_bf16 v[154:157], v[28:31], v[60:63], v[48:51]
	s_barrier
	s_setprio 0
	s_add_i32 s57, s48, s36
	v_lshl_add_u64 v[250:251], s[74:75], 0, v[128:129]
	s_add_i32 s58, s57, 0x2000
	v_lshl_add_u64 v[120:121], v[250:251], 0, s[60:61]
	s_mov_b32 m0, s57
	v_lshl_add_u64 v[252:253], s[74:75], 0, v[130:131]
	s_add_u32 s78, s74, 0x20100
	ds_read_b128 v[48:51], v149 offset:16384
	ds_read_b128 v[56:59], v149 offset:17408
	ds_read_b128 v[60:63], v149 offset:18432
	ds_read_b128 v[88:91], v149 offset:19456
	ds_read_b128 v[96:99], v149 offset:20480
	ds_read_b128 v[104:107], v149 offset:21504
	ds_read_b128 v[112:115], v149 offset:22528
	ds_read_b128 v[116:119], v149 offset:23552
	global_load_lds_dwordx4 v[120:121], off
	v_lshl_add_u64 v[120:121], v[252:253], 0, s[60:61]
	s_mov_b32 m0, s58
	s_addc_u32 s79, s75, 0
	s_add_i32 s59, s49, s36
	global_load_lds_dwordx4 v[120:121], off
	v_lshl_add_u64 v[120:121], s[78:79], 0, v[128:129]
	s_mov_b32 m0, s59
	s_add_i32 s65, s59, 0x2000
	global_load_lds_dwordx4 v128, s[78:79]
	v_lshl_add_u64 v[120:121], s[78:79], 0, v[130:131]
	s_mov_b32 m0, s65
	v_lshl_add_u64 v[140:141], s[76:77], 0, v[134:135]
	global_load_lds_dwordx4 v130, s[78:79]
	v_lshl_add_u64 v[120:121], v[140:141], 0, s[60:61]
	s_mov_b32 m0, s0
	v_lshl_add_u64 v[142:143], s[76:77], 0, v[132:133]
	global_load_lds_dwordx4 v[120:121], off
	v_lshl_add_u64 v[120:121], v[142:143], 0, s[60:61]
	s_mov_b32 m0, s1
	s_nop 0
	global_load_lds_dwordx4 v[120:121], off
	s_waitcnt vmcnt(24) lgkmcnt(0)
	s_cmp_lg_u32 s98, 0
	s_cbranch_scc1 .Lpw_14
	s_waitcnt vmcnt(8)
.Lpw_14:
	s_setprio 1
	s_barrier
	v_mfma_f32_16x16x32_bf16 v[120:123], v[0:3], v[48:51], 0
	v_mfma_f32_16x16x32_bf16 v[158:161], v[4:7], v[56:59], v[120:123]
	v_mfma_f32_16x16x32_bf16 v[120:123], v[8:11], v[48:51], 0
	v_mfma_f32_16x16x32_bf16 v[162:165], v[12:15], v[56:59], v[120:123]
	v_mfma_f32_16x16x32_bf16 v[120:123], v[0:3], v[60:63], 0
	v_mfma_f32_16x16x32_bf16 v[166:169], v[4:7], v[88:91], v[120:123]
	v_mfma_f32_16x16x32_bf16 v[120:123], v[8:11], v[60:63], 0
	v_mfma_f32_16x16x32_bf16 v[170:173], v[12:15], v[88:91], v[120:123]
	v_mfma_f32_16x16x32_bf16 v[120:123], v[0:3], v[96:99], 0
	v_mfma_f32_16x16x32_bf16 v[0:3], v[0:3], v[112:115], 0
	v_mfma_f32_16x16x32_bf16 v[174:177], v[4:7], v[104:107], v[120:123]
	v_mfma_f32_16x16x32_bf16 v[0:3], v[4:7], v[116:119], v[0:3]
	v_mfma_f32_16x16x32_bf16 v[4:7], v[8:11], v[112:115], 0
	v_mfma_f32_16x16x32_bf16 v[120:123], v[8:11], v[96:99], 0
	v_mfma_f32_16x16x32_bf16 v[4:7], v[12:15], v[116:119], v[4:7]
	v_mfma_f32_16x16x32_bf16 v[178:181], v[12:15], v[104:107], v[120:123]
	v_mfma_f32_16x16x32_bf16 v[8:11], v[16:19], v[48:51], 0
	v_mfma_f32_16x16x32_bf16 v[182:185], v[20:23], v[56:59], v[8:11]
	v_mfma_f32_16x16x32_bf16 v[8:11], v[24:27], v[48:51], 0
	v_mfma_f32_16x16x32_bf16 v[186:189], v[28:31], v[56:59], v[8:11]
	v_mfma_f32_16x16x32_bf16 v[8:11], v[16:19], v[60:63], 0
	v_mfma_f32_16x16x32_bf16 v[190:193], v[20:23], v[88:91], v[8:11]
	v_mfma_f32_16x16x32_bf16 v[8:11], v[24:27], v[60:63], 0
	v_mfma_f32_16x16x32_bf16 v[194:197], v[28:31], v[88:91], v[8:11]
	v_mfma_f32_16x16x32_bf16 v[8:11], v[16:19], v[96:99], 0
	v_mfma_f32_16x16x32_bf16 v[198:201], v[20:23], v[104:107], v[8:11]
	v_mfma_f32_16x16x32_bf16 v[8:11], v[24:27], v[96:99], 0
	v_mfma_f32_16x16x32_bf16 v[202:205], v[28:31], v[104:107], v[8:11]
	v_mfma_f32_16x16x32_bf16 v[8:11], v[16:19], v[112:115], 0
	v_mfma_f32_16x16x32_bf16 v[206:209], v[20:23], v[116:119], v[8:11]
	v_mfma_f32_16x16x32_bf16 v[8:11], v[24:27], v[112:115], 0
	v_mfma_f32_16x16x32_bf16 v[210:213], v[28:31], v[116:119], v[8:11]
	s_barrier
; template <class Epi, class Sched, bool ALIGN_EPI = false, bool SP2 = false, bool A_TILED = false>
; __device__ __forceinline__ void gemm_phase(PG8_LAS unsigned char* lds, const Gemm g, const Sched& S, const Epi& E, const int wave_s) {
;     ...
;     Unit cur, nxt; int ui = 0;
;     if (!S.next(0, cur)) return;
;     f32x4 acc[2][2][4][2];
;     bf16x8 At[4][2], B0[2][2], B1[2][2];
;     const char* cA = (const char*)g.A + (size_t)cur.pm * tstepA; const char* cB = (const char*)g.Bt + (size_t)cur.pn * tstep;
;     S.a_ready(cur);
;     if constexpr (SP2) {
;         PG8_STAGE(PG8_SB(0, 0), cB, voffB); PG8_STAGE(PG8_SB(0, 1), cB + hstep, voffB); PG8_STAGE(PG8_SA(0, 0), cA, voffA); PG8_STAGE(PG8_SA(0, 1), cA + hstepA, voffA);
;         if (wr == 1) PG8_BAR;
;         PG8_WAIT_V(2); PG8_BAR;
;         PG8_STAGE(PG8_SB(1, 0), cB + kstep, voffB); PG8_STAGE(PG8_SA(1, 0), cA + kstepA, voffA); PG8_STAGE(PG8_SB(1, 1), cB + hstep + kstep, voffB);
;         PG8_WAIT_V(6); PG8_BAR;
;     } else {
;         PG8_STAGE(PG8_SB(0, 0), cB, voffB); PG8_STAGE(PG8_SA(0, 0), cA, voffA); PG8_STAGE(PG8_SB(0, 1), cB + hstep, voffB); PG8_STAGE(PG8_SA(0, 1), cA + hstepA, voffA);
;         if (wr == 1) PG8_BAR;
;         PG8_WAIT_V(4); PG8_BAR;
;         PG8_STAGE(PG8_SB(1, 0), cB + kstep, voffB); PG8_STAGE(PG8_SA(1, 0), cA + kstepA, voffA); PG8_STAGE(PG8_SB(1, 1), cB + hstep + kstep, voffB);
;         PG8_WAIT_V(6); PG8_BAR;
;     }
;     for (;;) {
;         const bool has_next = Epi::AFTER_DRAIN ? false : S.next(ui + 1, nxt);
;         const char* nA = has_next ? (const char*)g.A + (size_t)nxt.pm * tstepA : cA; const char* nB = has_next ? (const char*)g.Bt + (size_t)nxt.pn * tstep : cB;
;         constexpr bool PEEL = SP2 && !Epi::AFTER_DRAIN;
;         if constexpr (PEEL) {
;             const char* a1 = cA + kstepA; const char* a2 = cA + 2 * kstepA; const char* b2 = cB + 2 * kstep; const char* a3 = a2 + kstepA; const char* b3 = b2 + kstep;
;             PG8_ITER(PG8_MMAZ)
;         } else {
; #pragma unroll
;             for (int a = 0; a < 2; ++a)
; #pragma unroll
;                 for (int b = 0; b < 2; ++b)
; #pragma unroll
;                     for (int m = 0; m < 4; ++m)
; #pragma unroll
;                         for (int n = 0; n < 2; ++n) acc[a][b][m][n] = (f32x4){0.f, 0.f, 0.f, 0.f};
;         }
; #pragma nounroll
;         for (int t = PEEL ? 2 : 0; t < nt; t += 2) {
	s_setprio 0
	s_add_i32 s67, 0, 0x18000
	s_add_i32 s80, 0, 0x1c000
	v_add_u32_e32 v144, s67, v146
	v_add_u32_e32 v145, s80, v146
	s_nop 0
	ds_read_b128 v[8:11], v144
	ds_read_b128 v[12:15], v144 offset:1024
	ds_read_b128 v[16:19], v144 offset:2048
	ds_read_b128 v[20:23], v144 offset:3072
	ds_read_b128 v[214:217], v145
	ds_read_b128 v[218:221], v145 offset:1024
	ds_read_b128 v[222:225], v145 offset:2048
	ds_read_b128 v[226:229], v145 offset:3072
	s_add_u32 s78, s76, 0x20100
	s_addc_u32 s79, s77, 0
	s_mov_b32 m0, s37
	v_lshl_add_u64 v[48:49], s[78:79], 0, v[134:135]
	ds_read_b128 v[24:27], v149 offset:32768
	ds_read_b128 v[28:31], v149 offset:33792
	ds_read_b128 v[60:63], v149 offset:34816
	ds_read_b128 v[230:233], v149 offset:35840
	ds_read_b128 v[234:237], v149 offset:36864
	ds_read_b128 v[238:241], v149 offset:37888
	ds_read_b128 v[242:245], v149 offset:38912
	ds_read_b128 v[246:249], v149 offset:39936
	global_load_lds_dwordx4 v134, s[78:79]
	v_lshl_add_u64 v[48:49], s[78:79], 0, v[132:133]
	s_mov_b32 m0, s38
	s_nop 0
	global_load_lds_dwordx4 v132, s[78:79]
	s_waitcnt vmcnt(8) lgkmcnt(0)
	s_setprio 1
	s_barrier
	v_mfma_f32_16x16x32_bf16 v[48:51], v[8:11], v[24:27], v[64:67]
	v_mfma_f32_16x16x32_bf16 v[120:123], v[12:15], v[28:31], v[48:51]
	v_mfma_f32_16x16x32_bf16 v[48:51], v[16:19], v[24:27], v[68:71]
	v_mfma_f32_16x16x32_bf16 v[112:115], v[20:23], v[28:31], v[48:51]
	v_mfma_f32_16x16x32_bf16 v[48:51], v[8:11], v[60:63], v[72:75]
	v_mfma_f32_16x16x32_bf16 v[104:107], v[12:15], v[230:233], v[48:51]
	v_mfma_f32_16x16x32_bf16 v[48:51], v[16:19], v[60:63], v[76:79]
	v_mfma_f32_16x16x32_bf16 v[96:99], v[20:23], v[230:233], v[48:51]
	v_mfma_f32_16x16x32_bf16 v[48:51], v[8:11], v[234:237], v[80:83]
	v_mfma_f32_16x16x32_bf16 v[88:91], v[12:15], v[238:241], v[48:51]
	v_mfma_f32_16x16x32_bf16 v[48:51], v[16:19], v[234:237], v[84:87]
	v_mfma_f32_16x16x32_bf16 v[80:83], v[20:23], v[238:241], v[48:51]
	v_mfma_f32_16x16x32_bf16 v[48:51], v[8:11], v[242:245], v[92:95]
	v_mfma_f32_16x16x32_bf16 v[56:59], v[12:15], v[246:249], v[48:51]
	v_mfma_f32_16x16x32_bf16 v[48:51], v[16:19], v[242:245], v[100:103]
	v_mfma_f32_16x16x32_bf16 v[48:51], v[20:23], v[246:249], v[48:51]
	v_mfma_f32_16x16x32_bf16 v[64:67], v[214:217], v[24:27], v[108:111]
	v_mfma_f32_16x16x32_bf16 v[24:27], v[222:225], v[24:27], v[32:35]
	v_mfma_f32_16x16x32_bf16 v[116:119], v[226:229], v[28:31], v[24:27]
	v_mfma_f32_16x16x32_bf16 v[24:27], v[214:217], v[60:63], v[36:39]
	v_mfma_f32_16x16x32_bf16 v[108:111], v[218:221], v[230:233], v[24:27]
	v_mfma_f32_16x16x32_bf16 v[24:27], v[222:225], v[60:63], v[40:43]
	v_mfma_f32_16x16x32_bf16 v[100:103], v[226:229], v[230:233], v[24:27]
	v_mfma_f32_16x16x32_bf16 v[24:27], v[214:217], v[234:237], v[44:47]
	v_mfma_f32_16x16x32_bf16 v[92:95], v[218:221], v[238:241], v[24:27]
	v_mfma_f32_16x16x32_bf16 v[24:27], v[222:225], v[234:237], v[52:55]
	v_mfma_f32_16x16x32_bf16 v[84:87], v[226:229], v[238:241], v[24:27]
	v_mfma_f32_16x16x32_bf16 v[24:27], v[214:217], v[242:245], v[150:153]
	v_mfma_f32_16x16x32_bf16 v[60:63], v[218:221], v[246:249], v[24:27]
	v_mfma_f32_16x16x32_bf16 v[24:27], v[222:225], v[242:245], v[154:157]
	v_mfma_f32_16x16x32_bf16 v[124:127], v[218:221], v[28:31], v[64:67]
	v_mfma_f32_16x16x32_bf16 v[52:55], v[226:229], v[246:249], v[24:27]
	s_barrier
	s_setprio 0
	s_add_i32 s67, s67, s36
	s_add_i32 s71, s67, 0x2000
	s_nop 1
	v_lshl_add_u64 v[24:25], v[250:251], 0, s[62:63]
	s_mov_b32 m0, s67
	s_add_u32 s78, s74, 0x20180
	ds_read_b128 v[32:35], v149 offset:49152
	ds_read_b128 v[36:39], v149 offset:50176
	ds_read_b128 v[150:153], v149 offset:51200
	ds_read_b128 v[154:157], v149 offset:52224
	ds_read_b128 v[230:233], v149 offset:53248
	ds_read_b128 v[234:237], v149 offset:54272
	ds_read_b128 v[238:241], v149 offset:55296
	ds_read_b128 v[242:245], v149 offset:56320
	global_load_lds_dwordx4 v[24:25], off
	v_lshl_add_u64 v[24:25], v[252:253], 0, s[62:63]
	s_mov_b32 m0, s71
	s_addc_u32 s79, s75, 0
	s_add_i32 s80, s80, s36
	global_load_lds_dwordx4 v[24:25], off
	v_lshl_add_u64 v[24:25], s[78:79], 0, v[128:129]
	s_mov_b32 m0, s80
	s_add_i32 s81, s80, 0x2000
	global_load_lds_dwordx4 v128, s[78:79]
	v_lshl_add_u64 v[24:25], s[78:79], 0, v[130:131]
	s_mov_b32 m0, s81
	s_nop 0
	global_load_lds_dwordx4 v130, s[78:79]
	v_lshl_add_u64 v[24:25], v[140:141], 0, s[62:63]
	s_mov_b32 m0, s42
	s_nop 0
	global_load_lds_dwordx4 v[24:25], off
	v_lshl_add_u64 v[24:25], v[142:143], 0, s[62:63]
	s_mov_b32 m0, s43
	s_nop 0
	global_load_lds_dwordx4 v[24:25], off
	s_waitcnt vmcnt(8) lgkmcnt(0)
	s_setprio 1
	s_barrier
	v_mfma_f32_16x16x32_bf16 v[24:27], v[8:11], v[32:35], v[158:161]
	v_mfma_f32_16x16x32_bf16 v[76:79], v[12:15], v[36:39], v[24:27]
	v_mfma_f32_16x16x32_bf16 v[24:27], v[16:19], v[32:35], v[162:165]
	v_mfma_f32_16x16x32_bf16 v[72:75], v[20:23], v[36:39], v[24:27]
	v_mfma_f32_16x16x32_bf16 v[24:27], v[8:11], v[150:153], v[166:169]
	v_mfma_f32_16x16x32_bf16 v[44:47], v[12:15], v[154:157], v[24:27]
	v_mfma_f32_16x16x32_bf16 v[24:27], v[16:19], v[150:153], v[170:173]
	v_mfma_f32_16x16x32_bf16 v[40:43], v[20:23], v[154:157], v[24:27]
	v_mfma_f32_16x16x32_bf16 v[24:27], v[8:11], v[230:233], v[174:177]
	v_mfma_f32_16x16x32_bf16 v[0:3], v[8:11], v[238:241], v[0:3]
	v_mfma_f32_16x16x32_bf16 v[28:31], v[12:15], v[234:237], v[24:27]
	v_mfma_f32_16x16x32_bf16 v[24:27], v[16:19], v[230:233], v[178:181]
	v_mfma_f32_16x16x32_bf16 v[12:15], v[12:15], v[242:245], v[0:3]
	v_mfma_f32_16x16x32_bf16 v[0:3], v[16:19], v[238:241], v[4:7]
	v_mfma_f32_16x16x32_bf16 v[24:27], v[20:23], v[234:237], v[24:27]
	v_mfma_f32_16x16x32_bf16 v[8:11], v[20:23], v[242:245], v[0:3]
	v_mfma_f32_16x16x32_bf16 v[0:3], v[214:217], v[32:35], v[182:185]
	v_mfma_f32_16x16x32_bf16 v[68:71], v[218:221], v[36:39], v[0:3]
	v_mfma_f32_16x16x32_bf16 v[0:3], v[222:225], v[32:35], v[186:189]
	v_mfma_f32_16x16x32_bf16 v[64:67], v[226:229], v[36:39], v[0:3]
	v_mfma_f32_16x16x32_bf16 v[0:3], v[214:217], v[150:153], v[190:193]
	v_mfma_f32_16x16x32_bf16 v[36:39], v[218:221], v[154:157], v[0:3]
	v_mfma_f32_16x16x32_bf16 v[0:3], v[222:225], v[150:153], v[194:197]
	v_mfma_f32_16x16x32_bf16 v[32:35], v[226:229], v[154:157], v[0:3]
	v_mfma_f32_16x16x32_bf16 v[0:3], v[214:217], v[230:233], v[198:201]
	v_mfma_f32_16x16x32_bf16 v[20:23], v[218:221], v[234:237], v[0:3]
	v_mfma_f32_16x16x32_bf16 v[0:3], v[222:225], v[230:233], v[202:205]
	v_mfma_f32_16x16x32_bf16 v[16:19], v[226:229], v[234:237], v[0:3]
	v_mfma_f32_16x16x32_bf16 v[0:3], v[214:217], v[238:241], v[206:209]
	v_mfma_f32_16x16x32_bf16 v[4:7], v[218:221], v[242:245], v[0:3]
	v_mfma_f32_16x16x32_bf16 v[0:3], v[222:225], v[238:241], v[210:213]
	v_mfma_f32_16x16x32_bf16 v[0:3], v[226:229], v[242:245], v[0:3]
	s_barrier
	s_setprio 0
	s_add_u32 s82, s74, 0x200
	s_addc_u32 s83, s75, 0
	s_add_u32 s74, s76, 0x20180
	s_addc_u32 s75, s77, 0
	s_mov_b32 s85, 0
; #define PG8_MMA(ai, bj, At, Bt) do { __builtin_amdgcn_s_setprio(1); _Pragma("unroll") for (int m = 0; m < 4; ++m) _Pragma("unroll") for (int n = 0; n < 2; ++n) _Pragma("unroll") for (int k = 0; k < 2; ++k) \
;         acc[ai][bj][m][n] = __builtin_amdgcn_mfma_f32_16x16x32_bf16(Bt[n][k], At[m][k], acc[ai][bj][m][n], 0, 0, 0); __builtin_amdgcn_s_setprio(0); } while (0)
; template <class Epi, class Sched, bool ALIGN_EPI = false, bool SP2 = false, bool A_TILED = false>
; __device__ __forceinline__ void gemm_phase(PG8_LAS unsigned char* lds, const Gemm g, const Sched& S, const Epi& E, const int wave_s) {
;     ...
;         for (int t = PEEL ? 2 : 0; t < nt; t += 2) {
;             const bool last = (t == nt - 2);
;             const char* a1 = cA + (size_t)(t + 1) * kstepA;
;             const char* a2 = last ? nA : cA + (size_t)(t + 2) * kstepA; const char* b2 = last ? nB : cB + (size_t)(t + 2) * kstep;
;             const char* a3 = a2 + kstepA; const char* b3 = b2 + kstep;
;             if (last && has_next) S.a_ready(nxt);
;             if constexpr (SP2) {
;             PG8_ITER(PG8_MMA)
.LBB0_2566:
	ds_read_b128 v[150:153], v147
	ds_read_b128 v[154:157], v147 offset:1024
	ds_read_b128 v[158:161], v147 offset:2048
	ds_read_b128 v[162:165], v147 offset:3072
	ds_read_b128 v[166:169], v148
	ds_read_b128 v[170:173], v148 offset:1024
	ds_read_b128 v[174:177], v148 offset:2048
	ds_read_b128 v[178:181], v148 offset:3072
	s_add_u32 s76, s74, 0xfffe0080
	s_addc_u32 s77, s75, -1
	s_cmp_eq_u32 s85, 4
	s_cselect_b32 s79, s51, s77
	s_cselect_b32 s78, s52, s76
	s_cselect_b32 s77, s53, s83
	s_cselect_b32 s76, s54, s82
	s_mov_b32 m0, s55
	v_lshl_add_u64 v[140:141], s[74:75], 0, v[138:139]
	ds_read_b128 v[182:185], v149
	ds_read_b128 v[186:189], v149 offset:1024
	ds_read_b128 v[190:193], v149 offset:2048
	ds_read_b128 v[194:197], v149 offset:3072
	ds_read_b128 v[198:201], v149 offset:4096
	ds_read_b128 v[202:205], v149 offset:5120
	ds_read_b128 v[206:209], v149 offset:6144
	ds_read_b128 v[210:213], v149 offset:7168
	global_load_lds_dwordx4 v138, s[74:75]
	v_lshl_add_u64 v[140:141], s[74:75], 0, v[136:137]
	s_mov_b32 m0, s56
	s_nop 0
	global_load_lds_dwordx4 v136, s[74:75]
	s_waitcnt vmcnt(8) lgkmcnt(0)
	s_setprio 1
	s_barrier
	v_mfma_f32_16x16x32_bf16 v[120:123], v[150:153], v[182:185], v[120:123]
	v_mfma_f32_16x16x32_bf16 v[112:115], v[158:161], v[182:185], v[112:115]
	v_mfma_f32_16x16x32_bf16 v[104:107], v[150:153], v[190:193], v[104:107]
	v_mfma_f32_16x16x32_bf16 v[96:99], v[158:161], v[190:193], v[96:99]
	v_mfma_f32_16x16x32_bf16 v[88:91], v[150:153], v[198:201], v[88:91]
	v_mfma_f32_16x16x32_bf16 v[80:83], v[158:161], v[198:201], v[80:83]
	v_mfma_f32_16x16x32_bf16 v[56:59], v[150:153], v[206:209], v[56:59]
	v_mfma_f32_16x16x32_bf16 v[48:51], v[158:161], v[206:209], v[48:51]
	v_mfma_f32_16x16x32_bf16 v[120:123], v[154:157], v[186:189], v[120:123]
	v_mfma_f32_16x16x32_bf16 v[112:115], v[162:165], v[186:189], v[112:115]
	v_mfma_f32_16x16x32_bf16 v[104:107], v[154:157], v[194:197], v[104:107]
	v_mfma_f32_16x16x32_bf16 v[96:99], v[162:165], v[194:197], v[96:99]
	v_mfma_f32_16x16x32_bf16 v[88:91], v[154:157], v[202:205], v[88:91]
	v_mfma_f32_16x16x32_bf16 v[80:83], v[162:165], v[202:205], v[80:83]
	v_mfma_f32_16x16x32_bf16 v[56:59], v[154:157], v[210:213], v[56:59]
	v_mfma_f32_16x16x32_bf16 v[48:51], v[162:165], v[210:213], v[48:51]
	v_mfma_f32_16x16x32_bf16 v[124:127], v[166:169], v[182:185], v[124:127]
	v_mfma_f32_16x16x32_bf16 v[116:119], v[174:177], v[182:185], v[116:119]
	v_mfma_f32_16x16x32_bf16 v[108:111], v[166:169], v[190:193], v[108:111]
	v_mfma_f32_16x16x32_bf16 v[100:103], v[174:177], v[190:193], v[100:103]
	v_mfma_f32_16x16x32_bf16 v[92:95], v[166:169], v[198:201], v[92:95]
	v_mfma_f32_16x16x32_bf16 v[84:87], v[174:177], v[198:201], v[84:87]
	v_mfma_f32_16x16x32_bf16 v[60:63], v[166:169], v[206:209], v[60:63]
	v_mfma_f32_16x16x32_bf16 v[52:55], v[174:177], v[206:209], v[52:55]
	v_mfma_f32_16x16x32_bf16 v[124:127], v[170:173], v[186:189], v[124:127]
	v_mfma_f32_16x16x32_bf16 v[116:119], v[178:181], v[186:189], v[116:119]
	v_mfma_f32_16x16x32_bf16 v[108:111], v[170:173], v[194:197], v[108:111]
	v_mfma_f32_16x16x32_bf16 v[100:103], v[178:181], v[194:197], v[100:103]
	v_mfma_f32_16x16x32_bf16 v[92:95], v[170:173], v[202:205], v[92:95]
	v_mfma_f32_16x16x32_bf16 v[84:87], v[178:181], v[202:205], v[84:87]
	v_mfma_f32_16x16x32_bf16 v[60:63], v[170:173], v[210:213], v[60:63]
	v_mfma_f32_16x16x32_bf16 v[52:55], v[178:181], v[210:213], v[52:55]
	s_barrier
	s_setprio 0
	s_mov_b32 m0, s57
	v_lshl_add_u64 v[140:141], s[76:77], 0, v[128:129]
	s_add_u32 s88, s76, 0x20000
	ds_read_b128 v[182:185], v149 offset:16384
	ds_read_b128 v[186:189], v149 offset:17408
	ds_read_b128 v[190:193], v149 offset:18432
	ds_read_b128 v[194:197], v149 offset:19456
	ds_read_b128 v[198:201], v149 offset:20480
	ds_read_b128 v[202:205], v149 offset:21504
	ds_read_b128 v[206:209], v149 offset:22528
	ds_read_b128 v[210:213], v149 offset:23552
	global_load_lds_dwordx4 v128, s[76:77]
	v_lshl_add_u64 v[142:143], s[76:77], 0, v[130:131]
	s_mov_b32 m0, s58
	s_addc_u32 s89, s77, 0
	global_load_lds_dwordx4 v130, s[76:77]
	v_lshl_add_u64 v[214:215], s[88:89], 0, v[128:129]
	s_mov_b32 m0, s59
	v_lshl_add_u64 v[216:217], s[78:79], 0, v[132:133]
	global_load_lds_dwordx4 v128, s[88:89]
	v_lshl_add_u64 v[214:215], s[88:89], 0, v[130:131]
	s_mov_b32 m0, s65
	s_nop 0
	global_load_lds_dwordx4 v130, s[88:89]
	v_lshl_add_u64 v[214:215], s[78:79], 0, v[134:135]
	s_mov_b32 m0, s0
	s_nop 0
	global_load_lds_dwordx4 v134, s[78:79]
	s_mov_b32 m0, s1
	s_nop 0
	global_load_lds_dwordx4 v132, s[78:79]
	s_waitcnt vmcnt(8) lgkmcnt(0)
	s_setprio 1
	s_barrier
	v_mfma_f32_16x16x32_bf16 v[76:79], v[150:153], v[182:185], v[76:79]
	v_mfma_f32_16x16x32_bf16 v[72:75], v[158:161], v[182:185], v[72:75]
	v_mfma_f32_16x16x32_bf16 v[44:47], v[150:153], v[190:193], v[44:47]
	v_mfma_f32_16x16x32_bf16 v[40:43], v[158:161], v[190:193], v[40:43]
	v_mfma_f32_16x16x32_bf16 v[28:31], v[150:153], v[198:201], v[28:31]
	v_mfma_f32_16x16x32_bf16 v[24:27], v[158:161], v[198:201], v[24:27]
	v_mfma_f32_16x16x32_bf16 v[12:15], v[150:153], v[206:209], v[12:15]
	v_mfma_f32_16x16x32_bf16 v[8:11], v[158:161], v[206:209], v[8:11]
	v_mfma_f32_16x16x32_bf16 v[76:79], v[154:157], v[186:189], v[76:79]
	v_mfma_f32_16x16x32_bf16 v[72:75], v[162:165], v[186:189], v[72:75]
	v_mfma_f32_16x16x32_bf16 v[44:47], v[154:157], v[194:197], v[44:47]
	v_mfma_f32_16x16x32_bf16 v[40:43], v[162:165], v[194:197], v[40:43]
	v_mfma_f32_16x16x32_bf16 v[28:31], v[154:157], v[202:205], v[28:31]
	v_mfma_f32_16x16x32_bf16 v[24:27], v[162:165], v[202:205], v[24:27]
	v_mfma_f32_16x16x32_bf16 v[12:15], v[154:157], v[210:213], v[12:15]
	v_mfma_f32_16x16x32_bf16 v[8:11], v[162:165], v[210:213], v[8:11]
	v_mfma_f32_16x16x32_bf16 v[68:71], v[166:169], v[182:185], v[68:71]
	v_mfma_f32_16x16x32_bf16 v[64:67], v[174:177], v[182:185], v[64:67]
	v_mfma_f32_16x16x32_bf16 v[36:39], v[166:169], v[190:193], v[36:39]
	v_mfma_f32_16x16x32_bf16 v[32:35], v[174:177], v[190:193], v[32:35]
	v_mfma_f32_16x16x32_bf16 v[20:23], v[166:169], v[198:201], v[20:23]
	v_mfma_f32_16x16x32_bf16 v[16:19], v[174:177], v[198:201], v[16:19]
	v_mfma_f32_16x16x32_bf16 v[4:7], v[166:169], v[206:209], v[4:7]
	v_mfma_f32_16x16x32_bf16 v[0:3], v[174:177], v[206:209], v[0:3]
	v_mfma_f32_16x16x32_bf16 v[68:71], v[170:173], v[186:189], v[68:71]
	v_mfma_f32_16x16x32_bf16 v[64:67], v[178:181], v[186:189], v[64:67]
	v_mfma_f32_16x16x32_bf16 v[36:39], v[170:173], v[194:197], v[36:39]
	v_mfma_f32_16x16x32_bf16 v[32:35], v[178:181], v[194:197], v[32:35]
	v_mfma_f32_16x16x32_bf16 v[20:23], v[170:173], v[202:205], v[20:23]
	v_mfma_f32_16x16x32_bf16 v[16:19], v[178:181], v[202:205], v[16:19]
	v_mfma_f32_16x16x32_bf16 v[4:7], v[170:173], v[210:213], v[4:7]
	v_mfma_f32_16x16x32_bf16 v[0:3], v[178:181], v[210:213], v[0:3]
	s_barrier
	s_setprio 0
	ds_read_b128 v[150:153], v144
	ds_read_b128 v[154:157], v144 offset:1024
	ds_read_b128 v[158:161], v144 offset:2048
	ds_read_b128 v[162:165], v144 offset:3072
	ds_read_b128 v[166:169], v145
	ds_read_b128 v[170:173], v145 offset:1024
	ds_read_b128 v[174:177], v145 offset:2048
	ds_read_b128 v[178:181], v145 offset:3072
	s_add_u32 s78, s78, 0x20000
	s_addc_u32 s79, s79, 0
	s_mov_b32 m0, s37
	v_lshl_add_u64 v[218:219], s[78:79], 0, v[134:135]
	ds_read_b128 v[182:185], v149 offset:32768
	ds_read_b128 v[186:189], v149 offset:33792
	ds_read_b128 v[190:193], v149 offset:34816
	ds_read_b128 v[194:197], v149 offset:35840
	ds_read_b128 v[198:201], v149 offset:36864
	ds_read_b128 v[202:205], v149 offset:37888
	ds_read_b128 v[206:209], v149 offset:38912
	ds_read_b128 v[210:213], v149 offset:39936
	global_load_lds_dwordx4 v134, s[78:79]
	v_lshl_add_u64 v[218:219], s[78:79], 0, v[132:133]
	s_mov_b32 m0, s38
	s_nop 0
	global_load_lds_dwordx4 v132, s[78:79]
	s_waitcnt vmcnt(8) lgkmcnt(0)
	s_setprio 1
	s_barrier
	v_mfma_f32_16x16x32_bf16 v[120:123], v[150:153], v[182:185], v[120:123]
	v_mfma_f32_16x16x32_bf16 v[112:115], v[158:161], v[182:185], v[112:115]
	v_mfma_f32_16x16x32_bf16 v[104:107], v[150:153], v[190:193], v[104:107]
	v_mfma_f32_16x16x32_bf16 v[96:99], v[158:161], v[190:193], v[96:99]
	v_mfma_f32_16x16x32_bf16 v[88:91], v[150:153], v[198:201], v[88:91]
	v_mfma_f32_16x16x32_bf16 v[80:83], v[158:161], v[198:201], v[80:83]
	v_mfma_f32_16x16x32_bf16 v[56:59], v[150:153], v[206:209], v[56:59]
	v_mfma_f32_16x16x32_bf16 v[48:51], v[158:161], v[206:209], v[48:51]
	v_mfma_f32_16x16x32_bf16 v[120:123], v[154:157], v[186:189], v[120:123]
	v_mfma_f32_16x16x32_bf16 v[112:115], v[162:165], v[186:189], v[112:115]
	v_mfma_f32_16x16x32_bf16 v[104:107], v[154:157], v[194:197], v[104:107]
	v_mfma_f32_16x16x32_bf16 v[96:99], v[162:165], v[194:197], v[96:99]
	v_mfma_f32_16x16x32_bf16 v[88:91], v[154:157], v[202:205], v[88:91]
	v_mfma_f32_16x16x32_bf16 v[80:83], v[162:165], v[202:205], v[80:83]
	v_mfma_f32_16x16x32_bf16 v[56:59], v[154:157], v[210:213], v[56:59]
	v_mfma_f32_16x16x32_bf16 v[48:51], v[162:165], v[210:213], v[48:51]
	v_mfma_f32_16x16x32_bf16 v[124:127], v[166:169], v[182:185], v[124:127]
	v_mfma_f32_16x16x32_bf16 v[116:119], v[174:177], v[182:185], v[116:119]
	v_mfma_f32_16x16x32_bf16 v[108:111], v[166:169], v[190:193], v[108:111]
	v_mfma_f32_16x16x32_bf16 v[100:103], v[174:177], v[190:193], v[100:103]
	v_mfma_f32_16x16x32_bf16 v[92:95], v[166:169], v[198:201], v[92:95]
	v_mfma_f32_16x16x32_bf16 v[84:87], v[174:177], v[198:201], v[84:87]
	v_mfma_f32_16x16x32_bf16 v[60:63], v[166:169], v[206:209], v[60:63]
	v_mfma_f32_16x16x32_bf16 v[52:55], v[174:177], v[206:209], v[52:55]
	v_mfma_f32_16x16x32_bf16 v[124:127], v[170:173], v[186:189], v[124:127]
	v_mfma_f32_16x16x32_bf16 v[116:119], v[178:181], v[186:189], v[116:119]
	v_mfma_f32_16x16x32_bf16 v[108:111], v[170:173], v[194:197], v[108:111]
	v_mfma_f32_16x16x32_bf16 v[100:103], v[178:181], v[194:197], v[100:103]
	v_mfma_f32_16x16x32_bf16 v[92:95], v[170:173], v[202:205], v[92:95]
	v_mfma_f32_16x16x32_bf16 v[84:87], v[178:181], v[202:205], v[84:87]
	v_mfma_f32_16x16x32_bf16 v[60:63], v[170:173], v[210:213], v[60:63]
	v_mfma_f32_16x16x32_bf16 v[52:55], v[178:181], v[210:213], v[52:55]
	s_barrier
; #define PG8_STAGE(bufoff, gbase, voff) do { _Pragma("unroll") for (int _i = 0; _i < 2; ++_i) \
;         __builtin_amdgcn_global_load_lds((const unsigned*)((const char*)(gbase) + (voff)[_i]), (PG8_LAS unsigned*)(lds + (bufoff) + ldsw + _i * 8192), 16, 0, 0); } while (0)
; #define PG8_BAR __builtin_amdgcn_s_barrier()
; template <class Epi, class Sched, bool ALIGN_EPI = false, bool SP2 = false, bool A_TILED = false>
; __device__ __forceinline__ void gemm_phase(PG8_LAS unsigned char* lds, const Gemm g, const Sched& S, const Epi& E, const int wave_s) {
;     ...
;         for (int t = PEEL ? 2 : 0; t < nt; t += 2) {
;             const bool last = (t == nt - 2);
;             const char* a1 = cA + (size_t)(t + 1) * kstepA;
;             const char* a2 = last ? nA : cA + (size_t)(t + 2) * kstepA; const char* b2 = last ? nB : cB + (size_t)(t + 2) * kstep;
;             const char* a3 = a2 + kstepA; const char* b3 = b2 + kstep;
;             if (last && has_next) S.a_ready(nxt);
;             if constexpr (SP2) {
;             PG8_ITER(PG8_MMA)
;             } else {
;             PG8_LDB(B0, 0, 0); PG8_SCHED; PG8_LDA(At, 0, 0); PG8_STAGE(PG8_SA(1, 1), a1 + hstepA, voffA);
;             PG8_WAIT_L(8); PG8_BAR; PG8_WAIT_L(0); PG8_MMA(0, 0, At, B0); PG8_BAR; PG8_SCHED;
;             PG8_LDB(B1, 0, 1); PG8_STAGE(PG8_SB(0, 0), b2, voffB);
;             PG8_BAR; PG8_WAIT_L(0); PG8_MMA(0, 1, At, B1); PG8_BAR;
;             PG8_LDA(At, 0, 1); PG8_STAGE(PG8_SA(0, 0), a2, voffA);
;             PG8_BAR; PG8_WAIT_L(0); PG8_MMA(1, 0, At, B0); PG8_BAR; PG8_SCHED;
;             PG8_STAGE(PG8_SB(0, 1), b2 + hstep, voffB);
;             PG8_WAIT_V(6); PG8_BAR; PG8_MMA(1, 1, At, B1); PG8_BAR;
;             PG8_LDB(B0, 1, 0); PG8_SCHED; PG8_LDA(At, 1, 0); PG8_STAGE(PG8_SA(0, 1), a2 + hstepA, voffA);
;             PG8_WAIT_L(8); PG8_BAR; PG8_WAIT_L(0); PG8_MMA(0, 0, At, B0); PG8_BAR; PG8_SCHED;
;             PG8_LDB(B1, 1, 1); PG8_STAGE(PG8_SB(1, 0), b3, voffB);
;             PG8_BAR; PG8_WAIT_L(0); PG8_MMA(0, 1, At, B1); PG8_BAR;
;             PG8_LDA(At, 1, 1); PG8_STAGE(PG8_SA(1, 0), a3, voffA);
;             PG8_BAR; PG8_WAIT_L(0); PG8_MMA(1, 0, At, B0); PG8_BAR; PG8_SCHED;
;             PG8_STAGE(PG8_SB(1, 1), b3 + hstep, voffB);
;             PG8_WAIT_V(6); PG8_BAR; PG8_MMA(1, 1, At, B1); PG8_BAR;
;             }
;         }
;         if constexpr (ALIGN_EPI) { if (wr == 0) PG8_BAR; }
	s_setprio 0
	s_mov_b32 m0, s67
	v_lshl_add_u64 v[140:141], v[140:141], 0, s[44:45]
	s_add_u32 s76, s76, 0x20080
	ds_read_b128 v[182:185], v149 offset:49152
	ds_read_b128 v[186:189], v149 offset:50176
	ds_read_b128 v[190:193], v149 offset:51200
	ds_read_b128 v[194:197], v149 offset:52224
	ds_read_b128 v[198:201], v149 offset:53248
	ds_read_b128 v[202:205], v149 offset:54272
	ds_read_b128 v[206:209], v149 offset:55296
	ds_read_b128 v[210:213], v149 offset:56320
	global_load_lds_dwordx4 v[140:141], off
	v_lshl_add_u64 v[140:141], v[142:143], 0, s[44:45]
	s_mov_b32 m0, s71
	s_addc_u32 s77, s77, 0
	global_load_lds_dwordx4 v[140:141], off
	v_lshl_add_u64 v[140:141], s[76:77], 0, v[128:129]
	s_mov_b32 m0, s80
	s_nop 0
	global_load_lds_dwordx4 v128, s[76:77]
	v_lshl_add_u64 v[140:141], s[76:77], 0, v[130:131]
	s_mov_b32 m0, s81
	s_nop 0
	global_load_lds_dwordx4 v130, s[76:77]
	v_lshl_add_u64 v[140:141], v[214:215], 0, s[44:45]
	s_mov_b32 m0, s42
	s_nop 0
	global_load_lds_dwordx4 v[140:141], off
	v_lshl_add_u64 v[140:141], v[216:217], 0, s[44:45]
	s_mov_b32 m0, s43
	s_nop 0
	global_load_lds_dwordx4 v[140:141], off
	s_waitcnt vmcnt(8) lgkmcnt(0)
	s_setprio 1
	s_barrier
	v_mfma_f32_16x16x32_bf16 v[76:79], v[150:153], v[182:185], v[76:79]
	v_mfma_f32_16x16x32_bf16 v[72:75], v[158:161], v[182:185], v[72:75]
	v_mfma_f32_16x16x32_bf16 v[44:47], v[150:153], v[190:193], v[44:47]
	v_mfma_f32_16x16x32_bf16 v[40:43], v[158:161], v[190:193], v[40:43]
	v_mfma_f32_16x16x32_bf16 v[28:31], v[150:153], v[198:201], v[28:31]
	v_mfma_f32_16x16x32_bf16 v[24:27], v[158:161], v[198:201], v[24:27]
	v_mfma_f32_16x16x32_bf16 v[12:15], v[150:153], v[206:209], v[12:15]
	v_mfma_f32_16x16x32_bf16 v[8:11], v[158:161], v[206:209], v[8:11]
	v_mfma_f32_16x16x32_bf16 v[76:79], v[154:157], v[186:189], v[76:79]
	v_mfma_f32_16x16x32_bf16 v[72:75], v[162:165], v[186:189], v[72:75]
	v_mfma_f32_16x16x32_bf16 v[44:47], v[154:157], v[194:197], v[44:47]
	v_mfma_f32_16x16x32_bf16 v[40:43], v[162:165], v[194:197], v[40:43]
	v_mfma_f32_16x16x32_bf16 v[28:31], v[154:157], v[202:205], v[28:31]
	v_mfma_f32_16x16x32_bf16 v[24:27], v[162:165], v[202:205], v[24:27]
	v_mfma_f32_16x16x32_bf16 v[12:15], v[154:157], v[210:213], v[12:15]
	v_mfma_f32_16x16x32_bf16 v[8:11], v[162:165], v[210:213], v[8:11]
	v_mfma_f32_16x16x32_bf16 v[68:71], v[166:169], v[182:185], v[68:71]
	v_mfma_f32_16x16x32_bf16 v[64:67], v[174:177], v[182:185], v[64:67]
	v_mfma_f32_16x16x32_bf16 v[36:39], v[166:169], v[190:193], v[36:39]
	v_mfma_f32_16x16x32_bf16 v[32:35], v[174:177], v[190:193], v[32:35]
	v_mfma_f32_16x16x32_bf16 v[20:23], v[166:169], v[198:201], v[20:23]
	v_mfma_f32_16x16x32_bf16 v[16:19], v[174:177], v[198:201], v[16:19]
	v_mfma_f32_16x16x32_bf16 v[4:7], v[166:169], v[206:209], v[4:7]
	v_mfma_f32_16x16x32_bf16 v[0:3], v[174:177], v[206:209], v[0:3]
	v_mfma_f32_16x16x32_bf16 v[68:71], v[170:173], v[186:189], v[68:71]
	v_mfma_f32_16x16x32_bf16 v[64:67], v[178:181], v[186:189], v[64:67]
	v_mfma_f32_16x16x32_bf16 v[36:39], v[170:173], v[194:197], v[36:39]
	v_mfma_f32_16x16x32_bf16 v[32:35], v[178:181], v[194:197], v[32:35]
	v_mfma_f32_16x16x32_bf16 v[20:23], v[170:173], v[202:205], v[20:23]
	v_mfma_f32_16x16x32_bf16 v[16:19], v[178:181], v[202:205], v[16:19]
	v_mfma_f32_16x16x32_bf16 v[4:7], v[170:173], v[210:213], v[4:7]
	v_mfma_f32_16x16x32_bf16 v[0:3], v[178:181], v[210:213], v[0:3]
	s_barrier
	s_setprio 0
	s_add_i32 s85, s85, 2
	s_add_u32 s82, s82, 0x100
	s_addc_u32 s83, s83, 0
	s_add_u32 s74, s74, 0x100
	s_addc_u32 s75, s75, 0
	s_cmp_gt_u32 s85, 5
	s_cbranch_scc0 .LBB0_2566
	s_and_b64 vcc, exec, s[46:47]
	s_cbranch_vccz .LBB0_2569
	s_barrier

; #define PG8_MMA(ai, bj, At, Bt) do { __builtin_amdgcn_s_setprio(1); _Pragma("unroll") for (int m = 0; m < 4; ++m) _Pragma("unroll") for (int n = 0; n < 2; ++n) _Pragma("unroll") for (int k = 0; k < 2; ++k) \
;         acc[ai][bj][m][n] = __builtin_amdgcn_mfma_f32_16x16x32_bf16(Bt[n][k], At[m][k], acc[ai][bj][m][n], 0, 0, 0); __builtin_amdgcn_s_setprio(0); } while (0)
; template <class Epi, class Sched, bool ALIGN_EPI = false, bool SP2 = false, bool A_TILED = false>
; __device__ __forceinline__ void gemm_phase(PG8_LAS unsigned char* lds, const Gemm g, const Sched& S, const Epi& E, const int wave_s) {
;     ...
;         for (int t = PEEL ? 2 : 0; t < nt; t += 2) {
;             const bool last = (t == nt - 2);
;             const char* a1 = cA + (size_t)(t + 1) * kstepA;
;             const char* a2 = last ? nA : cA + (size_t)(t + 2) * kstepA; const char* b2 = last ? nB : cB + (size_t)(t + 2) * kstep;
;             const char* a3 = a2 + kstepA; const char* b3 = b2 + kstep;
;             if (last && has_next) S.a_ready(nxt);
;             if constexpr (SP2) {
;             PG8_ITER(PG8_MMA)
.LBB0_2729:
	ds_read_b128 v[146:149], v140
	ds_read_b128 v[150:153], v140 offset:1024
	ds_read_b128 v[154:157], v140 offset:2048
	ds_read_b128 v[158:161], v140 offset:3072
	ds_read_b128 v[162:165], v141
	ds_read_b128 v[166:169], v141 offset:1024
	ds_read_b128 v[170:173], v141 offset:2048
	ds_read_b128 v[174:177], v141 offset:3072
	s_add_u32 s55, s44, s39
	s_addc_u32 s56, s45, s40
	s_add_u32 s57, s44, s37
	s_addc_u32 s58, s45, s38
	s_cmp_eq_u32 s41, 28
	s_cselect_b32 s67, s7, s56
	s_cselect_b32 s66, s6, s55
	s_cselect_b32 s65, s3, s58
	s_cselect_b32 s64, s2, s57
	s_mov_b32 m0, s42
	v_lshl_add_u64 v[210:211], s[44:45], 0, v[138:139]
	ds_read_b128 v[178:181], v142
	ds_read_b128 v[182:185], v142 offset:1024
	ds_read_b128 v[186:189], v142 offset:2048
	ds_read_b128 v[190:193], v142 offset:3072
	ds_read_b128 v[194:197], v142 offset:4096
	ds_read_b128 v[198:201], v142 offset:5120
	ds_read_b128 v[202:205], v142 offset:6144
	ds_read_b128 v[206:209], v142 offset:7168
	global_load_lds_dwordx4 v[210:211], off
	v_lshl_add_u64 v[210:211], s[44:45], 0, v[136:137]
	s_mov_b32 m0, s43
	s_nop 0
	global_load_lds_dwordx4 v[210:211], off
	s_waitcnt vmcnt(8) lgkmcnt(0)
	s_setprio 1
	s_barrier
	v_mfma_f32_16x16x32_bf16 v[8:11], v[146:149], v[178:181], v[8:11]
	v_mfma_f32_16x16x32_bf16 v[12:15], v[154:157], v[178:181], v[12:15]
	v_mfma_f32_16x16x32_bf16 v[60:63], v[146:149], v[186:189], v[60:63]
	v_mfma_f32_16x16x32_bf16 v[20:23], v[154:157], v[186:189], v[20:23]
	v_mfma_f32_16x16x32_bf16 v[76:79], v[146:149], v[194:197], v[76:79]
	v_mfma_f32_16x16x32_bf16 v[52:55], v[154:157], v[194:197], v[52:55]
	v_mfma_f32_16x16x32_bf16 v[128:131], v[146:149], v[202:205], v[128:131]
	v_mfma_f32_16x16x32_bf16 v[68:71], v[154:157], v[202:205], v[68:71]
	v_mfma_f32_16x16x32_bf16 v[8:11], v[150:153], v[182:185], v[8:11]
	v_mfma_f32_16x16x32_bf16 v[12:15], v[158:161], v[182:185], v[12:15]
	v_mfma_f32_16x16x32_bf16 v[60:63], v[150:153], v[190:193], v[60:63]
	v_mfma_f32_16x16x32_bf16 v[20:23], v[158:161], v[190:193], v[20:23]
	v_mfma_f32_16x16x32_bf16 v[76:79], v[150:153], v[198:201], v[76:79]
	v_mfma_f32_16x16x32_bf16 v[52:55], v[158:161], v[198:201], v[52:55]
	v_mfma_f32_16x16x32_bf16 v[128:131], v[150:153], v[206:209], v[128:131]
	v_mfma_f32_16x16x32_bf16 v[68:71], v[158:161], v[206:209], v[68:71]
	v_mfma_f32_16x16x32_bf16 v[24:27], v[162:165], v[178:181], v[24:27]
	v_mfma_f32_16x16x32_bf16 v[16:19], v[170:173], v[178:181], v[16:19]
	v_mfma_f32_16x16x32_bf16 v[56:59], v[162:165], v[186:189], v[56:59]
	v_mfma_f32_16x16x32_bf16 v[48:51], v[170:173], v[186:189], v[48:51]
	v_mfma_f32_16x16x32_bf16 v[72:75], v[162:165], v[194:197], v[72:75]
	v_mfma_f32_16x16x32_bf16 v[64:67], v[170:173], v[194:197], v[64:67]
	v_mfma_f32_16x16x32_bf16 v[108:111], v[162:165], v[202:205], v[108:111]
	v_mfma_f32_16x16x32_bf16 v[96:99], v[170:173], v[202:205], v[96:99]
	v_mfma_f32_16x16x32_bf16 v[24:27], v[166:169], v[182:185], v[24:27]
	v_mfma_f32_16x16x32_bf16 v[16:19], v[174:177], v[182:185], v[16:19]
	v_mfma_f32_16x16x32_bf16 v[56:59], v[166:169], v[190:193], v[56:59]
	v_mfma_f32_16x16x32_bf16 v[48:51], v[174:177], v[190:193], v[48:51]
	v_mfma_f32_16x16x32_bf16 v[72:75], v[166:169], v[198:201], v[72:75]
	v_mfma_f32_16x16x32_bf16 v[64:67], v[174:177], v[198:201], v[64:67]
	v_mfma_f32_16x16x32_bf16 v[108:111], v[166:169], v[206:209], v[108:111]
	v_mfma_f32_16x16x32_bf16 v[96:99], v[174:177], v[206:209], v[96:99]
	s_barrier
	s_setprio 0
	s_mov_b32 m0, s47
	v_lshl_add_u64 v[210:211], s[64:65], 0, v[34:35]
	s_add_u32 s56, s64, 0x80000
	ds_read_b128 v[178:181], v142 offset:16384
	ds_read_b128 v[182:185], v142 offset:17408
	ds_read_b128 v[186:189], v142 offset:18432
	ds_read_b128 v[190:193], v142 offset:19456
	ds_read_b128 v[194:197], v142 offset:20480
	ds_read_b128 v[198:201], v142 offset:21504
	ds_read_b128 v[202:205], v142 offset:22528
	ds_read_b128 v[206:209], v142 offset:23552
	global_load_lds_dwordx4 v34, s[64:65]
	v_lshl_add_u64 v[212:213], s[64:65], 0, v[134:135]
	s_mov_b32 m0, s48
	s_addc_u32 s57, s65, 0
	global_load_lds_dwordx4 v134, s[64:65]
	v_lshl_add_u64 v[214:215], s[56:57], 0, v[34:35]
	s_mov_b32 m0, s49
	v_lshl_add_u64 v[216:217], s[66:67], 0, v[132:133]
	global_load_lds_dwordx4 v34, s[56:57]
	v_lshl_add_u64 v[214:215], s[56:57], 0, v[134:135]
	s_mov_b32 m0, s50
	s_nop 0
	global_load_lds_dwordx4 v134, s[56:57]
	v_lshl_add_u64 v[214:215], s[66:67], 0, v[32:33]
	s_mov_b32 m0, s14
	s_nop 0
	global_load_lds_dwordx4 v32, s[66:67]
	s_mov_b32 m0, s15
	s_nop 0
	global_load_lds_dwordx4 v132, s[66:67]
	s_waitcnt vmcnt(8) lgkmcnt(0)
	s_setprio 1
	s_barrier
	v_mfma_f32_16x16x32_bf16 v[100:103], v[146:149], v[178:181], v[100:103]
	v_mfma_f32_16x16x32_bf16 v[104:107], v[154:157], v[178:181], v[104:107]
	v_mfma_f32_16x16x32_bf16 v[116:119], v[146:149], v[186:189], v[116:119]
	v_mfma_f32_16x16x32_bf16 v[120:123], v[154:157], v[186:189], v[120:123]
	v_mfma_f32_16x16x32_bf16 v[84:87], v[146:149], v[194:197], v[84:87]
	v_mfma_f32_16x16x32_bf16 v[80:83], v[154:157], v[194:197], v[80:83]
	v_mfma_f32_16x16x32_bf16 v[36:39], v[146:149], v[202:205], v[36:39]
	v_mfma_f32_16x16x32_bf16 v[28:31], v[154:157], v[202:205], v[28:31]
	v_mfma_f32_16x16x32_bf16 v[100:103], v[150:153], v[182:185], v[100:103]
	v_mfma_f32_16x16x32_bf16 v[104:107], v[158:161], v[182:185], v[104:107]
	v_mfma_f32_16x16x32_bf16 v[116:119], v[150:153], v[190:193], v[116:119]
	v_mfma_f32_16x16x32_bf16 v[120:123], v[158:161], v[190:193], v[120:123]
	v_mfma_f32_16x16x32_bf16 v[84:87], v[150:153], v[198:201], v[84:87]
	v_mfma_f32_16x16x32_bf16 v[80:83], v[158:161], v[198:201], v[80:83]
	v_mfma_f32_16x16x32_bf16 v[36:39], v[150:153], v[206:209], v[36:39]
	v_mfma_f32_16x16x32_bf16 v[28:31], v[158:161], v[206:209], v[28:31]
	v_mfma_f32_16x16x32_bf16 v[124:127], v[162:165], v[178:181], v[124:127]
	v_mfma_f32_16x16x32_bf16 v[112:115], v[170:173], v[178:181], v[112:115]
	v_mfma_f32_16x16x32_bf16 v[92:95], v[162:165], v[186:189], v[92:95]
	v_mfma_f32_16x16x32_bf16 v[88:91], v[170:173], v[186:189], v[88:91]
	v_mfma_f32_16x16x32_bf16 v[44:47], v[162:165], v[194:197], v[44:47]
	v_mfma_f32_16x16x32_bf16 v[40:43], v[170:173], v[194:197], v[40:43]
	v_mfma_f32_16x16x32_bf16 v[4:7], v[162:165], v[202:205], v[4:7]
	v_mfma_f32_16x16x32_bf16 v[0:3], v[170:173], v[202:205], v[0:3]
	v_mfma_f32_16x16x32_bf16 v[124:127], v[166:169], v[182:185], v[124:127]
	v_mfma_f32_16x16x32_bf16 v[112:115], v[174:177], v[182:185], v[112:115]
	v_mfma_f32_16x16x32_bf16 v[92:95], v[166:169], v[190:193], v[92:95]
	v_mfma_f32_16x16x32_bf16 v[88:91], v[174:177], v[190:193], v[88:91]
	v_mfma_f32_16x16x32_bf16 v[44:47], v[166:169], v[198:201], v[44:47]
	v_mfma_f32_16x16x32_bf16 v[40:43], v[174:177], v[198:201], v[40:43]
	v_mfma_f32_16x16x32_bf16 v[4:7], v[166:169], v[206:209], v[4:7]
	v_mfma_f32_16x16x32_bf16 v[0:3], v[174:177], v[206:209], v[0:3]
	s_barrier
	s_setprio 0
	ds_read_b128 v[146:149], v143
	ds_read_b128 v[150:153], v143 offset:1024
	ds_read_b128 v[154:157], v143 offset:2048
	ds_read_b128 v[158:161], v143 offset:3072
	ds_read_b128 v[162:165], v144
	ds_read_b128 v[166:169], v144 offset:1024
	ds_read_b128 v[170:173], v144 offset:2048
	ds_read_b128 v[174:177], v144 offset:3072
	s_add_u32 s56, s66, 0x80000
	s_addc_u32 s57, s67, 0
	s_mov_b32 m0, s21
	v_lshl_add_u64 v[218:219], s[56:57], 0, v[32:33]
	ds_read_b128 v[178:181], v142 offset:32768
	ds_read_b128 v[182:185], v142 offset:33792
	ds_read_b128 v[186:189], v142 offset:34816
	ds_read_b128 v[190:193], v142 offset:35840
	ds_read_b128 v[194:197], v142 offset:36864
	ds_read_b128 v[198:201], v142 offset:37888
	ds_read_b128 v[202:205], v142 offset:38912
	ds_read_b128 v[206:209], v142 offset:39936
	global_load_lds_dwordx4 v32, s[56:57]
	v_lshl_add_u64 v[218:219], s[56:57], 0, v[132:133]
	s_mov_b32 m0, s22
	s_nop 0
	global_load_lds_dwordx4 v132, s[56:57]
	s_waitcnt vmcnt(8) lgkmcnt(0)
	s_setprio 1
	s_barrier
	v_mfma_f32_16x16x32_bf16 v[8:11], v[146:149], v[178:181], v[8:11]
	v_mfma_f32_16x16x32_bf16 v[12:15], v[154:157], v[178:181], v[12:15]
	v_mfma_f32_16x16x32_bf16 v[60:63], v[146:149], v[186:189], v[60:63]
	v_mfma_f32_16x16x32_bf16 v[20:23], v[154:157], v[186:189], v[20:23]
	v_mfma_f32_16x16x32_bf16 v[76:79], v[146:149], v[194:197], v[76:79]
	v_mfma_f32_16x16x32_bf16 v[52:55], v[154:157], v[194:197], v[52:55]
	v_mfma_f32_16x16x32_bf16 v[128:131], v[146:149], v[202:205], v[128:131]
	v_mfma_f32_16x16x32_bf16 v[68:71], v[154:157], v[202:205], v[68:71]
	v_mfma_f32_16x16x32_bf16 v[8:11], v[150:153], v[182:185], v[8:11]
	v_mfma_f32_16x16x32_bf16 v[12:15], v[158:161], v[182:185], v[12:15]
	v_mfma_f32_16x16x32_bf16 v[60:63], v[150:153], v[190:193], v[60:63]
	v_mfma_f32_16x16x32_bf16 v[20:23], v[158:161], v[190:193], v[20:23]
	v_mfma_f32_16x16x32_bf16 v[76:79], v[150:153], v[198:201], v[76:79]
	v_mfma_f32_16x16x32_bf16 v[52:55], v[158:161], v[198:201], v[52:55]
	v_mfma_f32_16x16x32_bf16 v[128:131], v[150:153], v[206:209], v[128:131]
	v_mfma_f32_16x16x32_bf16 v[68:71], v[158:161], v[206:209], v[68:71]
	v_mfma_f32_16x16x32_bf16 v[24:27], v[162:165], v[178:181], v[24:27]
	v_mfma_f32_16x16x32_bf16 v[16:19], v[170:173], v[178:181], v[16:19]
	v_mfma_f32_16x16x32_bf16 v[56:59], v[162:165], v[186:189], v[56:59]
	v_mfma_f32_16x16x32_bf16 v[48:51], v[170:173], v[186:189], v[48:51]
	v_mfma_f32_16x16x32_bf16 v[72:75], v[162:165], v[194:197], v[72:75]
	v_mfma_f32_16x16x32_bf16 v[64:67], v[170:173], v[194:197], v[64:67]
	v_mfma_f32_16x16x32_bf16 v[108:111], v[162:165], v[202:205], v[108:111]
	v_mfma_f32_16x16x32_bf16 v[96:99], v[170:173], v[202:205], v[96:99]
	v_mfma_f32_16x16x32_bf16 v[24:27], v[166:169], v[182:185], v[24:27]
	v_mfma_f32_16x16x32_bf16 v[16:19], v[174:177], v[182:185], v[16:19]
	v_mfma_f32_16x16x32_bf16 v[56:59], v[166:169], v[190:193], v[56:59]
	v_mfma_f32_16x16x32_bf16 v[48:51], v[174:177], v[190:193], v[48:51]
	v_mfma_f32_16x16x32_bf16 v[72:75], v[166:169], v[198:201], v[72:75]
	v_mfma_f32_16x16x32_bf16 v[64:67], v[174:177], v[198:201], v[64:67]
	v_mfma_f32_16x16x32_bf16 v[108:111], v[166:169], v[206:209], v[108:111]
	v_mfma_f32_16x16x32_bf16 v[96:99], v[174:177], v[206:209], v[96:99]
	s_barrier
; #define PG8_MMA(ai, bj, At, Bt) do { __builtin_amdgcn_s_setprio(1); _Pragma("unroll") for (int m = 0; m < 4; ++m) _Pragma("unroll") for (int n = 0; n < 2; ++n) _Pragma("unroll") for (int k = 0; k < 2; ++k) \
;         acc[ai][bj][m][n] = __builtin_amdgcn_mfma_f32_16x16x32_bf16(Bt[n][k], At[m][k], acc[ai][bj][m][n], 0, 0, 0); __builtin_amdgcn_s_setprio(0); } while (0)
; template <class Epi, class Sched, bool ALIGN_EPI = false, bool SP2 = false, bool A_TILED = false>
; __device__ __forceinline__ void gemm_phase(PG8_LAS unsigned char* lds, const Gemm g, const Sched& S, const Epi& E, const int wave_s) {
;     ...
;         for (int t = PEEL ? 2 : 0; t < nt; t += 2) {
;             const bool last = (t == nt - 2);
;             const char* a1 = cA + (size_t)(t + 1) * kstepA;
;             const char* a2 = last ? nA : cA + (size_t)(t + 2) * kstepA; const char* b2 = last ? nB : cB + (size_t)(t + 2) * kstep;
;             const char* a3 = a2 + kstepA; const char* b3 = b2 + kstep;
;             if (last && has_next) S.a_ready(nxt);
;             if constexpr (SP2) {
;             PG8_ITER(PG8_MMA)
	s_setprio 0
	s_mov_b32 m0, s51
	v_lshl_add_u64 v[210:211], v[210:211], 0, s[60:61]
	s_add_u32 s56, s64, 0x80080
	ds_read_b128 v[178:181], v142 offset:49152
	ds_read_b128 v[182:185], v142 offset:50176
	ds_read_b128 v[186:189], v142 offset:51200
	ds_read_b128 v[190:193], v142 offset:52224
	ds_read_b128 v[194:197], v142 offset:53248
	ds_read_b128 v[198:201], v142 offset:54272
	ds_read_b128 v[202:205], v142 offset:55296
	ds_read_b128 v[206:209], v142 offset:56320
	global_load_lds_dwordx4 v[210:211], off
	v_lshl_add_u64 v[210:211], v[212:213], 0, s[60:61]
	s_mov_b32 m0, s52
	s_addc_u32 s57, s65, 0
	global_load_lds_dwordx4 v[210:211], off
	v_lshl_add_u64 v[210:211], s[56:57], 0, v[34:35]
	s_mov_b32 m0, s53
	s_nop 0
	global_load_lds_dwordx4 v34, s[56:57]
	v_lshl_add_u64 v[210:211], s[56:57], 0, v[134:135]
	s_mov_b32 m0, s54
	s_nop 0
	global_load_lds_dwordx4 v134, s[56:57]
	v_lshl_add_u64 v[210:211], v[214:215], 0, s[60:61]
	s_mov_b32 m0, s23
	s_nop 0
	global_load_lds_dwordx4 v[210:211], off
	v_lshl_add_u64 v[210:211], v[216:217], 0, s[60:61]
	s_mov_b32 m0, s36
	s_nop 0
	global_load_lds_dwordx4 v[210:211], off
	s_waitcnt vmcnt(8) lgkmcnt(0)
	s_setprio 1
	s_barrier
	v_mfma_f32_16x16x32_bf16 v[100:103], v[146:149], v[178:181], v[100:103]
	v_mfma_f32_16x16x32_bf16 v[104:107], v[154:157], v[178:181], v[104:107]
	v_mfma_f32_16x16x32_bf16 v[116:119], v[146:149], v[186:189], v[116:119]
	v_mfma_f32_16x16x32_bf16 v[120:123], v[154:157], v[186:189], v[120:123]
	v_mfma_f32_16x16x32_bf16 v[84:87], v[146:149], v[194:197], v[84:87]
	v_mfma_f32_16x16x32_bf16 v[80:83], v[154:157], v[194:197], v[80:83]
	v_mfma_f32_16x16x32_bf16 v[36:39], v[146:149], v[202:205], v[36:39]
	v_mfma_f32_16x16x32_bf16 v[28:31], v[154:157], v[202:205], v[28:31]
	v_mfma_f32_16x16x32_bf16 v[100:103], v[150:153], v[182:185], v[100:103]
	v_mfma_f32_16x16x32_bf16 v[104:107], v[158:161], v[182:185], v[104:107]
	v_mfma_f32_16x16x32_bf16 v[116:119], v[150:153], v[190:193], v[116:119]
	v_mfma_f32_16x16x32_bf16 v[120:123], v[158:161], v[190:193], v[120:123]
	v_mfma_f32_16x16x32_bf16 v[84:87], v[150:153], v[198:201], v[84:87]
	v_mfma_f32_16x16x32_bf16 v[80:83], v[158:161], v[198:201], v[80:83]
	v_mfma_f32_16x16x32_bf16 v[36:39], v[150:153], v[206:209], v[36:39]
	v_mfma_f32_16x16x32_bf16 v[28:31], v[158:161], v[206:209], v[28:31]
	v_mfma_f32_16x16x32_bf16 v[124:127], v[162:165], v[178:181], v[124:127]
	v_mfma_f32_16x16x32_bf16 v[112:115], v[170:173], v[178:181], v[112:115]
	v_mfma_f32_16x16x32_bf16 v[92:95], v[162:165], v[186:189], v[92:95]
	v_mfma_f32_16x16x32_bf16 v[88:91], v[170:173], v[186:189], v[88:91]
	v_mfma_f32_16x16x32_bf16 v[44:47], v[162:165], v[194:197], v[44:47]
	v_mfma_f32_16x16x32_bf16 v[40:43], v[170:173], v[194:197], v[40:43]
	v_mfma_f32_16x16x32_bf16 v[4:7], v[162:165], v[202:205], v[4:7]
	v_mfma_f32_16x16x32_bf16 v[0:3], v[170:173], v[202:205], v[0:3]
	v_mfma_f32_16x16x32_bf16 v[124:127], v[166:169], v[182:185], v[124:127]
	v_mfma_f32_16x16x32_bf16 v[112:115], v[174:177], v[182:185], v[112:115]
	v_mfma_f32_16x16x32_bf16 v[92:95], v[166:169], v[190:193], v[92:95]
	v_mfma_f32_16x16x32_bf16 v[88:91], v[174:177], v[190:193], v[88:91]
	v_mfma_f32_16x16x32_bf16 v[44:47], v[166:169], v[198:201], v[44:47]
	v_mfma_f32_16x16x32_bf16 v[40:43], v[174:177], v[198:201], v[40:43]
	v_mfma_f32_16x16x32_bf16 v[4:7], v[166:169], v[206:209], v[4:7]
	v_mfma_f32_16x16x32_bf16 v[0:3], v[174:177], v[206:209], v[0:3]
	s_barrier
	s_setprio 0
	s_add_i32 s41, s41, 2
	s_add_u32 s37, s37, 0x100
	s_addc_u32 s38, s38, 0
	s_add_u32 s39, s39, 0x100
	s_addc_u32 s40, s40, 0
	v_lshl_add_u64 v[136:137], v[136:137], 0, s[62:63]
	s_cmp_gt_u32 s41, 29
	v_lshl_add_u64 v[138:139], v[138:139], 0, s[62:63]
	s_cbranch_scc0 .LBB0_2729
	s_waitcnt vmcnt(0)
	s_cmpk_lt_u32 s0, 0x100
	s_cbranch_scc0 .LBB0_2732
	s_barrier

.Lpw_15:
	s_setprio 1
	s_barrier
	v_mfma_f32_16x16x32_bf16 v[88:91], v[0:3], v[56:59], 0
	v_mfma_f32_16x16x32_bf16 v[64:67], v[0:3], v[32:35], 0
	v_mfma_f32_16x16x32_bf16 v[68:71], v[8:11], v[32:35], 0
	v_mfma_f32_16x16x32_bf16 v[72:75], v[0:3], v[40:43], 0
	v_mfma_f32_16x16x32_bf16 v[76:79], v[8:11], v[40:43], 0
	v_mfma_f32_16x16x32_bf16 v[80:83], v[0:3], v[48:51], 0
	v_mfma_f32_16x16x32_bf16 v[84:87], v[8:11], v[48:51], 0
	v_mfma_f32_16x16x32_bf16 v[96:99], v[4:7], v[60:63], v[88:91]
	v_mfma_f32_16x16x32_bf16 v[88:91], v[8:11], v[56:59], 0
	v_mfma_f32_16x16x32_bf16 v[64:67], v[4:7], v[36:39], v[64:67]
	v_mfma_f32_16x16x32_bf16 v[68:71], v[12:15], v[36:39], v[68:71]
	v_mfma_f32_16x16x32_bf16 v[72:75], v[4:7], v[44:47], v[72:75]
	v_mfma_f32_16x16x32_bf16 v[76:79], v[12:15], v[44:47], v[76:79]
	v_mfma_f32_16x16x32_bf16 v[80:83], v[4:7], v[52:55], v[80:83]
	v_mfma_f32_16x16x32_bf16 v[84:87], v[12:15], v[52:55], v[84:87]
	v_mfma_f32_16x16x32_bf16 v[100:103], v[12:15], v[60:63], v[88:91]
	v_mfma_f32_16x16x32_bf16 v[88:91], v[16:19], v[32:35], 0
	v_mfma_f32_16x16x32_bf16 v[32:35], v[24:27], v[32:35], 0
	v_mfma_f32_16x16x32_bf16 v[112:115], v[20:23], v[36:39], v[88:91]
	v_mfma_f32_16x16x32_bf16 v[32:35], v[28:31], v[36:39], v[32:35]
	v_mfma_f32_16x16x32_bf16 v[36:39], v[16:19], v[40:43], 0
	v_mfma_f32_16x16x32_bf16 v[40:43], v[24:27], v[40:43], 0
	v_mfma_f32_16x16x32_bf16 v[36:39], v[20:23], v[44:47], v[36:39]
	v_mfma_f32_16x16x32_bf16 v[40:43], v[28:31], v[44:47], v[40:43]
	v_mfma_f32_16x16x32_bf16 v[44:47], v[16:19], v[48:51], 0
	v_mfma_f32_16x16x32_bf16 v[48:51], v[24:27], v[48:51], 0
	v_mfma_f32_16x16x32_bf16 v[44:47], v[20:23], v[52:55], v[44:47]
	v_mfma_f32_16x16x32_bf16 v[48:51], v[28:31], v[52:55], v[48:51]
	v_mfma_f32_16x16x32_bf16 v[52:55], v[16:19], v[56:59], 0
	v_mfma_f32_16x16x32_bf16 v[56:59], v[24:27], v[56:59], 0
	v_mfma_f32_16x16x32_bf16 v[52:55], v[20:23], v[60:63], v[52:55]
	v_mfma_f32_16x16x32_bf16 v[56:59], v[28:31], v[60:63], v[56:59]
	s_barrier
	s_setprio 0
	s_add_i32 s63, s51, s15
	v_lshl_add_u64 v[242:243], s[72:73], 0, v[128:129]
	s_add_i32 s65, s63, 0x2000
	v_lshl_add_u64 v[148:149], v[242:243], 0, s[46:47]
	s_mov_b32 m0, s63
	v_lshl_add_u64 v[244:245], s[72:73], 0, v[130:131]
	s_add_u32 s76, s72, 0x80100
	ds_read_b128 v[60:63], v147 offset:16384
	ds_read_b128 v[88:91], v147 offset:17408
	ds_read_b128 v[92:95], v147 offset:18432
	ds_read_b128 v[104:107], v147 offset:19456
	ds_read_b128 v[108:111], v147 offset:20480
	ds_read_b128 v[116:119], v147 offset:21504
	ds_read_b128 v[120:123], v147 offset:22528
	ds_read_b128 v[124:127], v147 offset:23552
	global_load_lds_dwordx4 v[148:149], off
	v_lshl_add_u64 v[148:149], v[244:245], 0, s[46:47]
	s_mov_b32 m0, s65
	s_addc_u32 s77, s73, 0
	s_add_i32 s71, s52, s15
	global_load_lds_dwordx4 v[148:149], off
	v_lshl_add_u64 v[148:149], s[76:77], 0, v[128:129]
	s_mov_b32 m0, s71
	s_add_i32 s78, s71, 0x2000
	global_load_lds_dwordx4 v128, s[76:77]
	v_lshl_add_u64 v[148:149], s[76:77], 0, v[130:131]
	s_mov_b32 m0, s78
	v_lshl_add_u64 v[246:247], s[74:75], 0, v[134:135]
	global_load_lds_dwordx4 v130, s[76:77]
	v_lshl_add_u64 v[148:149], v[246:247], 0, s[46:47]
	s_mov_b32 m0, s22
	v_lshl_add_u64 v[248:249], s[74:75], 0, v[132:133]
	global_load_lds_dwordx4 v[148:149], off
	v_lshl_add_u64 v[148:149], v[248:249], 0, s[46:47]
	s_mov_b32 m0, s23
	s_nop 0
	global_load_lds_dwordx4 v[148:149], off
	s_waitcnt vmcnt(24) lgkmcnt(0)
	s_cmp_lg_u32 s98, 0
	s_cbranch_scc1 .Lpw_16
	s_waitcnt vmcnt(8)
.Lpw_16:
	s_setprio 1
	s_barrier
	v_mfma_f32_16x16x32_bf16 v[148:151], v[0:3], v[60:63], 0
	v_mfma_f32_16x16x32_bf16 v[158:161], v[0:3], v[92:95], 0
	v_mfma_f32_16x16x32_bf16 v[166:169], v[0:3], v[108:111], 0
	v_mfma_f32_16x16x32_bf16 v[0:3], v[0:3], v[120:123], 0
	v_mfma_f32_16x16x32_bf16 v[150:153], v[4:7], v[88:91], v[148:151]
	v_mfma_f32_16x16x32_bf16 v[158:161], v[4:7], v[104:107], v[158:161]
	v_mfma_f32_16x16x32_bf16 v[166:169], v[4:7], v[116:119], v[166:169]
	v_mfma_f32_16x16x32_bf16 v[0:3], v[4:7], v[124:127], v[0:3]
	v_mfma_f32_16x16x32_bf16 v[4:7], v[8:11], v[120:123], 0
	v_mfma_f32_16x16x32_bf16 v[154:157], v[8:11], v[60:63], 0
	v_mfma_f32_16x16x32_bf16 v[162:165], v[8:11], v[92:95], 0
	v_mfma_f32_16x16x32_bf16 v[170:173], v[8:11], v[108:111], 0
	v_mfma_f32_16x16x32_bf16 v[4:7], v[12:15], v[124:127], v[4:7]
	v_mfma_f32_16x16x32_bf16 v[154:157], v[12:15], v[88:91], v[154:157]
	v_mfma_f32_16x16x32_bf16 v[162:165], v[12:15], v[104:107], v[162:165]
	v_mfma_f32_16x16x32_bf16 v[170:173], v[12:15], v[116:119], v[170:173]
	v_mfma_f32_16x16x32_bf16 v[8:11], v[16:19], v[60:63], 0
	v_mfma_f32_16x16x32_bf16 v[174:177], v[20:23], v[88:91], v[8:11]
	v_mfma_f32_16x16x32_bf16 v[8:11], v[24:27], v[60:63], 0
	v_mfma_f32_16x16x32_bf16 v[60:63], v[28:31], v[88:91], v[8:11]
	v_mfma_f32_16x16x32_bf16 v[8:11], v[16:19], v[92:95], 0
	v_mfma_f32_16x16x32_bf16 v[178:181], v[20:23], v[104:107], v[8:11]
	v_mfma_f32_16x16x32_bf16 v[8:11], v[24:27], v[92:95], 0
	v_mfma_f32_16x16x32_bf16 v[182:185], v[28:31], v[104:107], v[8:11]
	v_mfma_f32_16x16x32_bf16 v[8:11], v[16:19], v[108:111], 0
	v_mfma_f32_16x16x32_bf16 v[186:189], v[20:23], v[116:119], v[8:11]
	v_mfma_f32_16x16x32_bf16 v[8:11], v[24:27], v[108:111], 0
	v_mfma_f32_16x16x32_bf16 v[190:193], v[28:31], v[116:119], v[8:11]
	v_mfma_f32_16x16x32_bf16 v[8:11], v[16:19], v[120:123], 0
	v_mfma_f32_16x16x32_bf16 v[194:197], v[20:23], v[124:127], v[8:11]
	v_mfma_f32_16x16x32_bf16 v[8:11], v[24:27], v[120:123], 0
	v_mfma_f32_16x16x32_bf16 v[198:201], v[28:31], v[124:127], v[8:11]
	s_barrier
; template <class Epi, class Sched, bool ALIGN_EPI = false, bool SP2 = false, bool A_TILED = false>
; __device__ __forceinline__ void gemm_phase(PG8_LAS unsigned char* lds, const Gemm g, const Sched& S, const Epi& E, const int wave_s) {
;     ...
;             const char* a1 = cA + kstepA; const char* a2 = cA + 2 * kstepA; const char* b2 = cB + 2 * kstep; const char* a3 = a2 + kstepA; const char* b3 = b2 + kstep;
;             PG8_ITER(PG8_MMAZ)
	s_setprio 0
	s_add_i32 s79, 0, 0x18000
	s_add_i32 s81, 0, 0x1c000
	v_add_u32_e32 v148, s79, v144
	v_add_u32_e32 v149, s81, v144
	s_nop 0
	ds_read_b128 v[8:11], v148
	ds_read_b128 v[12:15], v148 offset:1024
	ds_read_b128 v[16:19], v148 offset:2048
	ds_read_b128 v[20:23], v148 offset:3072
	ds_read_b128 v[202:205], v149
	ds_read_b128 v[206:209], v149 offset:1024
	ds_read_b128 v[210:213], v149 offset:2048
	ds_read_b128 v[214:217], v149 offset:3072
	s_add_u32 s76, s74, 0x80100
	s_addc_u32 s77, s75, 0
	s_mov_b32 m0, s36
	v_lshl_add_u64 v[88:89], s[76:77], 0, v[134:135]
	ds_read_b128 v[24:27], v147 offset:32768
	ds_read_b128 v[28:31], v147 offset:33792
	ds_read_b128 v[218:221], v147 offset:34816
	ds_read_b128 v[222:225], v147 offset:35840
	ds_read_b128 v[226:229], v147 offset:36864
	ds_read_b128 v[230:233], v147 offset:37888
	ds_read_b128 v[234:237], v147 offset:38912
	ds_read_b128 v[238:241], v147 offset:39936
	global_load_lds_dwordx4 v134, s[76:77]
	v_lshl_add_u64 v[88:89], s[76:77], 0, v[132:133]
	s_mov_b32 m0, s37
	s_nop 0
	global_load_lds_dwordx4 v132, s[76:77]
	s_waitcnt vmcnt(8) lgkmcnt(0)
	s_setprio 1
	s_barrier
	v_mfma_f32_16x16x32_bf16 v[64:67], v[8:11], v[24:27], v[64:67]
	v_mfma_f32_16x16x32_bf16 v[120:123], v[12:15], v[28:31], v[64:67]
	v_mfma_f32_16x16x32_bf16 v[64:67], v[16:19], v[24:27], v[68:71]
	v_mfma_f32_16x16x32_bf16 v[124:127], v[20:23], v[28:31], v[64:67]
	v_mfma_f32_16x16x32_bf16 v[64:67], v[8:11], v[218:221], v[72:75]
	v_mfma_f32_16x16x32_bf16 v[104:107], v[12:15], v[222:225], v[64:67]
	v_mfma_f32_16x16x32_bf16 v[64:67], v[16:19], v[218:221], v[76:79]
	v_mfma_f32_16x16x32_bf16 v[108:111], v[20:23], v[222:225], v[64:67]
	v_mfma_f32_16x16x32_bf16 v[64:67], v[8:11], v[226:229], v[80:83]
	v_mfma_f32_16x16x32_bf16 v[88:91], v[12:15], v[230:233], v[64:67]
	v_mfma_f32_16x16x32_bf16 v[64:67], v[16:19], v[226:229], v[84:87]
	v_mfma_f32_16x16x32_bf16 v[92:95], v[20:23], v[230:233], v[64:67]
	v_mfma_f32_16x16x32_bf16 v[64:67], v[8:11], v[234:237], v[96:99]
	v_mfma_f32_16x16x32_bf16 v[68:71], v[16:19], v[234:237], v[100:103]
	v_mfma_f32_16x16x32_bf16 v[64:67], v[12:15], v[238:241], v[64:67]
	v_mfma_f32_16x16x32_bf16 v[68:71], v[20:23], v[238:241], v[68:71]
	v_mfma_f32_16x16x32_bf16 v[72:75], v[202:205], v[24:27], v[112:115]
	v_mfma_f32_16x16x32_bf16 v[24:27], v[210:213], v[24:27], v[32:35]
	v_mfma_f32_16x16x32_bf16 v[116:119], v[214:217], v[28:31], v[24:27]
	v_mfma_f32_16x16x32_bf16 v[24:27], v[202:205], v[218:221], v[36:39]
	v_mfma_f32_16x16x32_bf16 v[96:99], v[206:209], v[222:225], v[24:27]
	v_mfma_f32_16x16x32_bf16 v[24:27], v[210:213], v[218:221], v[40:43]
	v_mfma_f32_16x16x32_bf16 v[100:103], v[214:217], v[222:225], v[24:27]
	v_mfma_f32_16x16x32_bf16 v[24:27], v[202:205], v[226:229], v[44:47]
	v_mfma_f32_16x16x32_bf16 v[80:83], v[206:209], v[230:233], v[24:27]
	v_mfma_f32_16x16x32_bf16 v[24:27], v[210:213], v[226:229], v[48:51]
	v_mfma_f32_16x16x32_bf16 v[84:87], v[214:217], v[230:233], v[24:27]
	v_mfma_f32_16x16x32_bf16 v[24:27], v[202:205], v[234:237], v[52:55]
	v_mfma_f32_16x16x32_bf16 v[48:51], v[206:209], v[238:241], v[24:27]
	v_mfma_f32_16x16x32_bf16 v[24:27], v[210:213], v[234:237], v[56:59]
	v_mfma_f32_16x16x32_bf16 v[112:115], v[206:209], v[28:31], v[72:75]
	v_mfma_f32_16x16x32_bf16 v[52:55], v[214:217], v[238:241], v[24:27]
	s_barrier
	s_setprio 0
	s_add_i32 s79, s79, s15
	s_add_i32 s80, s79, 0x2000
	s_nop 1
	v_lshl_add_u64 v[24:25], v[242:243], 0, s[60:61]
	s_mov_b32 m0, s79
	s_add_u32 s76, s72, 0x80180
	ds_read_b128 v[32:35], v147 offset:49152
	ds_read_b128 v[36:39], v147 offset:50176
	ds_read_b128 v[218:221], v147 offset:51200
	ds_read_b128 v[222:225], v147 offset:52224
	ds_read_b128 v[226:229], v147 offset:53248
	ds_read_b128 v[230:233], v147 offset:54272
	ds_read_b128 v[234:237], v147 offset:55296
	ds_read_b128 v[238:241], v147 offset:56320
	global_load_lds_dwordx4 v[24:25], off
	v_lshl_add_u64 v[24:25], v[244:245], 0, s[60:61]
	s_mov_b32 m0, s80
	s_addc_u32 s77, s73, 0
	s_add_i32 s81, s81, s15
	global_load_lds_dwordx4 v[24:25], off
	v_lshl_add_u64 v[24:25], s[76:77], 0, v[128:129]
	s_mov_b32 m0, s81
	s_add_i32 s82, s81, 0x2000
	global_load_lds_dwordx4 v128, s[76:77]
	v_lshl_add_u64 v[24:25], s[76:77], 0, v[130:131]
	s_mov_b32 m0, s82
	s_nop 0
	global_load_lds_dwordx4 v130, s[76:77]
	v_lshl_add_u64 v[24:25], v[246:247], 0, s[60:61]
	s_mov_b32 m0, s43
	s_nop 0
	global_load_lds_dwordx4 v[24:25], off
	v_lshl_add_u64 v[24:25], v[248:249], 0, s[60:61]
	s_mov_b32 m0, s48
	s_nop 0
	global_load_lds_dwordx4 v[24:25], off
	s_waitcnt vmcnt(8) lgkmcnt(0)
	s_setprio 1
	s_barrier
	v_mfma_f32_16x16x32_bf16 v[24:27], v[8:11], v[32:35], v[150:153]
	v_mfma_f32_16x16x32_bf16 v[72:75], v[12:15], v[36:39], v[24:27]
	v_mfma_f32_16x16x32_bf16 v[24:27], v[16:19], v[32:35], v[154:157]
	v_mfma_f32_16x16x32_bf16 v[76:79], v[20:23], v[36:39], v[24:27]
	v_mfma_f32_16x16x32_bf16 v[24:27], v[8:11], v[218:221], v[158:161]
	v_mfma_f32_16x16x32_bf16 v[40:43], v[12:15], v[222:225], v[24:27]
	v_mfma_f32_16x16x32_bf16 v[24:27], v[16:19], v[218:221], v[162:165]
	v_mfma_f32_16x16x32_bf16 v[0:3], v[8:11], v[234:237], v[0:3]
	v_mfma_f32_16x16x32_bf16 v[44:47], v[20:23], v[222:225], v[24:27]
	v_mfma_f32_16x16x32_bf16 v[24:27], v[8:11], v[226:229], v[166:169]
	v_mfma_f32_16x16x32_bf16 v[28:31], v[16:19], v[226:229], v[170:173]
	v_mfma_f32_16x16x32_bf16 v[8:11], v[12:15], v[238:241], v[0:3]
	v_mfma_f32_16x16x32_bf16 v[0:3], v[16:19], v[234:237], v[4:7]
	v_mfma_f32_16x16x32_bf16 v[24:27], v[12:15], v[230:233], v[24:27]
	v_mfma_f32_16x16x32_bf16 v[28:31], v[20:23], v[230:233], v[28:31]
	v_mfma_f32_16x16x32_bf16 v[12:15], v[20:23], v[238:241], v[0:3]
	v_mfma_f32_16x16x32_bf16 v[0:3], v[202:205], v[32:35], v[174:177]
	v_mfma_f32_16x16x32_bf16 v[56:59], v[206:209], v[36:39], v[0:3]
	v_mfma_f32_16x16x32_bf16 v[0:3], v[210:213], v[32:35], v[60:63]
	v_mfma_f32_16x16x32_bf16 v[60:63], v[214:217], v[36:39], v[0:3]
	v_mfma_f32_16x16x32_bf16 v[0:3], v[202:205], v[218:221], v[178:181]
	v_mfma_f32_16x16x32_bf16 v[32:35], v[206:209], v[222:225], v[0:3]
	v_mfma_f32_16x16x32_bf16 v[0:3], v[210:213], v[218:221], v[182:185]
	v_mfma_f32_16x16x32_bf16 v[36:39], v[214:217], v[222:225], v[0:3]
	v_mfma_f32_16x16x32_bf16 v[0:3], v[202:205], v[226:229], v[186:189]
	v_mfma_f32_16x16x32_bf16 v[16:19], v[206:209], v[230:233], v[0:3]
	v_mfma_f32_16x16x32_bf16 v[0:3], v[210:213], v[226:229], v[190:193]
	v_mfma_f32_16x16x32_bf16 v[20:23], v[214:217], v[230:233], v[0:3]
	v_mfma_f32_16x16x32_bf16 v[0:3], v[202:205], v[234:237], v[194:197]
	v_mfma_f32_16x16x32_bf16 v[4:7], v[210:213], v[234:237], v[198:201]
	v_mfma_f32_16x16x32_bf16 v[0:3], v[206:209], v[238:241], v[0:3]
	v_mfma_f32_16x16x32_bf16 v[4:7], v[214:217], v[238:241], v[4:7]
	s_barrier
	s_setprio 0
	s_add_u32 s83, s72, 0x200
	s_addc_u32 s85, s73, 0
	s_add_u32 s72, s74, 0x80180
	s_addc_u32 s73, s75, 0
	s_mov_b32 s88, 0
; template <class Epi, class Sched, bool ALIGN_EPI = false, bool SP2 = false, bool A_TILED = false>
; __device__ __forceinline__ void gemm_phase(PG8_LAS unsigned char* lds, const Gemm g, const Sched& S, const Epi& E, const int wave_s) {
;     ...
;         for (int t = PEEL ? 2 : 0; t < nt; t += 2) {
;             const bool last = (t == nt - 2);
;             const char* a1 = cA + (size_t)(t + 1) * kstepA;
;             const char* a2 = last ? nA : cA + (size_t)(t + 2) * kstepA; const char* b2 = last ? nB : cB + (size_t)(t + 2) * kstep;
;             const char* a3 = a2 + kstepA; const char* b3 = b2 + kstep;
.LBB0_2841:
	ds_read_b128 v[150:153], v145
	ds_read_b128 v[154:157], v145 offset:1024
	ds_read_b128 v[158:161], v145 offset:2048
	ds_read_b128 v[162:165], v145 offset:3072
	ds_read_b128 v[166:169], v146
	ds_read_b128 v[170:173], v146 offset:1024
	ds_read_b128 v[174:177], v146 offset:2048
	ds_read_b128 v[178:181], v146 offset:3072
	s_add_u32 s74, s72, 0xfff80080
	s_addc_u32 s75, s73, -1
	s_cmp_eq_u32 s88, 28
	s_cselect_b32 s77, s54, s75
	s_cselect_b32 s76, s55, s74
	s_cselect_b32 s75, s56, s85
	s_cselect_b32 s74, s57, s83
	s_mov_b32 m0, s58
	v_lshl_add_u64 v[214:215], s[72:73], 0, v[138:139]
	ds_read_b128 v[182:185], v147
	ds_read_b128 v[186:189], v147 offset:1024
	ds_read_b128 v[190:193], v147 offset:2048
	ds_read_b128 v[194:197], v147 offset:3072
	ds_read_b128 v[198:201], v147 offset:4096
	ds_read_b128 v[202:205], v147 offset:5120
	ds_read_b128 v[206:209], v147 offset:6144
	ds_read_b128 v[210:213], v147 offset:7168
	global_load_lds_dwordx4 v138, s[72:73]
	v_lshl_add_u64 v[214:215], s[72:73], 0, v[136:137]
	s_mov_b32 m0, s59
	s_nop 0
	global_load_lds_dwordx4 v136, s[72:73]
	s_waitcnt vmcnt(8) lgkmcnt(0)
	s_setprio 1
	s_barrier
	v_mfma_f32_16x16x32_bf16 v[120:123], v[150:153], v[182:185], v[120:123]
	v_mfma_f32_16x16x32_bf16 v[124:127], v[158:161], v[182:185], v[124:127]
	v_mfma_f32_16x16x32_bf16 v[104:107], v[150:153], v[190:193], v[104:107]
	v_mfma_f32_16x16x32_bf16 v[108:111], v[158:161], v[190:193], v[108:111]
	v_mfma_f32_16x16x32_bf16 v[88:91], v[150:153], v[198:201], v[88:91]
	v_mfma_f32_16x16x32_bf16 v[92:95], v[158:161], v[198:201], v[92:95]
	v_mfma_f32_16x16x32_bf16 v[64:67], v[150:153], v[206:209], v[64:67]
	v_mfma_f32_16x16x32_bf16 v[68:71], v[158:161], v[206:209], v[68:71]
	v_mfma_f32_16x16x32_bf16 v[120:123], v[154:157], v[186:189], v[120:123]
	v_mfma_f32_16x16x32_bf16 v[124:127], v[162:165], v[186:189], v[124:127]
	v_mfma_f32_16x16x32_bf16 v[104:107], v[154:157], v[194:197], v[104:107]
	v_mfma_f32_16x16x32_bf16 v[108:111], v[162:165], v[194:197], v[108:111]
	v_mfma_f32_16x16x32_bf16 v[88:91], v[154:157], v[202:205], v[88:91]
	v_mfma_f32_16x16x32_bf16 v[92:95], v[162:165], v[202:205], v[92:95]
	v_mfma_f32_16x16x32_bf16 v[64:67], v[154:157], v[210:213], v[64:67]
	v_mfma_f32_16x16x32_bf16 v[68:71], v[162:165], v[210:213], v[68:71]
	v_mfma_f32_16x16x32_bf16 v[112:115], v[166:169], v[182:185], v[112:115]
	v_mfma_f32_16x16x32_bf16 v[116:119], v[174:177], v[182:185], v[116:119]
	v_mfma_f32_16x16x32_bf16 v[96:99], v[166:169], v[190:193], v[96:99]
	v_mfma_f32_16x16x32_bf16 v[100:103], v[174:177], v[190:193], v[100:103]
	v_mfma_f32_16x16x32_bf16 v[80:83], v[166:169], v[198:201], v[80:83]
	v_mfma_f32_16x16x32_bf16 v[84:87], v[174:177], v[198:201], v[84:87]
	v_mfma_f32_16x16x32_bf16 v[48:51], v[166:169], v[206:209], v[48:51]
	v_mfma_f32_16x16x32_bf16 v[52:55], v[174:177], v[206:209], v[52:55]
	v_mfma_f32_16x16x32_bf16 v[112:115], v[170:173], v[186:189], v[112:115]
	v_mfma_f32_16x16x32_bf16 v[116:119], v[178:181], v[186:189], v[116:119]
	v_mfma_f32_16x16x32_bf16 v[96:99], v[170:173], v[194:197], v[96:99]
	v_mfma_f32_16x16x32_bf16 v[100:103], v[178:181], v[194:197], v[100:103]
	v_mfma_f32_16x16x32_bf16 v[80:83], v[170:173], v[202:205], v[80:83]
	v_mfma_f32_16x16x32_bf16 v[84:87], v[178:181], v[202:205], v[84:87]
	v_mfma_f32_16x16x32_bf16 v[48:51], v[170:173], v[210:213], v[48:51]
	v_mfma_f32_16x16x32_bf16 v[52:55], v[178:181], v[210:213], v[52:55]
	s_barrier
	s_setprio 0
	s_mov_b32 m0, s63
	v_lshl_add_u64 v[214:215], s[74:75], 0, v[128:129]
	s_add_u32 s90, s74, 0x80000
	ds_read_b128 v[182:185], v147 offset:16384
	ds_read_b128 v[186:189], v147 offset:17408
	ds_read_b128 v[190:193], v147 offset:18432
	ds_read_b128 v[194:197], v147 offset:19456
	ds_read_b128 v[198:201], v147 offset:20480
	ds_read_b128 v[202:205], v147 offset:21504
	ds_read_b128 v[206:209], v147 offset:22528
	ds_read_b128 v[210:213], v147 offset:23552
	global_load_lds_dwordx4 v128, s[74:75]
	v_lshl_add_u64 v[216:217], s[74:75], 0, v[130:131]
	s_mov_b32 m0, s65
	s_addc_u32 s91, s75, 0
	global_load_lds_dwordx4 v130, s[74:75]
	v_lshl_add_u64 v[218:219], s[90:91], 0, v[128:129]
	s_mov_b32 m0, s71
	v_lshl_add_u64 v[220:221], s[76:77], 0, v[132:133]
	global_load_lds_dwordx4 v128, s[90:91]
	v_lshl_add_u64 v[218:219], s[90:91], 0, v[130:131]
	s_mov_b32 m0, s78
	s_nop 0
	global_load_lds_dwordx4 v130, s[90:91]
	v_lshl_add_u64 v[218:219], s[76:77], 0, v[134:135]
	s_mov_b32 m0, s22
	s_nop 0
	global_load_lds_dwordx4 v134, s[76:77]
	s_mov_b32 m0, s23
	s_nop 0
	global_load_lds_dwordx4 v132, s[76:77]
	s_waitcnt vmcnt(8) lgkmcnt(0)
	s_setprio 1
	s_barrier
	v_mfma_f32_16x16x32_bf16 v[72:75], v[150:153], v[182:185], v[72:75]
	v_mfma_f32_16x16x32_bf16 v[76:79], v[158:161], v[182:185], v[76:79]
	v_mfma_f32_16x16x32_bf16 v[40:43], v[150:153], v[190:193], v[40:43]
	v_mfma_f32_16x16x32_bf16 v[44:47], v[158:161], v[190:193], v[44:47]
	v_mfma_f32_16x16x32_bf16 v[24:27], v[150:153], v[198:201], v[24:27]
	v_mfma_f32_16x16x32_bf16 v[28:31], v[158:161], v[198:201], v[28:31]
	v_mfma_f32_16x16x32_bf16 v[8:11], v[150:153], v[206:209], v[8:11]
	v_mfma_f32_16x16x32_bf16 v[12:15], v[158:161], v[206:209], v[12:15]
	v_mfma_f32_16x16x32_bf16 v[72:75], v[154:157], v[186:189], v[72:75]
	v_mfma_f32_16x16x32_bf16 v[76:79], v[162:165], v[186:189], v[76:79]
	v_mfma_f32_16x16x32_bf16 v[40:43], v[154:157], v[194:197], v[40:43]
	v_mfma_f32_16x16x32_bf16 v[44:47], v[162:165], v[194:197], v[44:47]
	v_mfma_f32_16x16x32_bf16 v[24:27], v[154:157], v[202:205], v[24:27]
	v_mfma_f32_16x16x32_bf16 v[28:31], v[162:165], v[202:205], v[28:31]
	v_mfma_f32_16x16x32_bf16 v[8:11], v[154:157], v[210:213], v[8:11]
	v_mfma_f32_16x16x32_bf16 v[12:15], v[162:165], v[210:213], v[12:15]
	v_mfma_f32_16x16x32_bf16 v[56:59], v[166:169], v[182:185], v[56:59]
	v_mfma_f32_16x16x32_bf16 v[60:63], v[174:177], v[182:185], v[60:63]
	v_mfma_f32_16x16x32_bf16 v[32:35], v[166:169], v[190:193], v[32:35]
	v_mfma_f32_16x16x32_bf16 v[36:39], v[174:177], v[190:193], v[36:39]
	v_mfma_f32_16x16x32_bf16 v[16:19], v[166:169], v[198:201], v[16:19]
	v_mfma_f32_16x16x32_bf16 v[20:23], v[174:177], v[198:201], v[20:23]
	v_mfma_f32_16x16x32_bf16 v[0:3], v[166:169], v[206:209], v[0:3]
	v_mfma_f32_16x16x32_bf16 v[4:7], v[174:177], v[206:209], v[4:7]
	v_mfma_f32_16x16x32_bf16 v[56:59], v[170:173], v[186:189], v[56:59]
	v_mfma_f32_16x16x32_bf16 v[60:63], v[178:181], v[186:189], v[60:63]
	v_mfma_f32_16x16x32_bf16 v[32:35], v[170:173], v[194:197], v[32:35]
	v_mfma_f32_16x16x32_bf16 v[36:39], v[178:181], v[194:197], v[36:39]
	v_mfma_f32_16x16x32_bf16 v[16:19], v[170:173], v[202:205], v[16:19]
	v_mfma_f32_16x16x32_bf16 v[20:23], v[178:181], v[202:205], v[20:23]
	v_mfma_f32_16x16x32_bf16 v[0:3], v[170:173], v[210:213], v[0:3]
	v_mfma_f32_16x16x32_bf16 v[4:7], v[178:181], v[210:213], v[4:7]
	s_barrier
	s_setprio 0
	ds_read_b128 v[150:153], v148
	ds_read_b128 v[154:157], v148 offset:1024
	ds_read_b128 v[158:161], v148 offset:2048
	ds_read_b128 v[162:165], v148 offset:3072
	ds_read_b128 v[166:169], v149
	ds_read_b128 v[170:173], v149 offset:1024
	ds_read_b128 v[174:177], v149 offset:2048
	ds_read_b128 v[178:181], v149 offset:3072
	s_add_u32 s76, s76, 0x80000
	s_addc_u32 s77, s77, 0
	s_mov_b32 m0, s36
	v_lshl_add_u64 v[222:223], s[76:77], 0, v[134:135]
	ds_read_b128 v[182:185], v147 offset:32768
	ds_read_b128 v[186:189], v147 offset:33792
	ds_read_b128 v[190:193], v147 offset:34816
	ds_read_b128 v[194:197], v147 offset:35840
	ds_read_b128 v[198:201], v147 offset:36864
	ds_read_b128 v[202:205], v147 offset:37888
	ds_read_b128 v[206:209], v147 offset:38912
	ds_read_b128 v[210:213], v147 offset:39936
	global_load_lds_dwordx4 v134, s[76:77]
	v_lshl_add_u64 v[222:223], s[76:77], 0, v[132:133]
	s_mov_b32 m0, s37
	s_nop 0
	global_load_lds_dwordx4 v132, s[76:77]
	s_waitcnt vmcnt(8) lgkmcnt(0)
	s_setprio 1
	s_barrier
	v_mfma_f32_16x16x32_bf16 v[120:123], v[150:153], v[182:185], v[120:123]
	v_mfma_f32_16x16x32_bf16 v[124:127], v[158:161], v[182:185], v[124:127]
	v_mfma_f32_16x16x32_bf16 v[104:107], v[150:153], v[190:193], v[104:107]
	v_mfma_f32_16x16x32_bf16 v[108:111], v[158:161], v[190:193], v[108:111]
	v_mfma_f32_16x16x32_bf16 v[88:91], v[150:153], v[198:201], v[88:91]
	v_mfma_f32_16x16x32_bf16 v[92:95], v[158:161], v[198:201], v[92:95]
	v_mfma_f32_16x16x32_bf16 v[64:67], v[150:153], v[206:209], v[64:67]
	v_mfma_f32_16x16x32_bf16 v[68:71], v[158:161], v[206:209], v[68:71]
	v_mfma_f32_16x16x32_bf16 v[120:123], v[154:157], v[186:189], v[120:123]
	v_mfma_f32_16x16x32_bf16 v[124:127], v[162:165], v[186:189], v[124:127]
	v_mfma_f32_16x16x32_bf16 v[104:107], v[154:157], v[194:197], v[104:107]
	v_mfma_f32_16x16x32_bf16 v[108:111], v[162:165], v[194:197], v[108:111]
	v_mfma_f32_16x16x32_bf16 v[88:91], v[154:157], v[202:205], v[88:91]
	v_mfma_f32_16x16x32_bf16 v[92:95], v[162:165], v[202:205], v[92:95]
	v_mfma_f32_16x16x32_bf16 v[64:67], v[154:157], v[210:213], v[64:67]
	v_mfma_f32_16x16x32_bf16 v[68:71], v[162:165], v[210:213], v[68:71]
	v_mfma_f32_16x16x32_bf16 v[112:115], v[166:169], v[182:185], v[112:115]
	v_mfma_f32_16x16x32_bf16 v[116:119], v[174:177], v[182:185], v[116:119]
	v_mfma_f32_16x16x32_bf16 v[96:99], v[166:169], v[190:193], v[96:99]
	v_mfma_f32_16x16x32_bf16 v[100:103], v[174:177], v[190:193], v[100:103]
	v_mfma_f32_16x16x32_bf16 v[80:83], v[166:169], v[198:201], v[80:83]
	v_mfma_f32_16x16x32_bf16 v[84:87], v[174:177], v[198:201], v[84:87]
	v_mfma_f32_16x16x32_bf16 v[48:51], v[166:169], v[206:209], v[48:51]
	v_mfma_f32_16x16x32_bf16 v[52:55], v[174:177], v[206:209], v[52:55]
	v_mfma_f32_16x16x32_bf16 v[112:115], v[170:173], v[186:189], v[112:115]
	v_mfma_f32_16x16x32_bf16 v[116:119], v[178:181], v[186:189], v[116:119]
	v_mfma_f32_16x16x32_bf16 v[96:99], v[170:173], v[194:197], v[96:99]
	v_mfma_f32_16x16x32_bf16 v[100:103], v[178:181], v[194:197], v[100:103]
	v_mfma_f32_16x16x32_bf16 v[80:83], v[170:173], v[202:205], v[80:83]
	v_mfma_f32_16x16x32_bf16 v[84:87], v[178:181], v[202:205], v[84:87]
	v_mfma_f32_16x16x32_bf16 v[48:51], v[170:173], v[210:213], v[48:51]
	v_mfma_f32_16x16x32_bf16 v[52:55], v[178:181], v[210:213], v[52:55]
	s_barrier
; #define PG8_BAR __builtin_amdgcn_s_barrier()
; template <class Epi, class Sched, bool ALIGN_EPI = false, bool SP2 = false, bool A_TILED = false>
; __device__ __forceinline__ void gemm_phase(PG8_LAS unsigned char* lds, const Gemm g, const Sched& S, const Epi& E, const int wave_s) {
;     ...
;         if constexpr (ALIGN_EPI) { if (wr == 0) PG8_BAR; }
	s_setprio 0
	s_mov_b32 m0, s79
	v_lshl_add_u64 v[214:215], v[214:215], 0, s[12:13]
	s_add_u32 s74, s74, 0x80080
	ds_read_b128 v[182:185], v147 offset:49152
	ds_read_b128 v[186:189], v147 offset:50176
	ds_read_b128 v[190:193], v147 offset:51200
	ds_read_b128 v[194:197], v147 offset:52224
	ds_read_b128 v[198:201], v147 offset:53248
	ds_read_b128 v[202:205], v147 offset:54272
	ds_read_b128 v[206:209], v147 offset:55296
	ds_read_b128 v[210:213], v147 offset:56320
	global_load_lds_dwordx4 v[214:215], off
	v_lshl_add_u64 v[214:215], v[216:217], 0, s[12:13]
	s_mov_b32 m0, s80
	s_addc_u32 s75, s75, 0
	global_load_lds_dwordx4 v[214:215], off
	v_lshl_add_u64 v[214:215], s[74:75], 0, v[128:129]
	s_mov_b32 m0, s81
	s_nop 0
	global_load_lds_dwordx4 v128, s[74:75]
	v_lshl_add_u64 v[214:215], s[74:75], 0, v[130:131]
	s_mov_b32 m0, s82
	s_nop 0
	global_load_lds_dwordx4 v130, s[74:75]
	v_lshl_add_u64 v[214:215], v[218:219], 0, s[12:13]
	s_mov_b32 m0, s43
	s_nop 0
	global_load_lds_dwordx4 v[214:215], off
	v_lshl_add_u64 v[214:215], v[220:221], 0, s[12:13]
	s_mov_b32 m0, s48
	s_nop 0
	global_load_lds_dwordx4 v[214:215], off
	s_waitcnt vmcnt(8) lgkmcnt(0)
	s_setprio 1
	s_barrier
	v_mfma_f32_16x16x32_bf16 v[72:75], v[150:153], v[182:185], v[72:75]
	v_mfma_f32_16x16x32_bf16 v[76:79], v[158:161], v[182:185], v[76:79]
	v_mfma_f32_16x16x32_bf16 v[40:43], v[150:153], v[190:193], v[40:43]
	v_mfma_f32_16x16x32_bf16 v[44:47], v[158:161], v[190:193], v[44:47]
	v_mfma_f32_16x16x32_bf16 v[24:27], v[150:153], v[198:201], v[24:27]
	v_mfma_f32_16x16x32_bf16 v[28:31], v[158:161], v[198:201], v[28:31]
	v_mfma_f32_16x16x32_bf16 v[8:11], v[150:153], v[206:209], v[8:11]
	v_mfma_f32_16x16x32_bf16 v[12:15], v[158:161], v[206:209], v[12:15]
	v_mfma_f32_16x16x32_bf16 v[72:75], v[154:157], v[186:189], v[72:75]
	v_mfma_f32_16x16x32_bf16 v[76:79], v[162:165], v[186:189], v[76:79]
	v_mfma_f32_16x16x32_bf16 v[40:43], v[154:157], v[194:197], v[40:43]
	v_mfma_f32_16x16x32_bf16 v[44:47], v[162:165], v[194:197], v[44:47]
	v_mfma_f32_16x16x32_bf16 v[24:27], v[154:157], v[202:205], v[24:27]
	v_mfma_f32_16x16x32_bf16 v[28:31], v[162:165], v[202:205], v[28:31]
	v_mfma_f32_16x16x32_bf16 v[8:11], v[154:157], v[210:213], v[8:11]
	v_mfma_f32_16x16x32_bf16 v[12:15], v[162:165], v[210:213], v[12:15]
	v_mfma_f32_16x16x32_bf16 v[56:59], v[166:169], v[182:185], v[56:59]
	v_mfma_f32_16x16x32_bf16 v[60:63], v[174:177], v[182:185], v[60:63]
	v_mfma_f32_16x16x32_bf16 v[32:35], v[166:169], v[190:193], v[32:35]
	v_mfma_f32_16x16x32_bf16 v[36:39], v[174:177], v[190:193], v[36:39]
	v_mfma_f32_16x16x32_bf16 v[16:19], v[166:169], v[198:201], v[16:19]
	v_mfma_f32_16x16x32_bf16 v[20:23], v[174:177], v[198:201], v[20:23]
	v_mfma_f32_16x16x32_bf16 v[0:3], v[166:169], v[206:209], v[0:3]
	v_mfma_f32_16x16x32_bf16 v[4:7], v[174:177], v[206:209], v[4:7]
	v_mfma_f32_16x16x32_bf16 v[56:59], v[170:173], v[186:189], v[56:59]
	v_mfma_f32_16x16x32_bf16 v[60:63], v[178:181], v[186:189], v[60:63]
	v_mfma_f32_16x16x32_bf16 v[32:35], v[170:173], v[194:197], v[32:35]
	v_mfma_f32_16x16x32_bf16 v[36:39], v[178:181], v[194:197], v[36:39]
	v_mfma_f32_16x16x32_bf16 v[16:19], v[170:173], v[202:205], v[16:19]
	v_mfma_f32_16x16x32_bf16 v[20:23], v[178:181], v[202:205], v[20:23]
	v_mfma_f32_16x16x32_bf16 v[0:3], v[170:173], v[210:213], v[0:3]
	v_mfma_f32_16x16x32_bf16 v[4:7], v[178:181], v[210:213], v[4:7]
	s_barrier
	s_setprio 0
	s_add_i32 s88, s88, 2
	s_add_u32 s83, s83, 0x100
	s_addc_u32 s85, s85, 0
	s_add_u32 s72, s72, 0x100
	s_addc_u32 s73, s73, 0
	s_cmp_gt_u32 s88, 29
	s_cbranch_scc0 .LBB0_2841
	s_and_b64 vcc, exec, s[44:45]
	s_cbranch_vccz .LBB0_2844
	s_barrier

; template <class Epi, class Sched, bool ALIGN_EPI = false, bool SP2 = false, bool A_TILED = false>
; __device__ __forceinline__ void gemm_phase(PG8_LAS unsigned char* lds, const Gemm g, const Sched& S, const Epi& E, const int wave_s) {
;     ...
;         for (int t = PEEL ? 2 : 0; t < nt; t += 2) {
;             const bool last = (t == nt - 2);
;             const char* a1 = cA + (size_t)(t + 1) * kstepA;
;             const char* a2 = last ? nA : cA + (size_t)(t + 2) * kstepA; const char* b2 = last ? nB : cB + (size_t)(t + 2) * kstep;
;             const char* a3 = a2 + kstepA; const char* b3 = b2 + kstep;
.LBB0_2914:
	ds_read_b128 v[146:149], v140
	ds_read_b128 v[150:153], v140 offset:1024
	ds_read_b128 v[154:157], v140 offset:2048
	ds_read_b128 v[158:161], v140 offset:3072
	ds_read_b128 v[162:165], v141
	ds_read_b128 v[166:169], v141 offset:1024
	ds_read_b128 v[170:173], v141 offset:2048
	ds_read_b128 v[174:177], v141 offset:3072
	s_add_u32 s55, s44, s39
	s_addc_u32 s56, s45, s40
	s_add_u32 s57, s44, s37
	s_addc_u32 s58, s45, s38
	s_cmpk_eq_i32 s41, 0x7c
	s_cselect_b32 s68, s6, s55
	s_cselect_b32 s69, s7, s56
	s_cselect_b32 s66, s2, s57
	s_cselect_b32 s67, s3, s58
	s_add_u32 s64, s68, 0x8000
	s_addc_u32 s65, s69, 0
	s_mov_b32 m0, s42
	v_lshl_add_u64 v[210:211], s[44:45], 0, v[138:139]
	ds_read_b128 v[178:181], v142
	ds_read_b128 v[182:185], v142 offset:1024
	ds_read_b128 v[186:189], v142 offset:2048
	ds_read_b128 v[190:193], v142 offset:3072
	ds_read_b128 v[194:197], v142 offset:4096
	ds_read_b128 v[198:201], v142 offset:5120
	ds_read_b128 v[202:205], v142 offset:6144
	ds_read_b128 v[206:209], v142 offset:7168
	global_load_lds_dwordx4 v[210:211], off
	v_lshl_add_u64 v[210:211], s[44:45], 0, v[136:137]
	s_mov_b32 m0, s43
	s_nop 0
	global_load_lds_dwordx4 v[210:211], off
	s_waitcnt vmcnt(8) lgkmcnt(0)
	s_setprio 1
	s_barrier
	v_mfma_f32_16x16x32_bf16 v[8:11], v[146:149], v[178:181], v[8:11]
	v_mfma_f32_16x16x32_bf16 v[12:15], v[154:157], v[178:181], v[12:15]
	v_mfma_f32_16x16x32_bf16 v[60:63], v[146:149], v[186:189], v[60:63]
	v_mfma_f32_16x16x32_bf16 v[20:23], v[154:157], v[186:189], v[20:23]
	v_mfma_f32_16x16x32_bf16 v[76:79], v[146:149], v[194:197], v[76:79]
	v_mfma_f32_16x16x32_bf16 v[52:55], v[154:157], v[194:197], v[52:55]
	v_mfma_f32_16x16x32_bf16 v[128:131], v[146:149], v[202:205], v[128:131]
	v_mfma_f32_16x16x32_bf16 v[68:71], v[154:157], v[202:205], v[68:71]
	v_mfma_f32_16x16x32_bf16 v[8:11], v[150:153], v[182:185], v[8:11]
	v_mfma_f32_16x16x32_bf16 v[12:15], v[158:161], v[182:185], v[12:15]
	v_mfma_f32_16x16x32_bf16 v[60:63], v[150:153], v[190:193], v[60:63]
	v_mfma_f32_16x16x32_bf16 v[20:23], v[158:161], v[190:193], v[20:23]
	v_mfma_f32_16x16x32_bf16 v[76:79], v[150:153], v[198:201], v[76:79]
	v_mfma_f32_16x16x32_bf16 v[52:55], v[158:161], v[198:201], v[52:55]
	v_mfma_f32_16x16x32_bf16 v[128:131], v[150:153], v[206:209], v[128:131]
	v_mfma_f32_16x16x32_bf16 v[68:71], v[158:161], v[206:209], v[68:71]
	v_mfma_f32_16x16x32_bf16 v[28:31], v[162:165], v[178:181], v[28:31]
	v_mfma_f32_16x16x32_bf16 v[16:19], v[170:173], v[178:181], v[16:19]
	v_mfma_f32_16x16x32_bf16 v[56:59], v[162:165], v[186:189], v[56:59]
	v_mfma_f32_16x16x32_bf16 v[48:51], v[170:173], v[186:189], v[48:51]
	v_mfma_f32_16x16x32_bf16 v[72:75], v[162:165], v[194:197], v[72:75]
	v_mfma_f32_16x16x32_bf16 v[64:67], v[170:173], v[194:197], v[64:67]
	v_mfma_f32_16x16x32_bf16 v[108:111], v[162:165], v[202:205], v[108:111]
	v_mfma_f32_16x16x32_bf16 v[96:99], v[170:173], v[202:205], v[96:99]
	v_mfma_f32_16x16x32_bf16 v[28:31], v[166:169], v[182:185], v[28:31]
	v_mfma_f32_16x16x32_bf16 v[16:19], v[174:177], v[182:185], v[16:19]
	v_mfma_f32_16x16x32_bf16 v[56:59], v[166:169], v[190:193], v[56:59]
	v_mfma_f32_16x16x32_bf16 v[48:51], v[174:177], v[190:193], v[48:51]
	v_mfma_f32_16x16x32_bf16 v[72:75], v[166:169], v[198:201], v[72:75]
	v_mfma_f32_16x16x32_bf16 v[64:67], v[174:177], v[198:201], v[64:67]
	v_mfma_f32_16x16x32_bf16 v[108:111], v[166:169], v[206:209], v[108:111]
	v_mfma_f32_16x16x32_bf16 v[96:99], v[174:177], v[206:209], v[96:99]
	s_barrier
	s_setprio 0
	s_mov_b32 m0, s47
	v_lshl_add_u64 v[210:211], s[66:67], 0, v[34:35]
	s_add_u32 s56, s66, 0x200000
	ds_read_b128 v[178:181], v142 offset:16384
	ds_read_b128 v[182:185], v142 offset:17408
	ds_read_b128 v[186:189], v142 offset:18432
	ds_read_b128 v[190:193], v142 offset:19456
	ds_read_b128 v[194:197], v142 offset:20480
	ds_read_b128 v[198:201], v142 offset:21504
	ds_read_b128 v[202:205], v142 offset:22528
	ds_read_b128 v[206:209], v142 offset:23552
	global_load_lds_dwordx4 v34, s[66:67]
	v_lshl_add_u64 v[212:213], s[66:67], 0, v[134:135]
	s_mov_b32 m0, s48
	s_addc_u32 s57, s67, 0
	global_load_lds_dwordx4 v134, s[66:67]
	v_lshl_add_u64 v[214:215], s[56:57], 0, v[34:35]
	s_mov_b32 m0, s49
	s_nop 0
	global_load_lds_dwordx4 v34, s[56:57]
	v_lshl_add_u64 v[214:215], s[56:57], 0, v[134:135]
	s_mov_b32 m0, s50
	s_nop 0
	global_load_lds_dwordx4 v134, s[56:57]
	v_lshl_add_u64 v[214:215], s[68:69], 0, v[32:33]
	s_mov_b32 m0, s14
	s_nop 0
	global_load_lds_dwordx4 v32, s[68:69]
	v_lshl_add_u64 v[214:215], s[68:69], 0, v[132:133]
	s_mov_b32 m0, s15
	s_nop 0
	global_load_lds_dwordx4 v132, s[68:69]
	s_waitcnt vmcnt(8) lgkmcnt(0)
	s_setprio 1
	s_barrier
	v_mfma_f32_16x16x32_bf16 v[100:103], v[146:149], v[178:181], v[100:103]
	v_mfma_f32_16x16x32_bf16 v[104:107], v[154:157], v[178:181], v[104:107]
	v_mfma_f32_16x16x32_bf16 v[116:119], v[146:149], v[186:189], v[116:119]
	v_mfma_f32_16x16x32_bf16 v[120:123], v[154:157], v[186:189], v[120:123]
	v_mfma_f32_16x16x32_bf16 v[84:87], v[146:149], v[194:197], v[84:87]
	v_mfma_f32_16x16x32_bf16 v[80:83], v[154:157], v[194:197], v[80:83]
	v_mfma_f32_16x16x32_bf16 v[36:39], v[146:149], v[202:205], v[36:39]
	v_mfma_f32_16x16x32_bf16 v[24:27], v[154:157], v[202:205], v[24:27]
	v_mfma_f32_16x16x32_bf16 v[100:103], v[150:153], v[182:185], v[100:103]
	v_mfma_f32_16x16x32_bf16 v[104:107], v[158:161], v[182:185], v[104:107]
	v_mfma_f32_16x16x32_bf16 v[116:119], v[150:153], v[190:193], v[116:119]
	v_mfma_f32_16x16x32_bf16 v[120:123], v[158:161], v[190:193], v[120:123]
	v_mfma_f32_16x16x32_bf16 v[84:87], v[150:153], v[198:201], v[84:87]
	v_mfma_f32_16x16x32_bf16 v[80:83], v[158:161], v[198:201], v[80:83]
	v_mfma_f32_16x16x32_bf16 v[36:39], v[150:153], v[206:209], v[36:39]
	v_mfma_f32_16x16x32_bf16 v[24:27], v[158:161], v[206:209], v[24:27]
	v_mfma_f32_16x16x32_bf16 v[124:127], v[162:165], v[178:181], v[124:127]
	v_mfma_f32_16x16x32_bf16 v[112:115], v[170:173], v[178:181], v[112:115]
	v_mfma_f32_16x16x32_bf16 v[92:95], v[162:165], v[186:189], v[92:95]
	v_mfma_f32_16x16x32_bf16 v[88:91], v[170:173], v[186:189], v[88:91]
	v_mfma_f32_16x16x32_bf16 v[44:47], v[162:165], v[194:197], v[44:47]
	v_mfma_f32_16x16x32_bf16 v[40:43], v[170:173], v[194:197], v[40:43]
	v_mfma_f32_16x16x32_bf16 v[4:7], v[162:165], v[202:205], v[4:7]
	v_mfma_f32_16x16x32_bf16 v[0:3], v[170:173], v[202:205], v[0:3]
	v_mfma_f32_16x16x32_bf16 v[124:127], v[166:169], v[182:185], v[124:127]
	v_mfma_f32_16x16x32_bf16 v[112:115], v[174:177], v[182:185], v[112:115]
	v_mfma_f32_16x16x32_bf16 v[92:95], v[166:169], v[190:193], v[92:95]
	v_mfma_f32_16x16x32_bf16 v[88:91], v[174:177], v[190:193], v[88:91]
	v_mfma_f32_16x16x32_bf16 v[44:47], v[166:169], v[198:201], v[44:47]
	v_mfma_f32_16x16x32_bf16 v[40:43], v[174:177], v[198:201], v[40:43]
	v_mfma_f32_16x16x32_bf16 v[4:7], v[166:169], v[206:209], v[4:7]
	v_mfma_f32_16x16x32_bf16 v[0:3], v[174:177], v[206:209], v[0:3]
	s_barrier
	s_setprio 0
	ds_read_b128 v[146:149], v143
	ds_read_b128 v[150:153], v143 offset:1024
	ds_read_b128 v[154:157], v143 offset:2048
	ds_read_b128 v[158:161], v143 offset:3072
	ds_read_b128 v[162:165], v144
	ds_read_b128 v[166:169], v144 offset:1024
	ds_read_b128 v[170:173], v144 offset:2048
	ds_read_b128 v[174:177], v144 offset:3072
	s_add_u32 s56, s68, 0x4000
	s_addc_u32 s57, s69, 0
	s_mov_b32 m0, s21
	v_lshl_add_u64 v[214:215], s[56:57], 0, v[32:33]
	ds_read_b128 v[178:181], v142 offset:32768
	ds_read_b128 v[182:185], v142 offset:33792
	ds_read_b128 v[186:189], v142 offset:34816
	ds_read_b128 v[190:193], v142 offset:35840
	ds_read_b128 v[194:197], v142 offset:36864
	ds_read_b128 v[198:201], v142 offset:37888
	ds_read_b128 v[202:205], v142 offset:38912
	ds_read_b128 v[206:209], v142 offset:39936
	global_load_lds_dwordx4 v32, s[56:57]
	v_lshl_add_u64 v[214:215], s[56:57], 0, v[132:133]
	s_mov_b32 m0, s22
	s_nop 0
	global_load_lds_dwordx4 v132, s[56:57]
	s_waitcnt vmcnt(8) lgkmcnt(0)
	s_setprio 1
	s_barrier
	v_mfma_f32_16x16x32_bf16 v[8:11], v[146:149], v[178:181], v[8:11]
	v_mfma_f32_16x16x32_bf16 v[12:15], v[154:157], v[178:181], v[12:15]
	v_mfma_f32_16x16x32_bf16 v[60:63], v[146:149], v[186:189], v[60:63]
	v_mfma_f32_16x16x32_bf16 v[20:23], v[154:157], v[186:189], v[20:23]
	v_mfma_f32_16x16x32_bf16 v[76:79], v[146:149], v[194:197], v[76:79]
	v_mfma_f32_16x16x32_bf16 v[52:55], v[154:157], v[194:197], v[52:55]
	v_mfma_f32_16x16x32_bf16 v[128:131], v[146:149], v[202:205], v[128:131]
	v_mfma_f32_16x16x32_bf16 v[68:71], v[154:157], v[202:205], v[68:71]
	v_mfma_f32_16x16x32_bf16 v[8:11], v[150:153], v[182:185], v[8:11]
	v_mfma_f32_16x16x32_bf16 v[12:15], v[158:161], v[182:185], v[12:15]
	v_mfma_f32_16x16x32_bf16 v[60:63], v[150:153], v[190:193], v[60:63]
	v_mfma_f32_16x16x32_bf16 v[20:23], v[158:161], v[190:193], v[20:23]
	v_mfma_f32_16x16x32_bf16 v[76:79], v[150:153], v[198:201], v[76:79]
	v_mfma_f32_16x16x32_bf16 v[52:55], v[158:161], v[198:201], v[52:55]
	v_mfma_f32_16x16x32_bf16 v[128:131], v[150:153], v[206:209], v[128:131]
	v_mfma_f32_16x16x32_bf16 v[68:71], v[158:161], v[206:209], v[68:71]
	v_mfma_f32_16x16x32_bf16 v[28:31], v[162:165], v[178:181], v[28:31]
	v_mfma_f32_16x16x32_bf16 v[16:19], v[170:173], v[178:181], v[16:19]
	v_mfma_f32_16x16x32_bf16 v[56:59], v[162:165], v[186:189], v[56:59]
	v_mfma_f32_16x16x32_bf16 v[48:51], v[170:173], v[186:189], v[48:51]
	v_mfma_f32_16x16x32_bf16 v[72:75], v[162:165], v[194:197], v[72:75]
	v_mfma_f32_16x16x32_bf16 v[64:67], v[170:173], v[194:197], v[64:67]
	v_mfma_f32_16x16x32_bf16 v[108:111], v[162:165], v[202:205], v[108:111]
	v_mfma_f32_16x16x32_bf16 v[96:99], v[170:173], v[202:205], v[96:99]
	v_mfma_f32_16x16x32_bf16 v[28:31], v[166:169], v[182:185], v[28:31]
	v_mfma_f32_16x16x32_bf16 v[16:19], v[174:177], v[182:185], v[16:19]
	v_mfma_f32_16x16x32_bf16 v[56:59], v[166:169], v[190:193], v[56:59]
	v_mfma_f32_16x16x32_bf16 v[48:51], v[174:177], v[190:193], v[48:51]
	v_mfma_f32_16x16x32_bf16 v[72:75], v[166:169], v[198:201], v[72:75]
	v_mfma_f32_16x16x32_bf16 v[64:67], v[174:177], v[198:201], v[64:67]
	v_mfma_f32_16x16x32_bf16 v[108:111], v[166:169], v[206:209], v[108:111]
	v_mfma_f32_16x16x32_bf16 v[96:99], v[174:177], v[206:209], v[96:99]
	s_barrier
; #define PG8_WAIT_V(n) asm volatile("s_waitcnt vmcnt(" #n ")" ::: "memory")
; #define PG8_BAR __builtin_amdgcn_s_barrier()
; template <class Epi, class Sched, bool ALIGN_EPI = false, bool SP2 = false, bool A_TILED = false>
; __device__ __forceinline__ void gemm_phase(PG8_LAS unsigned char* lds, const Gemm g, const Sched& S, const Epi& E, const int wave_s) {
;     ...
;     PG8_WAIT_V(0);
;     if constexpr (!ALIGN_EPI) { if (wr == 0) PG8_BAR; }
	s_setprio 0
	s_mov_b32 m0, s51
	v_lshl_add_u64 v[210:211], v[210:211], 0, s[60:61]
	s_add_u32 s56, s66, 0x200080
	ds_read_b128 v[178:181], v142 offset:49152
	ds_read_b128 v[182:185], v142 offset:50176
	ds_read_b128 v[186:189], v142 offset:51200
	ds_read_b128 v[190:193], v142 offset:52224
	ds_read_b128 v[194:197], v142 offset:53248
	ds_read_b128 v[198:201], v142 offset:54272
	ds_read_b128 v[202:205], v142 offset:55296
	ds_read_b128 v[206:209], v142 offset:56320
	global_load_lds_dwordx4 v[210:211], off
	v_lshl_add_u64 v[210:211], v[212:213], 0, s[60:61]
	s_mov_b32 m0, s52
	s_addc_u32 s57, s67, 0
	global_load_lds_dwordx4 v[210:211], off
	v_lshl_add_u64 v[210:211], s[56:57], 0, v[34:35]
	s_mov_b32 m0, s53
	s_nop 0
	global_load_lds_dwordx4 v34, s[56:57]
	v_lshl_add_u64 v[210:211], s[56:57], 0, v[134:135]
	s_mov_b32 m0, s54
	s_nop 0
	global_load_lds_dwordx4 v134, s[56:57]
	v_lshl_add_u64 v[210:211], s[64:65], 0, v[32:33]
	s_mov_b32 m0, s23
	s_nop 0
	global_load_lds_dwordx4 v32, s[64:65]
	v_lshl_add_u64 v[210:211], s[64:65], 0, v[132:133]
	s_mov_b32 m0, s36
	s_nop 0
	global_load_lds_dwordx4 v132, s[64:65]
	s_waitcnt vmcnt(8) lgkmcnt(0)
	s_setprio 1
	s_barrier
	v_mfma_f32_16x16x32_bf16 v[100:103], v[146:149], v[178:181], v[100:103]
	v_mfma_f32_16x16x32_bf16 v[104:107], v[154:157], v[178:181], v[104:107]
	v_mfma_f32_16x16x32_bf16 v[116:119], v[146:149], v[186:189], v[116:119]
	v_mfma_f32_16x16x32_bf16 v[120:123], v[154:157], v[186:189], v[120:123]
	v_mfma_f32_16x16x32_bf16 v[84:87], v[146:149], v[194:197], v[84:87]
	v_mfma_f32_16x16x32_bf16 v[80:83], v[154:157], v[194:197], v[80:83]
	v_mfma_f32_16x16x32_bf16 v[36:39], v[146:149], v[202:205], v[36:39]
	v_mfma_f32_16x16x32_bf16 v[24:27], v[154:157], v[202:205], v[24:27]
	v_mfma_f32_16x16x32_bf16 v[100:103], v[150:153], v[182:185], v[100:103]
	v_mfma_f32_16x16x32_bf16 v[104:107], v[158:161], v[182:185], v[104:107]
	v_mfma_f32_16x16x32_bf16 v[116:119], v[150:153], v[190:193], v[116:119]
	v_mfma_f32_16x16x32_bf16 v[120:123], v[158:161], v[190:193], v[120:123]
	v_mfma_f32_16x16x32_bf16 v[84:87], v[150:153], v[198:201], v[84:87]
	v_mfma_f32_16x16x32_bf16 v[80:83], v[158:161], v[198:201], v[80:83]
	v_mfma_f32_16x16x32_bf16 v[36:39], v[150:153], v[206:209], v[36:39]
	v_mfma_f32_16x16x32_bf16 v[24:27], v[158:161], v[206:209], v[24:27]
	v_mfma_f32_16x16x32_bf16 v[124:127], v[162:165], v[178:181], v[124:127]
	v_mfma_f32_16x16x32_bf16 v[112:115], v[170:173], v[178:181], v[112:115]
	v_mfma_f32_16x16x32_bf16 v[92:95], v[162:165], v[186:189], v[92:95]
	v_mfma_f32_16x16x32_bf16 v[88:91], v[170:173], v[186:189], v[88:91]
	v_mfma_f32_16x16x32_bf16 v[44:47], v[162:165], v[194:197], v[44:47]
	v_mfma_f32_16x16x32_bf16 v[40:43], v[170:173], v[194:197], v[40:43]
	v_mfma_f32_16x16x32_bf16 v[4:7], v[162:165], v[202:205], v[4:7]
	v_mfma_f32_16x16x32_bf16 v[0:3], v[170:173], v[202:205], v[0:3]
	v_mfma_f32_16x16x32_bf16 v[124:127], v[166:169], v[182:185], v[124:127]
	v_mfma_f32_16x16x32_bf16 v[112:115], v[174:177], v[182:185], v[112:115]
	v_mfma_f32_16x16x32_bf16 v[92:95], v[166:169], v[190:193], v[92:95]
	v_mfma_f32_16x16x32_bf16 v[88:91], v[174:177], v[190:193], v[88:91]
	v_mfma_f32_16x16x32_bf16 v[44:47], v[166:169], v[198:201], v[44:47]
	v_mfma_f32_16x16x32_bf16 v[40:43], v[174:177], v[198:201], v[40:43]
	v_mfma_f32_16x16x32_bf16 v[4:7], v[166:169], v[206:209], v[4:7]
	v_mfma_f32_16x16x32_bf16 v[0:3], v[174:177], v[206:209], v[0:3]
	s_barrier
	s_setprio 0
	s_add_i32 s41, s41, 2
	s_add_u32 s37, s37, 0x100
	s_addc_u32 s38, s38, 0
	s_add_u32 s39, s39, 0x10000
	s_addc_u32 s40, s40, 0
	v_lshl_add_u64 v[136:137], v[136:137], 0, s[62:63]
	s_cmpk_gt_u32 s41, 0x7d
	v_lshl_add_u64 v[138:139], v[138:139], 0, s[62:63]
	s_cbranch_scc0 .LBB0_2914
	s_waitcnt vmcnt(0)
	s_cmpk_lt_u32 s0, 0x100
	s_cbranch_scc0 .LBB0_2917
	s_barrier

.Lpw_17:
	s_setprio 1
	s_barrier
	v_mfma_f32_16x16x32_bf16 v[88:91], v[0:3], v[56:59], 0
	v_mfma_f32_16x16x32_bf16 v[64:67], v[0:3], v[32:35], 0
	v_mfma_f32_16x16x32_bf16 v[68:71], v[8:11], v[32:35], 0
	v_mfma_f32_16x16x32_bf16 v[72:75], v[0:3], v[40:43], 0
	v_mfma_f32_16x16x32_bf16 v[76:79], v[8:11], v[40:43], 0
	v_mfma_f32_16x16x32_bf16 v[80:83], v[0:3], v[48:51], 0
	v_mfma_f32_16x16x32_bf16 v[84:87], v[8:11], v[48:51], 0
	v_mfma_f32_16x16x32_bf16 v[92:95], v[4:7], v[60:63], v[88:91]
	v_mfma_f32_16x16x32_bf16 v[88:91], v[8:11], v[56:59], 0
	v_mfma_f32_16x16x32_bf16 v[64:67], v[4:7], v[36:39], v[64:67]
	v_mfma_f32_16x16x32_bf16 v[68:71], v[12:15], v[36:39], v[68:71]
	v_mfma_f32_16x16x32_bf16 v[72:75], v[4:7], v[44:47], v[72:75]
	v_mfma_f32_16x16x32_bf16 v[76:79], v[12:15], v[44:47], v[76:79]
	v_mfma_f32_16x16x32_bf16 v[80:83], v[4:7], v[52:55], v[80:83]
	v_mfma_f32_16x16x32_bf16 v[84:87], v[12:15], v[52:55], v[84:87]
	v_mfma_f32_16x16x32_bf16 v[100:103], v[12:15], v[60:63], v[88:91]
	v_mfma_f32_16x16x32_bf16 v[88:91], v[16:19], v[32:35], 0
	v_mfma_f32_16x16x32_bf16 v[32:35], v[24:27], v[32:35], 0
	v_mfma_f32_16x16x32_bf16 v[108:111], v[20:23], v[36:39], v[88:91]
	v_mfma_f32_16x16x32_bf16 v[32:35], v[28:31], v[36:39], v[32:35]
	v_mfma_f32_16x16x32_bf16 v[36:39], v[16:19], v[40:43], 0
	v_mfma_f32_16x16x32_bf16 v[40:43], v[24:27], v[40:43], 0
	v_mfma_f32_16x16x32_bf16 v[36:39], v[20:23], v[44:47], v[36:39]
	v_mfma_f32_16x16x32_bf16 v[40:43], v[28:31], v[44:47], v[40:43]
	v_mfma_f32_16x16x32_bf16 v[44:47], v[16:19], v[48:51], 0
	v_mfma_f32_16x16x32_bf16 v[48:51], v[24:27], v[48:51], 0
	v_mfma_f32_16x16x32_bf16 v[44:47], v[20:23], v[52:55], v[44:47]
	v_mfma_f32_16x16x32_bf16 v[52:55], v[28:31], v[52:55], v[48:51]
	v_mfma_f32_16x16x32_bf16 v[48:51], v[16:19], v[56:59], 0
	v_mfma_f32_16x16x32_bf16 v[152:155], v[20:23], v[60:63], v[48:51]
	v_mfma_f32_16x16x32_bf16 v[48:51], v[24:27], v[56:59], 0
	v_mfma_f32_16x16x32_bf16 v[156:159], v[28:31], v[60:63], v[48:51]
	s_barrier
	s_setprio 0
	s_add_i32 s69, s61, s49
	v_lshl_add_u64 v[146:147], s[42:43], 0, v[128:129]
	s_add_i32 s70, s69, 0x2000
	v_lshl_add_u64 v[120:121], v[146:147], 0, s[20:21]
	s_mov_b32 m0, s69
	v_lshl_add_u64 v[252:253], s[42:43], 0, v[130:131]
	s_add_u32 s46, s42, 0x80100
	ds_read_b128 v[48:51], v151 offset:16384
	ds_read_b128 v[56:59], v151 offset:17408
	ds_read_b128 v[60:63], v151 offset:18432
	ds_read_b128 v[88:91], v151 offset:19456
	ds_read_b128 v[96:99], v151 offset:20480
	ds_read_b128 v[104:107], v151 offset:21504
	ds_read_b128 v[112:115], v151 offset:22528
	ds_read_b128 v[116:119], v151 offset:23552
	global_load_lds_dwordx4 v[120:121], off
	v_lshl_add_u64 v[120:121], v[252:253], 0, s[20:21]
	s_mov_b32 m0, s70
	s_addc_u32 s47, s43, 0
	s_add_i32 s71, s62, s49
	global_load_lds_dwordx4 v[120:121], off
	v_lshl_add_u64 v[120:121], s[46:47], 0, v[128:129]
	s_mov_b32 m0, s71
	s_add_i32 s72, s71, 0x2000
	global_load_lds_dwordx4 v128, s[46:47]
	v_lshl_add_u64 v[120:121], s[46:47], 0, v[130:131]
	s_mov_b32 m0, s72
	v_lshl_add_u64 v[140:141], s[44:45], 0, v[134:135]
	global_load_lds_dwordx4 v130, s[46:47]
	v_lshl_add_u64 v[120:121], v[140:141], 0, s[20:21]
	s_mov_b32 m0, s41
	v_lshl_add_u64 v[142:143], s[44:45], 0, v[132:133]
	global_load_lds_dwordx4 v[120:121], off
	v_lshl_add_u64 v[120:121], v[142:143], 0, s[20:21]
	s_mov_b32 m0, s52
	s_nop 0
	global_load_lds_dwordx4 v[120:121], off
	s_waitcnt vmcnt(24) lgkmcnt(0)
	s_cmp_lg_u32 s98, 0
	s_cbranch_scc1 .Lpw_18
	s_waitcnt vmcnt(8)
.Lpw_18:
	s_setprio 1
	s_barrier
	v_mfma_f32_16x16x32_bf16 v[120:123], v[0:3], v[48:51], 0
	v_mfma_f32_16x16x32_bf16 v[160:163], v[4:7], v[56:59], v[120:123]
	v_mfma_f32_16x16x32_bf16 v[120:123], v[8:11], v[48:51], 0
	v_mfma_f32_16x16x32_bf16 v[164:167], v[12:15], v[56:59], v[120:123]
	v_mfma_f32_16x16x32_bf16 v[120:123], v[0:3], v[60:63], 0
	v_mfma_f32_16x16x32_bf16 v[168:171], v[4:7], v[88:91], v[120:123]
	v_mfma_f32_16x16x32_bf16 v[120:123], v[8:11], v[60:63], 0
	v_mfma_f32_16x16x32_bf16 v[172:175], v[12:15], v[88:91], v[120:123]
	v_mfma_f32_16x16x32_bf16 v[120:123], v[0:3], v[96:99], 0
	v_mfma_f32_16x16x32_bf16 v[0:3], v[0:3], v[112:115], 0
	v_mfma_f32_16x16x32_bf16 v[176:179], v[4:7], v[104:107], v[120:123]
	v_mfma_f32_16x16x32_bf16 v[0:3], v[4:7], v[116:119], v[0:3]
	v_mfma_f32_16x16x32_bf16 v[4:7], v[8:11], v[112:115], 0
	v_mfma_f32_16x16x32_bf16 v[120:123], v[8:11], v[96:99], 0
	v_mfma_f32_16x16x32_bf16 v[4:7], v[12:15], v[116:119], v[4:7]
	v_mfma_f32_16x16x32_bf16 v[180:183], v[12:15], v[104:107], v[120:123]
	v_mfma_f32_16x16x32_bf16 v[8:11], v[16:19], v[48:51], 0
	v_mfma_f32_16x16x32_bf16 v[12:15], v[20:23], v[56:59], v[8:11]
	v_mfma_f32_16x16x32_bf16 v[8:11], v[24:27], v[48:51], 0
	v_mfma_f32_16x16x32_bf16 v[184:187], v[28:31], v[56:59], v[8:11]
	v_mfma_f32_16x16x32_bf16 v[8:11], v[16:19], v[60:63], 0
	v_mfma_f32_16x16x32_bf16 v[188:191], v[20:23], v[88:91], v[8:11]
	v_mfma_f32_16x16x32_bf16 v[8:11], v[24:27], v[60:63], 0
	v_mfma_f32_16x16x32_bf16 v[192:195], v[28:31], v[88:91], v[8:11]
	v_mfma_f32_16x16x32_bf16 v[8:11], v[16:19], v[96:99], 0
	v_mfma_f32_16x16x32_bf16 v[196:199], v[20:23], v[104:107], v[8:11]
	v_mfma_f32_16x16x32_bf16 v[8:11], v[24:27], v[96:99], 0
	v_mfma_f32_16x16x32_bf16 v[200:203], v[28:31], v[104:107], v[8:11]
	v_mfma_f32_16x16x32_bf16 v[8:11], v[16:19], v[112:115], 0
	v_mfma_f32_16x16x32_bf16 v[204:207], v[20:23], v[116:119], v[8:11]
	v_mfma_f32_16x16x32_bf16 v[8:11], v[24:27], v[112:115], 0
	v_mfma_f32_16x16x32_bf16 v[208:211], v[28:31], v[116:119], v[8:11]
	s_barrier
; template <class Epi, class Sched, bool ALIGN_EPI = false, bool SP2 = false, bool A_TILED = false>
; __device__ __forceinline__ void gemm_phase(PG8_LAS unsigned char* lds, const Gemm g, const Sched& S, const Epi& E, const int wave_s) {
;     ...
;             const char* a1 = cA + kstepA; const char* a2 = cA + 2 * kstepA; const char* b2 = cB + 2 * kstep; const char* a3 = a2 + kstepA; const char* b3 = b2 + kstep;
;             PG8_ITER(PG8_MMAZ)
	s_setprio 0
	s_add_i32 s73, 0, 0x18000
	s_add_i32 s75, 0, 0x1c000
	v_add_u32_e32 v144, s73, v148
	v_add_u32_e32 v145, s75, v148
	s_nop 0
	ds_read_b128 v[8:11], v144
	ds_read_b128 v[20:23], v144 offset:1024
	ds_read_b128 v[28:31], v144 offset:2048
	ds_read_b128 v[212:215], v144 offset:3072
	ds_read_b128 v[216:219], v145
	ds_read_b128 v[220:223], v145 offset:1024
	ds_read_b128 v[224:227], v145 offset:2048
	ds_read_b128 v[228:231], v145 offset:3072
	s_add_u32 s46, s44, 0x80100
	s_addc_u32 s47, s45, 0
	s_mov_b32 m0, s53
	v_lshl_add_u64 v[48:49], s[46:47], 0, v[134:135]
	ds_read_b128 v[16:19], v151 offset:32768
	ds_read_b128 v[24:27], v151 offset:33792
	ds_read_b128 v[60:63], v151 offset:34816
	ds_read_b128 v[232:235], v151 offset:35840
	ds_read_b128 v[236:239], v151 offset:36864
	ds_read_b128 v[240:243], v151 offset:37888
	ds_read_b128 v[244:247], v151 offset:38912
	ds_read_b128 v[248:251], v151 offset:39936
	global_load_lds_dwordx4 v134, s[46:47]
	v_lshl_add_u64 v[48:49], s[46:47], 0, v[132:133]
	s_mov_b32 m0, s54
	s_nop 0
	global_load_lds_dwordx4 v132, s[46:47]
	s_waitcnt vmcnt(8) lgkmcnt(0)
	s_setprio 1
	s_barrier
	v_mfma_f32_16x16x32_bf16 v[48:51], v[8:11], v[16:19], v[64:67]
	v_mfma_f32_16x16x32_bf16 v[120:123], v[20:23], v[24:27], v[48:51]
	v_mfma_f32_16x16x32_bf16 v[48:51], v[28:31], v[16:19], v[68:71]
	v_mfma_f32_16x16x32_bf16 v[112:115], v[212:215], v[24:27], v[48:51]
	v_mfma_f32_16x16x32_bf16 v[48:51], v[8:11], v[60:63], v[72:75]
	v_mfma_f32_16x16x32_bf16 v[104:107], v[20:23], v[232:235], v[48:51]
	v_mfma_f32_16x16x32_bf16 v[48:51], v[28:31], v[60:63], v[76:79]
	v_mfma_f32_16x16x32_bf16 v[96:99], v[212:215], v[232:235], v[48:51]
	v_mfma_f32_16x16x32_bf16 v[48:51], v[8:11], v[236:239], v[80:83]
	v_mfma_f32_16x16x32_bf16 v[88:91], v[20:23], v[240:243], v[48:51]
	v_mfma_f32_16x16x32_bf16 v[48:51], v[28:31], v[236:239], v[84:87]
	v_mfma_f32_16x16x32_bf16 v[80:83], v[212:215], v[240:243], v[48:51]
	v_mfma_f32_16x16x32_bf16 v[48:51], v[8:11], v[244:247], v[92:95]
	v_mfma_f32_16x16x32_bf16 v[56:59], v[20:23], v[248:251], v[48:51]
	v_mfma_f32_16x16x32_bf16 v[48:51], v[28:31], v[244:247], v[100:103]
	v_mfma_f32_16x16x32_bf16 v[48:51], v[212:215], v[248:251], v[48:51]
	v_mfma_f32_16x16x32_bf16 v[64:67], v[216:219], v[16:19], v[108:111]
	v_mfma_f32_16x16x32_bf16 v[16:19], v[224:227], v[16:19], v[32:35]
	v_mfma_f32_16x16x32_bf16 v[116:119], v[228:231], v[24:27], v[16:19]
	v_mfma_f32_16x16x32_bf16 v[16:19], v[216:219], v[60:63], v[36:39]
	v_mfma_f32_16x16x32_bf16 v[108:111], v[220:223], v[232:235], v[16:19]
	v_mfma_f32_16x16x32_bf16 v[16:19], v[224:227], v[60:63], v[40:43]
	v_mfma_f32_16x16x32_bf16 v[100:103], v[228:231], v[232:235], v[16:19]
	v_mfma_f32_16x16x32_bf16 v[16:19], v[216:219], v[236:239], v[44:47]
	v_mfma_f32_16x16x32_bf16 v[92:95], v[220:223], v[240:243], v[16:19]
	v_mfma_f32_16x16x32_bf16 v[16:19], v[224:227], v[236:239], v[52:55]
	v_mfma_f32_16x16x32_bf16 v[84:87], v[228:231], v[240:243], v[16:19]
	v_mfma_f32_16x16x32_bf16 v[16:19], v[216:219], v[244:247], v[152:155]
	v_mfma_f32_16x16x32_bf16 v[60:63], v[220:223], v[248:251], v[16:19]
	v_mfma_f32_16x16x32_bf16 v[16:19], v[224:227], v[244:247], v[156:159]
	v_mfma_f32_16x16x32_bf16 v[124:127], v[220:223], v[24:27], v[64:67]
	v_mfma_f32_16x16x32_bf16 v[52:55], v[228:231], v[248:251], v[16:19]
	s_barrier
	s_setprio 0
	s_add_i32 s73, s73, s49
	s_add_i32 s74, s73, 0x2000
	s_nop 1
	v_lshl_add_u64 v[16:17], v[146:147], 0, s[16:17]
	s_mov_b32 m0, s73
	s_add_u32 s46, s42, 0x80180
	ds_read_b128 v[36:39], v151 offset:49152
	ds_read_b128 v[44:47], v151 offset:50176
	ds_read_b128 v[152:155], v151 offset:51200
	ds_read_b128 v[156:159], v151 offset:52224
	ds_read_b128 v[232:235], v151 offset:53248
	ds_read_b128 v[236:239], v151 offset:54272
	ds_read_b128 v[240:243], v151 offset:55296
	ds_read_b128 v[244:247], v151 offset:56320
	global_load_lds_dwordx4 v[16:17], off
	v_lshl_add_u64 v[16:17], v[252:253], 0, s[16:17]
	s_mov_b32 m0, s74
	s_addc_u32 s47, s43, 0
	s_add_i32 s75, s75, s49
	global_load_lds_dwordx4 v[16:17], off
	v_lshl_add_u64 v[16:17], s[46:47], 0, v[128:129]
	s_mov_b32 m0, s75
	s_add_i32 s76, s75, 0x2000
	global_load_lds_dwordx4 v128, s[46:47]
	v_lshl_add_u64 v[16:17], s[46:47], 0, v[130:131]
	s_mov_b32 m0, s76
	s_nop 0
	global_load_lds_dwordx4 v130, s[46:47]
	v_lshl_add_u64 v[16:17], v[140:141], 0, s[16:17]
	s_mov_b32 m0, s59
	s_nop 0
	global_load_lds_dwordx4 v[16:17], off
	v_lshl_add_u64 v[16:17], v[142:143], 0, s[16:17]
	s_mov_b32 m0, s60
	s_nop 0
	global_load_lds_dwordx4 v[16:17], off
	s_waitcnt vmcnt(8) lgkmcnt(0)
	s_setprio 1
	s_barrier
	v_mfma_f32_16x16x32_bf16 v[16:19], v[8:11], v[36:39], v[160:163]
	v_mfma_f32_16x16x32_bf16 v[72:75], v[20:23], v[44:47], v[16:19]
	v_mfma_f32_16x16x32_bf16 v[16:19], v[28:31], v[36:39], v[164:167]
	v_mfma_f32_16x16x32_bf16 v[64:67], v[212:215], v[44:47], v[16:19]
	v_mfma_f32_16x16x32_bf16 v[16:19], v[8:11], v[152:155], v[168:171]
	v_mfma_f32_16x16x32_bf16 v[40:43], v[20:23], v[156:159], v[16:19]
	v_mfma_f32_16x16x32_bf16 v[16:19], v[28:31], v[152:155], v[172:175]
	v_mfma_f32_16x16x32_bf16 v[32:35], v[212:215], v[156:159], v[16:19]
	v_mfma_f32_16x16x32_bf16 v[16:19], v[8:11], v[232:235], v[176:179]
	v_mfma_f32_16x16x32_bf16 v[0:3], v[8:11], v[240:243], v[0:3]
	v_mfma_f32_16x16x32_bf16 v[24:27], v[20:23], v[236:239], v[16:19]
	v_mfma_f32_16x16x32_bf16 v[16:19], v[28:31], v[232:235], v[180:183]
	v_mfma_f32_16x16x32_bf16 v[8:11], v[20:23], v[244:247], v[0:3]
	v_mfma_f32_16x16x32_bf16 v[0:3], v[28:31], v[240:243], v[4:7]
	v_mfma_f32_16x16x32_bf16 v[16:19], v[212:215], v[236:239], v[16:19]
	v_mfma_f32_16x16x32_bf16 v[0:3], v[212:215], v[244:247], v[0:3]
	v_mfma_f32_16x16x32_bf16 v[4:7], v[216:219], v[36:39], v[12:15]
	v_mfma_f32_16x16x32_bf16 v[76:79], v[220:223], v[44:47], v[4:7]
	v_mfma_f32_16x16x32_bf16 v[4:7], v[224:227], v[36:39], v[184:187]
	v_mfma_f32_16x16x32_bf16 v[68:71], v[228:231], v[44:47], v[4:7]
	v_mfma_f32_16x16x32_bf16 v[4:7], v[216:219], v[152:155], v[188:191]
	v_mfma_f32_16x16x32_bf16 v[44:47], v[220:223], v[156:159], v[4:7]
	v_mfma_f32_16x16x32_bf16 v[4:7], v[224:227], v[152:155], v[192:195]
	v_mfma_f32_16x16x32_bf16 v[36:39], v[228:231], v[156:159], v[4:7]
	v_mfma_f32_16x16x32_bf16 v[4:7], v[216:219], v[232:235], v[196:199]
	v_mfma_f32_16x16x32_bf16 v[28:31], v[220:223], v[236:239], v[4:7]
	v_mfma_f32_16x16x32_bf16 v[4:7], v[224:227], v[232:235], v[200:203]
	v_mfma_f32_16x16x32_bf16 v[20:23], v[228:231], v[236:239], v[4:7]
	v_mfma_f32_16x16x32_bf16 v[4:7], v[216:219], v[240:243], v[204:207]
	v_mfma_f32_16x16x32_bf16 v[12:15], v[220:223], v[244:247], v[4:7]
	v_mfma_f32_16x16x32_bf16 v[4:7], v[224:227], v[240:243], v[208:211]
	v_mfma_f32_16x16x32_bf16 v[4:7], v[228:231], v[244:247], v[4:7]
	s_barrier
	s_setprio 0
	s_add_u32 s77, s42, 0x200
	s_addc_u32 s78, s43, 0
	s_add_u32 s42, s44, 0x80180
	s_addc_u32 s43, s45, 0
	s_mov_b32 s79, 0
; template <class Epi, class Sched, bool ALIGN_EPI = false, bool SP2 = false, bool A_TILED = false>
; __device__ __forceinline__ void gemm_phase(PG8_LAS unsigned char* lds, const Gemm g, const Sched& S, const Epi& E, const int wave_s) {
;     ...
;         for (int t = PEEL ? 2 : 0; t < nt; t += 2) {
;             const bool last = (t == nt - 2);
;             const char* a1 = cA + (size_t)(t + 1) * kstepA;
;             const char* a2 = last ? nA : cA + (size_t)(t + 2) * kstepA; const char* b2 = last ? nB : cB + (size_t)(t + 2) * kstep;
;             const char* a3 = a2 + kstepA; const char* b3 = b2 + kstep;
.LBB0_3342:
	ds_read_b128 v[152:155], v149
	ds_read_b128 v[156:159], v149 offset:1024
	ds_read_b128 v[160:163], v149 offset:2048
	ds_read_b128 v[164:167], v149 offset:3072
	ds_read_b128 v[168:171], v150
	ds_read_b128 v[172:175], v150 offset:1024
	ds_read_b128 v[176:179], v150 offset:2048
	ds_read_b128 v[180:183], v150 offset:3072
	s_add_u32 s44, s42, 0xfff80080
	s_addc_u32 s45, s43, -1
	s_cmp_eq_u32 s79, 28
	s_cselect_b32 s47, s25, s45
	s_cselect_b32 s46, s67, s44
	s_cselect_b32 s45, s23, s78
	s_cselect_b32 s44, s68, s77
	s_mov_b32 m0, s64
	v_lshl_add_u64 v[140:141], s[42:43], 0, v[138:139]
	ds_read_b128 v[184:187], v151
	ds_read_b128 v[188:191], v151 offset:1024
	ds_read_b128 v[192:195], v151 offset:2048
	ds_read_b128 v[196:199], v151 offset:3072
	ds_read_b128 v[200:203], v151 offset:4096
	ds_read_b128 v[204:207], v151 offset:5120
	ds_read_b128 v[208:211], v151 offset:6144
	ds_read_b128 v[212:215], v151 offset:7168
	global_load_lds_dwordx4 v138, s[42:43]
	v_lshl_add_u64 v[140:141], s[42:43], 0, v[136:137]
	s_mov_b32 m0, s65
	s_nop 0
	global_load_lds_dwordx4 v136, s[42:43]
	s_waitcnt vmcnt(8) lgkmcnt(0)
	s_setprio 1
	s_barrier
	v_mfma_f32_16x16x32_bf16 v[120:123], v[152:155], v[184:187], v[120:123]
	v_mfma_f32_16x16x32_bf16 v[112:115], v[160:163], v[184:187], v[112:115]
	v_mfma_f32_16x16x32_bf16 v[104:107], v[152:155], v[192:195], v[104:107]
	v_mfma_f32_16x16x32_bf16 v[96:99], v[160:163], v[192:195], v[96:99]
	v_mfma_f32_16x16x32_bf16 v[88:91], v[152:155], v[200:203], v[88:91]
	v_mfma_f32_16x16x32_bf16 v[80:83], v[160:163], v[200:203], v[80:83]
	v_mfma_f32_16x16x32_bf16 v[56:59], v[152:155], v[208:211], v[56:59]
	v_mfma_f32_16x16x32_bf16 v[48:51], v[160:163], v[208:211], v[48:51]
	v_mfma_f32_16x16x32_bf16 v[120:123], v[156:159], v[188:191], v[120:123]
	v_mfma_f32_16x16x32_bf16 v[112:115], v[164:167], v[188:191], v[112:115]
	v_mfma_f32_16x16x32_bf16 v[104:107], v[156:159], v[196:199], v[104:107]
	v_mfma_f32_16x16x32_bf16 v[96:99], v[164:167], v[196:199], v[96:99]
	v_mfma_f32_16x16x32_bf16 v[88:91], v[156:159], v[204:207], v[88:91]
	v_mfma_f32_16x16x32_bf16 v[80:83], v[164:167], v[204:207], v[80:83]
	v_mfma_f32_16x16x32_bf16 v[56:59], v[156:159], v[212:215], v[56:59]
	v_mfma_f32_16x16x32_bf16 v[48:51], v[164:167], v[212:215], v[48:51]
	v_mfma_f32_16x16x32_bf16 v[124:127], v[168:171], v[184:187], v[124:127]
	v_mfma_f32_16x16x32_bf16 v[116:119], v[176:179], v[184:187], v[116:119]
	v_mfma_f32_16x16x32_bf16 v[108:111], v[168:171], v[192:195], v[108:111]
	v_mfma_f32_16x16x32_bf16 v[100:103], v[176:179], v[192:195], v[100:103]
	v_mfma_f32_16x16x32_bf16 v[92:95], v[168:171], v[200:203], v[92:95]
	v_mfma_f32_16x16x32_bf16 v[84:87], v[176:179], v[200:203], v[84:87]
	v_mfma_f32_16x16x32_bf16 v[60:63], v[168:171], v[208:211], v[60:63]
	v_mfma_f32_16x16x32_bf16 v[52:55], v[176:179], v[208:211], v[52:55]
	v_mfma_f32_16x16x32_bf16 v[124:127], v[172:175], v[188:191], v[124:127]
	v_mfma_f32_16x16x32_bf16 v[116:119], v[180:183], v[188:191], v[116:119]
	v_mfma_f32_16x16x32_bf16 v[108:111], v[172:175], v[196:199], v[108:111]
	v_mfma_f32_16x16x32_bf16 v[100:103], v[180:183], v[196:199], v[100:103]
	v_mfma_f32_16x16x32_bf16 v[92:95], v[172:175], v[204:207], v[92:95]
	v_mfma_f32_16x16x32_bf16 v[84:87], v[180:183], v[204:207], v[84:87]
	v_mfma_f32_16x16x32_bf16 v[60:63], v[172:175], v[212:215], v[60:63]
	v_mfma_f32_16x16x32_bf16 v[52:55], v[180:183], v[212:215], v[52:55]
	s_barrier
	s_setprio 0
	s_mov_b32 m0, s69
	v_lshl_add_u64 v[140:141], s[44:45], 0, v[128:129]
	s_add_u32 s80, s44, 0x80000
	ds_read_b128 v[184:187], v151 offset:16384
	ds_read_b128 v[188:191], v151 offset:17408
	ds_read_b128 v[192:195], v151 offset:18432
	ds_read_b128 v[196:199], v151 offset:19456
	ds_read_b128 v[200:203], v151 offset:20480
	ds_read_b128 v[204:207], v151 offset:21504
	ds_read_b128 v[208:211], v151 offset:22528
	ds_read_b128 v[212:215], v151 offset:23552
	global_load_lds_dwordx4 v128, s[44:45]
	v_lshl_add_u64 v[142:143], s[44:45], 0, v[130:131]
	s_mov_b32 m0, s70
	s_addc_u32 s81, s45, 0
	global_load_lds_dwordx4 v130, s[44:45]
	v_lshl_add_u64 v[146:147], s[80:81], 0, v[128:129]
	s_mov_b32 m0, s71
	v_lshl_add_u64 v[216:217], s[46:47], 0, v[132:133]
	global_load_lds_dwordx4 v128, s[80:81]
	v_lshl_add_u64 v[146:147], s[80:81], 0, v[130:131]
	s_mov_b32 m0, s72
	s_nop 0
	global_load_lds_dwordx4 v130, s[80:81]
	v_lshl_add_u64 v[146:147], s[46:47], 0, v[134:135]
	s_mov_b32 m0, s41
	s_nop 0
	global_load_lds_dwordx4 v134, s[46:47]
	s_mov_b32 m0, s52
	s_nop 0
	global_load_lds_dwordx4 v132, s[46:47]
	s_waitcnt vmcnt(8) lgkmcnt(0)
	s_setprio 1
	s_barrier
	v_mfma_f32_16x16x32_bf16 v[72:75], v[152:155], v[184:187], v[72:75]
	v_mfma_f32_16x16x32_bf16 v[64:67], v[160:163], v[184:187], v[64:67]
	v_mfma_f32_16x16x32_bf16 v[40:43], v[152:155], v[192:195], v[40:43]
	v_mfma_f32_16x16x32_bf16 v[32:35], v[160:163], v[192:195], v[32:35]
	v_mfma_f32_16x16x32_bf16 v[24:27], v[152:155], v[200:203], v[24:27]
	v_mfma_f32_16x16x32_bf16 v[16:19], v[160:163], v[200:203], v[16:19]
	v_mfma_f32_16x16x32_bf16 v[8:11], v[152:155], v[208:211], v[8:11]
	v_mfma_f32_16x16x32_bf16 v[0:3], v[160:163], v[208:211], v[0:3]
	v_mfma_f32_16x16x32_bf16 v[72:75], v[156:159], v[188:191], v[72:75]
	v_mfma_f32_16x16x32_bf16 v[64:67], v[164:167], v[188:191], v[64:67]
	v_mfma_f32_16x16x32_bf16 v[40:43], v[156:159], v[196:199], v[40:43]
	v_mfma_f32_16x16x32_bf16 v[32:35], v[164:167], v[196:199], v[32:35]
	v_mfma_f32_16x16x32_bf16 v[24:27], v[156:159], v[204:207], v[24:27]
	v_mfma_f32_16x16x32_bf16 v[16:19], v[164:167], v[204:207], v[16:19]
	v_mfma_f32_16x16x32_bf16 v[8:11], v[156:159], v[212:215], v[8:11]
	v_mfma_f32_16x16x32_bf16 v[0:3], v[164:167], v[212:215], v[0:3]
	v_mfma_f32_16x16x32_bf16 v[76:79], v[168:171], v[184:187], v[76:79]
	v_mfma_f32_16x16x32_bf16 v[68:71], v[176:179], v[184:187], v[68:71]
	v_mfma_f32_16x16x32_bf16 v[44:47], v[168:171], v[192:195], v[44:47]
	v_mfma_f32_16x16x32_bf16 v[36:39], v[176:179], v[192:195], v[36:39]
	v_mfma_f32_16x16x32_bf16 v[28:31], v[168:171], v[200:203], v[28:31]
	v_mfma_f32_16x16x32_bf16 v[20:23], v[176:179], v[200:203], v[20:23]
	v_mfma_f32_16x16x32_bf16 v[12:15], v[168:171], v[208:211], v[12:15]
	v_mfma_f32_16x16x32_bf16 v[4:7], v[176:179], v[208:211], v[4:7]
	v_mfma_f32_16x16x32_bf16 v[76:79], v[172:175], v[188:191], v[76:79]
	v_mfma_f32_16x16x32_bf16 v[68:71], v[180:183], v[188:191], v[68:71]
	v_mfma_f32_16x16x32_bf16 v[44:47], v[172:175], v[196:199], v[44:47]
	v_mfma_f32_16x16x32_bf16 v[36:39], v[180:183], v[196:199], v[36:39]
	v_mfma_f32_16x16x32_bf16 v[28:31], v[172:175], v[204:207], v[28:31]
	v_mfma_f32_16x16x32_bf16 v[20:23], v[180:183], v[204:207], v[20:23]
	v_mfma_f32_16x16x32_bf16 v[12:15], v[172:175], v[212:215], v[12:15]
	v_mfma_f32_16x16x32_bf16 v[4:7], v[180:183], v[212:215], v[4:7]
	s_barrier
	s_setprio 0
	ds_read_b128 v[152:155], v144
	ds_read_b128 v[156:159], v144 offset:1024
	ds_read_b128 v[160:163], v144 offset:2048
	ds_read_b128 v[164:167], v144 offset:3072
	ds_read_b128 v[168:171], v145
	ds_read_b128 v[172:175], v145 offset:1024
	ds_read_b128 v[176:179], v145 offset:2048
	ds_read_b128 v[180:183], v145 offset:3072
	s_add_u32 s46, s46, 0x80000
	s_addc_u32 s47, s47, 0
	s_mov_b32 m0, s53
	v_lshl_add_u64 v[218:219], s[46:47], 0, v[134:135]
	ds_read_b128 v[184:187], v151 offset:32768
	ds_read_b128 v[188:191], v151 offset:33792
	ds_read_b128 v[192:195], v151 offset:34816
	ds_read_b128 v[196:199], v151 offset:35840
	ds_read_b128 v[200:203], v151 offset:36864
	ds_read_b128 v[204:207], v151 offset:37888
	ds_read_b128 v[208:211], v151 offset:38912
	ds_read_b128 v[212:215], v151 offset:39936
	global_load_lds_dwordx4 v134, s[46:47]
	v_lshl_add_u64 v[218:219], s[46:47], 0, v[132:133]
	s_mov_b32 m0, s54
	s_nop 0
	global_load_lds_dwordx4 v132, s[46:47]
	s_waitcnt vmcnt(8) lgkmcnt(0)
	s_setprio 1
	s_barrier
	v_mfma_f32_16x16x32_bf16 v[120:123], v[152:155], v[184:187], v[120:123]
	v_mfma_f32_16x16x32_bf16 v[112:115], v[160:163], v[184:187], v[112:115]
	v_mfma_f32_16x16x32_bf16 v[104:107], v[152:155], v[192:195], v[104:107]
	v_mfma_f32_16x16x32_bf16 v[96:99], v[160:163], v[192:195], v[96:99]
	v_mfma_f32_16x16x32_bf16 v[88:91], v[152:155], v[200:203], v[88:91]
	v_mfma_f32_16x16x32_bf16 v[80:83], v[160:163], v[200:203], v[80:83]
	v_mfma_f32_16x16x32_bf16 v[56:59], v[152:155], v[208:211], v[56:59]
	v_mfma_f32_16x16x32_bf16 v[48:51], v[160:163], v[208:211], v[48:51]
	v_mfma_f32_16x16x32_bf16 v[120:123], v[156:159], v[188:191], v[120:123]
	v_mfma_f32_16x16x32_bf16 v[112:115], v[164:167], v[188:191], v[112:115]
	v_mfma_f32_16x16x32_bf16 v[104:107], v[156:159], v[196:199], v[104:107]
	v_mfma_f32_16x16x32_bf16 v[96:99], v[164:167], v[196:199], v[96:99]
	v_mfma_f32_16x16x32_bf16 v[88:91], v[156:159], v[204:207], v[88:91]
	v_mfma_f32_16x16x32_bf16 v[80:83], v[164:167], v[204:207], v[80:83]
	v_mfma_f32_16x16x32_bf16 v[56:59], v[156:159], v[212:215], v[56:59]
	v_mfma_f32_16x16x32_bf16 v[48:51], v[164:167], v[212:215], v[48:51]
	v_mfma_f32_16x16x32_bf16 v[124:127], v[168:171], v[184:187], v[124:127]
	v_mfma_f32_16x16x32_bf16 v[116:119], v[176:179], v[184:187], v[116:119]
	v_mfma_f32_16x16x32_bf16 v[108:111], v[168:171], v[192:195], v[108:111]
	v_mfma_f32_16x16x32_bf16 v[100:103], v[176:179], v[192:195], v[100:103]
	v_mfma_f32_16x16x32_bf16 v[92:95], v[168:171], v[200:203], v[92:95]
	v_mfma_f32_16x16x32_bf16 v[84:87], v[176:179], v[200:203], v[84:87]
	v_mfma_f32_16x16x32_bf16 v[60:63], v[168:171], v[208:211], v[60:63]
	v_mfma_f32_16x16x32_bf16 v[52:55], v[176:179], v[208:211], v[52:55]
	v_mfma_f32_16x16x32_bf16 v[124:127], v[172:175], v[188:191], v[124:127]
	v_mfma_f32_16x16x32_bf16 v[116:119], v[180:183], v[188:191], v[116:119]
	v_mfma_f32_16x16x32_bf16 v[108:111], v[172:175], v[196:199], v[108:111]
	v_mfma_f32_16x16x32_bf16 v[100:103], v[180:183], v[196:199], v[100:103]
	v_mfma_f32_16x16x32_bf16 v[92:95], v[172:175], v[204:207], v[92:95]
	v_mfma_f32_16x16x32_bf16 v[84:87], v[180:183], v[204:207], v[84:87]
	v_mfma_f32_16x16x32_bf16 v[60:63], v[172:175], v[212:215], v[60:63]
	v_mfma_f32_16x16x32_bf16 v[52:55], v[180:183], v[212:215], v[52:55]
	s_barrier
; #define PG8_BAR __builtin_amdgcn_s_barrier()
; template <class Epi, class Sched, bool ALIGN_EPI = false, bool SP2 = false, bool A_TILED = false>
; __device__ __forceinline__ void gemm_phase(PG8_LAS unsigned char* lds, const Gemm g, const Sched& S, const Epi& E, const int wave_s) {
;     ...
;         if constexpr (ALIGN_EPI) { if (wr == 0) PG8_BAR; }
	s_setprio 0
	s_mov_b32 m0, s73
	v_lshl_add_u64 v[140:141], v[140:141], 0, s[12:13]
	s_add_u32 s44, s44, 0x80080
	ds_read_b128 v[184:187], v151 offset:49152
	ds_read_b128 v[188:191], v151 offset:50176
	ds_read_b128 v[192:195], v151 offset:51200
	ds_read_b128 v[196:199], v151 offset:52224
	ds_read_b128 v[200:203], v151 offset:53248
	ds_read_b128 v[204:207], v151 offset:54272
	ds_read_b128 v[208:211], v151 offset:55296
	ds_read_b128 v[212:215], v151 offset:56320
	global_load_lds_dwordx4 v[140:141], off
	v_lshl_add_u64 v[140:141], v[142:143], 0, s[12:13]
	s_mov_b32 m0, s74
	s_addc_u32 s45, s45, 0
	global_load_lds_dwordx4 v[140:141], off
	v_lshl_add_u64 v[140:141], s[44:45], 0, v[128:129]
	s_mov_b32 m0, s75
	s_nop 0
	global_load_lds_dwordx4 v128, s[44:45]
	v_lshl_add_u64 v[140:141], s[44:45], 0, v[130:131]
	s_mov_b32 m0, s76
	s_nop 0
	global_load_lds_dwordx4 v130, s[44:45]
	v_lshl_add_u64 v[140:141], v[146:147], 0, s[12:13]
	s_mov_b32 m0, s59
	s_nop 0
	global_load_lds_dwordx4 v[140:141], off
	v_lshl_add_u64 v[140:141], v[216:217], 0, s[12:13]
	s_mov_b32 m0, s60
	s_nop 0
	global_load_lds_dwordx4 v[140:141], off
	s_waitcnt vmcnt(8) lgkmcnt(0)
	s_setprio 1
	s_barrier
	v_mfma_f32_16x16x32_bf16 v[72:75], v[152:155], v[184:187], v[72:75]
	v_mfma_f32_16x16x32_bf16 v[64:67], v[160:163], v[184:187], v[64:67]
	v_mfma_f32_16x16x32_bf16 v[40:43], v[152:155], v[192:195], v[40:43]
	v_mfma_f32_16x16x32_bf16 v[32:35], v[160:163], v[192:195], v[32:35]
	v_mfma_f32_16x16x32_bf16 v[24:27], v[152:155], v[200:203], v[24:27]
	v_mfma_f32_16x16x32_bf16 v[16:19], v[160:163], v[200:203], v[16:19]
	v_mfma_f32_16x16x32_bf16 v[8:11], v[152:155], v[208:211], v[8:11]
	v_mfma_f32_16x16x32_bf16 v[0:3], v[160:163], v[208:211], v[0:3]
	v_mfma_f32_16x16x32_bf16 v[72:75], v[156:159], v[188:191], v[72:75]
	v_mfma_f32_16x16x32_bf16 v[64:67], v[164:167], v[188:191], v[64:67]
	v_mfma_f32_16x16x32_bf16 v[40:43], v[156:159], v[196:199], v[40:43]
	v_mfma_f32_16x16x32_bf16 v[32:35], v[164:167], v[196:199], v[32:35]
	v_mfma_f32_16x16x32_bf16 v[24:27], v[156:159], v[204:207], v[24:27]
	v_mfma_f32_16x16x32_bf16 v[16:19], v[164:167], v[204:207], v[16:19]
	v_mfma_f32_16x16x32_bf16 v[8:11], v[156:159], v[212:215], v[8:11]
	v_mfma_f32_16x16x32_bf16 v[0:3], v[164:167], v[212:215], v[0:3]
	v_mfma_f32_16x16x32_bf16 v[76:79], v[168:171], v[184:187], v[76:79]
	v_mfma_f32_16x16x32_bf16 v[68:71], v[176:179], v[184:187], v[68:71]
	v_mfma_f32_16x16x32_bf16 v[44:47], v[168:171], v[192:195], v[44:47]
	v_mfma_f32_16x16x32_bf16 v[36:39], v[176:179], v[192:195], v[36:39]
	v_mfma_f32_16x16x32_bf16 v[28:31], v[168:171], v[200:203], v[28:31]
	v_mfma_f32_16x16x32_bf16 v[20:23], v[176:179], v[200:203], v[20:23]
	v_mfma_f32_16x16x32_bf16 v[12:15], v[168:171], v[208:211], v[12:15]
	v_mfma_f32_16x16x32_bf16 v[4:7], v[176:179], v[208:211], v[4:7]
	v_mfma_f32_16x16x32_bf16 v[76:79], v[172:175], v[188:191], v[76:79]
	v_mfma_f32_16x16x32_bf16 v[68:71], v[180:183], v[188:191], v[68:71]
	v_mfma_f32_16x16x32_bf16 v[44:47], v[172:175], v[196:199], v[44:47]
	v_mfma_f32_16x16x32_bf16 v[36:39], v[180:183], v[196:199], v[36:39]
	v_mfma_f32_16x16x32_bf16 v[28:31], v[172:175], v[204:207], v[28:31]
	v_mfma_f32_16x16x32_bf16 v[20:23], v[180:183], v[204:207], v[20:23]
	v_mfma_f32_16x16x32_bf16 v[12:15], v[172:175], v[212:215], v[12:15]
	v_mfma_f32_16x16x32_bf16 v[4:7], v[180:183], v[212:215], v[4:7]
	s_barrier
	s_setprio 0
	s_add_i32 s79, s79, 2
	s_add_u32 s77, s77, 0x100
	s_addc_u32 s78, s78, 0
	s_add_u32 s42, s42, 0x100
	s_addc_u32 s43, s43, 0
	s_cmp_gt_u32 s79, 29
	s_cbranch_scc0 .LBB0_3342
	s_and_b64 vcc, exec, s[14:15]
	s_cbranch_vccz .LBB0_3345
	s_barrier

; template <class Epi, class Sched, bool ALIGN_EPI = false, bool SP2 = false, bool A_TILED = false>
; __device__ __forceinline__ void gemm_phase(PG8_LAS unsigned char* lds, const Gemm g, const Sched& S, const Epi& E, const int wave_s) {
;     ...
;         for (int t = PEEL ? 2 : 0; t < nt; t += 2) {
;             const bool last = (t == nt - 2);
;             const char* a1 = cA + (size_t)(t + 1) * kstepA;
;             const char* a2 = last ? nA : cA + (size_t)(t + 2) * kstepA; const char* b2 = last ? nB : cB + (size_t)(t + 2) * kstep;
;             const char* a3 = a2 + kstepA; const char* b3 = b2 + kstep;
.LBB0_3608:
	ds_read_b128 v[146:149], v140
	ds_read_b128 v[150:153], v140 offset:1024
	ds_read_b128 v[154:157], v140 offset:2048
	ds_read_b128 v[158:161], v140 offset:3072
	ds_read_b128 v[162:165], v141
	ds_read_b128 v[166:169], v141 offset:1024
	ds_read_b128 v[170:173], v141 offset:2048
	ds_read_b128 v[174:177], v141 offset:3072
	s_add_u32 s20, s8, s43
	s_addc_u32 s21, s9, s44
	s_add_u32 s56, s8, s41
	s_addc_u32 s57, s9, s42
	s_cmp_eq_u32 s45, 28
	s_cselect_b32 s23, s5, s21
	s_cselect_b32 s22, s4, s20
	s_cselect_b32 s21, s1, s57
	s_cselect_b32 s20, s0, s56
	s_mov_b32 m0, s46
	v_lshl_add_u64 v[210:211], s[8:9], 0, v[138:139]
	ds_read_b128 v[178:181], v142
	ds_read_b128 v[182:185], v142 offset:1024
	ds_read_b128 v[186:189], v142 offset:2048
	ds_read_b128 v[190:193], v142 offset:3072
	ds_read_b128 v[194:197], v142 offset:4096
	ds_read_b128 v[198:201], v142 offset:5120
	ds_read_b128 v[202:205], v142 offset:6144
	ds_read_b128 v[206:209], v142 offset:7168
	global_load_lds_dwordx4 v[210:211], off
	v_lshl_add_u64 v[210:211], s[8:9], 0, v[136:137]
	s_mov_b32 m0, s47
	s_nop 0
	global_load_lds_dwordx4 v[210:211], off
	s_waitcnt vmcnt(8) lgkmcnt(0)
	s_setprio 1
	s_barrier
	v_mfma_f32_16x16x32_bf16 v[8:11], v[146:149], v[178:181], v[8:11]
	v_mfma_f32_16x16x32_bf16 v[12:15], v[154:157], v[178:181], v[12:15]
	v_mfma_f32_16x16x32_bf16 v[60:63], v[146:149], v[186:189], v[60:63]
	v_mfma_f32_16x16x32_bf16 v[20:23], v[154:157], v[186:189], v[20:23]
	v_mfma_f32_16x16x32_bf16 v[76:79], v[146:149], v[194:197], v[76:79]
	v_mfma_f32_16x16x32_bf16 v[52:55], v[154:157], v[194:197], v[52:55]
	v_mfma_f32_16x16x32_bf16 v[128:131], v[146:149], v[202:205], v[128:131]
	v_mfma_f32_16x16x32_bf16 v[68:71], v[154:157], v[202:205], v[68:71]
	v_mfma_f32_16x16x32_bf16 v[8:11], v[150:153], v[182:185], v[8:11]
	v_mfma_f32_16x16x32_bf16 v[12:15], v[158:161], v[182:185], v[12:15]
	v_mfma_f32_16x16x32_bf16 v[60:63], v[150:153], v[190:193], v[60:63]
	v_mfma_f32_16x16x32_bf16 v[20:23], v[158:161], v[190:193], v[20:23]
	v_mfma_f32_16x16x32_bf16 v[76:79], v[150:153], v[198:201], v[76:79]
	v_mfma_f32_16x16x32_bf16 v[52:55], v[158:161], v[198:201], v[52:55]
	v_mfma_f32_16x16x32_bf16 v[128:131], v[150:153], v[206:209], v[128:131]
	v_mfma_f32_16x16x32_bf16 v[68:71], v[158:161], v[206:209], v[68:71]
	v_mfma_f32_16x16x32_bf16 v[24:27], v[162:165], v[178:181], v[24:27]
	v_mfma_f32_16x16x32_bf16 v[16:19], v[170:173], v[178:181], v[16:19]
	v_mfma_f32_16x16x32_bf16 v[56:59], v[162:165], v[186:189], v[56:59]
	v_mfma_f32_16x16x32_bf16 v[48:51], v[170:173], v[186:189], v[48:51]
	v_mfma_f32_16x16x32_bf16 v[72:75], v[162:165], v[194:197], v[72:75]
	v_mfma_f32_16x16x32_bf16 v[64:67], v[170:173], v[194:197], v[64:67]
	v_mfma_f32_16x16x32_bf16 v[108:111], v[162:165], v[202:205], v[108:111]
	v_mfma_f32_16x16x32_bf16 v[96:99], v[170:173], v[202:205], v[96:99]
	v_mfma_f32_16x16x32_bf16 v[24:27], v[166:169], v[182:185], v[24:27]
	v_mfma_f32_16x16x32_bf16 v[16:19], v[174:177], v[182:185], v[16:19]
	v_mfma_f32_16x16x32_bf16 v[56:59], v[166:169], v[190:193], v[56:59]
	v_mfma_f32_16x16x32_bf16 v[48:51], v[174:177], v[190:193], v[48:51]
	v_mfma_f32_16x16x32_bf16 v[72:75], v[166:169], v[198:201], v[72:75]
	v_mfma_f32_16x16x32_bf16 v[64:67], v[174:177], v[198:201], v[64:67]
	v_mfma_f32_16x16x32_bf16 v[108:111], v[166:169], v[206:209], v[108:111]
	v_mfma_f32_16x16x32_bf16 v[96:99], v[174:177], v[206:209], v[96:99]
	s_barrier
	s_setprio 0
	s_mov_b32 m0, s48
	v_lshl_add_u64 v[210:211], s[20:21], 0, v[34:35]
	s_add_u32 s56, s20, 0x80000
	ds_read_b128 v[178:181], v142 offset:16384
	ds_read_b128 v[182:185], v142 offset:17408
	ds_read_b128 v[186:189], v142 offset:18432
	ds_read_b128 v[190:193], v142 offset:19456
	ds_read_b128 v[194:197], v142 offset:20480
	ds_read_b128 v[198:201], v142 offset:21504
	ds_read_b128 v[202:205], v142 offset:22528
	ds_read_b128 v[206:209], v142 offset:23552
	global_load_lds_dwordx4 v34, s[20:21]
	v_lshl_add_u64 v[212:213], s[20:21], 0, v[134:135]
	s_mov_b32 m0, s49
	s_addc_u32 s57, s21, 0
	global_load_lds_dwordx4 v134, s[20:21]
	v_lshl_add_u64 v[214:215], s[56:57], 0, v[34:35]
	s_mov_b32 m0, s50
	v_lshl_add_u64 v[216:217], s[22:23], 0, v[132:133]
	global_load_lds_dwordx4 v34, s[56:57]
	v_lshl_add_u64 v[214:215], s[56:57], 0, v[134:135]
	s_mov_b32 m0, s51
	s_nop 0
	global_load_lds_dwordx4 v134, s[56:57]
	v_lshl_add_u64 v[214:215], s[22:23], 0, v[32:33]
	s_mov_b32 m0, s27
	s_nop 0
	global_load_lds_dwordx4 v32, s[22:23]
	s_mov_b32 m0, s36
	s_nop 0
	global_load_lds_dwordx4 v132, s[22:23]
	s_waitcnt vmcnt(8) lgkmcnt(0)
	s_setprio 1
	s_barrier
	v_mfma_f32_16x16x32_bf16 v[100:103], v[146:149], v[178:181], v[100:103]
	v_mfma_f32_16x16x32_bf16 v[104:107], v[154:157], v[178:181], v[104:107]
	v_mfma_f32_16x16x32_bf16 v[116:119], v[146:149], v[186:189], v[116:119]
	v_mfma_f32_16x16x32_bf16 v[120:123], v[154:157], v[186:189], v[120:123]
	v_mfma_f32_16x16x32_bf16 v[84:87], v[146:149], v[194:197], v[84:87]
	v_mfma_f32_16x16x32_bf16 v[80:83], v[154:157], v[194:197], v[80:83]
	v_mfma_f32_16x16x32_bf16 v[36:39], v[146:149], v[202:205], v[36:39]
	v_mfma_f32_16x16x32_bf16 v[28:31], v[154:157], v[202:205], v[28:31]
	v_mfma_f32_16x16x32_bf16 v[100:103], v[150:153], v[182:185], v[100:103]
	v_mfma_f32_16x16x32_bf16 v[104:107], v[158:161], v[182:185], v[104:107]
	v_mfma_f32_16x16x32_bf16 v[116:119], v[150:153], v[190:193], v[116:119]
	v_mfma_f32_16x16x32_bf16 v[120:123], v[158:161], v[190:193], v[120:123]
	v_mfma_f32_16x16x32_bf16 v[84:87], v[150:153], v[198:201], v[84:87]
	v_mfma_f32_16x16x32_bf16 v[80:83], v[158:161], v[198:201], v[80:83]
	v_mfma_f32_16x16x32_bf16 v[36:39], v[150:153], v[206:209], v[36:39]
	v_mfma_f32_16x16x32_bf16 v[28:31], v[158:161], v[206:209], v[28:31]
	v_mfma_f32_16x16x32_bf16 v[124:127], v[162:165], v[178:181], v[124:127]
	v_mfma_f32_16x16x32_bf16 v[112:115], v[170:173], v[178:181], v[112:115]
	v_mfma_f32_16x16x32_bf16 v[92:95], v[162:165], v[186:189], v[92:95]
	v_mfma_f32_16x16x32_bf16 v[88:91], v[170:173], v[186:189], v[88:91]
	v_mfma_f32_16x16x32_bf16 v[44:47], v[162:165], v[194:197], v[44:47]
	v_mfma_f32_16x16x32_bf16 v[40:43], v[170:173], v[194:197], v[40:43]
	v_mfma_f32_16x16x32_bf16 v[4:7], v[162:165], v[202:205], v[4:7]
	v_mfma_f32_16x16x32_bf16 v[0:3], v[170:173], v[202:205], v[0:3]
	v_mfma_f32_16x16x32_bf16 v[124:127], v[166:169], v[182:185], v[124:127]
	v_mfma_f32_16x16x32_bf16 v[112:115], v[174:177], v[182:185], v[112:115]
	v_mfma_f32_16x16x32_bf16 v[92:95], v[166:169], v[190:193], v[92:95]
	v_mfma_f32_16x16x32_bf16 v[88:91], v[174:177], v[190:193], v[88:91]
	v_mfma_f32_16x16x32_bf16 v[44:47], v[166:169], v[198:201], v[44:47]
	v_mfma_f32_16x16x32_bf16 v[40:43], v[174:177], v[198:201], v[40:43]
	v_mfma_f32_16x16x32_bf16 v[4:7], v[166:169], v[206:209], v[4:7]
	v_mfma_f32_16x16x32_bf16 v[0:3], v[174:177], v[206:209], v[0:3]
	s_barrier
	s_setprio 0
	ds_read_b128 v[146:149], v143
	ds_read_b128 v[150:153], v143 offset:1024
	ds_read_b128 v[154:157], v143 offset:2048
	ds_read_b128 v[158:161], v143 offset:3072
	ds_read_b128 v[162:165], v144
	ds_read_b128 v[166:169], v144 offset:1024
	ds_read_b128 v[170:173], v144 offset:2048
	ds_read_b128 v[174:177], v144 offset:3072
	s_add_u32 s22, s22, 0x80000
	s_addc_u32 s23, s23, 0
	s_mov_b32 m0, s37
	v_lshl_add_u64 v[218:219], s[22:23], 0, v[32:33]
	ds_read_b128 v[178:181], v142 offset:32768
	ds_read_b128 v[182:185], v142 offset:33792
	ds_read_b128 v[186:189], v142 offset:34816
	ds_read_b128 v[190:193], v142 offset:35840
	ds_read_b128 v[194:197], v142 offset:36864
	ds_read_b128 v[198:201], v142 offset:37888
	ds_read_b128 v[202:205], v142 offset:38912
	ds_read_b128 v[206:209], v142 offset:39936
	global_load_lds_dwordx4 v32, s[22:23]
	v_lshl_add_u64 v[218:219], s[22:23], 0, v[132:133]
	s_mov_b32 m0, s38
	s_nop 0
	global_load_lds_dwordx4 v132, s[22:23]
	s_waitcnt vmcnt(8) lgkmcnt(0)
	s_setprio 1
	s_barrier
	v_mfma_f32_16x16x32_bf16 v[8:11], v[146:149], v[178:181], v[8:11]
	v_mfma_f32_16x16x32_bf16 v[12:15], v[154:157], v[178:181], v[12:15]
	v_mfma_f32_16x16x32_bf16 v[60:63], v[146:149], v[186:189], v[60:63]
	v_mfma_f32_16x16x32_bf16 v[20:23], v[154:157], v[186:189], v[20:23]
	v_mfma_f32_16x16x32_bf16 v[76:79], v[146:149], v[194:197], v[76:79]
	v_mfma_f32_16x16x32_bf16 v[52:55], v[154:157], v[194:197], v[52:55]
	v_mfma_f32_16x16x32_bf16 v[128:131], v[146:149], v[202:205], v[128:131]
	v_mfma_f32_16x16x32_bf16 v[68:71], v[154:157], v[202:205], v[68:71]
	v_mfma_f32_16x16x32_bf16 v[8:11], v[150:153], v[182:185], v[8:11]
	v_mfma_f32_16x16x32_bf16 v[12:15], v[158:161], v[182:185], v[12:15]
	v_mfma_f32_16x16x32_bf16 v[60:63], v[150:153], v[190:193], v[60:63]
	v_mfma_f32_16x16x32_bf16 v[20:23], v[158:161], v[190:193], v[20:23]
	v_mfma_f32_16x16x32_bf16 v[76:79], v[150:153], v[198:201], v[76:79]
	v_mfma_f32_16x16x32_bf16 v[52:55], v[158:161], v[198:201], v[52:55]
	v_mfma_f32_16x16x32_bf16 v[128:131], v[150:153], v[206:209], v[128:131]
	v_mfma_f32_16x16x32_bf16 v[68:71], v[158:161], v[206:209], v[68:71]
	v_mfma_f32_16x16x32_bf16 v[24:27], v[162:165], v[178:181], v[24:27]
	v_mfma_f32_16x16x32_bf16 v[16:19], v[170:173], v[178:181], v[16:19]
	v_mfma_f32_16x16x32_bf16 v[56:59], v[162:165], v[186:189], v[56:59]
	v_mfma_f32_16x16x32_bf16 v[48:51], v[170:173], v[186:189], v[48:51]
	v_mfma_f32_16x16x32_bf16 v[72:75], v[162:165], v[194:197], v[72:75]
	v_mfma_f32_16x16x32_bf16 v[64:67], v[170:173], v[194:197], v[64:67]
	v_mfma_f32_16x16x32_bf16 v[108:111], v[162:165], v[202:205], v[108:111]
	v_mfma_f32_16x16x32_bf16 v[96:99], v[170:173], v[202:205], v[96:99]
	v_mfma_f32_16x16x32_bf16 v[24:27], v[166:169], v[182:185], v[24:27]
	v_mfma_f32_16x16x32_bf16 v[16:19], v[174:177], v[182:185], v[16:19]
	v_mfma_f32_16x16x32_bf16 v[56:59], v[166:169], v[190:193], v[56:59]
	v_mfma_f32_16x16x32_bf16 v[48:51], v[174:177], v[190:193], v[48:51]
	v_mfma_f32_16x16x32_bf16 v[72:75], v[166:169], v[198:201], v[72:75]
	v_mfma_f32_16x16x32_bf16 v[64:67], v[174:177], v[198:201], v[64:67]
	v_mfma_f32_16x16x32_bf16 v[108:111], v[166:169], v[206:209], v[108:111]
	v_mfma_f32_16x16x32_bf16 v[96:99], v[174:177], v[206:209], v[96:99]
	s_barrier
; #define PG8_WAIT_V(n) asm volatile("s_waitcnt vmcnt(" #n ")" ::: "memory")
; #define PG8_BAR __builtin_amdgcn_s_barrier()
; template <class Epi, class Sched, bool ALIGN_EPI = false, bool SP2 = false, bool A_TILED = false>
; __device__ __forceinline__ void gemm_phase(PG8_LAS unsigned char* lds, const Gemm g, const Sched& S, const Epi& E, const int wave_s) {
;     ...
;     PG8_WAIT_V(0);
;     if constexpr (!ALIGN_EPI) { if (wr == 0) PG8_BAR; }
	s_setprio 0
	s_mov_b32 m0, s52
	v_lshl_add_u64 v[210:211], v[210:211], 0, s[14:15]
	s_add_u32 s20, s20, 0x80080
	ds_read_b128 v[178:181], v142 offset:49152
	ds_read_b128 v[182:185], v142 offset:50176
	ds_read_b128 v[186:189], v142 offset:51200
	ds_read_b128 v[190:193], v142 offset:52224
	ds_read_b128 v[194:197], v142 offset:53248
	ds_read_b128 v[198:201], v142 offset:54272
	ds_read_b128 v[202:205], v142 offset:55296
	ds_read_b128 v[206:209], v142 offset:56320
	global_load_lds_dwordx4 v[210:211], off
	v_lshl_add_u64 v[210:211], v[212:213], 0, s[14:15]
	s_mov_b32 m0, s53
	s_addc_u32 s21, s21, 0
	global_load_lds_dwordx4 v[210:211], off
	v_lshl_add_u64 v[210:211], s[20:21], 0, v[34:35]
	s_mov_b32 m0, s54
	s_nop 0
	global_load_lds_dwordx4 v34, s[20:21]
	v_lshl_add_u64 v[210:211], s[20:21], 0, v[134:135]
	s_mov_b32 m0, s55
	s_nop 0
	global_load_lds_dwordx4 v134, s[20:21]
	v_lshl_add_u64 v[210:211], v[214:215], 0, s[14:15]
	s_mov_b32 m0, s39
	s_nop 0
	global_load_lds_dwordx4 v[210:211], off
	v_lshl_add_u64 v[210:211], v[216:217], 0, s[14:15]
	s_mov_b32 m0, s40
	s_nop 0
	global_load_lds_dwordx4 v[210:211], off
	s_waitcnt vmcnt(8) lgkmcnt(0)
	s_setprio 1
	s_barrier
	v_mfma_f32_16x16x32_bf16 v[100:103], v[146:149], v[178:181], v[100:103]
	v_mfma_f32_16x16x32_bf16 v[104:107], v[154:157], v[178:181], v[104:107]
	v_mfma_f32_16x16x32_bf16 v[116:119], v[146:149], v[186:189], v[116:119]
	v_mfma_f32_16x16x32_bf16 v[120:123], v[154:157], v[186:189], v[120:123]
	v_mfma_f32_16x16x32_bf16 v[84:87], v[146:149], v[194:197], v[84:87]
	v_mfma_f32_16x16x32_bf16 v[80:83], v[154:157], v[194:197], v[80:83]
	v_mfma_f32_16x16x32_bf16 v[36:39], v[146:149], v[202:205], v[36:39]
	v_mfma_f32_16x16x32_bf16 v[28:31], v[154:157], v[202:205], v[28:31]
	v_mfma_f32_16x16x32_bf16 v[100:103], v[150:153], v[182:185], v[100:103]
	v_mfma_f32_16x16x32_bf16 v[104:107], v[158:161], v[182:185], v[104:107]
	v_mfma_f32_16x16x32_bf16 v[116:119], v[150:153], v[190:193], v[116:119]
	v_mfma_f32_16x16x32_bf16 v[120:123], v[158:161], v[190:193], v[120:123]
	v_mfma_f32_16x16x32_bf16 v[84:87], v[150:153], v[198:201], v[84:87]
	v_mfma_f32_16x16x32_bf16 v[80:83], v[158:161], v[198:201], v[80:83]
	v_mfma_f32_16x16x32_bf16 v[36:39], v[150:153], v[206:209], v[36:39]
	v_mfma_f32_16x16x32_bf16 v[28:31], v[158:161], v[206:209], v[28:31]
	v_mfma_f32_16x16x32_bf16 v[124:127], v[162:165], v[178:181], v[124:127]
	v_mfma_f32_16x16x32_bf16 v[112:115], v[170:173], v[178:181], v[112:115]
	v_mfma_f32_16x16x32_bf16 v[92:95], v[162:165], v[186:189], v[92:95]
	v_mfma_f32_16x16x32_bf16 v[88:91], v[170:173], v[186:189], v[88:91]
	v_mfma_f32_16x16x32_bf16 v[44:47], v[162:165], v[194:197], v[44:47]
	v_mfma_f32_16x16x32_bf16 v[40:43], v[170:173], v[194:197], v[40:43]
	v_mfma_f32_16x16x32_bf16 v[4:7], v[162:165], v[202:205], v[4:7]
	v_mfma_f32_16x16x32_bf16 v[0:3], v[170:173], v[202:205], v[0:3]
	v_mfma_f32_16x16x32_bf16 v[124:127], v[166:169], v[182:185], v[124:127]
	v_mfma_f32_16x16x32_bf16 v[112:115], v[174:177], v[182:185], v[112:115]
	v_mfma_f32_16x16x32_bf16 v[92:95], v[166:169], v[190:193], v[92:95]
	v_mfma_f32_16x16x32_bf16 v[88:91], v[174:177], v[190:193], v[88:91]
	v_mfma_f32_16x16x32_bf16 v[44:47], v[166:169], v[198:201], v[44:47]
	v_mfma_f32_16x16x32_bf16 v[40:43], v[174:177], v[198:201], v[40:43]
	v_mfma_f32_16x16x32_bf16 v[4:7], v[166:169], v[206:209], v[4:7]
	v_mfma_f32_16x16x32_bf16 v[0:3], v[174:177], v[206:209], v[0:3]
	s_barrier
	s_setprio 0
	s_add_i32 s45, s45, 2
	s_add_u32 s41, s41, 0x100
	s_addc_u32 s42, s42, 0
	s_add_u32 s43, s43, 0x100
	s_addc_u32 s44, s44, 0
	v_lshl_add_u64 v[136:137], v[136:137], 0, s[16:17]
	s_cmp_gt_u32 s45, 29
	v_lshl_add_u64 v[138:139], v[138:139], 0, s[16:17]
	s_cbranch_scc0 .LBB0_3608
	s_waitcnt vmcnt(0)
	s_cmpk_lt_u32 s24, 0x100
	s_cbranch_scc0 .LBB0_3611
	s_barrier

.Lpw_19:
	s_setprio 1
	s_barrier
	v_mfma_f32_16x16x32_bf16 v[88:91], v[0:3], v[56:59], 0
	v_mfma_f32_16x16x32_bf16 v[64:67], v[0:3], v[32:35], 0
	v_mfma_f32_16x16x32_bf16 v[68:71], v[8:11], v[32:35], 0
	v_mfma_f32_16x16x32_bf16 v[72:75], v[0:3], v[40:43], 0
	v_mfma_f32_16x16x32_bf16 v[76:79], v[8:11], v[40:43], 0
	v_mfma_f32_16x16x32_bf16 v[80:83], v[0:3], v[48:51], 0
	v_mfma_f32_16x16x32_bf16 v[84:87], v[8:11], v[48:51], 0
	v_mfma_f32_16x16x32_bf16 v[96:99], v[4:7], v[60:63], v[88:91]
	v_mfma_f32_16x16x32_bf16 v[88:91], v[8:11], v[56:59], 0
	v_mfma_f32_16x16x32_bf16 v[64:67], v[4:7], v[36:39], v[64:67]
	v_mfma_f32_16x16x32_bf16 v[68:71], v[12:15], v[36:39], v[68:71]
	v_mfma_f32_16x16x32_bf16 v[72:75], v[4:7], v[44:47], v[72:75]
	v_mfma_f32_16x16x32_bf16 v[76:79], v[12:15], v[44:47], v[76:79]
	v_mfma_f32_16x16x32_bf16 v[80:83], v[4:7], v[52:55], v[80:83]
	v_mfma_f32_16x16x32_bf16 v[84:87], v[12:15], v[52:55], v[84:87]
	v_mfma_f32_16x16x32_bf16 v[100:103], v[12:15], v[60:63], v[88:91]
	v_mfma_f32_16x16x32_bf16 v[88:91], v[16:19], v[32:35], 0
	v_mfma_f32_16x16x32_bf16 v[32:35], v[24:27], v[32:35], 0
	v_mfma_f32_16x16x32_bf16 v[112:115], v[20:23], v[36:39], v[88:91]
	v_mfma_f32_16x16x32_bf16 v[32:35], v[28:31], v[36:39], v[32:35]
	v_mfma_f32_16x16x32_bf16 v[36:39], v[16:19], v[40:43], 0
	v_mfma_f32_16x16x32_bf16 v[40:43], v[24:27], v[40:43], 0
	v_mfma_f32_16x16x32_bf16 v[36:39], v[20:23], v[44:47], v[36:39]
	v_mfma_f32_16x16x32_bf16 v[40:43], v[28:31], v[44:47], v[40:43]
	v_mfma_f32_16x16x32_bf16 v[44:47], v[16:19], v[48:51], 0
	v_mfma_f32_16x16x32_bf16 v[48:51], v[24:27], v[48:51], 0
	v_mfma_f32_16x16x32_bf16 v[44:47], v[20:23], v[52:55], v[44:47]
	v_mfma_f32_16x16x32_bf16 v[48:51], v[28:31], v[52:55], v[48:51]
	v_mfma_f32_16x16x32_bf16 v[52:55], v[16:19], v[56:59], 0
	v_mfma_f32_16x16x32_bf16 v[56:59], v[24:27], v[56:59], 0
	v_mfma_f32_16x16x32_bf16 v[52:55], v[20:23], v[60:63], v[52:55]
	v_mfma_f32_16x16x32_bf16 v[56:59], v[28:31], v[60:63], v[56:59]
	s_barrier
	s_setprio 0
	s_add_i32 s66, s60, s45
	v_lshl_add_u64 v[242:243], s[26:27], 0, v[128:129]
	s_add_i32 s67, s66, 0x2000
	v_lshl_add_u64 v[148:149], v[242:243], 0, s[12:13]
	s_mov_b32 m0, s66
	v_lshl_add_u64 v[244:245], s[26:27], 0, v[130:131]
	s_add_u32 s38, s26, 0x80100
	ds_read_b128 v[60:63], v147 offset:16384
	ds_read_b128 v[88:91], v147 offset:17408
	ds_read_b128 v[92:95], v147 offset:18432
	ds_read_b128 v[104:107], v147 offset:19456
	ds_read_b128 v[108:111], v147 offset:20480
	ds_read_b128 v[116:119], v147 offset:21504
	ds_read_b128 v[120:123], v147 offset:22528
	ds_read_b128 v[124:127], v147 offset:23552
	global_load_lds_dwordx4 v[148:149], off
	v_lshl_add_u64 v[148:149], v[244:245], 0, s[12:13]
	s_mov_b32 m0, s67
	s_addc_u32 s39, s27, 0
	s_add_i32 s68, s61, s45
	global_load_lds_dwordx4 v[148:149], off
	v_lshl_add_u64 v[148:149], s[38:39], 0, v[128:129]
	s_mov_b32 m0, s68
	s_add_i32 s69, s68, 0x2000
	global_load_lds_dwordx4 v128, s[38:39]
	v_lshl_add_u64 v[148:149], s[38:39], 0, v[130:131]
	s_mov_b32 m0, s69
	v_lshl_add_u64 v[246:247], s[36:37], 0, v[134:135]
	global_load_lds_dwordx4 v130, s[38:39]
	v_lshl_add_u64 v[148:149], v[246:247], 0, s[12:13]
	s_mov_b32 m0, s47
	v_lshl_add_u64 v[248:249], s[36:37], 0, v[132:133]
	global_load_lds_dwordx4 v[148:149], off
	v_lshl_add_u64 v[148:149], v[248:249], 0, s[12:13]
	s_mov_b32 m0, s48
	s_nop 0
	global_load_lds_dwordx4 v[148:149], off
	s_waitcnt vmcnt(24) lgkmcnt(0)
	s_cmp_lg_u32 s98, 0
	s_cbranch_scc1 .Lpw_20
	s_waitcnt vmcnt(8)
.Lpw_20:
	s_setprio 1
	s_barrier
	v_mfma_f32_16x16x32_bf16 v[148:151], v[0:3], v[60:63], 0
	v_mfma_f32_16x16x32_bf16 v[158:161], v[0:3], v[92:95], 0
	v_mfma_f32_16x16x32_bf16 v[166:169], v[0:3], v[108:111], 0
	v_mfma_f32_16x16x32_bf16 v[0:3], v[0:3], v[120:123], 0
	v_mfma_f32_16x16x32_bf16 v[150:153], v[4:7], v[88:91], v[148:151]
	v_mfma_f32_16x16x32_bf16 v[158:161], v[4:7], v[104:107], v[158:161]
	v_mfma_f32_16x16x32_bf16 v[166:169], v[4:7], v[116:119], v[166:169]
	v_mfma_f32_16x16x32_bf16 v[0:3], v[4:7], v[124:127], v[0:3]
	v_mfma_f32_16x16x32_bf16 v[4:7], v[8:11], v[120:123], 0
	v_mfma_f32_16x16x32_bf16 v[154:157], v[8:11], v[60:63], 0
	v_mfma_f32_16x16x32_bf16 v[162:165], v[8:11], v[92:95], 0
	v_mfma_f32_16x16x32_bf16 v[170:173], v[8:11], v[108:111], 0
	v_mfma_f32_16x16x32_bf16 v[4:7], v[12:15], v[124:127], v[4:7]
	v_mfma_f32_16x16x32_bf16 v[154:157], v[12:15], v[88:91], v[154:157]
	v_mfma_f32_16x16x32_bf16 v[162:165], v[12:15], v[104:107], v[162:165]
	v_mfma_f32_16x16x32_bf16 v[170:173], v[12:15], v[116:119], v[170:173]
	v_mfma_f32_16x16x32_bf16 v[8:11], v[16:19], v[60:63], 0
	v_mfma_f32_16x16x32_bf16 v[174:177], v[20:23], v[88:91], v[8:11]
	v_mfma_f32_16x16x32_bf16 v[8:11], v[24:27], v[60:63], 0
	v_mfma_f32_16x16x32_bf16 v[60:63], v[28:31], v[88:91], v[8:11]
	v_mfma_f32_16x16x32_bf16 v[8:11], v[16:19], v[92:95], 0
	v_mfma_f32_16x16x32_bf16 v[178:181], v[20:23], v[104:107], v[8:11]
	v_mfma_f32_16x16x32_bf16 v[8:11], v[24:27], v[92:95], 0
	v_mfma_f32_16x16x32_bf16 v[182:185], v[28:31], v[104:107], v[8:11]
	v_mfma_f32_16x16x32_bf16 v[8:11], v[16:19], v[108:111], 0
	v_mfma_f32_16x16x32_bf16 v[186:189], v[20:23], v[116:119], v[8:11]
	v_mfma_f32_16x16x32_bf16 v[8:11], v[24:27], v[108:111], 0
	v_mfma_f32_16x16x32_bf16 v[190:193], v[28:31], v[116:119], v[8:11]
	v_mfma_f32_16x16x32_bf16 v[8:11], v[16:19], v[120:123], 0
	v_mfma_f32_16x16x32_bf16 v[194:197], v[20:23], v[124:127], v[8:11]
	v_mfma_f32_16x16x32_bf16 v[8:11], v[24:27], v[120:123], 0
	v_mfma_f32_16x16x32_bf16 v[198:201], v[28:31], v[124:127], v[8:11]
	s_barrier
; template <class Epi, class Sched, bool ALIGN_EPI = false, bool SP2 = false, bool A_TILED = false>
; __device__ __forceinline__ void gemm_phase(PG8_LAS unsigned char* lds, const Gemm g, const Sched& S, const Epi& E, const int wave_s) {
;     ...
;             const char* a1 = cA + kstepA; const char* a2 = cA + 2 * kstepA; const char* b2 = cB + 2 * kstep; const char* a3 = a2 + kstepA; const char* b3 = b2 + kstep;
;             PG8_ITER(PG8_MMAZ)
	s_setprio 0
	s_add_i32 s70, 0, 0x18000
	s_add_i32 s72, 0, 0x1c000
	v_add_u32_e32 v148, s70, v144
	v_add_u32_e32 v149, s72, v144
	s_nop 0
	ds_read_b128 v[8:11], v148
	ds_read_b128 v[12:15], v148 offset:1024
	ds_read_b128 v[16:19], v148 offset:2048
	ds_read_b128 v[20:23], v148 offset:3072
	ds_read_b128 v[202:205], v149
	ds_read_b128 v[206:209], v149 offset:1024
	ds_read_b128 v[210:213], v149 offset:2048
	ds_read_b128 v[214:217], v149 offset:3072
	s_add_u32 s38, s36, 0x80100
	s_addc_u32 s39, s37, 0
	s_mov_b32 m0, s49
	v_lshl_add_u64 v[88:89], s[38:39], 0, v[134:135]
	ds_read_b128 v[24:27], v147 offset:32768
	ds_read_b128 v[28:31], v147 offset:33792
	ds_read_b128 v[218:221], v147 offset:34816
	ds_read_b128 v[222:225], v147 offset:35840
	ds_read_b128 v[226:229], v147 offset:36864
	ds_read_b128 v[230:233], v147 offset:37888
	ds_read_b128 v[234:237], v147 offset:38912
	ds_read_b128 v[238:241], v147 offset:39936
	global_load_lds_dwordx4 v134, s[38:39]
	v_lshl_add_u64 v[88:89], s[38:39], 0, v[132:133]
	s_mov_b32 m0, s50
	s_nop 0
	global_load_lds_dwordx4 v132, s[38:39]
	s_waitcnt vmcnt(8) lgkmcnt(0)
	s_setprio 1
	s_barrier
	v_mfma_f32_16x16x32_bf16 v[64:67], v[8:11], v[24:27], v[64:67]
	v_mfma_f32_16x16x32_bf16 v[120:123], v[12:15], v[28:31], v[64:67]
	v_mfma_f32_16x16x32_bf16 v[64:67], v[16:19], v[24:27], v[68:71]
	v_mfma_f32_16x16x32_bf16 v[124:127], v[20:23], v[28:31], v[64:67]
	v_mfma_f32_16x16x32_bf16 v[64:67], v[8:11], v[218:221], v[72:75]
	v_mfma_f32_16x16x32_bf16 v[104:107], v[12:15], v[222:225], v[64:67]
	v_mfma_f32_16x16x32_bf16 v[64:67], v[16:19], v[218:221], v[76:79]
	v_mfma_f32_16x16x32_bf16 v[108:111], v[20:23], v[222:225], v[64:67]
	v_mfma_f32_16x16x32_bf16 v[64:67], v[8:11], v[226:229], v[80:83]
	v_mfma_f32_16x16x32_bf16 v[88:91], v[12:15], v[230:233], v[64:67]
	v_mfma_f32_16x16x32_bf16 v[64:67], v[16:19], v[226:229], v[84:87]
	v_mfma_f32_16x16x32_bf16 v[92:95], v[20:23], v[230:233], v[64:67]
	v_mfma_f32_16x16x32_bf16 v[64:67], v[8:11], v[234:237], v[96:99]
	v_mfma_f32_16x16x32_bf16 v[68:71], v[16:19], v[234:237], v[100:103]
	v_mfma_f32_16x16x32_bf16 v[64:67], v[12:15], v[238:241], v[64:67]
	v_mfma_f32_16x16x32_bf16 v[68:71], v[20:23], v[238:241], v[68:71]
	v_mfma_f32_16x16x32_bf16 v[72:75], v[202:205], v[24:27], v[112:115]
	v_mfma_f32_16x16x32_bf16 v[24:27], v[210:213], v[24:27], v[32:35]
	v_mfma_f32_16x16x32_bf16 v[116:119], v[214:217], v[28:31], v[24:27]
	v_mfma_f32_16x16x32_bf16 v[24:27], v[202:205], v[218:221], v[36:39]
	v_mfma_f32_16x16x32_bf16 v[96:99], v[206:209], v[222:225], v[24:27]
	v_mfma_f32_16x16x32_bf16 v[24:27], v[210:213], v[218:221], v[40:43]
	v_mfma_f32_16x16x32_bf16 v[100:103], v[214:217], v[222:225], v[24:27]
	v_mfma_f32_16x16x32_bf16 v[24:27], v[202:205], v[226:229], v[44:47]
	v_mfma_f32_16x16x32_bf16 v[80:83], v[206:209], v[230:233], v[24:27]
	v_mfma_f32_16x16x32_bf16 v[24:27], v[210:213], v[226:229], v[48:51]
	v_mfma_f32_16x16x32_bf16 v[84:87], v[214:217], v[230:233], v[24:27]
	v_mfma_f32_16x16x32_bf16 v[24:27], v[202:205], v[234:237], v[52:55]
	v_mfma_f32_16x16x32_bf16 v[48:51], v[206:209], v[238:241], v[24:27]
	v_mfma_f32_16x16x32_bf16 v[24:27], v[210:213], v[234:237], v[56:59]
	v_mfma_f32_16x16x32_bf16 v[112:115], v[206:209], v[28:31], v[72:75]
	v_mfma_f32_16x16x32_bf16 v[52:55], v[214:217], v[238:241], v[24:27]
	s_barrier
	s_setprio 0
	s_add_i32 s70, s70, s45
	s_add_i32 s71, s70, 0x2000
	s_nop 1
	v_lshl_add_u64 v[24:25], v[242:243], 0, s[14:15]
	s_mov_b32 m0, s70
	s_add_u32 s38, s26, 0x80180
	ds_read_b128 v[32:35], v147 offset:49152
	ds_read_b128 v[36:39], v147 offset:50176
	ds_read_b128 v[218:221], v147 offset:51200
	ds_read_b128 v[222:225], v147 offset:52224
	ds_read_b128 v[226:229], v147 offset:53248
	ds_read_b128 v[230:233], v147 offset:54272
	ds_read_b128 v[234:237], v147 offset:55296
	ds_read_b128 v[238:241], v147 offset:56320
	global_load_lds_dwordx4 v[24:25], off
	v_lshl_add_u64 v[24:25], v[244:245], 0, s[14:15]
	s_mov_b32 m0, s71
	s_addc_u32 s39, s27, 0
	s_add_i32 s72, s72, s45
	global_load_lds_dwordx4 v[24:25], off
	v_lshl_add_u64 v[24:25], s[38:39], 0, v[128:129]
	s_mov_b32 m0, s72
	s_add_i32 s73, s72, 0x2000
	global_load_lds_dwordx4 v128, s[38:39]
	v_lshl_add_u64 v[24:25], s[38:39], 0, v[130:131]
	s_mov_b32 m0, s73
	s_nop 0
	global_load_lds_dwordx4 v130, s[38:39]
	v_lshl_add_u64 v[24:25], v[246:247], 0, s[14:15]
	s_mov_b32 m0, s56
	s_nop 0
	global_load_lds_dwordx4 v[24:25], off
	v_lshl_add_u64 v[24:25], v[248:249], 0, s[14:15]
	s_mov_b32 m0, s57
	s_nop 0
	global_load_lds_dwordx4 v[24:25], off
	s_waitcnt vmcnt(8) lgkmcnt(0)
	s_setprio 1
	s_barrier
	v_mfma_f32_16x16x32_bf16 v[24:27], v[8:11], v[32:35], v[150:153]
	v_mfma_f32_16x16x32_bf16 v[72:75], v[12:15], v[36:39], v[24:27]
	v_mfma_f32_16x16x32_bf16 v[24:27], v[16:19], v[32:35], v[154:157]
	v_mfma_f32_16x16x32_bf16 v[76:79], v[20:23], v[36:39], v[24:27]
	v_mfma_f32_16x16x32_bf16 v[24:27], v[8:11], v[218:221], v[158:161]
	v_mfma_f32_16x16x32_bf16 v[40:43], v[12:15], v[222:225], v[24:27]
	v_mfma_f32_16x16x32_bf16 v[24:27], v[16:19], v[218:221], v[162:165]
	v_mfma_f32_16x16x32_bf16 v[0:3], v[8:11], v[234:237], v[0:3]
	v_mfma_f32_16x16x32_bf16 v[44:47], v[20:23], v[222:225], v[24:27]
	v_mfma_f32_16x16x32_bf16 v[24:27], v[8:11], v[226:229], v[166:169]
	v_mfma_f32_16x16x32_bf16 v[28:31], v[16:19], v[226:229], v[170:173]
	v_mfma_f32_16x16x32_bf16 v[8:11], v[12:15], v[238:241], v[0:3]
	v_mfma_f32_16x16x32_bf16 v[0:3], v[16:19], v[234:237], v[4:7]
	v_mfma_f32_16x16x32_bf16 v[24:27], v[12:15], v[230:233], v[24:27]
	v_mfma_f32_16x16x32_bf16 v[28:31], v[20:23], v[230:233], v[28:31]
	v_mfma_f32_16x16x32_bf16 v[12:15], v[20:23], v[238:241], v[0:3]
	v_mfma_f32_16x16x32_bf16 v[0:3], v[202:205], v[32:35], v[174:177]
	v_mfma_f32_16x16x32_bf16 v[56:59], v[206:209], v[36:39], v[0:3]
	v_mfma_f32_16x16x32_bf16 v[0:3], v[210:213], v[32:35], v[60:63]
	v_mfma_f32_16x16x32_bf16 v[60:63], v[214:217], v[36:39], v[0:3]
	v_mfma_f32_16x16x32_bf16 v[0:3], v[202:205], v[218:221], v[178:181]
	v_mfma_f32_16x16x32_bf16 v[32:35], v[206:209], v[222:225], v[0:3]
	v_mfma_f32_16x16x32_bf16 v[0:3], v[210:213], v[218:221], v[182:185]
	v_mfma_f32_16x16x32_bf16 v[36:39], v[214:217], v[222:225], v[0:3]
	v_mfma_f32_16x16x32_bf16 v[0:3], v[202:205], v[226:229], v[186:189]
	v_mfma_f32_16x16x32_bf16 v[16:19], v[206:209], v[230:233], v[0:3]
	v_mfma_f32_16x16x32_bf16 v[0:3], v[210:213], v[226:229], v[190:193]
	v_mfma_f32_16x16x32_bf16 v[20:23], v[214:217], v[230:233], v[0:3]
	v_mfma_f32_16x16x32_bf16 v[0:3], v[202:205], v[234:237], v[194:197]
	v_mfma_f32_16x16x32_bf16 v[4:7], v[210:213], v[234:237], v[198:201]
	v_mfma_f32_16x16x32_bf16 v[0:3], v[206:209], v[238:241], v[0:3]
	v_mfma_f32_16x16x32_bf16 v[4:7], v[214:217], v[238:241], v[4:7]
	s_barrier
	s_setprio 0
	s_add_u32 s74, s26, 0x200
	s_addc_u32 s75, s27, 0
	s_add_u32 s26, s36, 0x80180
	s_addc_u32 s27, s37, 0
	s_mov_b32 s76, 0
; template <class Epi, class Sched, bool ALIGN_EPI = false, bool SP2 = false, bool A_TILED = false>
; __device__ __forceinline__ void gemm_phase(PG8_LAS unsigned char* lds, const Gemm g, const Sched& S, const Epi& E, const int wave_s) {
;     ...
;         for (int t = PEEL ? 2 : 0; t < nt; t += 2) {
;             const bool last = (t == nt - 2);
;             const char* a1 = cA + (size_t)(t + 1) * kstepA;
;             const char* a2 = last ? nA : cA + (size_t)(t + 2) * kstepA; const char* b2 = last ? nB : cB + (size_t)(t + 2) * kstep;
;             const char* a3 = a2 + kstepA; const char* b3 = b2 + kstep;
.LBB0_3720:
	ds_read_b128 v[150:153], v145
	ds_read_b128 v[154:157], v145 offset:1024
	ds_read_b128 v[158:161], v145 offset:2048
	ds_read_b128 v[162:165], v145 offset:3072
	ds_read_b128 v[166:169], v146
	ds_read_b128 v[170:173], v146 offset:1024
	ds_read_b128 v[174:177], v146 offset:2048
	ds_read_b128 v[178:181], v146 offset:3072
	s_add_u32 s36, s26, 0xfff80080
	s_addc_u32 s37, s27, -1
	s_cmp_eq_u32 s76, 28
	s_cselect_b32 s39, s17, s37
	s_cselect_b32 s38, s19, s36
	s_cselect_b32 s37, s62, s75
	s_cselect_b32 s36, s63, s74
	s_mov_b32 m0, s64
	v_lshl_add_u64 v[214:215], s[26:27], 0, v[138:139]
	ds_read_b128 v[182:185], v147
	ds_read_b128 v[186:189], v147 offset:1024
	ds_read_b128 v[190:193], v147 offset:2048
	ds_read_b128 v[194:197], v147 offset:3072
	ds_read_b128 v[198:201], v147 offset:4096
	ds_read_b128 v[202:205], v147 offset:5120
	ds_read_b128 v[206:209], v147 offset:6144
	ds_read_b128 v[210:213], v147 offset:7168
	global_load_lds_dwordx4 v138, s[26:27]
	v_lshl_add_u64 v[214:215], s[26:27], 0, v[136:137]
	s_mov_b32 m0, s65
	s_nop 0
	global_load_lds_dwordx4 v136, s[26:27]
	s_waitcnt vmcnt(8) lgkmcnt(0)
	s_setprio 1
	s_barrier
	v_mfma_f32_16x16x32_bf16 v[120:123], v[150:153], v[182:185], v[120:123]
	v_mfma_f32_16x16x32_bf16 v[124:127], v[158:161], v[182:185], v[124:127]
	v_mfma_f32_16x16x32_bf16 v[104:107], v[150:153], v[190:193], v[104:107]
	v_mfma_f32_16x16x32_bf16 v[108:111], v[158:161], v[190:193], v[108:111]
	v_mfma_f32_16x16x32_bf16 v[88:91], v[150:153], v[198:201], v[88:91]
	v_mfma_f32_16x16x32_bf16 v[92:95], v[158:161], v[198:201], v[92:95]
	v_mfma_f32_16x16x32_bf16 v[64:67], v[150:153], v[206:209], v[64:67]
	v_mfma_f32_16x16x32_bf16 v[68:71], v[158:161], v[206:209], v[68:71]
	v_mfma_f32_16x16x32_bf16 v[120:123], v[154:157], v[186:189], v[120:123]
	v_mfma_f32_16x16x32_bf16 v[124:127], v[162:165], v[186:189], v[124:127]
	v_mfma_f32_16x16x32_bf16 v[104:107], v[154:157], v[194:197], v[104:107]
	v_mfma_f32_16x16x32_bf16 v[108:111], v[162:165], v[194:197], v[108:111]
	v_mfma_f32_16x16x32_bf16 v[88:91], v[154:157], v[202:205], v[88:91]
	v_mfma_f32_16x16x32_bf16 v[92:95], v[162:165], v[202:205], v[92:95]
	v_mfma_f32_16x16x32_bf16 v[64:67], v[154:157], v[210:213], v[64:67]
	v_mfma_f32_16x16x32_bf16 v[68:71], v[162:165], v[210:213], v[68:71]
	v_mfma_f32_16x16x32_bf16 v[112:115], v[166:169], v[182:185], v[112:115]
	v_mfma_f32_16x16x32_bf16 v[116:119], v[174:177], v[182:185], v[116:119]
	v_mfma_f32_16x16x32_bf16 v[96:99], v[166:169], v[190:193], v[96:99]
	v_mfma_f32_16x16x32_bf16 v[100:103], v[174:177], v[190:193], v[100:103]
	v_mfma_f32_16x16x32_bf16 v[80:83], v[166:169], v[198:201], v[80:83]
	v_mfma_f32_16x16x32_bf16 v[84:87], v[174:177], v[198:201], v[84:87]
	v_mfma_f32_16x16x32_bf16 v[48:51], v[166:169], v[206:209], v[48:51]
	v_mfma_f32_16x16x32_bf16 v[52:55], v[174:177], v[206:209], v[52:55]
	v_mfma_f32_16x16x32_bf16 v[112:115], v[170:173], v[186:189], v[112:115]
	v_mfma_f32_16x16x32_bf16 v[116:119], v[178:181], v[186:189], v[116:119]
	v_mfma_f32_16x16x32_bf16 v[96:99], v[170:173], v[194:197], v[96:99]
	v_mfma_f32_16x16x32_bf16 v[100:103], v[178:181], v[194:197], v[100:103]
	v_mfma_f32_16x16x32_bf16 v[80:83], v[170:173], v[202:205], v[80:83]
	v_mfma_f32_16x16x32_bf16 v[84:87], v[178:181], v[202:205], v[84:87]
	v_mfma_f32_16x16x32_bf16 v[48:51], v[170:173], v[210:213], v[48:51]
	v_mfma_f32_16x16x32_bf16 v[52:55], v[178:181], v[210:213], v[52:55]
	s_barrier
	s_setprio 0
	s_mov_b32 m0, s66
	v_lshl_add_u64 v[214:215], s[36:37], 0, v[128:129]
	s_add_u32 s78, s36, 0x80000
	ds_read_b128 v[182:185], v147 offset:16384
	ds_read_b128 v[186:189], v147 offset:17408
	ds_read_b128 v[190:193], v147 offset:18432
	ds_read_b128 v[194:197], v147 offset:19456
	ds_read_b128 v[198:201], v147 offset:20480
	ds_read_b128 v[202:205], v147 offset:21504
	ds_read_b128 v[206:209], v147 offset:22528
	ds_read_b128 v[210:213], v147 offset:23552
	global_load_lds_dwordx4 v128, s[36:37]
	v_lshl_add_u64 v[216:217], s[36:37], 0, v[130:131]
	s_mov_b32 m0, s67
	s_addc_u32 s79, s37, 0
	global_load_lds_dwordx4 v130, s[36:37]
	v_lshl_add_u64 v[218:219], s[78:79], 0, v[128:129]
	s_mov_b32 m0, s68
	v_lshl_add_u64 v[220:221], s[38:39], 0, v[132:133]
	global_load_lds_dwordx4 v128, s[78:79]
	v_lshl_add_u64 v[218:219], s[78:79], 0, v[130:131]
	s_mov_b32 m0, s69
	s_nop 0
	global_load_lds_dwordx4 v130, s[78:79]
	v_lshl_add_u64 v[218:219], s[38:39], 0, v[134:135]
	s_mov_b32 m0, s47
	s_nop 0
	global_load_lds_dwordx4 v134, s[38:39]
	s_mov_b32 m0, s48
	s_nop 0
	global_load_lds_dwordx4 v132, s[38:39]
	s_waitcnt vmcnt(8) lgkmcnt(0)
	s_setprio 1
	s_barrier
	v_mfma_f32_16x16x32_bf16 v[72:75], v[150:153], v[182:185], v[72:75]
	v_mfma_f32_16x16x32_bf16 v[76:79], v[158:161], v[182:185], v[76:79]
	v_mfma_f32_16x16x32_bf16 v[40:43], v[150:153], v[190:193], v[40:43]
	v_mfma_f32_16x16x32_bf16 v[44:47], v[158:161], v[190:193], v[44:47]
	v_mfma_f32_16x16x32_bf16 v[24:27], v[150:153], v[198:201], v[24:27]
	v_mfma_f32_16x16x32_bf16 v[28:31], v[158:161], v[198:201], v[28:31]
	v_mfma_f32_16x16x32_bf16 v[8:11], v[150:153], v[206:209], v[8:11]
	v_mfma_f32_16x16x32_bf16 v[12:15], v[158:161], v[206:209], v[12:15]
	v_mfma_f32_16x16x32_bf16 v[72:75], v[154:157], v[186:189], v[72:75]
	v_mfma_f32_16x16x32_bf16 v[76:79], v[162:165], v[186:189], v[76:79]
	v_mfma_f32_16x16x32_bf16 v[40:43], v[154:157], v[194:197], v[40:43]
	v_mfma_f32_16x16x32_bf16 v[44:47], v[162:165], v[194:197], v[44:47]
	v_mfma_f32_16x16x32_bf16 v[24:27], v[154:157], v[202:205], v[24:27]
	v_mfma_f32_16x16x32_bf16 v[28:31], v[162:165], v[202:205], v[28:31]
	v_mfma_f32_16x16x32_bf16 v[8:11], v[154:157], v[210:213], v[8:11]
	v_mfma_f32_16x16x32_bf16 v[12:15], v[162:165], v[210:213], v[12:15]
	v_mfma_f32_16x16x32_bf16 v[56:59], v[166:169], v[182:185], v[56:59]
	v_mfma_f32_16x16x32_bf16 v[60:63], v[174:177], v[182:185], v[60:63]
	v_mfma_f32_16x16x32_bf16 v[32:35], v[166:169], v[190:193], v[32:35]
	v_mfma_f32_16x16x32_bf16 v[36:39], v[174:177], v[190:193], v[36:39]
	v_mfma_f32_16x16x32_bf16 v[16:19], v[166:169], v[198:201], v[16:19]
	v_mfma_f32_16x16x32_bf16 v[20:23], v[174:177], v[198:201], v[20:23]
	v_mfma_f32_16x16x32_bf16 v[0:3], v[166:169], v[206:209], v[0:3]
	v_mfma_f32_16x16x32_bf16 v[4:7], v[174:177], v[206:209], v[4:7]
	v_mfma_f32_16x16x32_bf16 v[56:59], v[170:173], v[186:189], v[56:59]
	v_mfma_f32_16x16x32_bf16 v[60:63], v[178:181], v[186:189], v[60:63]
	v_mfma_f32_16x16x32_bf16 v[32:35], v[170:173], v[194:197], v[32:35]
	v_mfma_f32_16x16x32_bf16 v[36:39], v[178:181], v[194:197], v[36:39]
	v_mfma_f32_16x16x32_bf16 v[16:19], v[170:173], v[202:205], v[16:19]
	v_mfma_f32_16x16x32_bf16 v[20:23], v[178:181], v[202:205], v[20:23]
	v_mfma_f32_16x16x32_bf16 v[0:3], v[170:173], v[210:213], v[0:3]
	v_mfma_f32_16x16x32_bf16 v[4:7], v[178:181], v[210:213], v[4:7]
	s_barrier
	s_setprio 0
	ds_read_b128 v[150:153], v148
	ds_read_b128 v[154:157], v148 offset:1024
	ds_read_b128 v[158:161], v148 offset:2048
	ds_read_b128 v[162:165], v148 offset:3072
	ds_read_b128 v[166:169], v149
	ds_read_b128 v[170:173], v149 offset:1024
	ds_read_b128 v[174:177], v149 offset:2048
	ds_read_b128 v[178:181], v149 offset:3072
	s_add_u32 s38, s38, 0x80000
	s_addc_u32 s39, s39, 0
	s_mov_b32 m0, s49
	v_lshl_add_u64 v[222:223], s[38:39], 0, v[134:135]
	ds_read_b128 v[182:185], v147 offset:32768
	ds_read_b128 v[186:189], v147 offset:33792
	ds_read_b128 v[190:193], v147 offset:34816
	ds_read_b128 v[194:197], v147 offset:35840
	ds_read_b128 v[198:201], v147 offset:36864
	ds_read_b128 v[202:205], v147 offset:37888
	ds_read_b128 v[206:209], v147 offset:38912
	ds_read_b128 v[210:213], v147 offset:39936
	global_load_lds_dwordx4 v134, s[38:39]
	v_lshl_add_u64 v[222:223], s[38:39], 0, v[132:133]
	s_mov_b32 m0, s50
	s_nop 0
	global_load_lds_dwordx4 v132, s[38:39]
	s_waitcnt vmcnt(8) lgkmcnt(0)
	s_setprio 1
	s_barrier
	v_mfma_f32_16x16x32_bf16 v[120:123], v[150:153], v[182:185], v[120:123]
	v_mfma_f32_16x16x32_bf16 v[124:127], v[158:161], v[182:185], v[124:127]
	v_mfma_f32_16x16x32_bf16 v[104:107], v[150:153], v[190:193], v[104:107]
	v_mfma_f32_16x16x32_bf16 v[108:111], v[158:161], v[190:193], v[108:111]
	v_mfma_f32_16x16x32_bf16 v[88:91], v[150:153], v[198:201], v[88:91]
	v_mfma_f32_16x16x32_bf16 v[92:95], v[158:161], v[198:201], v[92:95]
	v_mfma_f32_16x16x32_bf16 v[64:67], v[150:153], v[206:209], v[64:67]
	v_mfma_f32_16x16x32_bf16 v[68:71], v[158:161], v[206:209], v[68:71]
	v_mfma_f32_16x16x32_bf16 v[120:123], v[154:157], v[186:189], v[120:123]
	v_mfma_f32_16x16x32_bf16 v[124:127], v[162:165], v[186:189], v[124:127]
	v_mfma_f32_16x16x32_bf16 v[104:107], v[154:157], v[194:197], v[104:107]
	v_mfma_f32_16x16x32_bf16 v[108:111], v[162:165], v[194:197], v[108:111]
	v_mfma_f32_16x16x32_bf16 v[88:91], v[154:157], v[202:205], v[88:91]
	v_mfma_f32_16x16x32_bf16 v[92:95], v[162:165], v[202:205], v[92:95]
	v_mfma_f32_16x16x32_bf16 v[64:67], v[154:157], v[210:213], v[64:67]
	v_mfma_f32_16x16x32_bf16 v[68:71], v[162:165], v[210:213], v[68:71]
	v_mfma_f32_16x16x32_bf16 v[112:115], v[166:169], v[182:185], v[112:115]
	v_mfma_f32_16x16x32_bf16 v[116:119], v[174:177], v[182:185], v[116:119]
	v_mfma_f32_16x16x32_bf16 v[96:99], v[166:169], v[190:193], v[96:99]
	v_mfma_f32_16x16x32_bf16 v[100:103], v[174:177], v[190:193], v[100:103]
	v_mfma_f32_16x16x32_bf16 v[80:83], v[166:169], v[198:201], v[80:83]
	v_mfma_f32_16x16x32_bf16 v[84:87], v[174:177], v[198:201], v[84:87]
	v_mfma_f32_16x16x32_bf16 v[48:51], v[166:169], v[206:209], v[48:51]
	v_mfma_f32_16x16x32_bf16 v[52:55], v[174:177], v[206:209], v[52:55]
	v_mfma_f32_16x16x32_bf16 v[112:115], v[170:173], v[186:189], v[112:115]
	v_mfma_f32_16x16x32_bf16 v[116:119], v[178:181], v[186:189], v[116:119]
	v_mfma_f32_16x16x32_bf16 v[96:99], v[170:173], v[194:197], v[96:99]
	v_mfma_f32_16x16x32_bf16 v[100:103], v[178:181], v[194:197], v[100:103]
	v_mfma_f32_16x16x32_bf16 v[80:83], v[170:173], v[202:205], v[80:83]
	v_mfma_f32_16x16x32_bf16 v[84:87], v[178:181], v[202:205], v[84:87]
	v_mfma_f32_16x16x32_bf16 v[48:51], v[170:173], v[210:213], v[48:51]
	v_mfma_f32_16x16x32_bf16 v[52:55], v[178:181], v[210:213], v[52:55]
	s_barrier
; #define PG8_BAR __builtin_amdgcn_s_barrier()
; template <class Epi, class Sched, bool ALIGN_EPI = false, bool SP2 = false, bool A_TILED = false>
; __device__ __forceinline__ void gemm_phase(PG8_LAS unsigned char* lds, const Gemm g, const Sched& S, const Epi& E, const int wave_s) {
;     ...
;         if constexpr (ALIGN_EPI) { if (wr == 0) PG8_BAR; }
	s_setprio 0
	s_mov_b32 m0, s70
	v_lshl_add_u64 v[214:215], v[214:215], 0, s[6:7]
	s_add_u32 s36, s36, 0x80080
	ds_read_b128 v[182:185], v147 offset:49152
	ds_read_b128 v[186:189], v147 offset:50176
	ds_read_b128 v[190:193], v147 offset:51200
	ds_read_b128 v[194:197], v147 offset:52224
	ds_read_b128 v[198:201], v147 offset:53248
	ds_read_b128 v[202:205], v147 offset:54272
	ds_read_b128 v[206:209], v147 offset:55296
	ds_read_b128 v[210:213], v147 offset:56320
	global_load_lds_dwordx4 v[214:215], off
	v_lshl_add_u64 v[214:215], v[216:217], 0, s[6:7]
	s_mov_b32 m0, s71
	s_addc_u32 s37, s37, 0
	global_load_lds_dwordx4 v[214:215], off
	v_lshl_add_u64 v[214:215], s[36:37], 0, v[128:129]
	s_mov_b32 m0, s72
	s_nop 0
	global_load_lds_dwordx4 v128, s[36:37]
	v_lshl_add_u64 v[214:215], s[36:37], 0, v[130:131]
	s_mov_b32 m0, s73
	s_nop 0
	global_load_lds_dwordx4 v130, s[36:37]
	v_lshl_add_u64 v[214:215], v[218:219], 0, s[6:7]
	s_mov_b32 m0, s56
	s_nop 0
	global_load_lds_dwordx4 v[214:215], off
	v_lshl_add_u64 v[214:215], v[220:221], 0, s[6:7]
	s_mov_b32 m0, s57
	s_nop 0
	global_load_lds_dwordx4 v[214:215], off
	s_waitcnt vmcnt(8) lgkmcnt(0)
	s_setprio 1
	s_barrier
	v_mfma_f32_16x16x32_bf16 v[72:75], v[150:153], v[182:185], v[72:75]
	v_mfma_f32_16x16x32_bf16 v[76:79], v[158:161], v[182:185], v[76:79]
	v_mfma_f32_16x16x32_bf16 v[40:43], v[150:153], v[190:193], v[40:43]
	v_mfma_f32_16x16x32_bf16 v[44:47], v[158:161], v[190:193], v[44:47]
	v_mfma_f32_16x16x32_bf16 v[24:27], v[150:153], v[198:201], v[24:27]
	v_mfma_f32_16x16x32_bf16 v[28:31], v[158:161], v[198:201], v[28:31]
	v_mfma_f32_16x16x32_bf16 v[8:11], v[150:153], v[206:209], v[8:11]
	v_mfma_f32_16x16x32_bf16 v[12:15], v[158:161], v[206:209], v[12:15]
	v_mfma_f32_16x16x32_bf16 v[72:75], v[154:157], v[186:189], v[72:75]
	v_mfma_f32_16x16x32_bf16 v[76:79], v[162:165], v[186:189], v[76:79]
	v_mfma_f32_16x16x32_bf16 v[40:43], v[154:157], v[194:197], v[40:43]
	v_mfma_f32_16x16x32_bf16 v[44:47], v[162:165], v[194:197], v[44:47]
	v_mfma_f32_16x16x32_bf16 v[24:27], v[154:157], v[202:205], v[24:27]
	v_mfma_f32_16x16x32_bf16 v[28:31], v[162:165], v[202:205], v[28:31]
	v_mfma_f32_16x16x32_bf16 v[8:11], v[154:157], v[210:213], v[8:11]
	v_mfma_f32_16x16x32_bf16 v[12:15], v[162:165], v[210:213], v[12:15]
	v_mfma_f32_16x16x32_bf16 v[56:59], v[166:169], v[182:185], v[56:59]
	v_mfma_f32_16x16x32_bf16 v[60:63], v[174:177], v[182:185], v[60:63]
	v_mfma_f32_16x16x32_bf16 v[32:35], v[166:169], v[190:193], v[32:35]
	v_mfma_f32_16x16x32_bf16 v[36:39], v[174:177], v[190:193], v[36:39]
	v_mfma_f32_16x16x32_bf16 v[16:19], v[166:169], v[198:201], v[16:19]
	v_mfma_f32_16x16x32_bf16 v[20:23], v[174:177], v[198:201], v[20:23]
	v_mfma_f32_16x16x32_bf16 v[0:3], v[166:169], v[206:209], v[0:3]
	v_mfma_f32_16x16x32_bf16 v[4:7], v[174:177], v[206:209], v[4:7]
	v_mfma_f32_16x16x32_bf16 v[56:59], v[170:173], v[186:189], v[56:59]
	v_mfma_f32_16x16x32_bf16 v[60:63], v[178:181], v[186:189], v[60:63]
	v_mfma_f32_16x16x32_bf16 v[32:35], v[170:173], v[194:197], v[32:35]
	v_mfma_f32_16x16x32_bf16 v[36:39], v[178:181], v[194:197], v[36:39]
	v_mfma_f32_16x16x32_bf16 v[16:19], v[170:173], v[202:205], v[16:19]
	v_mfma_f32_16x16x32_bf16 v[20:23], v[178:181], v[202:205], v[20:23]
	v_mfma_f32_16x16x32_bf16 v[0:3], v[170:173], v[210:213], v[0:3]
	v_mfma_f32_16x16x32_bf16 v[4:7], v[178:181], v[210:213], v[4:7]
	s_barrier
	s_setprio 0
	s_add_i32 s76, s76, 2
	s_add_u32 s74, s74, 0x100
	s_addc_u32 s75, s75, 0
	s_add_u32 s26, s26, 0x100
	s_addc_u32 s27, s27, 0
	s_cmp_gt_u32 s76, 29
	s_cbranch_scc0 .LBB0_3720
	s_and_b64 vcc, exec, s[8:9]
	s_cbranch_vccz .LBB0_3723
	s_barrier

; template <class Epi, class Sched, bool ALIGN_EPI = false, bool SP2 = false, bool A_TILED = false>
; __device__ __forceinline__ void gemm_phase(PG8_LAS unsigned char* lds, const Gemm g, const Sched& S, const Epi& E, const int wave_s) {
;     ...
;         for (int t = PEEL ? 2 : 0; t < nt; t += 2) {
;             const bool last = (t == nt - 2);
;             const char* a1 = cA + (size_t)(t + 1) * kstepA;
;             const char* a2 = last ? nA : cA + (size_t)(t + 2) * kstepA; const char* b2 = last ? nB : cB + (size_t)(t + 2) * kstep;
;             const char* a3 = a2 + kstepA; const char* b3 = b2 + kstep;
.LBB0_3793:
	ds_read_b128 v[146:149], v140
	ds_read_b128 v[150:153], v140 offset:1024
	ds_read_b128 v[154:157], v140 offset:2048
	ds_read_b128 v[158:161], v140 offset:3072
	ds_read_b128 v[162:165], v141
	ds_read_b128 v[166:169], v141 offset:1024
	ds_read_b128 v[170:173], v141 offset:2048
	ds_read_b128 v[174:177], v141 offset:3072
	s_add_u32 s16, s58, s40
	s_addc_u32 s17, s59, s41
	s_add_u32 s18, s58, s38
	s_addc_u32 s19, s59, s39
	s_cmpk_eq_i32 s42, 0x7c
	s_cselect_b32 s20, s4, s16
	s_cselect_b32 s21, s5, s17
	s_cselect_b32 s18, s0, s18
	s_cselect_b32 s19, s1, s19
	s_add_u32 s16, s20, 0x8000
	s_addc_u32 s17, s21, 0
	s_mov_b32 m0, s43
	v_lshl_add_u64 v[210:211], s[58:59], 0, v[138:139]
	ds_read_b128 v[178:181], v142
	ds_read_b128 v[182:185], v142 offset:1024
	ds_read_b128 v[186:189], v142 offset:2048
	ds_read_b128 v[190:193], v142 offset:3072
	ds_read_b128 v[194:197], v142 offset:4096
	ds_read_b128 v[198:201], v142 offset:5120
	ds_read_b128 v[202:205], v142 offset:6144
	ds_read_b128 v[206:209], v142 offset:7168
	global_load_lds_dwordx4 v[210:211], off
	v_lshl_add_u64 v[210:211], s[58:59], 0, v[136:137]
	s_mov_b32 m0, s44
	s_nop 0
	global_load_lds_dwordx4 v[210:211], off
	s_waitcnt vmcnt(8) lgkmcnt(0)
	s_setprio 1
	s_barrier
	v_mfma_f32_16x16x32_bf16 v[32:35], v[146:149], v[178:181], v[32:35]
	v_mfma_f32_16x16x32_bf16 v[36:39], v[154:157], v[178:181], v[36:39]
	v_mfma_f32_16x16x32_bf16 v[76:79], v[146:149], v[186:189], v[76:79]
	v_mfma_f32_16x16x32_bf16 v[80:83], v[154:157], v[186:189], v[80:83]
	v_mfma_f32_16x16x32_bf16 v[92:95], v[146:149], v[194:197], v[92:95]
	v_mfma_f32_16x16x32_bf16 v[84:87], v[154:157], v[194:197], v[84:87]
	v_mfma_f32_16x16x32_bf16 v[108:111], v[146:149], v[202:205], v[108:111]
	v_mfma_f32_16x16x32_bf16 v[104:107], v[154:157], v[202:205], v[104:107]
	v_mfma_f32_16x16x32_bf16 v[32:35], v[150:153], v[182:185], v[32:35]
	v_mfma_f32_16x16x32_bf16 v[36:39], v[158:161], v[182:185], v[36:39]
	v_mfma_f32_16x16x32_bf16 v[76:79], v[150:153], v[190:193], v[76:79]
	v_mfma_f32_16x16x32_bf16 v[80:83], v[158:161], v[190:193], v[80:83]
	v_mfma_f32_16x16x32_bf16 v[92:95], v[150:153], v[198:201], v[92:95]
	v_mfma_f32_16x16x32_bf16 v[84:87], v[158:161], v[198:201], v[84:87]
	v_mfma_f32_16x16x32_bf16 v[108:111], v[150:153], v[206:209], v[108:111]
	v_mfma_f32_16x16x32_bf16 v[104:107], v[158:161], v[206:209], v[104:107]
	v_mfma_f32_16x16x32_bf16 v[40:43], v[162:165], v[178:181], v[40:43]
	v_mfma_f32_16x16x32_bf16 v[44:47], v[170:173], v[178:181], v[44:47]
	v_mfma_f32_16x16x32_bf16 v[68:71], v[162:165], v[186:189], v[68:71]
	v_mfma_f32_16x16x32_bf16 v[64:67], v[170:173], v[186:189], v[64:67]
	v_mfma_f32_16x16x32_bf16 v[60:63], v[162:165], v[194:197], v[60:63]
	v_mfma_f32_16x16x32_bf16 v[56:59], v[170:173], v[194:197], v[56:59]
	v_mfma_f32_16x16x32_bf16 v[100:103], v[162:165], v[202:205], v[100:103]
	v_mfma_f32_16x16x32_bf16 v[96:99], v[170:173], v[202:205], v[96:99]
	v_mfma_f32_16x16x32_bf16 v[40:43], v[166:169], v[182:185], v[40:43]
	v_mfma_f32_16x16x32_bf16 v[44:47], v[174:177], v[182:185], v[44:47]
	v_mfma_f32_16x16x32_bf16 v[68:71], v[166:169], v[190:193], v[68:71]
	v_mfma_f32_16x16x32_bf16 v[64:67], v[174:177], v[190:193], v[64:67]
	v_mfma_f32_16x16x32_bf16 v[60:63], v[166:169], v[198:201], v[60:63]
	v_mfma_f32_16x16x32_bf16 v[56:59], v[174:177], v[198:201], v[56:59]
	v_mfma_f32_16x16x32_bf16 v[100:103], v[166:169], v[206:209], v[100:103]
	v_mfma_f32_16x16x32_bf16 v[96:99], v[174:177], v[206:209], v[96:99]
	s_barrier
	s_setprio 0
	s_mov_b32 m0, s45
	v_lshl_add_u64 v[210:211], s[18:19], 0, v[130:131]
	s_add_u32 s54, s18, 0x200000
	ds_read_b128 v[178:181], v142 offset:16384
	ds_read_b128 v[182:185], v142 offset:17408
	ds_read_b128 v[186:189], v142 offset:18432
	ds_read_b128 v[190:193], v142 offset:19456
	ds_read_b128 v[194:197], v142 offset:20480
	ds_read_b128 v[198:201], v142 offset:21504
	ds_read_b128 v[202:205], v142 offset:22528
	ds_read_b128 v[206:209], v142 offset:23552
	global_load_lds_dwordx4 v130, s[18:19]
	v_lshl_add_u64 v[212:213], s[18:19], 0, v[134:135]
	s_mov_b32 m0, s46
	s_addc_u32 s55, s19, 0
	global_load_lds_dwordx4 v134, s[18:19]
	v_lshl_add_u64 v[214:215], s[54:55], 0, v[130:131]
	s_mov_b32 m0, s47
	s_nop 0
	global_load_lds_dwordx4 v130, s[54:55]
	v_lshl_add_u64 v[214:215], s[54:55], 0, v[134:135]
	s_mov_b32 m0, s48
	s_nop 0
	global_load_lds_dwordx4 v134, s[54:55]
	v_lshl_add_u64 v[214:215], s[20:21], 0, v[128:129]
	s_mov_b32 m0, s25
	s_nop 0
	global_load_lds_dwordx4 v128, s[20:21]
	v_lshl_add_u64 v[214:215], s[20:21], 0, v[132:133]
	s_mov_b32 m0, s26
	s_nop 0
	global_load_lds_dwordx4 v132, s[20:21]
	s_waitcnt vmcnt(8) lgkmcnt(0)
	s_setprio 1
	s_barrier
; #define PG8_MMA(ai, bj, At, Bt) do { __builtin_amdgcn_s_setprio(1); _Pragma("unroll") for (int m = 0; m < 4; ++m) _Pragma("unroll") for (int n = 0; n < 2; ++n) _Pragma("unroll") for (int k = 0; k < 2; ++k) \
;         acc[ai][bj][m][n] = __builtin_amdgcn_mfma_f32_16x16x32_bf16(Bt[n][k], At[m][k], acc[ai][bj][m][n], 0, 0, 0); __builtin_amdgcn_s_setprio(0); } while (0)
; template <class Epi, class Sched, bool ALIGN_EPI = false, bool SP2 = false, bool A_TILED = false>
; __device__ __forceinline__ void gemm_phase(PG8_LAS unsigned char* lds, const Gemm g, const Sched& S, const Epi& E, const int wave_s) {
;     ...
;         for (int t = PEEL ? 2 : 0; t < nt; t += 2) {
;             const bool last = (t == nt - 2);
;             const char* a1 = cA + (size_t)(t + 1) * kstepA;
;             const char* a2 = last ? nA : cA + (size_t)(t + 2) * kstepA; const char* b2 = last ? nB : cB + (size_t)(t + 2) * kstep;
;             const char* a3 = a2 + kstepA; const char* b3 = b2 + kstep;
;             if (last && has_next) S.a_ready(nxt);
;             if constexpr (SP2) {
;             PG8_ITER(PG8_MMA)
	v_mfma_f32_16x16x32_bf16 v[124:127], v[146:149], v[178:181], v[124:127]
	v_mfma_f32_16x16x32_bf16 v[120:123], v[154:157], v[178:181], v[120:123]
	v_mfma_f32_16x16x32_bf16 v[88:91], v[146:149], v[186:189], v[88:91]
	v_mfma_f32_16x16x32_bf16 v[72:75], v[154:157], v[186:189], v[72:75]
	v_mfma_f32_16x16x32_bf16 v[28:31], v[146:149], v[194:197], v[28:31]
	v_mfma_f32_16x16x32_bf16 v[24:27], v[154:157], v[194:197], v[24:27]
	v_mfma_f32_16x16x32_bf16 v[12:15], v[146:149], v[202:205], v[12:15]
	v_mfma_f32_16x16x32_bf16 v[8:11], v[154:157], v[202:205], v[8:11]
	v_mfma_f32_16x16x32_bf16 v[124:127], v[150:153], v[182:185], v[124:127]
	v_mfma_f32_16x16x32_bf16 v[120:123], v[158:161], v[182:185], v[120:123]
	v_mfma_f32_16x16x32_bf16 v[88:91], v[150:153], v[190:193], v[88:91]
	v_mfma_f32_16x16x32_bf16 v[72:75], v[158:161], v[190:193], v[72:75]
	v_mfma_f32_16x16x32_bf16 v[28:31], v[150:153], v[198:201], v[28:31]
	v_mfma_f32_16x16x32_bf16 v[24:27], v[158:161], v[198:201], v[24:27]
	v_mfma_f32_16x16x32_bf16 v[12:15], v[150:153], v[206:209], v[12:15]
	v_mfma_f32_16x16x32_bf16 v[8:11], v[158:161], v[206:209], v[8:11]
	v_mfma_f32_16x16x32_bf16 v[116:119], v[162:165], v[178:181], v[116:119]
	v_mfma_f32_16x16x32_bf16 v[112:115], v[170:173], v[178:181], v[112:115]
	v_mfma_f32_16x16x32_bf16 v[52:55], v[162:165], v[186:189], v[52:55]
	v_mfma_f32_16x16x32_bf16 v[48:51], v[170:173], v[186:189], v[48:51]
	v_mfma_f32_16x16x32_bf16 v[20:23], v[162:165], v[194:197], v[20:23]
	v_mfma_f32_16x16x32_bf16 v[16:19], v[170:173], v[194:197], v[16:19]
	v_mfma_f32_16x16x32_bf16 v[4:7], v[162:165], v[202:205], v[4:7]
	v_mfma_f32_16x16x32_bf16 v[0:3], v[170:173], v[202:205], v[0:3]
	v_mfma_f32_16x16x32_bf16 v[116:119], v[166:169], v[182:185], v[116:119]
	v_mfma_f32_16x16x32_bf16 v[112:115], v[174:177], v[182:185], v[112:115]
	v_mfma_f32_16x16x32_bf16 v[52:55], v[166:169], v[190:193], v[52:55]
	v_mfma_f32_16x16x32_bf16 v[48:51], v[174:177], v[190:193], v[48:51]
	v_mfma_f32_16x16x32_bf16 v[20:23], v[166:169], v[198:201], v[20:23]
	v_mfma_f32_16x16x32_bf16 v[16:19], v[174:177], v[198:201], v[16:19]
	v_mfma_f32_16x16x32_bf16 v[4:7], v[166:169], v[206:209], v[4:7]
	v_mfma_f32_16x16x32_bf16 v[0:3], v[174:177], v[206:209], v[0:3]
	s_barrier
	s_setprio 0
	ds_read_b128 v[146:149], v143
	ds_read_b128 v[150:153], v143 offset:1024
	ds_read_b128 v[154:157], v143 offset:2048
	ds_read_b128 v[158:161], v143 offset:3072
	ds_read_b128 v[162:165], v144
	ds_read_b128 v[166:169], v144 offset:1024
	ds_read_b128 v[170:173], v144 offset:2048
	ds_read_b128 v[174:177], v144 offset:3072
	s_add_u32 s20, s20, 0x4000
	s_addc_u32 s21, s21, 0
	s_mov_b32 m0, s27
	v_lshl_add_u64 v[214:215], s[20:21], 0, v[128:129]
	ds_read_b128 v[178:181], v142 offset:32768
	ds_read_b128 v[182:185], v142 offset:33792
	ds_read_b128 v[186:189], v142 offset:34816
	ds_read_b128 v[190:193], v142 offset:35840
	ds_read_b128 v[194:197], v142 offset:36864
	ds_read_b128 v[198:201], v142 offset:37888
	ds_read_b128 v[202:205], v142 offset:38912
	ds_read_b128 v[206:209], v142 offset:39936
	global_load_lds_dwordx4 v128, s[20:21]
	v_lshl_add_u64 v[214:215], s[20:21], 0, v[132:133]
	s_mov_b32 m0, s34
	s_nop 0
	global_load_lds_dwordx4 v132, s[20:21]
	s_waitcnt vmcnt(8) lgkmcnt(0)
	s_setprio 1
	s_barrier
	v_mfma_f32_16x16x32_bf16 v[32:35], v[146:149], v[178:181], v[32:35]
	v_mfma_f32_16x16x32_bf16 v[36:39], v[154:157], v[178:181], v[36:39]
	v_mfma_f32_16x16x32_bf16 v[76:79], v[146:149], v[186:189], v[76:79]
	v_mfma_f32_16x16x32_bf16 v[80:83], v[154:157], v[186:189], v[80:83]
	v_mfma_f32_16x16x32_bf16 v[92:95], v[146:149], v[194:197], v[92:95]
	v_mfma_f32_16x16x32_bf16 v[84:87], v[154:157], v[194:197], v[84:87]
	v_mfma_f32_16x16x32_bf16 v[108:111], v[146:149], v[202:205], v[108:111]
	v_mfma_f32_16x16x32_bf16 v[104:107], v[154:157], v[202:205], v[104:107]
	v_mfma_f32_16x16x32_bf16 v[32:35], v[150:153], v[182:185], v[32:35]
	v_mfma_f32_16x16x32_bf16 v[36:39], v[158:161], v[182:185], v[36:39]
	v_mfma_f32_16x16x32_bf16 v[76:79], v[150:153], v[190:193], v[76:79]
	v_mfma_f32_16x16x32_bf16 v[80:83], v[158:161], v[190:193], v[80:83]
	v_mfma_f32_16x16x32_bf16 v[92:95], v[150:153], v[198:201], v[92:95]
	v_mfma_f32_16x16x32_bf16 v[84:87], v[158:161], v[198:201], v[84:87]
	v_mfma_f32_16x16x32_bf16 v[108:111], v[150:153], v[206:209], v[108:111]
	v_mfma_f32_16x16x32_bf16 v[104:107], v[158:161], v[206:209], v[104:107]
	v_mfma_f32_16x16x32_bf16 v[40:43], v[162:165], v[178:181], v[40:43]
	v_mfma_f32_16x16x32_bf16 v[44:47], v[170:173], v[178:181], v[44:47]
	v_mfma_f32_16x16x32_bf16 v[68:71], v[162:165], v[186:189], v[68:71]
	v_mfma_f32_16x16x32_bf16 v[64:67], v[170:173], v[186:189], v[64:67]
	v_mfma_f32_16x16x32_bf16 v[60:63], v[162:165], v[194:197], v[60:63]
	v_mfma_f32_16x16x32_bf16 v[56:59], v[170:173], v[194:197], v[56:59]
	v_mfma_f32_16x16x32_bf16 v[100:103], v[162:165], v[202:205], v[100:103]
	v_mfma_f32_16x16x32_bf16 v[96:99], v[170:173], v[202:205], v[96:99]
	v_mfma_f32_16x16x32_bf16 v[40:43], v[166:169], v[182:185], v[40:43]
	v_mfma_f32_16x16x32_bf16 v[44:47], v[174:177], v[182:185], v[44:47]
	v_mfma_f32_16x16x32_bf16 v[68:71], v[166:169], v[190:193], v[68:71]
	v_mfma_f32_16x16x32_bf16 v[64:67], v[174:177], v[190:193], v[64:67]
	v_mfma_f32_16x16x32_bf16 v[60:63], v[166:169], v[198:201], v[60:63]
	v_mfma_f32_16x16x32_bf16 v[56:59], v[174:177], v[198:201], v[56:59]
	v_mfma_f32_16x16x32_bf16 v[100:103], v[166:169], v[206:209], v[100:103]
	v_mfma_f32_16x16x32_bf16 v[96:99], v[174:177], v[206:209], v[96:99]
	s_barrier
; template <class Epi, class Sched, bool ALIGN_EPI = false, bool SP2 = false, bool A_TILED = false>
; __device__ __forceinline__ void gemm_phase(PG8_LAS unsigned char* lds, const Gemm g, const Sched& S, const Epi& E, const int wave_s) {
;     ...
;         for (int t = PEEL ? 2 : 0; t < nt; t += 2) {
;             const bool last = (t == nt - 2);
;             const char* a1 = cA + (size_t)(t + 1) * kstepA;
;             const char* a2 = last ? nA : cA + (size_t)(t + 2) * kstepA; const char* b2 = last ? nB : cB + (size_t)(t + 2) * kstep;
;             const char* a3 = a2 + kstepA; const char* b3 = b2 + kstep;
;             if (last && has_next) S.a_ready(nxt);
;             if constexpr (SP2) {
;             PG8_ITER(PG8_MMA)
;             } else {
;             PG8_LDB(B0, 0, 0); PG8_SCHED; PG8_LDA(At, 0, 0); PG8_STAGE(PG8_SA(1, 1), a1 + hstepA, voffA);
;             PG8_WAIT_L(8); PG8_BAR; PG8_WAIT_L(0); PG8_MMA(0, 0, At, B0); PG8_BAR; PG8_SCHED;
;             PG8_LDB(B1, 0, 1); PG8_STAGE(PG8_SB(0, 0), b2, voffB);
;             PG8_BAR; PG8_WAIT_L(0); PG8_MMA(0, 1, At, B1); PG8_BAR;
;             PG8_LDA(At, 0, 1); PG8_STAGE(PG8_SA(0, 0), a2, voffA);
;             PG8_BAR; PG8_WAIT_L(0); PG8_MMA(1, 0, At, B0); PG8_BAR; PG8_SCHED;
;             PG8_STAGE(PG8_SB(0, 1), b2 + hstep, voffB);
;             PG8_WAIT_V(6); PG8_BAR; PG8_MMA(1, 1, At, B1); PG8_BAR;
;             PG8_LDB(B0, 1, 0); PG8_SCHED; PG8_LDA(At, 1, 0); PG8_STAGE(PG8_SA(0, 1), a2 + hstepA, voffA);
;             PG8_WAIT_L(8); PG8_BAR; PG8_WAIT_L(0); PG8_MMA(0, 0, At, B0); PG8_BAR; PG8_SCHED;
;             PG8_LDB(B1, 1, 1); PG8_STAGE(PG8_SB(1, 0), b3, voffB);
;             PG8_BAR; PG8_WAIT_L(0); PG8_MMA(0, 1, At, B1); PG8_BAR;
;             PG8_LDA(At, 1, 1); PG8_STAGE(PG8_SA(1, 0), a3, voffA);
;             PG8_BAR; PG8_WAIT_L(0); PG8_MMA(1, 0, At, B0); PG8_BAR; PG8_SCHED;
;             PG8_STAGE(PG8_SB(1, 1), b3 + hstep, voffB);
;             PG8_WAIT_V(6); PG8_BAR; PG8_MMA(1, 1, At, B1); PG8_BAR;
;             }
;         }
;         if constexpr (ALIGN_EPI) { if (wr == 0) PG8_BAR; }
;         if constexpr (!Epi::AFTER_DRAIN) { int te = tid_now(wave_s); asm volatile("" : "+v"(te));
;             E(acc, cur, wr, wc, te & 15, (te & 63) >> 4); S.done(cur); }
;         if (!has_next) break;
;         cur = nxt; cA = nA; cB = nB; ++ui;
;         if constexpr (ALIGN_EPI) { if (wr == 1) PG8_BAR; }
	s_setprio 0
	s_mov_b32 m0, s49
	v_lshl_add_u64 v[210:211], v[210:211], 0, s[12:13]
	s_add_u32 s18, s18, 0x200080
	ds_read_b128 v[178:181], v142 offset:49152
	ds_read_b128 v[182:185], v142 offset:50176
	ds_read_b128 v[186:189], v142 offset:51200
	ds_read_b128 v[190:193], v142 offset:52224
	ds_read_b128 v[194:197], v142 offset:53248
	ds_read_b128 v[198:201], v142 offset:54272
	ds_read_b128 v[202:205], v142 offset:55296
	ds_read_b128 v[206:209], v142 offset:56320
	global_load_lds_dwordx4 v[210:211], off
	v_lshl_add_u64 v[210:211], v[212:213], 0, s[12:13]
	s_mov_b32 m0, s50
	s_addc_u32 s19, s19, 0
	global_load_lds_dwordx4 v[210:211], off
	v_lshl_add_u64 v[210:211], s[18:19], 0, v[130:131]
	s_mov_b32 m0, s51
	s_nop 0
	global_load_lds_dwordx4 v130, s[18:19]
	v_lshl_add_u64 v[210:211], s[18:19], 0, v[134:135]
	s_mov_b32 m0, s52
	s_nop 0
	global_load_lds_dwordx4 v134, s[18:19]
	v_lshl_add_u64 v[210:211], s[16:17], 0, v[128:129]
	s_mov_b32 m0, s36
	s_nop 0
	global_load_lds_dwordx4 v128, s[16:17]
	v_lshl_add_u64 v[210:211], s[16:17], 0, v[132:133]
	s_mov_b32 m0, s37
	s_nop 0
	global_load_lds_dwordx4 v132, s[16:17]
	s_waitcnt vmcnt(8) lgkmcnt(0)
	s_setprio 1
	s_barrier
	v_mfma_f32_16x16x32_bf16 v[124:127], v[146:149], v[178:181], v[124:127]
	v_mfma_f32_16x16x32_bf16 v[120:123], v[154:157], v[178:181], v[120:123]
	v_mfma_f32_16x16x32_bf16 v[88:91], v[146:149], v[186:189], v[88:91]
	v_mfma_f32_16x16x32_bf16 v[72:75], v[154:157], v[186:189], v[72:75]
	v_mfma_f32_16x16x32_bf16 v[28:31], v[146:149], v[194:197], v[28:31]
	v_mfma_f32_16x16x32_bf16 v[24:27], v[154:157], v[194:197], v[24:27]
	v_mfma_f32_16x16x32_bf16 v[12:15], v[146:149], v[202:205], v[12:15]
	v_mfma_f32_16x16x32_bf16 v[8:11], v[154:157], v[202:205], v[8:11]
	v_mfma_f32_16x16x32_bf16 v[124:127], v[150:153], v[182:185], v[124:127]
	v_mfma_f32_16x16x32_bf16 v[120:123], v[158:161], v[182:185], v[120:123]
	v_mfma_f32_16x16x32_bf16 v[88:91], v[150:153], v[190:193], v[88:91]
	v_mfma_f32_16x16x32_bf16 v[72:75], v[158:161], v[190:193], v[72:75]
	v_mfma_f32_16x16x32_bf16 v[28:31], v[150:153], v[198:201], v[28:31]
	v_mfma_f32_16x16x32_bf16 v[24:27], v[158:161], v[198:201], v[24:27]
	v_mfma_f32_16x16x32_bf16 v[12:15], v[150:153], v[206:209], v[12:15]
	v_mfma_f32_16x16x32_bf16 v[8:11], v[158:161], v[206:209], v[8:11]
	v_mfma_f32_16x16x32_bf16 v[116:119], v[162:165], v[178:181], v[116:119]
	v_mfma_f32_16x16x32_bf16 v[112:115], v[170:173], v[178:181], v[112:115]
	v_mfma_f32_16x16x32_bf16 v[52:55], v[162:165], v[186:189], v[52:55]
	v_mfma_f32_16x16x32_bf16 v[48:51], v[170:173], v[186:189], v[48:51]
	v_mfma_f32_16x16x32_bf16 v[20:23], v[162:165], v[194:197], v[20:23]
	v_mfma_f32_16x16x32_bf16 v[16:19], v[170:173], v[194:197], v[16:19]
	v_mfma_f32_16x16x32_bf16 v[4:7], v[162:165], v[202:205], v[4:7]
	v_mfma_f32_16x16x32_bf16 v[0:3], v[170:173], v[202:205], v[0:3]
	v_mfma_f32_16x16x32_bf16 v[116:119], v[166:169], v[182:185], v[116:119]
	v_mfma_f32_16x16x32_bf16 v[112:115], v[174:177], v[182:185], v[112:115]
	v_mfma_f32_16x16x32_bf16 v[52:55], v[166:169], v[190:193], v[52:55]
	v_mfma_f32_16x16x32_bf16 v[48:51], v[174:177], v[190:193], v[48:51]
	v_mfma_f32_16x16x32_bf16 v[20:23], v[166:169], v[198:201], v[20:23]
	v_mfma_f32_16x16x32_bf16 v[16:19], v[174:177], v[198:201], v[16:19]
	v_mfma_f32_16x16x32_bf16 v[4:7], v[166:169], v[206:209], v[4:7]
	v_mfma_f32_16x16x32_bf16 v[0:3], v[174:177], v[206:209], v[0:3]
	s_barrier
	s_setprio 0
	s_add_i32 s42, s42, 2
	s_add_u32 s38, s38, 0x100
	s_addc_u32 s39, s39, 0
	s_add_u32 s40, s40, 0x10000
	s_addc_u32 s41, s41, 0
	v_lshl_add_u64 v[136:137], v[136:137], 0, s[14:15]
	s_cmpk_gt_u32 s42, 0x7d
	v_lshl_add_u64 v[138:139], v[138:139], 0, s[14:15]
	s_cbranch_scc0 .LBB0_3793
	s_waitcnt vmcnt(0)
	s_cmpk_lt_u32 s22, 0x100
	s_cbranch_scc0 .LBB0_3796
	s_barrier
